# GEMM k-tile staging groups moved later (after MFMA 4,8,12,16)
# baseline (speedup 1.0000x reference)
; #define MFMA(a, b, c) __builtin_amdgcn_mfma_f32_32x32x16_bf16((a), (b), (c), 0, 0, 0)
; template <int TM, int TN>
; DI void gemm_mainloop(const u16* __restrict__ A, long lda, const u16* __restrict__ Bt, long ldb, int K, char* smem,
;                       f32x16 (&acc)[TM][TN]) {
;     ...
;   const int nk = K / 64;
;   const int lrow = tid >> 3, lch = (tid & 7) * 8;
;   const u16* gA = A + (long)lrow * lda + lch;
;   const u16* gB = Bt + (long)lrow * ldb + lch;
;   const int soff = lrow * LD + lch;
;     ...
;   GEMM_GLOAD(0)
;   __syncthreads();
;   GEMM_SSTORE(0)
;   if (nk > 1) GEMM_GLOAD(64)
;   __syncthreads();
;   for (int kt = 0; kt < nk; kt++) {
;     const int buf = kt & 1;
;     const u16* cA = sA + buf * BM * LD + (wm * 32 * TM + r) * LD + h * 8;
;     const u16* cB = sB + buf * BN * LD + (wn * 32 * TN + r) * LD + h * 8;
;     bf16x8 af[TM], bfr[TN];
; #pragma unroll
;     for (int tm = 0; tm < TM; tm++) af[tm] = *(const bf16x8*)(cA + tm * 32 * LD);
; #pragma unroll
;     for (int tn = 0; tn < TN; tn++) bfr[tn] = *(const bf16x8*)(cB + tn * 32 * LD);
;     if (kt + 1 < nk) GEMM_SSTORE(buf ^ 1)
;     __builtin_amdgcn_sched_barrier(0);
;     __builtin_amdgcn_s_setprio(1);
; #pragma unroll
;     for (int tm = 0; tm < TM; tm++)
; #pragma unroll
;       for (int tn = 0; tn < TN; tn++) acc[tm][tn] = MFMA(af[tm], bfr[tn], acc[tm][tn]);
; #pragma unroll
;     for (int tm = 0; tm < TM; tm++) af[tm] = *(const bf16x8*)(cA + tm * 32 * LD + 16);
; #pragma unroll
;     for (int tn = 0; tn < TN; tn++) bfr[tn] = *(const bf16x8*)(cB + tn * 32 * LD + 16);
; #pragma unroll
;     for (int tm = 0; tm < TM; tm++)
; #pragma unroll
;       for (int tn = 0; tn < TN; tn++) acc[tm][tn] = MFMA(af[tm], bfr[tn], acc[tm][tn]);
;     __builtin_amdgcn_sched_group_barrier(0x8, 4, 0);
;     if (kt + 2 < nk) GEMM_GLOAD((kt + 2) * 64)
; template <class Epi>
; DI void phase_gemm128(const Sched& sc, const u16* A, long lda, const u16* Bt, long ldb, int K, int MT, int NT, int SN, char* smem, const Epi& epi) {
;     ...
;     for (int st = xg; st < nfull; st += 8) {
;       int sm = st / sng, sn = st % sng;
;       int mt = sm * SM + xi / SN, nt = sn * SN + xi % SN;
;       gemm_tile<2, 2>(A, lda, Bt, ldb, K, mt * 128, nt * 128, smem, epi);
.LBB0_146:
	s_mul_hi_u32 s4, s36, 0xcccccccd
	s_lshr_b32 s4, s4, 2
	s_mul_i32 s5, s4, 5
	s_sub_i32 s5, s36, s5
	s_lshl_b32 s37, s4, 11
	s_add_i32 s37, s37, s3
	s_lshl_b32 s4, s5, 9
	s_add_i32 s4, s4, s20
	s_mul_i32 s16, s37, 0x880
	s_mul_hi_i32 s5, s37, 0x880
	s_add_u32 s16, s8, s16
	v_mov_b32_e32 v1, v0
	s_addc_u32 s17, s9, s5
	s_mul_i32 s5, s4, 0x880
	v_lshlrev_b32_e32 v2, 3, v1
	v_ashrrev_i32_e32 v68, 3, v1
	v_and_b32_e32 v69, 56, v2
	v_mov_b64_e32 v[2:3], s[16:17]
	v_mad_i64_i32 v[2:3], s[16:17], v68, s21, v[2:3]
	v_lshlrev_b32_e32 v66, 1, v69
	v_lshl_add_u64 v[72:73], v[2:3], 0, v[66:67]
	s_ashr_i32 s19, s5, 31
	v_add_co_u32_e32 v70, vcc, s23, v72
	s_add_u32 s18, s10, s5
	s_nop 0
	v_addc_co_u32_e32 v71, vcc, 0, v73, vcc
	s_addc_u32 s19, s11, s19
	v_add_co_u32_e32 v74, vcc, s24, v72
	v_mov_b64_e32 v[2:3], s[18:19]
	s_nop 0
	v_addc_co_u32_e32 v75, vcc, 0, v73, vcc
	v_mad_i64_i32 v[18:19], s[16:17], v68, s21, v[2:3]
	v_add_co_u32_e32 v76, vcc, s25, v72
	v_lshl_add_u64 v[78:79], v[18:19], 0, v[66:67]
	s_nop 0
	v_addc_co_u32_e32 v77, vcc, 0, v73, vcc
	v_add_co_u32_e32 v80, vcc, s23, v78
	global_load_dwordx4 v[2:5], v[72:73], off
	s_nop 0
	v_addc_co_u32_e32 v81, vcc, 0, v79, vcc
	v_add_co_u32_e32 v82, vcc, s24, v78
	global_load_dwordx4 v[6:9], v[70:71], off
	s_nop 0
	v_addc_co_u32_e32 v83, vcc, 0, v79, vcc
	v_add_co_u32_e32 v84, vcc, s25, v78
	global_load_dwordx4 v[10:13], v[74:75], off
	s_nop 0
	v_addc_co_u32_e32 v85, vcc, 0, v79, vcc
	global_load_dwordx4 v[14:17], v[76:77], off
	global_load_dwordx4 v[18:21], v[78:79], off
	global_load_dwordx4 v[22:25], v[80:81], off
	global_load_dwordx4 v[26:29], v[82:83], off
	global_load_dwordx4 v[30:33], v[84:85], off
	s_barrier
	global_load_dwordx4 v[34:37], v[72:73], off offset:128
	global_load_dwordx4 v[38:41], v[70:71], off offset:128
	global_load_dwordx4 v[42:45], v[74:75], off offset:128
	global_load_dwordx4 v[46:49], v[76:77], off offset:128
	global_load_dwordx4 v[50:53], v[78:79], off offset:128
	global_load_dwordx4 v[54:57], v[80:81], off offset:128
	global_load_dwordx4 v[58:61], v[82:83], off offset:128
	global_load_dwordx4 v[62:65], v[84:85], off offset:128
	v_and_b32_e32 v66, 31, v1
	v_lshrrev_b32_e32 v86, 1, v1
	v_and_b32_e32 v1, 0x5f, v1
	v_mul_lo_u32 v68, v68, s22
	v_and_or_b32 v87, v86, s26, v66
	v_and_b32_e32 v86, 16, v86
	v_add_lshl_u32 v66, v68, v69, 1
	v_mad_u64_u32 v[68:69], s[16:17], v87, s27, v[86:87]
	v_mad_u32_u24 v1, v1, s27, v86
	v_add_u32_e32 v69, 0x9000, v66
	s_waitcnt vmcnt(15)
	ds_write_b128 v66, v[2:5]
	s_waitcnt vmcnt(14)
	ds_write_b128 v66, v[6:9] offset:4608
	s_waitcnt vmcnt(13)
	ds_write_b128 v66, v[10:13] offset:9216
	s_waitcnt vmcnt(12)
	ds_write_b128 v66, v[14:17] offset:13824
	s_waitcnt vmcnt(11)
	ds_write_b128 v66, v[18:21] offset:36864
	s_waitcnt vmcnt(10)
	ds_write_b128 v66, v[22:25] offset:41472
	s_waitcnt vmcnt(9)
	ds_write_b128 v66, v[26:29] offset:46080
	s_waitcnt vmcnt(8)
	ds_write_b128 v66, v[30:33] offset:50688
	s_waitcnt lgkmcnt(0)
	s_barrier
	ds_read_b128 v[2:5], v68
	ds_read_b128 v[18:21], v68 offset:4608
	ds_read_b128 v[6:9], v1 offset:36864
	ds_read_b128 v[22:25], v1 offset:41472
	s_waitcnt vmcnt(7)
	ds_write_b128 v66, v[34:37] offset:18432
	s_waitcnt vmcnt(6)
	ds_write_b128 v66, v[38:41] offset:23040
	s_waitcnt vmcnt(5)
	ds_write_b128 v66, v[42:45] offset:27648
	s_waitcnt vmcnt(4)
	ds_write_b128 v66, v[46:49] offset:32256
	s_waitcnt vmcnt(3)
	ds_write_b128 v66, v[50:53] offset:55296
	s_waitcnt vmcnt(2)
	ds_write_b128 v66, v[54:57] offset:59904
	s_waitcnt vmcnt(1)
	ds_write_b128 v66, v[58:61] offset:64512
	s_waitcnt vmcnt(0)
	ds_write_b128 v69, v[62:65] offset:32256
	s_setprio 1
	ds_read_b128 v[86:89], v68 offset:32
	s_waitcnt lgkmcnt(10)
	v_mfma_f32_32x32x16_bf16 v[34:49], v[2:5], v[6:9], 0
	ds_read_b128 v[90:93], v1 offset:36896
	ds_read_b128 v[94:97], v1 offset:41504
	ds_read_b128 v[98:101], v68 offset:4704
	global_load_dwordx4 v[102:105], v[70:71], off offset:256
	global_load_dwordx4 v[106:109], v[74:75], off offset:256
	global_load_dwordx4 v[110:113], v[76:77], off offset:256
	global_load_dwordx4 v[114:117], v[84:85], off offset:256
	s_waitcnt lgkmcnt(12)
	v_mfma_f32_32x32x16_bf16 v[50:65], v[2:5], v[22:25], 0
	global_load_dwordx4 v[118:121], v[82:83], off offset:256
	global_load_dwordx4 v[122:125], v[80:81], off offset:256
	global_load_dwordx4 v[140:143], v[72:73], off offset:256
	global_load_dwordx4 v[144:147], v[78:79], off offset:256
	s_waitcnt lgkmcnt(2)
	v_mfma_f32_32x32x16_bf16 v[34:49], v[86:89], v[90:93], v[34:49]
	s_waitcnt lgkmcnt(1)
	v_mfma_f32_32x32x16_bf16 v[50:65], v[86:89], v[94:97], v[50:65]
	ds_read_b128 v[86:89], v68 offset:4640
	v_mfma_f32_32x32x16_bf16 v[2:17], v[18:21], v[6:9], 0
	v_mfma_f32_32x32x16_bf16 v[18:33], v[18:21], v[22:25], 0
	s_waitcnt lgkmcnt(0)
	v_mfma_f32_32x32x16_bf16 v[2:17], v[86:89], v[90:93], v[2:17]
	ds_read_b128 v[90:93], v1 offset:36928
	v_mfma_f32_32x32x16_bf16 v[18:33], v[86:89], v[94:97], v[18:33]
	ds_read_b128 v[86:89], v68 offset:64
	ds_read_b128 v[94:97], v1 offset:41536
	s_waitcnt lgkmcnt(1)
	v_mfma_f32_32x32x16_bf16 v[34:49], v[86:89], v[90:93], v[34:49]
	s_waitcnt lgkmcnt(0)
	v_mfma_f32_32x32x16_bf16 v[50:65], v[86:89], v[94:97], v[50:65]
	ds_read_b128 v[86:89], v68 offset:4672
	s_waitcnt lgkmcnt(0)
	v_mfma_f32_32x32x16_bf16 v[2:17], v[86:89], v[90:93], v[2:17]
	ds_read_b128 v[90:93], v1 offset:36960
	v_mfma_f32_32x32x16_bf16 v[18:33], v[86:89], v[94:97], v[18:33]
	ds_read_b128 v[86:89], v68 offset:96
	ds_read_b128 v[94:97], v1 offset:41568
	s_waitcnt lgkmcnt(1)
	v_mfma_f32_32x32x16_bf16 v[34:49], v[86:89], v[90:93], v[34:49]
	s_waitcnt lgkmcnt(0)
	v_mfma_f32_32x32x16_bf16 v[50:65], v[86:89], v[94:97], v[50:65]
	v_mfma_f32_32x32x16_bf16 v[2:17], v[98:101], v[90:93], v[2:17]
	v_mfma_f32_32x32x16_bf16 v[18:33], v[98:101], v[94:97], v[18:33]
	s_setprio 0
	s_barrier
; #define MFMA(a, b, c) __builtin_amdgcn_mfma_f32_32x32x16_bf16((a), (b), (c), 0, 0, 0)
; template <int TM, int TN>
; DI void gemm_mainloop(const u16* __restrict__ A, long lda, const u16* __restrict__ Bt, long ldb, int K, char* smem,
;                       f32x16 (&acc)[TM][TN]) {
;     ...
;   for (int kt = 0; kt < nk; kt++) {
;     const int buf = kt & 1;
;     const u16* cA = sA + buf * BM * LD + (wm * 32 * TM + r) * LD + h * 8;
;     const u16* cB = sB + buf * BN * LD + (wn * 32 * TN + r) * LD + h * 8;
;     bf16x8 af[TM], bfr[TN];
; #pragma unroll
;     for (int tm = 0; tm < TM; tm++) af[tm] = *(const bf16x8*)(cA + tm * 32 * LD);
; #pragma unroll
;     for (int tn = 0; tn < TN; tn++) bfr[tn] = *(const bf16x8*)(cB + tn * 32 * LD);
;     if (kt + 1 < nk) GEMM_SSTORE(buf ^ 1)
;     __builtin_amdgcn_sched_barrier(0);
;     __builtin_amdgcn_s_setprio(1);
; #pragma unroll
;     for (int tm = 0; tm < TM; tm++)
; #pragma unroll
;       for (int tn = 0; tn < TN; tn++) acc[tm][tn] = MFMA(af[tm], bfr[tn], acc[tm][tn]);
; #pragma unroll
;     for (int tm = 0; tm < TM; tm++) af[tm] = *(const bf16x8*)(cA + tm * 32 * LD + 16);
; #pragma unroll
;     for (int tn = 0; tn < TN; tn++) bfr[tn] = *(const bf16x8*)(cB + tn * 32 * LD + 16);
; #pragma unroll
;     for (int tm = 0; tm < TM; tm++)
; #pragma unroll
;       for (int tn = 0; tn < TN; tn++) acc[tm][tn] = MFMA(af[tm], bfr[tn], acc[tm][tn]);
;     __builtin_amdgcn_sched_group_barrier(0x8, 4, 0);
;     if (kt + 2 < nk) GEMM_GLOAD((kt + 2) * 64)
; #pragma unroll
;     for (int ks = 2; ks < 4; ks++) {
; #pragma unroll
;       for (int tm = 0; tm < TM; tm++) af[tm] = *(const bf16x8*)(cA + tm * 32 * LD + ks * 16);
; #pragma unroll
;       for (int tn = 0; tn < TN; tn++) bfr[tn] = *(const bf16x8*)(cB + tn * 32 * LD + ks * 16);
; #pragma unroll
;       for (int tm = 0; tm < TM; tm++)
; #pragma unroll
;         for (int tn = 0; tn < TN; tn++) acc[tm][tn] = MFMA(af[tm], bfr[tn], acc[tm][tn]);
;     }
	ds_read_b128 v[94:97], v68 offset:18432
	ds_read_b128 v[98:101], v68 offset:23040
	ds_read_b128 v[126:129], v1 offset:55296
	ds_read_b128 v[130:133], v1 offset:59904
	s_setprio 1
	ds_read_b128 v[86:89], v68 offset:18464
	s_waitcnt lgkmcnt(2)
	v_mfma_f32_32x32x16_bf16 v[34:49], v[94:97], v[126:129], v[34:49]
	ds_read_b128 v[90:93], v1 offset:55328
	s_waitcnt lgkmcnt(2)
	v_mfma_f32_32x32x16_bf16 v[50:65], v[94:97], v[130:133], v[50:65]
	ds_read_b128 v[94:97], v1 offset:59936
	s_waitcnt lgkmcnt(1)
	v_mfma_f32_32x32x16_bf16 v[34:49], v[86:89], v[90:93], v[34:49]
	s_waitcnt lgkmcnt(0)
	v_mfma_f32_32x32x16_bf16 v[50:65], v[86:89], v[94:97], v[50:65]
	s_waitcnt vmcnt(1)
	ds_write_b128 v66, v[140:143]
	ds_write_b128 v66, v[102:105] offset:4608
	global_load_dwordx4 v[140:143], v[72:73], off offset:384
	global_load_dwordx4 v[102:105], v[70:71], off offset:384
	ds_read_b128 v[86:89], v68 offset:23072
	v_mfma_f32_32x32x16_bf16 v[2:17], v[98:101], v[126:129], v[2:17]
	v_mfma_f32_32x32x16_bf16 v[18:33], v[98:101], v[130:133], v[18:33]
	ds_read_b128 v[98:101], v68 offset:23136
	s_waitcnt lgkmcnt(1)
	v_mfma_f32_32x32x16_bf16 v[2:17], v[86:89], v[90:93], v[2:17]
	ds_read_b128 v[90:93], v1 offset:55360
	v_mfma_f32_32x32x16_bf16 v[18:33], v[86:89], v[94:97], v[18:33]
	ds_write_b128 v66, v[106:109] offset:9216
	ds_write_b128 v66, v[110:113] offset:13824
	global_load_dwordx4 v[106:109], v[74:75], off offset:384
	global_load_dwordx4 v[110:113], v[76:77], off offset:384
	ds_read_b128 v[86:89], v68 offset:18496
	ds_read_b128 v[94:97], v1 offset:59968
	s_waitcnt lgkmcnt(1)
	v_mfma_f32_32x32x16_bf16 v[34:49], v[86:89], v[90:93], v[34:49]
	s_waitcnt lgkmcnt(0)
	v_mfma_f32_32x32x16_bf16 v[50:65], v[86:89], v[94:97], v[50:65]
	ds_read_b128 v[86:89], v68 offset:23104
	s_waitcnt lgkmcnt(0)
	v_mfma_f32_32x32x16_bf16 v[2:17], v[86:89], v[90:93], v[2:17]
	ds_read_b128 v[90:93], v1 offset:55392
	v_mfma_f32_32x32x16_bf16 v[18:33], v[86:89], v[94:97], v[18:33]
	s_waitcnt vmcnt(4)
	ds_write_b128 v66, v[144:147] offset:36864
	ds_write_b128 v66, v[122:125] offset:41472
	global_load_dwordx4 v[144:147], v[78:79], off offset:384
	global_load_dwordx4 v[122:125], v[80:81], off offset:384
	ds_read_b128 v[86:89], v68 offset:18528
	ds_read_b128 v[94:97], v1 offset:60000
	s_waitcnt lgkmcnt(1)
	v_mfma_f32_32x32x16_bf16 v[34:49], v[86:89], v[90:93], v[34:49]
	s_waitcnt lgkmcnt(0)
	v_mfma_f32_32x32x16_bf16 v[50:65], v[86:89], v[94:97], v[50:65]
	v_mfma_f32_32x32x16_bf16 v[2:17], v[98:101], v[90:93], v[2:17]
	v_mfma_f32_32x32x16_bf16 v[18:33], v[98:101], v[94:97], v[18:33]
	ds_write_b128 v66, v[118:121] offset:46080
	ds_write_b128 v66, v[114:117] offset:50688
	global_load_dwordx4 v[118:121], v[82:83], off offset:384
	global_load_dwordx4 v[114:117], v[84:85], off offset:384
	s_setprio 0
	s_waitcnt lgkmcnt(0)
	s_barrier
	ds_read_b128 v[94:97], v68
	ds_read_b128 v[98:101], v68 offset:4608
	ds_read_b128 v[126:129], v1 offset:36864
	ds_read_b128 v[130:133], v1 offset:41472
	s_setprio 1
	ds_read_b128 v[86:89], v68 offset:32
	s_waitcnt lgkmcnt(2)
	v_mfma_f32_32x32x16_bf16 v[34:49], v[94:97], v[126:129], v[34:49]
	ds_read_b128 v[90:93], v1 offset:36896
	s_waitcnt lgkmcnt(2)
	v_mfma_f32_32x32x16_bf16 v[50:65], v[94:97], v[130:133], v[50:65]
	ds_read_b128 v[94:97], v1 offset:41504
	s_waitcnt lgkmcnt(1)
	v_mfma_f32_32x32x16_bf16 v[34:49], v[86:89], v[90:93], v[34:49]
	s_waitcnt lgkmcnt(0)
	v_mfma_f32_32x32x16_bf16 v[50:65], v[86:89], v[94:97], v[50:65]
	s_waitcnt vmcnt(7)
	ds_write_b128 v66, v[140:143] offset:18432
	s_waitcnt vmcnt(6)
	ds_write_b128 v66, v[102:105] offset:23040
	global_load_dwordx4 v[140:143], v[72:73], off offset:512
	global_load_dwordx4 v[102:105], v[70:71], off offset:512
	ds_read_b128 v[86:89], v68 offset:4640
	v_mfma_f32_32x32x16_bf16 v[2:17], v[98:101], v[126:129], v[2:17]
	v_mfma_f32_32x32x16_bf16 v[18:33], v[98:101], v[130:133], v[18:33]
	ds_read_b128 v[98:101], v68 offset:4704
	s_waitcnt lgkmcnt(1)
	v_mfma_f32_32x32x16_bf16 v[2:17], v[86:89], v[90:93], v[2:17]
	ds_read_b128 v[90:93], v1 offset:36928
	v_mfma_f32_32x32x16_bf16 v[18:33], v[86:89], v[94:97], v[18:33]
	s_waitcnt vmcnt(7)
	ds_write_b128 v66, v[106:109] offset:27648
	s_waitcnt vmcnt(6)
	ds_write_b128 v66, v[110:113] offset:32256
	global_load_dwordx4 v[106:109], v[74:75], off offset:512
	global_load_dwordx4 v[110:113], v[76:77], off offset:512
	ds_read_b128 v[86:89], v68 offset:64
	ds_read_b128 v[94:97], v1 offset:41536
	s_waitcnt lgkmcnt(1)
	v_mfma_f32_32x32x16_bf16 v[34:49], v[86:89], v[90:93], v[34:49]
	s_waitcnt lgkmcnt(0)
	v_mfma_f32_32x32x16_bf16 v[50:65], v[86:89], v[94:97], v[50:65]
	ds_read_b128 v[86:89], v68 offset:4672
	s_waitcnt lgkmcnt(0)
	v_mfma_f32_32x32x16_bf16 v[2:17], v[86:89], v[90:93], v[2:17]
	ds_read_b128 v[90:93], v1 offset:36960
	v_mfma_f32_32x32x16_bf16 v[18:33], v[86:89], v[94:97], v[18:33]
	s_waitcnt vmcnt(7)
	ds_write_b128 v66, v[144:147] offset:55296
	s_waitcnt vmcnt(6)
	ds_write_b128 v66, v[122:125] offset:59904
	global_load_dwordx4 v[144:147], v[78:79], off offset:512
	global_load_dwordx4 v[122:125], v[80:81], off offset:512
	ds_read_b128 v[86:89], v68 offset:96
	ds_read_b128 v[94:97], v1 offset:41568
	s_waitcnt lgkmcnt(1)
	v_mfma_f32_32x32x16_bf16 v[34:49], v[86:89], v[90:93], v[34:49]
	s_waitcnt lgkmcnt(0)
	v_mfma_f32_32x32x16_bf16 v[50:65], v[86:89], v[94:97], v[50:65]
	v_mfma_f32_32x32x16_bf16 v[2:17], v[98:101], v[90:93], v[2:17]
	v_mfma_f32_32x32x16_bf16 v[18:33], v[98:101], v[94:97], v[18:33]
	s_waitcnt vmcnt(7)
	ds_write_b128 v66, v[118:121] offset:64512
	s_waitcnt vmcnt(6)
	ds_write_b128 v69, v[114:117] offset:32256
	global_load_dwordx4 v[118:121], v[82:83], off offset:512
	global_load_dwordx4 v[114:117], v[84:85], off offset:512
	s_setprio 0
	s_waitcnt lgkmcnt(0)
	s_barrier
; #define MFMA(a, b, c) __builtin_amdgcn_mfma_f32_32x32x16_bf16((a), (b), (c), 0, 0, 0)
; template <int TM, int TN>
; DI void gemm_mainloop(const u16* __restrict__ A, long lda, const u16* __restrict__ Bt, long ldb, int K, char* smem,
;                       f32x16 (&acc)[TM][TN]) {
;     ...
;   for (int kt = 0; kt < nk; kt++) {
;     const int buf = kt & 1;
;     const u16* cA = sA + buf * BM * LD + (wm * 32 * TM + r) * LD + h * 8;
;     const u16* cB = sB + buf * BN * LD + (wn * 32 * TN + r) * LD + h * 8;
;     bf16x8 af[TM], bfr[TN];
; #pragma unroll
;     for (int tm = 0; tm < TM; tm++) af[tm] = *(const bf16x8*)(cA + tm * 32 * LD);
; #pragma unroll
;     for (int tn = 0; tn < TN; tn++) bfr[tn] = *(const bf16x8*)(cB + tn * 32 * LD);
;     if (kt + 1 < nk) GEMM_SSTORE(buf ^ 1)
;     __builtin_amdgcn_sched_barrier(0);
;     __builtin_amdgcn_s_setprio(1);
; #pragma unroll
;     for (int tm = 0; tm < TM; tm++)
; #pragma unroll
;       for (int tn = 0; tn < TN; tn++) acc[tm][tn] = MFMA(af[tm], bfr[tn], acc[tm][tn]);
; #pragma unroll
;     for (int tm = 0; tm < TM; tm++) af[tm] = *(const bf16x8*)(cA + tm * 32 * LD + 16);
; #pragma unroll
;     for (int tn = 0; tn < TN; tn++) bfr[tn] = *(const bf16x8*)(cB + tn * 32 * LD + 16);
; #pragma unroll
;     for (int tm = 0; tm < TM; tm++)
; #pragma unroll
;       for (int tn = 0; tn < TN; tn++) acc[tm][tn] = MFMA(af[tm], bfr[tn], acc[tm][tn]);
;     __builtin_amdgcn_sched_group_barrier(0x8, 4, 0);
;     if (kt + 2 < nk) GEMM_GLOAD((kt + 2) * 64)
; #pragma unroll
;     for (int ks = 2; ks < 4; ks++) {
; #pragma unroll
;       for (int tm = 0; tm < TM; tm++) af[tm] = *(const bf16x8*)(cA + tm * 32 * LD + ks * 16);
; #pragma unroll
;       for (int tn = 0; tn < TN; tn++) bfr[tn] = *(const bf16x8*)(cB + tn * 32 * LD + ks * 16);
; #pragma unroll
;       for (int tm = 0; tm < TM; tm++)
; #pragma unroll
;         for (int tn = 0; tn < TN; tn++) acc[tm][tn] = MFMA(af[tm], bfr[tn], acc[tm][tn]);
;     }
	ds_read_b128 v[94:97], v68 offset:18432
	ds_read_b128 v[98:101], v68 offset:23040
	ds_read_b128 v[126:129], v1 offset:55296
	ds_read_b128 v[130:133], v1 offset:59904
	s_setprio 1
	ds_read_b128 v[86:89], v68 offset:18464
	s_waitcnt lgkmcnt(2)
	v_mfma_f32_32x32x16_bf16 v[34:49], v[94:97], v[126:129], v[34:49]
	ds_read_b128 v[90:93], v1 offset:55328
	s_waitcnt lgkmcnt(2)
	v_mfma_f32_32x32x16_bf16 v[50:65], v[94:97], v[130:133], v[50:65]
	ds_read_b128 v[94:97], v1 offset:59936
	s_waitcnt lgkmcnt(1)
	v_mfma_f32_32x32x16_bf16 v[34:49], v[86:89], v[90:93], v[34:49]
	s_waitcnt lgkmcnt(0)
	v_mfma_f32_32x32x16_bf16 v[50:65], v[86:89], v[94:97], v[50:65]
	s_waitcnt vmcnt(7)
	ds_write_b128 v66, v[140:143]
	s_waitcnt vmcnt(6)
	ds_write_b128 v66, v[102:105] offset:4608
	global_load_dwordx4 v[140:143], v[72:73], off offset:640
	global_load_dwordx4 v[102:105], v[70:71], off offset:640
	ds_read_b128 v[86:89], v68 offset:23072
	v_mfma_f32_32x32x16_bf16 v[2:17], v[98:101], v[126:129], v[2:17]
	v_mfma_f32_32x32x16_bf16 v[18:33], v[98:101], v[130:133], v[18:33]
	ds_read_b128 v[98:101], v68 offset:23136
	s_waitcnt lgkmcnt(1)
	v_mfma_f32_32x32x16_bf16 v[2:17], v[86:89], v[90:93], v[2:17]
	ds_read_b128 v[90:93], v1 offset:55360
	v_mfma_f32_32x32x16_bf16 v[18:33], v[86:89], v[94:97], v[18:33]
	s_waitcnt vmcnt(7)
	ds_write_b128 v66, v[106:109] offset:9216
	s_waitcnt vmcnt(6)
	ds_write_b128 v66, v[110:113] offset:13824
	global_load_dwordx4 v[106:109], v[74:75], off offset:640
	global_load_dwordx4 v[110:113], v[76:77], off offset:640
	ds_read_b128 v[86:89], v68 offset:18496
	ds_read_b128 v[94:97], v1 offset:59968
	s_waitcnt lgkmcnt(1)
	v_mfma_f32_32x32x16_bf16 v[34:49], v[86:89], v[90:93], v[34:49]
	s_waitcnt lgkmcnt(0)
	v_mfma_f32_32x32x16_bf16 v[50:65], v[86:89], v[94:97], v[50:65]
	ds_read_b128 v[86:89], v68 offset:23104
	s_waitcnt lgkmcnt(0)
	v_mfma_f32_32x32x16_bf16 v[2:17], v[86:89], v[90:93], v[2:17]
	ds_read_b128 v[90:93], v1 offset:55392
	v_mfma_f32_32x32x16_bf16 v[18:33], v[86:89], v[94:97], v[18:33]
	s_waitcnt vmcnt(7)
	ds_write_b128 v66, v[144:147] offset:36864
	s_waitcnt vmcnt(6)
	ds_write_b128 v66, v[122:125] offset:41472
	global_load_dwordx4 v[144:147], v[78:79], off offset:640
	global_load_dwordx4 v[122:125], v[80:81], off offset:640
	ds_read_b128 v[86:89], v68 offset:18528
	ds_read_b128 v[94:97], v1 offset:60000
	s_waitcnt lgkmcnt(1)
	v_mfma_f32_32x32x16_bf16 v[34:49], v[86:89], v[90:93], v[34:49]
	s_waitcnt lgkmcnt(0)
	v_mfma_f32_32x32x16_bf16 v[50:65], v[86:89], v[94:97], v[50:65]
	v_mfma_f32_32x32x16_bf16 v[2:17], v[98:101], v[90:93], v[2:17]
	v_mfma_f32_32x32x16_bf16 v[18:33], v[98:101], v[94:97], v[18:33]
	s_waitcnt vmcnt(7)
	ds_write_b128 v66, v[118:121] offset:46080
	s_waitcnt vmcnt(6)
	ds_write_b128 v66, v[114:117] offset:50688
	global_load_dwordx4 v[118:121], v[82:83], off offset:640
	global_load_dwordx4 v[114:117], v[84:85], off offset:640
	s_setprio 0
	s_waitcnt lgkmcnt(0)
	s_barrier
	ds_read_b128 v[94:97], v68
	ds_read_b128 v[98:101], v68 offset:4608
	ds_read_b128 v[126:129], v1 offset:36864
	ds_read_b128 v[130:133], v1 offset:41472
	s_setprio 1
	ds_read_b128 v[86:89], v68 offset:32
	s_waitcnt lgkmcnt(2)
	v_mfma_f32_32x32x16_bf16 v[34:49], v[94:97], v[126:129], v[34:49]
	ds_read_b128 v[90:93], v1 offset:36896
	s_waitcnt lgkmcnt(2)
	v_mfma_f32_32x32x16_bf16 v[50:65], v[94:97], v[130:133], v[50:65]
	ds_read_b128 v[94:97], v1 offset:41504
	s_waitcnt lgkmcnt(1)
	v_mfma_f32_32x32x16_bf16 v[34:49], v[86:89], v[90:93], v[34:49]
	s_waitcnt lgkmcnt(0)
	v_mfma_f32_32x32x16_bf16 v[50:65], v[86:89], v[94:97], v[50:65]
	s_waitcnt vmcnt(7)
	ds_write_b128 v66, v[140:143] offset:18432
	s_waitcnt vmcnt(6)
	ds_write_b128 v66, v[102:105] offset:23040
	global_load_dwordx4 v[140:143], v[72:73], off offset:768
	global_load_dwordx4 v[102:105], v[70:71], off offset:768
	ds_read_b128 v[86:89], v68 offset:4640
	v_mfma_f32_32x32x16_bf16 v[2:17], v[98:101], v[126:129], v[2:17]
	v_mfma_f32_32x32x16_bf16 v[18:33], v[98:101], v[130:133], v[18:33]
	ds_read_b128 v[98:101], v68 offset:4704
	s_waitcnt lgkmcnt(1)
	v_mfma_f32_32x32x16_bf16 v[2:17], v[86:89], v[90:93], v[2:17]
	ds_read_b128 v[90:93], v1 offset:36928
	v_mfma_f32_32x32x16_bf16 v[18:33], v[86:89], v[94:97], v[18:33]
	s_waitcnt vmcnt(7)
	ds_write_b128 v66, v[106:109] offset:27648
	s_waitcnt vmcnt(6)
	ds_write_b128 v66, v[110:113] offset:32256
	global_load_dwordx4 v[106:109], v[74:75], off offset:768
	global_load_dwordx4 v[110:113], v[76:77], off offset:768
	ds_read_b128 v[86:89], v68 offset:64
	ds_read_b128 v[94:97], v1 offset:41536
	s_waitcnt lgkmcnt(1)
	v_mfma_f32_32x32x16_bf16 v[34:49], v[86:89], v[90:93], v[34:49]
	s_waitcnt lgkmcnt(0)
	v_mfma_f32_32x32x16_bf16 v[50:65], v[86:89], v[94:97], v[50:65]
	ds_read_b128 v[86:89], v68 offset:4672
	s_waitcnt lgkmcnt(0)
	v_mfma_f32_32x32x16_bf16 v[2:17], v[86:89], v[90:93], v[2:17]
	ds_read_b128 v[90:93], v1 offset:36960
	v_mfma_f32_32x32x16_bf16 v[18:33], v[86:89], v[94:97], v[18:33]
	s_waitcnt vmcnt(7)
	ds_write_b128 v66, v[144:147] offset:55296
	s_waitcnt vmcnt(6)
	ds_write_b128 v66, v[122:125] offset:59904
	global_load_dwordx4 v[144:147], v[78:79], off offset:768
	global_load_dwordx4 v[122:125], v[80:81], off offset:768
	ds_read_b128 v[86:89], v68 offset:96
	ds_read_b128 v[94:97], v1 offset:41568
	s_waitcnt lgkmcnt(1)
	v_mfma_f32_32x32x16_bf16 v[34:49], v[86:89], v[90:93], v[34:49]
	s_waitcnt lgkmcnt(0)
	v_mfma_f32_32x32x16_bf16 v[50:65], v[86:89], v[94:97], v[50:65]
	v_mfma_f32_32x32x16_bf16 v[2:17], v[98:101], v[90:93], v[2:17]
	v_mfma_f32_32x32x16_bf16 v[18:33], v[98:101], v[94:97], v[18:33]
	s_waitcnt vmcnt(7)
	ds_write_b128 v66, v[118:121] offset:64512
	s_waitcnt vmcnt(6)
	ds_write_b128 v69, v[114:117] offset:32256
	global_load_dwordx4 v[118:121], v[82:83], off offset:768
	global_load_dwordx4 v[114:117], v[84:85], off offset:768
	s_setprio 0
	s_waitcnt lgkmcnt(0)
	s_barrier
; #define MFMA(a, b, c) __builtin_amdgcn_mfma_f32_32x32x16_bf16((a), (b), (c), 0, 0, 0)
; template <int TM, int TN>
; DI void gemm_mainloop(const u16* __restrict__ A, long lda, const u16* __restrict__ Bt, long ldb, int K, char* smem,
;                       f32x16 (&acc)[TM][TN]) {
;     ...
;   for (int kt = 0; kt < nk; kt++) {
;     const int buf = kt & 1;
;     const u16* cA = sA + buf * BM * LD + (wm * 32 * TM + r) * LD + h * 8;
;     const u16* cB = sB + buf * BN * LD + (wn * 32 * TN + r) * LD + h * 8;
;     bf16x8 af[TM], bfr[TN];
; #pragma unroll
;     for (int tm = 0; tm < TM; tm++) af[tm] = *(const bf16x8*)(cA + tm * 32 * LD);
; #pragma unroll
;     for (int tn = 0; tn < TN; tn++) bfr[tn] = *(const bf16x8*)(cB + tn * 32 * LD);
;     if (kt + 1 < nk) GEMM_SSTORE(buf ^ 1)
;     __builtin_amdgcn_sched_barrier(0);
;     __builtin_amdgcn_s_setprio(1);
; #pragma unroll
;     for (int tm = 0; tm < TM; tm++)
; #pragma unroll
;       for (int tn = 0; tn < TN; tn++) acc[tm][tn] = MFMA(af[tm], bfr[tn], acc[tm][tn]);
; #pragma unroll
;     for (int tm = 0; tm < TM; tm++) af[tm] = *(const bf16x8*)(cA + tm * 32 * LD + 16);
; #pragma unroll
;     for (int tn = 0; tn < TN; tn++) bfr[tn] = *(const bf16x8*)(cB + tn * 32 * LD + 16);
; #pragma unroll
;     for (int tm = 0; tm < TM; tm++)
; #pragma unroll
;       for (int tn = 0; tn < TN; tn++) acc[tm][tn] = MFMA(af[tm], bfr[tn], acc[tm][tn]);
;     __builtin_amdgcn_sched_group_barrier(0x8, 4, 0);
;     if (kt + 2 < nk) GEMM_GLOAD((kt + 2) * 64)
; #pragma unroll
;     for (int ks = 2; ks < 4; ks++) {
; #pragma unroll
;       for (int tm = 0; tm < TM; tm++) af[tm] = *(const bf16x8*)(cA + tm * 32 * LD + ks * 16);
; #pragma unroll
;       for (int tn = 0; tn < TN; tn++) bfr[tn] = *(const bf16x8*)(cB + tn * 32 * LD + ks * 16);
; #pragma unroll
;       for (int tm = 0; tm < TM; tm++)
; #pragma unroll
;         for (int tn = 0; tn < TN; tn++) acc[tm][tn] = MFMA(af[tm], bfr[tn], acc[tm][tn]);
;     }
	ds_read_b128 v[94:97], v68 offset:18432
	ds_read_b128 v[98:101], v68 offset:23040
	ds_read_b128 v[126:129], v1 offset:55296
	ds_read_b128 v[130:133], v1 offset:59904
	s_setprio 1
	ds_read_b128 v[86:89], v68 offset:18464
	s_waitcnt lgkmcnt(2)
	v_mfma_f32_32x32x16_bf16 v[34:49], v[94:97], v[126:129], v[34:49]
	ds_read_b128 v[90:93], v1 offset:55328
	s_waitcnt lgkmcnt(2)
	v_mfma_f32_32x32x16_bf16 v[50:65], v[94:97], v[130:133], v[50:65]
	ds_read_b128 v[94:97], v1 offset:59936
	s_waitcnt lgkmcnt(1)
	v_mfma_f32_32x32x16_bf16 v[34:49], v[86:89], v[90:93], v[34:49]
	s_waitcnt lgkmcnt(0)
	v_mfma_f32_32x32x16_bf16 v[50:65], v[86:89], v[94:97], v[50:65]
	s_waitcnt vmcnt(7)
	ds_write_b128 v66, v[140:143]
	s_waitcnt vmcnt(6)
	ds_write_b128 v66, v[102:105] offset:4608
	global_load_dwordx4 v[140:143], v[72:73], off offset:896
	global_load_dwordx4 v[102:105], v[70:71], off offset:896
	ds_read_b128 v[86:89], v68 offset:23072
	v_mfma_f32_32x32x16_bf16 v[2:17], v[98:101], v[126:129], v[2:17]
	v_mfma_f32_32x32x16_bf16 v[18:33], v[98:101], v[130:133], v[18:33]
	ds_read_b128 v[98:101], v68 offset:23136
	s_waitcnt lgkmcnt(1)
	v_mfma_f32_32x32x16_bf16 v[2:17], v[86:89], v[90:93], v[2:17]
	ds_read_b128 v[90:93], v1 offset:55360
	v_mfma_f32_32x32x16_bf16 v[18:33], v[86:89], v[94:97], v[18:33]
	s_waitcnt vmcnt(7)
	ds_write_b128 v66, v[106:109] offset:9216
	s_waitcnt vmcnt(6)
	ds_write_b128 v66, v[110:113] offset:13824
	global_load_dwordx4 v[106:109], v[74:75], off offset:896
	global_load_dwordx4 v[110:113], v[76:77], off offset:896
	ds_read_b128 v[86:89], v68 offset:18496
	ds_read_b128 v[94:97], v1 offset:59968
	s_waitcnt lgkmcnt(1)
	v_mfma_f32_32x32x16_bf16 v[34:49], v[86:89], v[90:93], v[34:49]
	s_waitcnt lgkmcnt(0)
	v_mfma_f32_32x32x16_bf16 v[50:65], v[86:89], v[94:97], v[50:65]
	ds_read_b128 v[86:89], v68 offset:23104
	s_waitcnt lgkmcnt(0)
	v_mfma_f32_32x32x16_bf16 v[2:17], v[86:89], v[90:93], v[2:17]
	ds_read_b128 v[90:93], v1 offset:55392
	v_mfma_f32_32x32x16_bf16 v[18:33], v[86:89], v[94:97], v[18:33]
	s_waitcnt vmcnt(7)
	ds_write_b128 v66, v[144:147] offset:36864
	s_waitcnt vmcnt(6)
	ds_write_b128 v66, v[122:125] offset:41472
	global_load_dwordx4 v[144:147], v[78:79], off offset:896
	global_load_dwordx4 v[122:125], v[80:81], off offset:896
	ds_read_b128 v[86:89], v68 offset:18528
	ds_read_b128 v[94:97], v1 offset:60000
	s_waitcnt lgkmcnt(1)
	v_mfma_f32_32x32x16_bf16 v[34:49], v[86:89], v[90:93], v[34:49]
	s_waitcnt lgkmcnt(0)
	v_mfma_f32_32x32x16_bf16 v[50:65], v[86:89], v[94:97], v[50:65]
	v_mfma_f32_32x32x16_bf16 v[2:17], v[98:101], v[90:93], v[2:17]
	v_mfma_f32_32x32x16_bf16 v[18:33], v[98:101], v[94:97], v[18:33]
	s_waitcnt vmcnt(7)
	ds_write_b128 v66, v[118:121] offset:46080
	s_waitcnt vmcnt(6)
	ds_write_b128 v66, v[114:117] offset:50688
	global_load_dwordx4 v[118:121], v[82:83], off offset:896
	global_load_dwordx4 v[114:117], v[84:85], off offset:896
	s_setprio 0
	s_waitcnt lgkmcnt(0)
	s_barrier
	ds_read_b128 v[94:97], v68
	ds_read_b128 v[98:101], v68 offset:4608
	ds_read_b128 v[126:129], v1 offset:36864
	ds_read_b128 v[130:133], v1 offset:41472
	s_setprio 1
	ds_read_b128 v[86:89], v68 offset:32
	s_waitcnt lgkmcnt(2)
	v_mfma_f32_32x32x16_bf16 v[34:49], v[94:97], v[126:129], v[34:49]
	ds_read_b128 v[90:93], v1 offset:36896
	s_waitcnt lgkmcnt(2)
	v_mfma_f32_32x32x16_bf16 v[50:65], v[94:97], v[130:133], v[50:65]
	ds_read_b128 v[94:97], v1 offset:41504
	s_waitcnt lgkmcnt(1)
	v_mfma_f32_32x32x16_bf16 v[34:49], v[86:89], v[90:93], v[34:49]
	s_waitcnt lgkmcnt(0)
	v_mfma_f32_32x32x16_bf16 v[50:65], v[86:89], v[94:97], v[50:65]
	s_waitcnt vmcnt(7)
	ds_write_b128 v66, v[140:143] offset:18432
	s_waitcnt vmcnt(6)
	ds_write_b128 v66, v[102:105] offset:23040
	global_load_dwordx4 v[140:143], v[72:73], off offset:1024
	global_load_dwordx4 v[102:105], v[70:71], off offset:1024
	ds_read_b128 v[86:89], v68 offset:4640
	v_mfma_f32_32x32x16_bf16 v[2:17], v[98:101], v[126:129], v[2:17]
	v_mfma_f32_32x32x16_bf16 v[18:33], v[98:101], v[130:133], v[18:33]
	ds_read_b128 v[98:101], v68 offset:4704
	s_waitcnt lgkmcnt(1)
	v_mfma_f32_32x32x16_bf16 v[2:17], v[86:89], v[90:93], v[2:17]
	ds_read_b128 v[90:93], v1 offset:36928
	v_mfma_f32_32x32x16_bf16 v[18:33], v[86:89], v[94:97], v[18:33]
	s_waitcnt vmcnt(7)
	ds_write_b128 v66, v[106:109] offset:27648
	s_waitcnt vmcnt(6)
	ds_write_b128 v66, v[110:113] offset:32256
	global_load_dwordx4 v[106:109], v[74:75], off offset:1024
	global_load_dwordx4 v[110:113], v[76:77], off offset:1024
	ds_read_b128 v[86:89], v68 offset:64
	ds_read_b128 v[94:97], v1 offset:41536
	s_waitcnt lgkmcnt(1)
	v_mfma_f32_32x32x16_bf16 v[34:49], v[86:89], v[90:93], v[34:49]
	s_waitcnt lgkmcnt(0)
	v_mfma_f32_32x32x16_bf16 v[50:65], v[86:89], v[94:97], v[50:65]
	ds_read_b128 v[86:89], v68 offset:4672
	s_waitcnt lgkmcnt(0)
	v_mfma_f32_32x32x16_bf16 v[2:17], v[86:89], v[90:93], v[2:17]
	ds_read_b128 v[90:93], v1 offset:36960
	v_mfma_f32_32x32x16_bf16 v[18:33], v[86:89], v[94:97], v[18:33]
	s_waitcnt vmcnt(7)
	ds_write_b128 v66, v[144:147] offset:55296
	s_waitcnt vmcnt(6)
	ds_write_b128 v66, v[122:125] offset:59904
	global_load_dwordx4 v[144:147], v[78:79], off offset:1024
	global_load_dwordx4 v[122:125], v[80:81], off offset:1024
	ds_read_b128 v[86:89], v68 offset:96
	ds_read_b128 v[94:97], v1 offset:41568
	s_waitcnt lgkmcnt(1)
	v_mfma_f32_32x32x16_bf16 v[34:49], v[86:89], v[90:93], v[34:49]
	s_waitcnt lgkmcnt(0)
	v_mfma_f32_32x32x16_bf16 v[50:65], v[86:89], v[94:97], v[50:65]
	v_mfma_f32_32x32x16_bf16 v[2:17], v[98:101], v[90:93], v[2:17]
	v_mfma_f32_32x32x16_bf16 v[18:33], v[98:101], v[94:97], v[18:33]
	s_waitcnt vmcnt(7)
	ds_write_b128 v66, v[118:121] offset:64512
	s_waitcnt vmcnt(6)
	ds_write_b128 v69, v[114:117] offset:32256
	global_load_dwordx4 v[118:121], v[82:83], off offset:1024
	global_load_dwordx4 v[114:117], v[84:85], off offset:1024
	s_setprio 0
	s_waitcnt lgkmcnt(0)
	s_barrier
; #define MFMA(a, b, c) __builtin_amdgcn_mfma_f32_32x32x16_bf16((a), (b), (c), 0, 0, 0)
; template <int TM, int TN>
; DI void gemm_mainloop(const u16* __restrict__ A, long lda, const u16* __restrict__ Bt, long ldb, int K, char* smem,
;                       f32x16 (&acc)[TM][TN]) {
;     ...
;   for (int kt = 0; kt < nk; kt++) {
;     const int buf = kt & 1;
;     const u16* cA = sA + buf * BM * LD + (wm * 32 * TM + r) * LD + h * 8;
;     const u16* cB = sB + buf * BN * LD + (wn * 32 * TN + r) * LD + h * 8;
;     bf16x8 af[TM], bfr[TN];
; #pragma unroll
;     for (int tm = 0; tm < TM; tm++) af[tm] = *(const bf16x8*)(cA + tm * 32 * LD);
; #pragma unroll
;     for (int tn = 0; tn < TN; tn++) bfr[tn] = *(const bf16x8*)(cB + tn * 32 * LD);
;     if (kt + 1 < nk) GEMM_SSTORE(buf ^ 1)
;     __builtin_amdgcn_sched_barrier(0);
;     __builtin_amdgcn_s_setprio(1);
; #pragma unroll
;     for (int tm = 0; tm < TM; tm++)
; #pragma unroll
;       for (int tn = 0; tn < TN; tn++) acc[tm][tn] = MFMA(af[tm], bfr[tn], acc[tm][tn]);
; #pragma unroll
;     for (int tm = 0; tm < TM; tm++) af[tm] = *(const bf16x8*)(cA + tm * 32 * LD + 16);
; #pragma unroll
;     for (int tn = 0; tn < TN; tn++) bfr[tn] = *(const bf16x8*)(cB + tn * 32 * LD + 16);
; #pragma unroll
;     for (int tm = 0; tm < TM; tm++)
; #pragma unroll
;       for (int tn = 0; tn < TN; tn++) acc[tm][tn] = MFMA(af[tm], bfr[tn], acc[tm][tn]);
;     __builtin_amdgcn_sched_group_barrier(0x8, 4, 0);
;     if (kt + 2 < nk) GEMM_GLOAD((kt + 2) * 64)
; #pragma unroll
;     for (int ks = 2; ks < 4; ks++) {
; #pragma unroll
;       for (int tm = 0; tm < TM; tm++) af[tm] = *(const bf16x8*)(cA + tm * 32 * LD + ks * 16);
; #pragma unroll
;       for (int tn = 0; tn < TN; tn++) bfr[tn] = *(const bf16x8*)(cB + tn * 32 * LD + ks * 16);
; #pragma unroll
;       for (int tm = 0; tm < TM; tm++)
; #pragma unroll
;         for (int tn = 0; tn < TN; tn++) acc[tm][tn] = MFMA(af[tm], bfr[tn], acc[tm][tn]);
;     }
	ds_read_b128 v[94:97], v68 offset:18432
	ds_read_b128 v[98:101], v68 offset:23040
	ds_read_b128 v[126:129], v1 offset:55296
	ds_read_b128 v[130:133], v1 offset:59904
	s_setprio 1
	ds_read_b128 v[86:89], v68 offset:18464
	s_waitcnt lgkmcnt(2)
	v_mfma_f32_32x32x16_bf16 v[34:49], v[94:97], v[126:129], v[34:49]
	ds_read_b128 v[90:93], v1 offset:55328
	s_waitcnt lgkmcnt(2)
	v_mfma_f32_32x32x16_bf16 v[50:65], v[94:97], v[130:133], v[50:65]
	ds_read_b128 v[94:97], v1 offset:59936
	s_waitcnt lgkmcnt(1)
	v_mfma_f32_32x32x16_bf16 v[34:49], v[86:89], v[90:93], v[34:49]
	s_waitcnt lgkmcnt(0)
	v_mfma_f32_32x32x16_bf16 v[50:65], v[86:89], v[94:97], v[50:65]
	s_waitcnt vmcnt(7)
	ds_write_b128 v66, v[140:143]
	s_waitcnt vmcnt(6)
	ds_write_b128 v66, v[102:105] offset:4608
	global_load_dwordx4 v[140:143], v[72:73], off offset:1152
	global_load_dwordx4 v[102:105], v[70:71], off offset:1152
	ds_read_b128 v[86:89], v68 offset:23072
	v_mfma_f32_32x32x16_bf16 v[2:17], v[98:101], v[126:129], v[2:17]
	v_mfma_f32_32x32x16_bf16 v[18:33], v[98:101], v[130:133], v[18:33]
	ds_read_b128 v[98:101], v68 offset:23136
	s_waitcnt lgkmcnt(1)
	v_mfma_f32_32x32x16_bf16 v[2:17], v[86:89], v[90:93], v[2:17]
	ds_read_b128 v[90:93], v1 offset:55360
	v_mfma_f32_32x32x16_bf16 v[18:33], v[86:89], v[94:97], v[18:33]
	s_waitcnt vmcnt(7)
	ds_write_b128 v66, v[106:109] offset:9216
	s_waitcnt vmcnt(6)
	ds_write_b128 v66, v[110:113] offset:13824
	global_load_dwordx4 v[106:109], v[74:75], off offset:1152
	global_load_dwordx4 v[110:113], v[76:77], off offset:1152
	ds_read_b128 v[86:89], v68 offset:18496
	ds_read_b128 v[94:97], v1 offset:59968
	s_waitcnt lgkmcnt(1)
	v_mfma_f32_32x32x16_bf16 v[34:49], v[86:89], v[90:93], v[34:49]
	s_waitcnt lgkmcnt(0)
	v_mfma_f32_32x32x16_bf16 v[50:65], v[86:89], v[94:97], v[50:65]
	ds_read_b128 v[86:89], v68 offset:23104
	s_waitcnt lgkmcnt(0)
	v_mfma_f32_32x32x16_bf16 v[2:17], v[86:89], v[90:93], v[2:17]
	ds_read_b128 v[90:93], v1 offset:55392
	v_mfma_f32_32x32x16_bf16 v[18:33], v[86:89], v[94:97], v[18:33]
	s_waitcnt vmcnt(7)
	ds_write_b128 v66, v[144:147] offset:36864
	s_waitcnt vmcnt(6)
	ds_write_b128 v66, v[122:125] offset:41472
	global_load_dwordx4 v[144:147], v[78:79], off offset:1152
	global_load_dwordx4 v[122:125], v[80:81], off offset:1152
	ds_read_b128 v[86:89], v68 offset:18528
	ds_read_b128 v[94:97], v1 offset:60000
	s_waitcnt lgkmcnt(1)
	v_mfma_f32_32x32x16_bf16 v[34:49], v[86:89], v[90:93], v[34:49]
	s_waitcnt lgkmcnt(0)
	v_mfma_f32_32x32x16_bf16 v[50:65], v[86:89], v[94:97], v[50:65]
	v_mfma_f32_32x32x16_bf16 v[2:17], v[98:101], v[90:93], v[2:17]
	v_mfma_f32_32x32x16_bf16 v[18:33], v[98:101], v[94:97], v[18:33]
	s_waitcnt vmcnt(7)
	ds_write_b128 v66, v[118:121] offset:46080
	s_waitcnt vmcnt(6)
	ds_write_b128 v66, v[114:117] offset:50688
	global_load_dwordx4 v[118:121], v[82:83], off offset:1152
	global_load_dwordx4 v[114:117], v[84:85], off offset:1152
	s_setprio 0
	s_waitcnt lgkmcnt(0)
	s_barrier
	ds_read_b128 v[94:97], v68
	ds_read_b128 v[98:101], v68 offset:4608
	ds_read_b128 v[126:129], v1 offset:36864
	ds_read_b128 v[130:133], v1 offset:41472
	s_setprio 1
	ds_read_b128 v[86:89], v68 offset:32
	s_waitcnt lgkmcnt(2)
	v_mfma_f32_32x32x16_bf16 v[34:49], v[94:97], v[126:129], v[34:49]
	ds_read_b128 v[90:93], v1 offset:36896
	s_waitcnt lgkmcnt(2)
	v_mfma_f32_32x32x16_bf16 v[50:65], v[94:97], v[130:133], v[50:65]
	ds_read_b128 v[94:97], v1 offset:41504
	s_waitcnt lgkmcnt(1)
	v_mfma_f32_32x32x16_bf16 v[34:49], v[86:89], v[90:93], v[34:49]
	s_waitcnt lgkmcnt(0)
	v_mfma_f32_32x32x16_bf16 v[50:65], v[86:89], v[94:97], v[50:65]
	s_waitcnt vmcnt(7)
	ds_write_b128 v66, v[140:143] offset:18432
	s_waitcnt vmcnt(6)
	ds_write_b128 v66, v[102:105] offset:23040
	global_load_dwordx4 v[140:143], v[72:73], off offset:1280
	global_load_dwordx4 v[102:105], v[70:71], off offset:1280
	ds_read_b128 v[86:89], v68 offset:4640
	v_mfma_f32_32x32x16_bf16 v[2:17], v[98:101], v[126:129], v[2:17]
	v_mfma_f32_32x32x16_bf16 v[18:33], v[98:101], v[130:133], v[18:33]
	ds_read_b128 v[98:101], v68 offset:4704
	s_waitcnt lgkmcnt(1)
	v_mfma_f32_32x32x16_bf16 v[2:17], v[86:89], v[90:93], v[2:17]
	ds_read_b128 v[90:93], v1 offset:36928
	v_mfma_f32_32x32x16_bf16 v[18:33], v[86:89], v[94:97], v[18:33]
	s_waitcnt vmcnt(7)
	ds_write_b128 v66, v[106:109] offset:27648
	s_waitcnt vmcnt(6)
	ds_write_b128 v66, v[110:113] offset:32256
	global_load_dwordx4 v[106:109], v[74:75], off offset:1280
	global_load_dwordx4 v[110:113], v[76:77], off offset:1280
	ds_read_b128 v[86:89], v68 offset:64
	ds_read_b128 v[94:97], v1 offset:41536
	s_waitcnt lgkmcnt(1)
	v_mfma_f32_32x32x16_bf16 v[34:49], v[86:89], v[90:93], v[34:49]
	s_waitcnt lgkmcnt(0)
	v_mfma_f32_32x32x16_bf16 v[50:65], v[86:89], v[94:97], v[50:65]
	ds_read_b128 v[86:89], v68 offset:4672
	s_waitcnt lgkmcnt(0)
	v_mfma_f32_32x32x16_bf16 v[2:17], v[86:89], v[90:93], v[2:17]
	ds_read_b128 v[90:93], v1 offset:36960
	v_mfma_f32_32x32x16_bf16 v[18:33], v[86:89], v[94:97], v[18:33]
	s_waitcnt vmcnt(7)
	ds_write_b128 v66, v[144:147] offset:55296
	s_waitcnt vmcnt(6)
	ds_write_b128 v66, v[122:125] offset:59904
	global_load_dwordx4 v[144:147], v[78:79], off offset:1280
	global_load_dwordx4 v[122:125], v[80:81], off offset:1280
	ds_read_b128 v[86:89], v68 offset:96
	ds_read_b128 v[94:97], v1 offset:41568
	s_waitcnt lgkmcnt(1)
	v_mfma_f32_32x32x16_bf16 v[34:49], v[86:89], v[90:93], v[34:49]
	s_waitcnt lgkmcnt(0)
	v_mfma_f32_32x32x16_bf16 v[50:65], v[86:89], v[94:97], v[50:65]
	v_mfma_f32_32x32x16_bf16 v[2:17], v[98:101], v[90:93], v[2:17]
	v_mfma_f32_32x32x16_bf16 v[18:33], v[98:101], v[94:97], v[18:33]
	s_waitcnt vmcnt(7)
	ds_write_b128 v66, v[118:121] offset:64512
	s_waitcnt vmcnt(6)
	ds_write_b128 v69, v[114:117] offset:32256
	global_load_dwordx4 v[118:121], v[82:83], off offset:1280
	global_load_dwordx4 v[114:117], v[84:85], off offset:1280
	s_setprio 0
	s_waitcnt lgkmcnt(0)
	s_barrier
; #define MFMA(a, b, c) __builtin_amdgcn_mfma_f32_32x32x16_bf16((a), (b), (c), 0, 0, 0)
; template <int TM, int TN>
; DI void gemm_mainloop(const u16* __restrict__ A, long lda, const u16* __restrict__ Bt, long ldb, int K, char* smem,
;                       f32x16 (&acc)[TM][TN]) {
;     ...
;   for (int kt = 0; kt < nk; kt++) {
;     const int buf = kt & 1;
;     const u16* cA = sA + buf * BM * LD + (wm * 32 * TM + r) * LD + h * 8;
;     const u16* cB = sB + buf * BN * LD + (wn * 32 * TN + r) * LD + h * 8;
;     bf16x8 af[TM], bfr[TN];
; #pragma unroll
;     for (int tm = 0; tm < TM; tm++) af[tm] = *(const bf16x8*)(cA + tm * 32 * LD);
; #pragma unroll
;     for (int tn = 0; tn < TN; tn++) bfr[tn] = *(const bf16x8*)(cB + tn * 32 * LD);
;     if (kt + 1 < nk) GEMM_SSTORE(buf ^ 1)
;     __builtin_amdgcn_sched_barrier(0);
;     __builtin_amdgcn_s_setprio(1);
; #pragma unroll
;     for (int tm = 0; tm < TM; tm++)
; #pragma unroll
;       for (int tn = 0; tn < TN; tn++) acc[tm][tn] = MFMA(af[tm], bfr[tn], acc[tm][tn]);
; #pragma unroll
;     for (int tm = 0; tm < TM; tm++) af[tm] = *(const bf16x8*)(cA + tm * 32 * LD + 16);
; #pragma unroll
;     for (int tn = 0; tn < TN; tn++) bfr[tn] = *(const bf16x8*)(cB + tn * 32 * LD + 16);
; #pragma unroll
;     for (int tm = 0; tm < TM; tm++)
; #pragma unroll
;       for (int tn = 0; tn < TN; tn++) acc[tm][tn] = MFMA(af[tm], bfr[tn], acc[tm][tn]);
;     __builtin_amdgcn_sched_group_barrier(0x8, 4, 0);
;     if (kt + 2 < nk) GEMM_GLOAD((kt + 2) * 64)
; #pragma unroll
;     for (int ks = 2; ks < 4; ks++) {
; #pragma unroll
;       for (int tm = 0; tm < TM; tm++) af[tm] = *(const bf16x8*)(cA + tm * 32 * LD + ks * 16);
; #pragma unroll
;       for (int tn = 0; tn < TN; tn++) bfr[tn] = *(const bf16x8*)(cB + tn * 32 * LD + ks * 16);
; #pragma unroll
;       for (int tm = 0; tm < TM; tm++)
; #pragma unroll
;         for (int tn = 0; tn < TN; tn++) acc[tm][tn] = MFMA(af[tm], bfr[tn], acc[tm][tn]);
;     }
;     __builtin_amdgcn_s_setprio(0);
;     __syncthreads();
;   }
	ds_read_b128 v[94:97], v68 offset:18432
	ds_read_b128 v[98:101], v68 offset:23040
	ds_read_b128 v[126:129], v1 offset:55296
	ds_read_b128 v[130:133], v1 offset:59904
	s_setprio 1
	ds_read_b128 v[86:89], v68 offset:18464
	s_waitcnt lgkmcnt(2)
	v_mfma_f32_32x32x16_bf16 v[34:49], v[94:97], v[126:129], v[34:49]
	ds_read_b128 v[90:93], v1 offset:55328
	s_waitcnt lgkmcnt(2)
	v_mfma_f32_32x32x16_bf16 v[50:65], v[94:97], v[130:133], v[50:65]
	ds_read_b128 v[94:97], v1 offset:59936
	s_waitcnt lgkmcnt(1)
	v_mfma_f32_32x32x16_bf16 v[34:49], v[86:89], v[90:93], v[34:49]
	s_waitcnt lgkmcnt(0)
	v_mfma_f32_32x32x16_bf16 v[50:65], v[86:89], v[94:97], v[50:65]
	s_waitcnt vmcnt(7)
	ds_write_b128 v66, v[140:143]
	s_waitcnt vmcnt(6)
	ds_write_b128 v66, v[102:105] offset:4608
	global_load_dwordx4 v[140:143], v[72:73], off offset:1408
	global_load_dwordx4 v[102:105], v[70:71], off offset:1408
	ds_read_b128 v[86:89], v68 offset:23072
	v_mfma_f32_32x32x16_bf16 v[2:17], v[98:101], v[126:129], v[2:17]
	v_mfma_f32_32x32x16_bf16 v[18:33], v[98:101], v[130:133], v[18:33]
	ds_read_b128 v[98:101], v68 offset:23136
	s_waitcnt lgkmcnt(1)
	v_mfma_f32_32x32x16_bf16 v[2:17], v[86:89], v[90:93], v[2:17]
	ds_read_b128 v[90:93], v1 offset:55360
	v_mfma_f32_32x32x16_bf16 v[18:33], v[86:89], v[94:97], v[18:33]
	s_waitcnt vmcnt(7)
	ds_write_b128 v66, v[106:109] offset:9216
	s_waitcnt vmcnt(6)
	ds_write_b128 v66, v[110:113] offset:13824
	global_load_dwordx4 v[106:109], v[74:75], off offset:1408
	global_load_dwordx4 v[110:113], v[76:77], off offset:1408
	ds_read_b128 v[86:89], v68 offset:18496
	ds_read_b128 v[94:97], v1 offset:59968
	s_waitcnt lgkmcnt(1)
	v_mfma_f32_32x32x16_bf16 v[34:49], v[86:89], v[90:93], v[34:49]
	s_waitcnt lgkmcnt(0)
	v_mfma_f32_32x32x16_bf16 v[50:65], v[86:89], v[94:97], v[50:65]
	ds_read_b128 v[86:89], v68 offset:23104
	s_waitcnt lgkmcnt(0)
	v_mfma_f32_32x32x16_bf16 v[2:17], v[86:89], v[90:93], v[2:17]
	ds_read_b128 v[90:93], v1 offset:55392
	v_mfma_f32_32x32x16_bf16 v[18:33], v[86:89], v[94:97], v[18:33]
	s_waitcnt vmcnt(7)
	ds_write_b128 v66, v[144:147] offset:36864
	s_waitcnt vmcnt(6)
	ds_write_b128 v66, v[122:125] offset:41472
	global_load_dwordx4 v[144:147], v[78:79], off offset:1408
	global_load_dwordx4 v[122:125], v[80:81], off offset:1408
	ds_read_b128 v[86:89], v68 offset:18528
	ds_read_b128 v[94:97], v1 offset:60000
	s_waitcnt lgkmcnt(1)
	v_mfma_f32_32x32x16_bf16 v[34:49], v[86:89], v[90:93], v[34:49]
	s_waitcnt lgkmcnt(0)
	v_mfma_f32_32x32x16_bf16 v[50:65], v[86:89], v[94:97], v[50:65]
	v_mfma_f32_32x32x16_bf16 v[2:17], v[98:101], v[90:93], v[2:17]
	v_mfma_f32_32x32x16_bf16 v[18:33], v[98:101], v[94:97], v[18:33]
	s_waitcnt vmcnt(7)
	ds_write_b128 v66, v[118:121] offset:46080
	s_waitcnt vmcnt(6)
	ds_write_b128 v66, v[114:117] offset:50688
	global_load_dwordx4 v[118:121], v[82:83], off offset:1408
	global_load_dwordx4 v[114:117], v[84:85], off offset:1408
	s_setprio 0
	s_waitcnt lgkmcnt(0)
	s_barrier
	ds_read_b128 v[94:97], v68
	ds_read_b128 v[98:101], v68 offset:4608
	ds_read_b128 v[126:129], v1 offset:36864
	ds_read_b128 v[130:133], v1 offset:41472
	s_setprio 1
	ds_read_b128 v[86:89], v68 offset:32
	s_waitcnt lgkmcnt(2)
	v_mfma_f32_32x32x16_bf16 v[34:49], v[94:97], v[126:129], v[34:49]
	ds_read_b128 v[90:93], v1 offset:36896
	s_waitcnt lgkmcnt(2)
	v_mfma_f32_32x32x16_bf16 v[50:65], v[94:97], v[130:133], v[50:65]
	ds_read_b128 v[94:97], v1 offset:41504
	s_waitcnt lgkmcnt(1)
	v_mfma_f32_32x32x16_bf16 v[34:49], v[86:89], v[90:93], v[34:49]
	s_waitcnt lgkmcnt(0)
	v_mfma_f32_32x32x16_bf16 v[50:65], v[86:89], v[94:97], v[50:65]
	s_waitcnt vmcnt(7)
	ds_write_b128 v66, v[140:143] offset:18432
	s_waitcnt vmcnt(6)
	ds_write_b128 v66, v[102:105] offset:23040
	global_load_dwordx4 v[140:143], v[72:73], off offset:1536
	global_load_dwordx4 v[102:105], v[70:71], off offset:1536
	ds_read_b128 v[86:89], v68 offset:4640
	v_mfma_f32_32x32x16_bf16 v[2:17], v[98:101], v[126:129], v[2:17]
	v_mfma_f32_32x32x16_bf16 v[18:33], v[98:101], v[130:133], v[18:33]
	ds_read_b128 v[98:101], v68 offset:4704
	s_waitcnt lgkmcnt(1)
	v_mfma_f32_32x32x16_bf16 v[2:17], v[86:89], v[90:93], v[2:17]
	ds_read_b128 v[90:93], v1 offset:36928
	v_mfma_f32_32x32x16_bf16 v[18:33], v[86:89], v[94:97], v[18:33]
	s_waitcnt vmcnt(7)
	ds_write_b128 v66, v[106:109] offset:27648
	s_waitcnt vmcnt(6)
	ds_write_b128 v66, v[110:113] offset:32256
	global_load_dwordx4 v[106:109], v[74:75], off offset:1536
	global_load_dwordx4 v[110:113], v[76:77], off offset:1536
	ds_read_b128 v[86:89], v68 offset:64
	ds_read_b128 v[94:97], v1 offset:41536
	s_waitcnt lgkmcnt(1)
	v_mfma_f32_32x32x16_bf16 v[34:49], v[86:89], v[90:93], v[34:49]
	s_waitcnt lgkmcnt(0)
	v_mfma_f32_32x32x16_bf16 v[50:65], v[86:89], v[94:97], v[50:65]
	ds_read_b128 v[86:89], v68 offset:4672
	s_waitcnt lgkmcnt(0)
	v_mfma_f32_32x32x16_bf16 v[2:17], v[86:89], v[90:93], v[2:17]
	ds_read_b128 v[90:93], v1 offset:36960
	v_mfma_f32_32x32x16_bf16 v[18:33], v[86:89], v[94:97], v[18:33]
	s_waitcnt vmcnt(7)
	ds_write_b128 v66, v[144:147] offset:55296
	s_waitcnt vmcnt(6)
	ds_write_b128 v66, v[122:125] offset:59904
	global_load_dwordx4 v[144:147], v[78:79], off offset:1536
	global_load_dwordx4 v[122:125], v[80:81], off offset:1536
	ds_read_b128 v[86:89], v68 offset:96
	ds_read_b128 v[94:97], v1 offset:41568
	s_waitcnt lgkmcnt(1)
	v_mfma_f32_32x32x16_bf16 v[34:49], v[86:89], v[90:93], v[34:49]
	s_waitcnt lgkmcnt(0)
	v_mfma_f32_32x32x16_bf16 v[50:65], v[86:89], v[94:97], v[50:65]
	v_mfma_f32_32x32x16_bf16 v[2:17], v[98:101], v[90:93], v[2:17]
	v_mfma_f32_32x32x16_bf16 v[18:33], v[98:101], v[94:97], v[18:33]
	s_waitcnt vmcnt(7)
	ds_write_b128 v66, v[118:121] offset:64512
	s_waitcnt vmcnt(6)
	ds_write_b128 v69, v[114:117] offset:32256
	global_load_dwordx4 v[118:121], v[82:83], off offset:1536
	global_load_dwordx4 v[114:117], v[84:85], off offset:1536
	s_setprio 0
	s_waitcnt lgkmcnt(0)
	s_barrier
; #define MFMA(a, b, c) __builtin_amdgcn_mfma_f32_32x32x16_bf16((a), (b), (c), 0, 0, 0)
; template <int TM, int TN>
; DI void gemm_mainloop(const u16* __restrict__ A, long lda, const u16* __restrict__ Bt, long ldb, int K, char* smem,
;                       f32x16 (&acc)[TM][TN]) {
;     ...
;   for (int kt = 0; kt < nk; kt++) {
;     const int buf = kt & 1;
;     const u16* cA = sA + buf * BM * LD + (wm * 32 * TM + r) * LD + h * 8;
;     const u16* cB = sB + buf * BN * LD + (wn * 32 * TN + r) * LD + h * 8;
;     bf16x8 af[TM], bfr[TN];
; #pragma unroll
;     for (int tm = 0; tm < TM; tm++) af[tm] = *(const bf16x8*)(cA + tm * 32 * LD);
; #pragma unroll
;     for (int tn = 0; tn < TN; tn++) bfr[tn] = *(const bf16x8*)(cB + tn * 32 * LD);
;     if (kt + 1 < nk) GEMM_SSTORE(buf ^ 1)
;     __builtin_amdgcn_sched_barrier(0);
;     __builtin_amdgcn_s_setprio(1);
; #pragma unroll
;     for (int tm = 0; tm < TM; tm++)
; #pragma unroll
;       for (int tn = 0; tn < TN; tn++) acc[tm][tn] = MFMA(af[tm], bfr[tn], acc[tm][tn]);
; #pragma unroll
;     for (int tm = 0; tm < TM; tm++) af[tm] = *(const bf16x8*)(cA + tm * 32 * LD + 16);
; #pragma unroll
;     for (int tn = 0; tn < TN; tn++) bfr[tn] = *(const bf16x8*)(cB + tn * 32 * LD + 16);
; #pragma unroll
;     for (int tm = 0; tm < TM; tm++)
; #pragma unroll
;       for (int tn = 0; tn < TN; tn++) acc[tm][tn] = MFMA(af[tm], bfr[tn], acc[tm][tn]);
;     __builtin_amdgcn_sched_group_barrier(0x8, 4, 0);
;     if (kt + 2 < nk) GEMM_GLOAD((kt + 2) * 64)
; #pragma unroll
;     for (int ks = 2; ks < 4; ks++) {
; #pragma unroll
;       for (int tm = 0; tm < TM; tm++) af[tm] = *(const bf16x8*)(cA + tm * 32 * LD + ks * 16);
; #pragma unroll
;       for (int tn = 0; tn < TN; tn++) bfr[tn] = *(const bf16x8*)(cB + tn * 32 * LD + ks * 16);
; #pragma unroll
;       for (int tm = 0; tm < TM; tm++)
; #pragma unroll
;         for (int tn = 0; tn < TN; tn++) acc[tm][tn] = MFMA(af[tm], bfr[tn], acc[tm][tn]);
;     }
;     __builtin_amdgcn_s_setprio(0);
;     __syncthreads();
;   }
	ds_read_b128 v[94:97], v68 offset:18432
	ds_read_b128 v[98:101], v68 offset:23040
	ds_read_b128 v[126:129], v1 offset:55296
	ds_read_b128 v[130:133], v1 offset:59904
	s_setprio 1
	ds_read_b128 v[86:89], v68 offset:18464
	s_waitcnt lgkmcnt(2)
	v_mfma_f32_32x32x16_bf16 v[34:49], v[94:97], v[126:129], v[34:49]
	ds_read_b128 v[90:93], v1 offset:55328
	s_waitcnt lgkmcnt(2)
	v_mfma_f32_32x32x16_bf16 v[50:65], v[94:97], v[130:133], v[50:65]
	ds_read_b128 v[94:97], v1 offset:59936
	s_waitcnt lgkmcnt(1)
	v_mfma_f32_32x32x16_bf16 v[34:49], v[86:89], v[90:93], v[34:49]
	s_waitcnt lgkmcnt(0)
	v_mfma_f32_32x32x16_bf16 v[50:65], v[86:89], v[94:97], v[50:65]
	s_waitcnt vmcnt(7)
	ds_write_b128 v66, v[140:143]
	s_waitcnt vmcnt(6)
	ds_write_b128 v66, v[102:105] offset:4608
	global_load_dwordx4 v[140:143], v[72:73], off offset:1664
	global_load_dwordx4 v[102:105], v[70:71], off offset:1664
	ds_read_b128 v[86:89], v68 offset:23072
	v_mfma_f32_32x32x16_bf16 v[2:17], v[98:101], v[126:129], v[2:17]
	v_mfma_f32_32x32x16_bf16 v[18:33], v[98:101], v[130:133], v[18:33]
	ds_read_b128 v[98:101], v68 offset:23136
	s_waitcnt lgkmcnt(1)
	v_mfma_f32_32x32x16_bf16 v[2:17], v[86:89], v[90:93], v[2:17]
	ds_read_b128 v[90:93], v1 offset:55360
	v_mfma_f32_32x32x16_bf16 v[18:33], v[86:89], v[94:97], v[18:33]
	s_waitcnt vmcnt(7)
	ds_write_b128 v66, v[106:109] offset:9216
	s_waitcnt vmcnt(6)
	ds_write_b128 v66, v[110:113] offset:13824
	global_load_dwordx4 v[106:109], v[74:75], off offset:1664
	global_load_dwordx4 v[110:113], v[76:77], off offset:1664
	ds_read_b128 v[86:89], v68 offset:18496
	ds_read_b128 v[94:97], v1 offset:59968
	s_waitcnt lgkmcnt(1)
	v_mfma_f32_32x32x16_bf16 v[34:49], v[86:89], v[90:93], v[34:49]
	s_waitcnt lgkmcnt(0)
	v_mfma_f32_32x32x16_bf16 v[50:65], v[86:89], v[94:97], v[50:65]
	ds_read_b128 v[86:89], v68 offset:23104
	s_waitcnt lgkmcnt(0)
	v_mfma_f32_32x32x16_bf16 v[2:17], v[86:89], v[90:93], v[2:17]
	ds_read_b128 v[90:93], v1 offset:55392
	v_mfma_f32_32x32x16_bf16 v[18:33], v[86:89], v[94:97], v[18:33]
	s_waitcnt vmcnt(7)
	ds_write_b128 v66, v[144:147] offset:36864
	s_waitcnt vmcnt(6)
	ds_write_b128 v66, v[122:125] offset:41472
	global_load_dwordx4 v[144:147], v[78:79], off offset:1664
	global_load_dwordx4 v[122:125], v[80:81], off offset:1664
	ds_read_b128 v[86:89], v68 offset:18528
	ds_read_b128 v[94:97], v1 offset:60000
	s_waitcnt lgkmcnt(1)
	v_mfma_f32_32x32x16_bf16 v[34:49], v[86:89], v[90:93], v[34:49]
	s_waitcnt lgkmcnt(0)
	v_mfma_f32_32x32x16_bf16 v[50:65], v[86:89], v[94:97], v[50:65]
	v_mfma_f32_32x32x16_bf16 v[2:17], v[98:101], v[90:93], v[2:17]
	v_mfma_f32_32x32x16_bf16 v[18:33], v[98:101], v[94:97], v[18:33]
	s_waitcnt vmcnt(7)
	ds_write_b128 v66, v[118:121] offset:46080
	s_waitcnt vmcnt(6)
	ds_write_b128 v66, v[114:117] offset:50688
	global_load_dwordx4 v[118:121], v[82:83], off offset:1664
	global_load_dwordx4 v[114:117], v[84:85], off offset:1664
	s_setprio 0
	s_waitcnt lgkmcnt(0)
	s_barrier
	ds_read_b128 v[94:97], v68
	ds_read_b128 v[98:101], v68 offset:4608
	ds_read_b128 v[126:129], v1 offset:36864
	ds_read_b128 v[130:133], v1 offset:41472
	s_setprio 1
	ds_read_b128 v[86:89], v68 offset:32
	s_waitcnt lgkmcnt(2)
	v_mfma_f32_32x32x16_bf16 v[34:49], v[94:97], v[126:129], v[34:49]
	ds_read_b128 v[90:93], v1 offset:36896
	s_waitcnt lgkmcnt(2)
	v_mfma_f32_32x32x16_bf16 v[50:65], v[94:97], v[130:133], v[50:65]
	ds_read_b128 v[94:97], v1 offset:41504
	s_waitcnt lgkmcnt(1)
	v_mfma_f32_32x32x16_bf16 v[34:49], v[86:89], v[90:93], v[34:49]
	s_waitcnt lgkmcnt(0)
	v_mfma_f32_32x32x16_bf16 v[50:65], v[86:89], v[94:97], v[50:65]
	s_waitcnt vmcnt(7)
	ds_write_b128 v66, v[140:143] offset:18432
	s_waitcnt vmcnt(6)
	ds_write_b128 v66, v[102:105] offset:23040
	global_load_dwordx4 v[140:143], v[72:73], off offset:1792
	global_load_dwordx4 v[102:105], v[70:71], off offset:1792
	ds_read_b128 v[86:89], v68 offset:4640
	v_mfma_f32_32x32x16_bf16 v[2:17], v[98:101], v[126:129], v[2:17]
	v_mfma_f32_32x32x16_bf16 v[18:33], v[98:101], v[130:133], v[18:33]
	ds_read_b128 v[98:101], v68 offset:4704
	s_waitcnt lgkmcnt(1)
	v_mfma_f32_32x32x16_bf16 v[2:17], v[86:89], v[90:93], v[2:17]
	ds_read_b128 v[90:93], v1 offset:36928
	v_mfma_f32_32x32x16_bf16 v[18:33], v[86:89], v[94:97], v[18:33]
	s_waitcnt vmcnt(7)
	ds_write_b128 v66, v[106:109] offset:27648
	s_waitcnt vmcnt(6)
	ds_write_b128 v66, v[110:113] offset:32256
	global_load_dwordx4 v[106:109], v[74:75], off offset:1792
	global_load_dwordx4 v[110:113], v[76:77], off offset:1792
	ds_read_b128 v[86:89], v68 offset:64
	ds_read_b128 v[94:97], v1 offset:41536
	s_waitcnt lgkmcnt(1)
	v_mfma_f32_32x32x16_bf16 v[34:49], v[86:89], v[90:93], v[34:49]
	s_waitcnt lgkmcnt(0)
	v_mfma_f32_32x32x16_bf16 v[50:65], v[86:89], v[94:97], v[50:65]
	ds_read_b128 v[86:89], v68 offset:4672
	s_waitcnt lgkmcnt(0)
	v_mfma_f32_32x32x16_bf16 v[2:17], v[86:89], v[90:93], v[2:17]
	ds_read_b128 v[90:93], v1 offset:36960
	v_mfma_f32_32x32x16_bf16 v[18:33], v[86:89], v[94:97], v[18:33]
	s_waitcnt vmcnt(7)
	ds_write_b128 v66, v[144:147] offset:55296
	s_waitcnt vmcnt(6)
	ds_write_b128 v66, v[122:125] offset:59904
	global_load_dwordx4 v[144:147], v[78:79], off offset:1792
	global_load_dwordx4 v[122:125], v[80:81], off offset:1792
	ds_read_b128 v[86:89], v68 offset:96
	ds_read_b128 v[94:97], v1 offset:41568
	s_waitcnt lgkmcnt(1)
	v_mfma_f32_32x32x16_bf16 v[34:49], v[86:89], v[90:93], v[34:49]
	s_waitcnt lgkmcnt(0)
	v_mfma_f32_32x32x16_bf16 v[50:65], v[86:89], v[94:97], v[50:65]
	v_mfma_f32_32x32x16_bf16 v[2:17], v[98:101], v[90:93], v[2:17]
	v_mfma_f32_32x32x16_bf16 v[18:33], v[98:101], v[94:97], v[18:33]
	s_waitcnt vmcnt(7)
	ds_write_b128 v66, v[118:121] offset:64512
	s_waitcnt vmcnt(6)
	ds_write_b128 v69, v[114:117] offset:32256
	global_load_dwordx4 v[118:121], v[82:83], off offset:1792
	global_load_dwordx4 v[114:117], v[84:85], off offset:1792
	s_setprio 0
	s_waitcnt lgkmcnt(0)
	s_barrier
; #define MFMA(a, b, c) __builtin_amdgcn_mfma_f32_32x32x16_bf16((a), (b), (c), 0, 0, 0)
; template <int TM, int TN>
; DI void gemm_mainloop(const u16* __restrict__ A, long lda, const u16* __restrict__ Bt, long ldb, int K, char* smem,
;                       f32x16 (&acc)[TM][TN]) {
;     ...
;   for (int kt = 0; kt < nk; kt++) {
;     const int buf = kt & 1;
;     const u16* cA = sA + buf * BM * LD + (wm * 32 * TM + r) * LD + h * 8;
;     const u16* cB = sB + buf * BN * LD + (wn * 32 * TN + r) * LD + h * 8;
;     bf16x8 af[TM], bfr[TN];
; #pragma unroll
;     for (int tm = 0; tm < TM; tm++) af[tm] = *(const bf16x8*)(cA + tm * 32 * LD);
; #pragma unroll
;     for (int tn = 0; tn < TN; tn++) bfr[tn] = *(const bf16x8*)(cB + tn * 32 * LD);
;     if (kt + 1 < nk) GEMM_SSTORE(buf ^ 1)
;     __builtin_amdgcn_sched_barrier(0);
;     __builtin_amdgcn_s_setprio(1);
; #pragma unroll
;     for (int tm = 0; tm < TM; tm++)
; #pragma unroll
;       for (int tn = 0; tn < TN; tn++) acc[tm][tn] = MFMA(af[tm], bfr[tn], acc[tm][tn]);
; #pragma unroll
;     for (int tm = 0; tm < TM; tm++) af[tm] = *(const bf16x8*)(cA + tm * 32 * LD + 16);
; #pragma unroll
;     for (int tn = 0; tn < TN; tn++) bfr[tn] = *(const bf16x8*)(cB + tn * 32 * LD + 16);
; #pragma unroll
;     for (int tm = 0; tm < TM; tm++)
; #pragma unroll
;       for (int tn = 0; tn < TN; tn++) acc[tm][tn] = MFMA(af[tm], bfr[tn], acc[tm][tn]);
;     __builtin_amdgcn_sched_group_barrier(0x8, 4, 0);
;     if (kt + 2 < nk) GEMM_GLOAD((kt + 2) * 64)
; #pragma unroll
;     for (int ks = 2; ks < 4; ks++) {
; #pragma unroll
;       for (int tm = 0; tm < TM; tm++) af[tm] = *(const bf16x8*)(cA + tm * 32 * LD + ks * 16);
; #pragma unroll
;       for (int tn = 0; tn < TN; tn++) bfr[tn] = *(const bf16x8*)(cB + tn * 32 * LD + ks * 16);
; #pragma unroll
;       for (int tm = 0; tm < TM; tm++)
; #pragma unroll
;         for (int tn = 0; tn < TN; tn++) acc[tm][tn] = MFMA(af[tm], bfr[tn], acc[tm][tn]);
;     }
;     __builtin_amdgcn_s_setprio(0);
;     __syncthreads();
;   }
	ds_read_b128 v[94:97], v68 offset:18432
	ds_read_b128 v[98:101], v68 offset:23040
	ds_read_b128 v[126:129], v1 offset:55296
	ds_read_b128 v[130:133], v1 offset:59904
	s_setprio 1
	ds_read_b128 v[86:89], v68 offset:18464
	s_waitcnt lgkmcnt(2)
	v_mfma_f32_32x32x16_bf16 v[34:49], v[94:97], v[126:129], v[34:49]
	ds_read_b128 v[90:93], v1 offset:55328
	s_waitcnt lgkmcnt(2)
	v_mfma_f32_32x32x16_bf16 v[50:65], v[94:97], v[130:133], v[50:65]
	ds_read_b128 v[94:97], v1 offset:59936
	s_waitcnt lgkmcnt(1)
	v_mfma_f32_32x32x16_bf16 v[34:49], v[86:89], v[90:93], v[34:49]
	s_waitcnt lgkmcnt(0)
	v_mfma_f32_32x32x16_bf16 v[50:65], v[86:89], v[94:97], v[50:65]
	s_waitcnt vmcnt(7)
	ds_write_b128 v66, v[140:143]
	s_waitcnt vmcnt(6)
	ds_write_b128 v66, v[102:105] offset:4608
	global_load_dwordx4 v[140:143], v[72:73], off offset:1920
	global_load_dwordx4 v[102:105], v[70:71], off offset:1920
	ds_read_b128 v[86:89], v68 offset:23072
	v_mfma_f32_32x32x16_bf16 v[2:17], v[98:101], v[126:129], v[2:17]
	v_mfma_f32_32x32x16_bf16 v[18:33], v[98:101], v[130:133], v[18:33]
	ds_read_b128 v[98:101], v68 offset:23136
	s_waitcnt lgkmcnt(1)
	v_mfma_f32_32x32x16_bf16 v[2:17], v[86:89], v[90:93], v[2:17]
	ds_read_b128 v[90:93], v1 offset:55360
	v_mfma_f32_32x32x16_bf16 v[18:33], v[86:89], v[94:97], v[18:33]
	s_waitcnt vmcnt(7)
	ds_write_b128 v66, v[106:109] offset:9216
	s_waitcnt vmcnt(6)
	ds_write_b128 v66, v[110:113] offset:13824
	global_load_dwordx4 v[106:109], v[74:75], off offset:1920
	global_load_dwordx4 v[110:113], v[76:77], off offset:1920
	ds_read_b128 v[86:89], v68 offset:18496
	ds_read_b128 v[94:97], v1 offset:59968
	s_waitcnt lgkmcnt(1)
	v_mfma_f32_32x32x16_bf16 v[34:49], v[86:89], v[90:93], v[34:49]
	s_waitcnt lgkmcnt(0)
	v_mfma_f32_32x32x16_bf16 v[50:65], v[86:89], v[94:97], v[50:65]
	ds_read_b128 v[86:89], v68 offset:23104
	s_waitcnt lgkmcnt(0)
	v_mfma_f32_32x32x16_bf16 v[2:17], v[86:89], v[90:93], v[2:17]
	ds_read_b128 v[90:93], v1 offset:55392
	v_mfma_f32_32x32x16_bf16 v[18:33], v[86:89], v[94:97], v[18:33]
	s_waitcnt vmcnt(7)
	ds_write_b128 v66, v[144:147] offset:36864
	s_waitcnt vmcnt(6)
	ds_write_b128 v66, v[122:125] offset:41472
	global_load_dwordx4 v[144:147], v[78:79], off offset:1920
	global_load_dwordx4 v[122:125], v[80:81], off offset:1920
	ds_read_b128 v[86:89], v68 offset:18528
	ds_read_b128 v[94:97], v1 offset:60000
	s_waitcnt lgkmcnt(1)
	v_mfma_f32_32x32x16_bf16 v[34:49], v[86:89], v[90:93], v[34:49]
	s_waitcnt lgkmcnt(0)
	v_mfma_f32_32x32x16_bf16 v[50:65], v[86:89], v[94:97], v[50:65]
	s_nop 0
	v_mfma_f32_32x32x16_bf16 v[2:17], v[98:101], v[90:93], v[2:17]
	v_mfma_f32_32x32x16_bf16 v[18:33], v[98:101], v[94:97], v[18:33]
	s_waitcnt vmcnt(7)
	ds_write_b128 v66, v[118:121] offset:46080
	s_waitcnt vmcnt(6)
	ds_write_b128 v66, v[114:117] offset:50688
	global_load_dwordx4 v[118:121], v[82:83], off offset:1920
	global_load_dwordx4 v[114:117], v[84:85], off offset:1920
	s_setprio 0
	s_waitcnt lgkmcnt(0)
	s_barrier
	ds_read_b128 v[74:77], v68
	ds_read_b128 v[78:81], v68 offset:4608
	ds_read_b128 v[82:85], v1 offset:36864
	ds_read_b128 v[90:93], v1 offset:41472
	s_setprio 1
	ds_read_b128 v[70:73], v68 offset:32
	s_waitcnt lgkmcnt(2)
	v_mfma_f32_32x32x16_bf16 v[34:49], v[74:77], v[82:85], v[34:49]
	s_waitcnt lgkmcnt(1)
	v_mfma_f32_32x32x16_bf16 v[50:65], v[74:77], v[90:93], v[50:65]
	ds_read_b128 v[74:77], v1 offset:36896
	v_mfma_f32_32x32x16_bf16 v[2:17], v[78:81], v[82:85], v[2:17]
	v_mfma_f32_32x32x16_bf16 v[18:33], v[78:81], v[90:93], v[18:33]
	s_waitcnt vmcnt(7)
	ds_write_b128 v66, v[140:143] offset:18432
	s_waitcnt vmcnt(6)
	ds_write_b128 v66, v[102:105] offset:23040
	ds_read_b128 v[78:81], v1 offset:41504
	s_waitcnt lgkmcnt(3)
	v_mfma_f32_32x32x16_bf16 v[34:49], v[70:73], v[74:77], v[34:49]
	s_waitcnt lgkmcnt(0)
	v_mfma_f32_32x32x16_bf16 v[50:65], v[70:73], v[78:81], v[50:65]
	ds_read_b128 v[70:73], v68 offset:4640
	s_waitcnt lgkmcnt(0)
	v_mfma_f32_32x32x16_bf16 v[2:17], v[70:73], v[74:77], v[2:17]
	ds_read_b128 v[74:77], v1 offset:36928
	v_mfma_f32_32x32x16_bf16 v[18:33], v[70:73], v[78:81], v[18:33]
	s_waitcnt vmcnt(5)
	ds_write_b128 v66, v[106:109] offset:27648
	s_waitcnt vmcnt(4)
	ds_write_b128 v66, v[110:113] offset:32256
	ds_read_b128 v[70:73], v68 offset:64
	ds_read_b128 v[78:81], v1 offset:41536
	s_waitcnt lgkmcnt(1)
	v_mfma_f32_32x32x16_bf16 v[34:49], v[70:73], v[74:77], v[34:49]
	s_waitcnt lgkmcnt(0)
	v_mfma_f32_32x32x16_bf16 v[50:65], v[70:73], v[78:81], v[50:65]
	ds_read_b128 v[70:73], v68 offset:4672
	s_waitcnt lgkmcnt(0)
	v_mfma_f32_32x32x16_bf16 v[2:17], v[70:73], v[74:77], v[2:17]
	ds_read_b128 v[74:77], v1 offset:36960
	v_mfma_f32_32x32x16_bf16 v[18:33], v[70:73], v[78:81], v[18:33]
	s_waitcnt vmcnt(3)
	ds_write_b128 v66, v[144:147] offset:55296
	s_waitcnt vmcnt(2)
	ds_write_b128 v66, v[122:125] offset:59904
	ds_read_b128 v[70:73], v68 offset:96
	ds_read_b128 v[78:81], v1 offset:41568
	s_waitcnt lgkmcnt(1)
	v_mfma_f32_32x32x16_bf16 v[34:49], v[70:73], v[74:77], v[34:49]
	s_waitcnt lgkmcnt(0)
	v_mfma_f32_32x32x16_bf16 v[50:65], v[70:73], v[78:81], v[50:65]
	ds_read_b128 v[70:73], v68 offset:4704
	s_waitcnt lgkmcnt(0)
	v_mfma_f32_32x32x16_bf16 v[2:17], v[70:73], v[74:77], v[2:17]
	v_mfma_f32_32x32x16_bf16 v[18:33], v[70:73], v[78:81], v[18:33]
	s_waitcnt vmcnt(1)
	ds_write_b128 v66, v[118:121] offset:64512
	s_waitcnt vmcnt(0)
	ds_write_b128 v69, v[114:117] offset:32256
	s_setprio 0
	s_waitcnt lgkmcnt(0)
	s_barrier
; #define MFMA(a, b, c) __builtin_amdgcn_mfma_f32_32x32x16_bf16((a), (b), (c), 0, 0, 0)
; DI int crow(int i, int h) { return (i & 3) + 8 * (i >> 2) + 4 * h; }
; template <int TM, int TN>
; DI void gemm_mainloop(const u16* __restrict__ A, long lda, const u16* __restrict__ Bt, long ldb, int K, char* smem,
;                       f32x16 (&acc)[TM][TN]) {
;     ...
;       for (int tm = 0; tm < TM; tm++)
; #pragma unroll
;         for (int tn = 0; tn < TN; tn++) acc[tm][tn] = MFMA(af[tm], bfr[tn], acc[tm][tn]);
;     }
;     __builtin_amdgcn_s_setprio(0);
;     __syncthreads();
;   }
; template <int TM, int TN, class Epi>
; DI void gemm_tile(const u16* A, long lda, const u16* Bt, long ldb, int K, int m0, int n0, char* smem, const Epi& epi) {
;     ...
; #pragma unroll
;   for (int tm = 0; tm < TM; tm++)
; #pragma unroll
;     for (int tn = 0; tn < TN; tn++)
; #pragma unroll
;       for (int i = 0; i < 16; i++)
;         Ct[(wm * 32 * TM + tm * 32 + crow(i, h)) * LDC + wn * 32 * TN + tn * 32 + r] = acc[tm][tn][i];
;   __syncthreads();
;   epi(Ct, LDC, m0, n0, tid, BM);
	ds_read_b128 v[70:73], v68 offset:18432
	ds_read_b128 v[74:77], v68 offset:23040
	ds_read_b128 v[78:81], v1 offset:55296
	ds_read_b128 v[82:85], v1 offset:59904
	s_setprio 1
	s_waitcnt lgkmcnt(1)
	v_mfma_f32_32x32x16_bf16 v[34:49], v[70:73], v[78:81], v[34:49]
	s_waitcnt lgkmcnt(0)
	v_mfma_f32_32x32x16_bf16 v[50:65], v[70:73], v[82:85], v[50:65]
	ds_read_b128 v[70:73], v68 offset:18464
	v_mfma_f32_32x32x16_bf16 v[2:17], v[74:77], v[78:81], v[2:17]
	ds_read_b128 v[78:81], v1 offset:59936
	v_mfma_f32_32x32x16_bf16 v[18:33], v[74:77], v[82:85], v[18:33]
	ds_read_b128 v[74:77], v1 offset:55328
	s_waitcnt lgkmcnt(0)
	v_mfma_f32_32x32x16_bf16 v[34:49], v[70:73], v[74:77], v[34:49]
	v_mfma_f32_32x32x16_bf16 v[50:65], v[70:73], v[78:81], v[50:65]
	ds_read_b128 v[70:73], v68 offset:23072
	s_waitcnt lgkmcnt(0)
	v_mfma_f32_32x32x16_bf16 v[2:17], v[70:73], v[74:77], v[2:17]
	ds_read_b128 v[74:77], v1 offset:55360
	v_mfma_f32_32x32x16_bf16 v[18:33], v[70:73], v[78:81], v[18:33]
	ds_read_b128 v[70:73], v68 offset:18496
	ds_read_b128 v[78:81], v1 offset:59968
	s_waitcnt lgkmcnt(1)
	v_mfma_f32_32x32x16_bf16 v[34:49], v[70:73], v[74:77], v[34:49]
	s_waitcnt lgkmcnt(0)
	v_mfma_f32_32x32x16_bf16 v[50:65], v[70:73], v[78:81], v[50:65]
	ds_read_b128 v[70:73], v68 offset:23104
	s_waitcnt lgkmcnt(0)
	v_mfma_f32_32x32x16_bf16 v[2:17], v[70:73], v[74:77], v[2:17]
	ds_read_b128 v[74:77], v1 offset:55392
	v_mfma_f32_32x32x16_bf16 v[18:33], v[70:73], v[78:81], v[18:33]
	ds_read_b128 v[70:73], v68 offset:18528
	ds_read_b128 v[78:81], v1 offset:60000
	s_waitcnt lgkmcnt(1)
	v_mfma_f32_32x32x16_bf16 v[34:49], v[70:73], v[74:77], v[34:49]
	s_waitcnt lgkmcnt(0)
	v_mfma_f32_32x32x16_bf16 v[50:65], v[70:73], v[78:81], v[50:65]
	ds_read_b128 v[68:71], v68 offset:23136
	s_waitcnt lgkmcnt(0)
	v_mfma_f32_32x32x16_bf16 v[2:17], v[68:71], v[74:77], v[2:17]
	v_mfma_f32_32x32x16_bf16 v[18:33], v[68:71], v[78:81], v[18:33]
	s_setprio 0
	v_mov_b32_e32 v1, v0
	s_barrier
	s_mov_b32 s38, 0
	v_lshrrev_b32_e32 v66, 1, v1
	v_and_b32_e32 v66, 0xfffffc0, v66
	v_lshrrev_b32_e32 v68, 3, v1
	v_and_or_b32 v66, v68, 4, v66
	v_and_b32_e32 v68, 0x5f, v1
	v_mul_lo_u32 v66, v66, s28
	v_lshl_add_u32 v66, v68, 2, v66
	ds_write2_b32 v66, v34, v50 offset1:32
	v_add_u32_e32 v34, 0x400, v66
	ds_write2_b32 v34, v36, v52 offset0:8 offset1:40
	ds_write2_b32 v34, v37, v53 offset0:140 offset1:172
	v_add_u32_e32 v34, 0x1000, v66
	ds_write2_b32 v34, v38, v54 offset0:32 offset1:64
	ds_write2_b32 v34, v39, v55 offset0:164 offset1:196
	v_add_u32_e32 v34, 0x1400, v66
	ds_write2_b32 v34, v40, v56 offset0:40 offset1:72
	ds_write2_b32 v34, v41, v57 offset0:172 offset1:204
	v_add_u32_e32 v34, 0x2000, v66
	ds_write2_b32 v34, v42, v58 offset0:64 offset1:96
	ds_write2_b32 v34, v43, v59 offset0:196 offset1:228
	v_add_u32_e32 v34, 0x2400, v66
	ds_write2_b32 v34, v44, v60 offset0:72 offset1:104
	ds_write2_b32 v34, v45, v61 offset0:204 offset1:236
	v_add_u32_e32 v34, 0x3000, v66
	ds_write2_b32 v34, v46, v62 offset0:96 offset1:128
	v_add_u32_e32 v34, 0x3200, v66
	ds_write2_b32 v34, v47, v63 offset0:100 offset1:132
	v_add_u32_e32 v34, 0x3400, v66
	ds_write2_b32 v34, v48, v64 offset0:104 offset1:136
	v_add_u32_e32 v34, 0x3600, v66
	ds_write2_b32 v34, v49, v65 offset0:108 offset1:140
	v_add_u32_e32 v34, 0x4000, v66
	ds_write2_b32 v34, v2, v18 offset0:128 offset1:160
	v_add_u32_e32 v2, 0x4400, v66
	ds_write2_b32 v2, v3, v19 offset0:4 offset1:36
	ds_write2_b32 v2, v4, v20 offset0:136 offset1:168
	v_add_u32_e32 v2, 0x4800, v66
	ds_write2_b32 v2, v5, v21 offset0:12 offset1:44
	v_add_u32_e32 v2, 0x5000, v66
	ds_write2_b32 v2, v6, v22 offset0:160 offset1:192
	v_add_u32_e32 v2, 0x5400, v66
	ds_write2_b32 v2, v7, v23 offset0:36 offset1:68
	ds_write2_b32 v2, v8, v24 offset0:168 offset1:200
	v_add_u32_e32 v2, 0x5800, v66
	ds_write2_b32 v2, v9, v25 offset0:44 offset1:76
	v_add_u32_e32 v2, 0x6000, v66
	ds_write2_b32 v2, v10, v26 offset0:192 offset1:224
	v_add_u32_e32 v2, 0x6400, v66
	ds_write2_b32 v2, v11, v27 offset0:68 offset1:100
	ds_write2_b32 v2, v12, v28 offset0:200 offset1:232
	v_add_u32_e32 v2, 0x6800, v66
	ds_write2_b32 v2, v13, v29 offset0:76 offset1:108
	v_add_u32_e32 v2, 0x7200, v66
	ds_write2_b32 v2, v14, v30 offset0:96 offset1:128
	v_add_u32_e32 v2, 0x7400, v66
	ds_write2_b32 v2, v15, v31 offset0:100 offset1:132
	v_add_u32_e32 v2, 0x7600, v66
	ds_write2_b32 v2, v16, v32 offset0:104 offset1:136
	v_add_u32_e32 v2, 0x7800, v66
	ds_write2_b32 v2, v17, v33 offset0:108 offset1:140
	v_lshlrev_b32_e32 v2, 3, v1
	v_and_b32_e32 v3, 0x78, v2
	v_or_b32_e32 v2, s4, v3
	v_lshlrev_b32_e32 v10, 2, v3
	v_ashrrev_i32_e32 v3, 31, v2
	v_cmp_eq_u32_e32 vcc, s29, v2
	v_cmp_gt_i32_e64 s[4:5], s30, v2
	v_lshl_add_u64 v[12:13], v[2:3], 1, s[6:7]
	ds_write2_b32 v66, v35, v51 offset0:132 offset1:164
	s_waitcnt lgkmcnt(0)
	s_barrier
	s_branch .LBB0_148

; #define MFMA(a, b, c) __builtin_amdgcn_mfma_f32_32x32x16_bf16((a), (b), (c), 0, 0, 0)
; DI u16* wsb(const Params& p, size_t off) { return (u16*)(p.ws + off); }
; template <int TM, int TN>
; DI void gemm_mainloop(const u16* __restrict__ A, long lda, const u16* __restrict__ Bt, long ldb, int K, char* smem,
;                       f32x16 (&acc)[TM][TN]) {
;     ...
;   const int nk = K / 64;
;   const int lrow = tid >> 3, lch = (tid & 7) * 8;
;   const u16* gA = A + (long)lrow * lda + lch;
;   const u16* gB = Bt + (long)lrow * ldb + lch;
;   const int soff = lrow * LD + lch;
;     ...
;   GEMM_GLOAD(0)
;   __syncthreads();
;   GEMM_SSTORE(0)
;   if (nk > 1) GEMM_GLOAD(64)
;   __syncthreads();
;   for (int kt = 0; kt < nk; kt++) {
;     const int buf = kt & 1;
;     const u16* cA = sA + buf * BM * LD + (wm * 32 * TM + r) * LD + h * 8;
;     const u16* cB = sB + buf * BN * LD + (wn * 32 * TN + r) * LD + h * 8;
;     bf16x8 af[TM], bfr[TN];
; #pragma unroll
;     for (int tm = 0; tm < TM; tm++) af[tm] = *(const bf16x8*)(cA + tm * 32 * LD);
; #pragma unroll
;     for (int tn = 0; tn < TN; tn++) bfr[tn] = *(const bf16x8*)(cB + tn * 32 * LD);
;     if (kt + 1 < nk) GEMM_SSTORE(buf ^ 1)
;     __builtin_amdgcn_sched_barrier(0);
;     __builtin_amdgcn_s_setprio(1);
; #pragma unroll
;     for (int tm = 0; tm < TM; tm++)
; #pragma unroll
;       for (int tn = 0; tn < TN; tn++) acc[tm][tn] = MFMA(af[tm], bfr[tn], acc[tm][tn]);
; #pragma unroll
;     for (int tm = 0; tm < TM; tm++) af[tm] = *(const bf16x8*)(cA + tm * 32 * LD + 16);
; #pragma unroll
;     for (int tn = 0; tn < TN; tn++) bfr[tn] = *(const bf16x8*)(cB + tn * 32 * LD + 16);
; #pragma unroll
;     for (int tm = 0; tm < TM; tm++)
; #pragma unroll
;       for (int tn = 0; tn < TN; tn++) acc[tm][tn] = MFMA(af[tm], bfr[tn], acc[tm][tn]);
;     __builtin_amdgcn_sched_group_barrier(0x8, 4, 0);
;     if (kt + 2 < nk) GEMM_GLOAD((kt + 2) * 64)
; DI void phase_inproj(const Params& p, const Sched& sc, int l, char* smem) {
;     ...
;     for (int u = blockIdx.x; u < 128; u += gridDim.x) {
;       int l2 = u >> 6, which = (u >> 5) & 1, mt = (u >> 3) & 3, nt = u & 7;
;       const u16* W2 = wsb(p, WS_W) + (size_t)l2 * W_LAYER + (which ? W_XV : W_XK);
;       EpiF32 epi{p.out + (which ? O_PMEMV : O_PMEMK) + (size_t)l2 * 524288, 1024};
;       gemm_tile<2, 2>(wsb(p, WS_HM), LDA, W2, LDW, 1024, mt * 128, nt * 128, smem, epi);
.LBB0_159:
	s_ashr_i32 s22, s21, 6
	s_ashr_i32 s23, s22, 31
	s_mul_i32 s25, s22, 0x2168000
	s_mul_hi_i32 s24, s22, 0x2168000
	s_add_u32 s25, s10, s25
	s_addc_u32 s24, s11, s24
	s_bitcmp0_b32 s21, 5
	s_cselect_b32 s26, s5, 0xc88000
	s_cselect_b32 s27, s6, 0xb50e040
	s_add_u32 s28, s25, s26
	s_addc_u32 s29, s24, 0
	s_add_u32 s26, s8, s27
	s_addc_u32 s27, s9, 0
	s_lshl_b64 s[24:25], s[22:23], 21
	s_add_u32 s23, s26, s24
	s_addc_u32 s24, s27, s25
	s_lshl_b32 s22, s21, 4
	s_and_b32 s22, s22, 0x180
	s_lshl_b32 s25, s21, 7
	s_and_b32 s25, s25, 0x380
	s_mul_i32 s26, s22, 0x880
	s_add_u32 s26, s3, s26
	v_mov_b32_e32 v1, v0
	s_addc_u32 s27, s4, 0
	s_mul_i32 s30, s25, 0x880
	v_lshlrev_b32_e32 v2, 3, v1
	v_ashrrev_i32_e32 v68, 3, v1
	v_and_b32_e32 v69, 56, v2
	v_mov_b64_e32 v[2:3], s[26:27]
	v_mad_i64_i32 v[2:3], s[26:27], v68, s7, v[2:3]
	v_lshlrev_b32_e32 v66, 1, v69
	v_lshl_add_u64 v[72:73], v[2:3], 0, v[66:67]
	v_add_co_u32_e32 v70, vcc, s15, v72
	s_add_u32 s28, s28, s30
	s_nop 0
	v_addc_co_u32_e32 v71, vcc, 0, v73, vcc
	s_addc_u32 s29, s29, 0
	v_add_co_u32_e32 v74, vcc, s16, v72
	v_mov_b64_e32 v[2:3], s[28:29]
	s_nop 0
	v_addc_co_u32_e32 v75, vcc, 0, v73, vcc
	v_mad_i64_i32 v[18:19], s[26:27], v68, s7, v[2:3]
	v_add_co_u32_e32 v78, vcc, s17, v72
	v_lshl_add_u64 v[76:77], v[18:19], 0, v[66:67]
	s_nop 0
	v_addc_co_u32_e32 v79, vcc, 0, v73, vcc
	v_add_co_u32_e32 v80, vcc, s15, v76
	global_load_dwordx4 v[2:5], v[72:73], off
	s_nop 0
	v_addc_co_u32_e32 v81, vcc, 0, v77, vcc
	v_add_co_u32_e32 v82, vcc, s16, v76
	global_load_dwordx4 v[6:9], v[70:71], off
	s_nop 0
	v_addc_co_u32_e32 v83, vcc, 0, v77, vcc
	v_add_co_u32_e32 v84, vcc, s17, v76
	global_load_dwordx4 v[10:13], v[74:75], off
	s_nop 0
	v_addc_co_u32_e32 v85, vcc, 0, v77, vcc
	global_load_dwordx4 v[14:17], v[78:79], off
	global_load_dwordx4 v[18:21], v[76:77], off
	global_load_dwordx4 v[22:25], v[80:81], off
	global_load_dwordx4 v[26:29], v[82:83], off
	global_load_dwordx4 v[30:33], v[84:85], off
	s_barrier
	global_load_dwordx4 v[34:37], v[72:73], off offset:128
	global_load_dwordx4 v[38:41], v[70:71], off offset:128
	global_load_dwordx4 v[42:45], v[74:75], off offset:128
	global_load_dwordx4 v[46:49], v[78:79], off offset:128
	global_load_dwordx4 v[50:53], v[76:77], off offset:128
	global_load_dwordx4 v[54:57], v[80:81], off offset:128
	global_load_dwordx4 v[58:61], v[82:83], off offset:128
	global_load_dwordx4 v[62:65], v[84:85], off offset:128
	v_and_b32_e32 v66, 31, v1
	v_lshrrev_b32_e32 v86, 1, v1
	v_mul_lo_u32 v68, v68, s14
	v_and_or_b32 v87, v86, s18, v66
	v_and_b32_e32 v86, 16, v86
	v_add_lshl_u32 v66, v68, v69, 1
	v_mad_u64_u32 v[68:69], s[26:27], v87, s19, v[86:87]
	v_and_b32_e32 v1, 0x5f, v1
	v_mad_u32_u24 v1, v1, s19, v86
	v_add_u32_e32 v69, 0x9000, v66
	s_waitcnt vmcnt(15)
	ds_write_b128 v66, v[2:5]
	s_waitcnt vmcnt(14)
	ds_write_b128 v66, v[6:9] offset:4608
	s_waitcnt vmcnt(13)
	ds_write_b128 v66, v[10:13] offset:9216
	s_waitcnt vmcnt(12)
	ds_write_b128 v66, v[14:17] offset:13824
	s_waitcnt vmcnt(11)
	ds_write_b128 v66, v[18:21] offset:36864
	s_waitcnt vmcnt(10)
	ds_write_b128 v66, v[22:25] offset:41472
	s_waitcnt vmcnt(9)
	ds_write_b128 v66, v[26:29] offset:46080
	s_waitcnt vmcnt(8)
	ds_write_b128 v66, v[30:33] offset:50688
	s_waitcnt lgkmcnt(0)
	s_barrier
	ds_read_b128 v[2:5], v68
	ds_read_b128 v[18:21], v68 offset:4608
	ds_read_b128 v[6:9], v1 offset:36864
	ds_read_b128 v[22:25], v1 offset:41472
	s_waitcnt vmcnt(7)
	ds_write_b128 v66, v[34:37] offset:18432
	s_waitcnt vmcnt(6)
	ds_write_b128 v66, v[38:41] offset:23040
	s_waitcnt vmcnt(5)
	ds_write_b128 v66, v[42:45] offset:27648
	s_waitcnt vmcnt(4)
	ds_write_b128 v66, v[46:49] offset:32256
	s_waitcnt vmcnt(3)
	ds_write_b128 v66, v[50:53] offset:55296
	s_waitcnt vmcnt(2)
	ds_write_b128 v66, v[54:57] offset:59904
	s_waitcnt vmcnt(1)
	ds_write_b128 v66, v[58:61] offset:64512
	s_waitcnt vmcnt(0)
	ds_write_b128 v69, v[62:65] offset:32256
	s_setprio 1
	ds_read_b128 v[86:89], v68 offset:32
	s_waitcnt lgkmcnt(10)
	v_mfma_f32_32x32x16_bf16 v[34:49], v[2:5], v[6:9], 0
	ds_read_b128 v[90:93], v1 offset:36896
	ds_read_b128 v[94:97], v1 offset:41504
	ds_read_b128 v[98:101], v68 offset:4704
	global_load_dwordx4 v[102:105], v[70:71], off offset:256
	global_load_dwordx4 v[106:109], v[74:75], off offset:256
	global_load_dwordx4 v[110:113], v[78:79], off offset:256
	global_load_dwordx4 v[114:117], v[84:85], off offset:256
	s_waitcnt lgkmcnt(12)
	v_mfma_f32_32x32x16_bf16 v[50:65], v[2:5], v[22:25], 0
	global_load_dwordx4 v[118:121], v[82:83], off offset:256
	global_load_dwordx4 v[122:125], v[80:81], off offset:256
	global_load_dwordx4 v[140:143], v[72:73], off offset:256
	global_load_dwordx4 v[144:147], v[76:77], off offset:256
	s_waitcnt lgkmcnt(2)
	v_mfma_f32_32x32x16_bf16 v[34:49], v[86:89], v[90:93], v[34:49]
	s_waitcnt lgkmcnt(1)
	v_mfma_f32_32x32x16_bf16 v[50:65], v[86:89], v[94:97], v[50:65]
	ds_read_b128 v[86:89], v68 offset:4640
	v_mfma_f32_32x32x16_bf16 v[2:17], v[18:21], v[6:9], 0
	v_mfma_f32_32x32x16_bf16 v[18:33], v[18:21], v[22:25], 0
	s_waitcnt lgkmcnt(0)
	v_mfma_f32_32x32x16_bf16 v[2:17], v[86:89], v[90:93], v[2:17]
	ds_read_b128 v[90:93], v1 offset:36928
	v_mfma_f32_32x32x16_bf16 v[18:33], v[86:89], v[94:97], v[18:33]
	ds_read_b128 v[86:89], v68 offset:64
	ds_read_b128 v[94:97], v1 offset:41536
	s_waitcnt lgkmcnt(1)
	v_mfma_f32_32x32x16_bf16 v[34:49], v[86:89], v[90:93], v[34:49]
	s_waitcnt lgkmcnt(0)
	v_mfma_f32_32x32x16_bf16 v[50:65], v[86:89], v[94:97], v[50:65]
	ds_read_b128 v[86:89], v68 offset:4672
	s_waitcnt lgkmcnt(0)
	v_mfma_f32_32x32x16_bf16 v[2:17], v[86:89], v[90:93], v[2:17]
	ds_read_b128 v[90:93], v1 offset:36960
	v_mfma_f32_32x32x16_bf16 v[18:33], v[86:89], v[94:97], v[18:33]
	ds_read_b128 v[86:89], v68 offset:96
	ds_read_b128 v[94:97], v1 offset:41568
	s_waitcnt lgkmcnt(1)
	v_mfma_f32_32x32x16_bf16 v[34:49], v[86:89], v[90:93], v[34:49]
	s_waitcnt lgkmcnt(0)
	v_mfma_f32_32x32x16_bf16 v[50:65], v[86:89], v[94:97], v[50:65]
	v_mfma_f32_32x32x16_bf16 v[2:17], v[98:101], v[90:93], v[2:17]
	v_mfma_f32_32x32x16_bf16 v[18:33], v[98:101], v[94:97], v[18:33]
	s_setprio 0
	s_barrier
; #define MFMA(a, b, c) __builtin_amdgcn_mfma_f32_32x32x16_bf16((a), (b), (c), 0, 0, 0)
; template <int TM, int TN>
; DI void gemm_mainloop(const u16* __restrict__ A, long lda, const u16* __restrict__ Bt, long ldb, int K, char* smem,
;                       f32x16 (&acc)[TM][TN]) {
;     ...
;   for (int kt = 0; kt < nk; kt++) {
;     const int buf = kt & 1;
;     const u16* cA = sA + buf * BM * LD + (wm * 32 * TM + r) * LD + h * 8;
;     const u16* cB = sB + buf * BN * LD + (wn * 32 * TN + r) * LD + h * 8;
;     bf16x8 af[TM], bfr[TN];
; #pragma unroll
;     for (int tm = 0; tm < TM; tm++) af[tm] = *(const bf16x8*)(cA + tm * 32 * LD);
; #pragma unroll
;     for (int tn = 0; tn < TN; tn++) bfr[tn] = *(const bf16x8*)(cB + tn * 32 * LD);
;     if (kt + 1 < nk) GEMM_SSTORE(buf ^ 1)
;     __builtin_amdgcn_sched_barrier(0);
;     __builtin_amdgcn_s_setprio(1);
; #pragma unroll
;     for (int tm = 0; tm < TM; tm++)
; #pragma unroll
;       for (int tn = 0; tn < TN; tn++) acc[tm][tn] = MFMA(af[tm], bfr[tn], acc[tm][tn]);
; #pragma unroll
;     for (int tm = 0; tm < TM; tm++) af[tm] = *(const bf16x8*)(cA + tm * 32 * LD + 16);
; #pragma unroll
;     for (int tn = 0; tn < TN; tn++) bfr[tn] = *(const bf16x8*)(cB + tn * 32 * LD + 16);
; #pragma unroll
;     for (int tm = 0; tm < TM; tm++)
; #pragma unroll
;       for (int tn = 0; tn < TN; tn++) acc[tm][tn] = MFMA(af[tm], bfr[tn], acc[tm][tn]);
;     __builtin_amdgcn_sched_group_barrier(0x8, 4, 0);
;     if (kt + 2 < nk) GEMM_GLOAD((kt + 2) * 64)
; #pragma unroll
;     for (int ks = 2; ks < 4; ks++) {
; #pragma unroll
;       for (int tm = 0; tm < TM; tm++) af[tm] = *(const bf16x8*)(cA + tm * 32 * LD + ks * 16);
; #pragma unroll
;       for (int tn = 0; tn < TN; tn++) bfr[tn] = *(const bf16x8*)(cB + tn * 32 * LD + ks * 16);
; #pragma unroll
;       for (int tm = 0; tm < TM; tm++)
; #pragma unroll
;         for (int tn = 0; tn < TN; tn++) acc[tm][tn] = MFMA(af[tm], bfr[tn], acc[tm][tn]);
;     }
;     __builtin_amdgcn_s_setprio(0);
;     __syncthreads();
;   }
	ds_read_b128 v[94:97], v68 offset:18432
	ds_read_b128 v[98:101], v68 offset:23040
	ds_read_b128 v[126:129], v1 offset:55296
	ds_read_b128 v[130:133], v1 offset:59904
	s_setprio 1
	ds_read_b128 v[86:89], v68 offset:18464
	s_waitcnt lgkmcnt(2)
	v_mfma_f32_32x32x16_bf16 v[34:49], v[94:97], v[126:129], v[34:49]
	ds_read_b128 v[90:93], v1 offset:55328
	s_waitcnt lgkmcnt(2)
	v_mfma_f32_32x32x16_bf16 v[50:65], v[94:97], v[130:133], v[50:65]
	ds_read_b128 v[94:97], v1 offset:59936
	s_waitcnt lgkmcnt(1)
	v_mfma_f32_32x32x16_bf16 v[34:49], v[86:89], v[90:93], v[34:49]
	s_waitcnt lgkmcnt(0)
	v_mfma_f32_32x32x16_bf16 v[50:65], v[86:89], v[94:97], v[50:65]
	s_waitcnt vmcnt(1)
	ds_write_b128 v66, v[140:143]
	ds_write_b128 v66, v[102:105] offset:4608
	global_load_dwordx4 v[140:143], v[72:73], off offset:384
	global_load_dwordx4 v[102:105], v[70:71], off offset:384
	ds_read_b128 v[86:89], v68 offset:23072
	v_mfma_f32_32x32x16_bf16 v[2:17], v[98:101], v[126:129], v[2:17]
	v_mfma_f32_32x32x16_bf16 v[18:33], v[98:101], v[130:133], v[18:33]
	ds_read_b128 v[98:101], v68 offset:23136
	s_waitcnt lgkmcnt(1)
	v_mfma_f32_32x32x16_bf16 v[2:17], v[86:89], v[90:93], v[2:17]
	ds_read_b128 v[90:93], v1 offset:55360
	v_mfma_f32_32x32x16_bf16 v[18:33], v[86:89], v[94:97], v[18:33]
	ds_write_b128 v66, v[106:109] offset:9216
	ds_write_b128 v66, v[110:113] offset:13824
	global_load_dwordx4 v[106:109], v[74:75], off offset:384
	global_load_dwordx4 v[110:113], v[78:79], off offset:384
	ds_read_b128 v[86:89], v68 offset:18496
	ds_read_b128 v[94:97], v1 offset:59968
	s_waitcnt lgkmcnt(1)
	v_mfma_f32_32x32x16_bf16 v[34:49], v[86:89], v[90:93], v[34:49]
	s_waitcnt lgkmcnt(0)
	v_mfma_f32_32x32x16_bf16 v[50:65], v[86:89], v[94:97], v[50:65]
	ds_read_b128 v[86:89], v68 offset:23104
	s_waitcnt lgkmcnt(0)
	v_mfma_f32_32x32x16_bf16 v[2:17], v[86:89], v[90:93], v[2:17]
	ds_read_b128 v[90:93], v1 offset:55392
	v_mfma_f32_32x32x16_bf16 v[18:33], v[86:89], v[94:97], v[18:33]
	s_waitcnt vmcnt(4)
	ds_write_b128 v66, v[144:147] offset:36864
	ds_write_b128 v66, v[122:125] offset:41472
	global_load_dwordx4 v[144:147], v[76:77], off offset:384
	global_load_dwordx4 v[122:125], v[80:81], off offset:384
	ds_read_b128 v[86:89], v68 offset:18528
	ds_read_b128 v[94:97], v1 offset:60000
	s_waitcnt lgkmcnt(1)
	v_mfma_f32_32x32x16_bf16 v[34:49], v[86:89], v[90:93], v[34:49]
	s_waitcnt lgkmcnt(0)
	v_mfma_f32_32x32x16_bf16 v[50:65], v[86:89], v[94:97], v[50:65]
	v_mfma_f32_32x32x16_bf16 v[2:17], v[98:101], v[90:93], v[2:17]
	v_mfma_f32_32x32x16_bf16 v[18:33], v[98:101], v[94:97], v[18:33]
	ds_write_b128 v66, v[118:121] offset:46080
	ds_write_b128 v66, v[114:117] offset:50688
	global_load_dwordx4 v[118:121], v[82:83], off offset:384
	global_load_dwordx4 v[114:117], v[84:85], off offset:384
	s_setprio 0
	s_waitcnt lgkmcnt(0)
	s_barrier
	ds_read_b128 v[94:97], v68
	ds_read_b128 v[98:101], v68 offset:4608
	ds_read_b128 v[126:129], v1 offset:36864
	ds_read_b128 v[130:133], v1 offset:41472
	s_setprio 1
	ds_read_b128 v[86:89], v68 offset:32
	s_waitcnt lgkmcnt(2)
	v_mfma_f32_32x32x16_bf16 v[34:49], v[94:97], v[126:129], v[34:49]
	ds_read_b128 v[90:93], v1 offset:36896
	s_waitcnt lgkmcnt(2)
	v_mfma_f32_32x32x16_bf16 v[50:65], v[94:97], v[130:133], v[50:65]
	ds_read_b128 v[94:97], v1 offset:41504
	s_waitcnt lgkmcnt(1)
	v_mfma_f32_32x32x16_bf16 v[34:49], v[86:89], v[90:93], v[34:49]
	s_waitcnt lgkmcnt(0)
	v_mfma_f32_32x32x16_bf16 v[50:65], v[86:89], v[94:97], v[50:65]
	s_waitcnt vmcnt(7)
	ds_write_b128 v66, v[140:143] offset:18432
	s_waitcnt vmcnt(6)
	ds_write_b128 v66, v[102:105] offset:23040
	global_load_dwordx4 v[140:143], v[72:73], off offset:512
	global_load_dwordx4 v[102:105], v[70:71], off offset:512
	ds_read_b128 v[86:89], v68 offset:4640
	v_mfma_f32_32x32x16_bf16 v[2:17], v[98:101], v[126:129], v[2:17]
	v_mfma_f32_32x32x16_bf16 v[18:33], v[98:101], v[130:133], v[18:33]
	ds_read_b128 v[98:101], v68 offset:4704
	s_waitcnt lgkmcnt(1)
	v_mfma_f32_32x32x16_bf16 v[2:17], v[86:89], v[90:93], v[2:17]
	ds_read_b128 v[90:93], v1 offset:36928
	v_mfma_f32_32x32x16_bf16 v[18:33], v[86:89], v[94:97], v[18:33]
	s_waitcnt vmcnt(7)
	ds_write_b128 v66, v[106:109] offset:27648
	s_waitcnt vmcnt(6)
	ds_write_b128 v66, v[110:113] offset:32256
	global_load_dwordx4 v[106:109], v[74:75], off offset:512
	global_load_dwordx4 v[110:113], v[78:79], off offset:512
	ds_read_b128 v[86:89], v68 offset:64
	ds_read_b128 v[94:97], v1 offset:41536
	s_waitcnt lgkmcnt(1)
	v_mfma_f32_32x32x16_bf16 v[34:49], v[86:89], v[90:93], v[34:49]
	s_waitcnt lgkmcnt(0)
	v_mfma_f32_32x32x16_bf16 v[50:65], v[86:89], v[94:97], v[50:65]
	ds_read_b128 v[86:89], v68 offset:4672
	s_waitcnt lgkmcnt(0)
	v_mfma_f32_32x32x16_bf16 v[2:17], v[86:89], v[90:93], v[2:17]
	ds_read_b128 v[90:93], v1 offset:36960
	v_mfma_f32_32x32x16_bf16 v[18:33], v[86:89], v[94:97], v[18:33]
	s_waitcnt vmcnt(7)
	ds_write_b128 v66, v[144:147] offset:55296
	s_waitcnt vmcnt(6)
	ds_write_b128 v66, v[122:125] offset:59904
	global_load_dwordx4 v[144:147], v[76:77], off offset:512
	global_load_dwordx4 v[122:125], v[80:81], off offset:512
	ds_read_b128 v[86:89], v68 offset:96
	ds_read_b128 v[94:97], v1 offset:41568
	s_waitcnt lgkmcnt(1)
	v_mfma_f32_32x32x16_bf16 v[34:49], v[86:89], v[90:93], v[34:49]
	s_waitcnt lgkmcnt(0)
	v_mfma_f32_32x32x16_bf16 v[50:65], v[86:89], v[94:97], v[50:65]
	v_mfma_f32_32x32x16_bf16 v[2:17], v[98:101], v[90:93], v[2:17]
	v_mfma_f32_32x32x16_bf16 v[18:33], v[98:101], v[94:97], v[18:33]
	s_waitcnt vmcnt(7)
	ds_write_b128 v66, v[118:121] offset:64512
	s_waitcnt vmcnt(6)
	ds_write_b128 v69, v[114:117] offset:32256
	global_load_dwordx4 v[118:121], v[82:83], off offset:512
	global_load_dwordx4 v[114:117], v[84:85], off offset:512
	s_setprio 0
	s_waitcnt lgkmcnt(0)
	s_barrier
; #define MFMA(a, b, c) __builtin_amdgcn_mfma_f32_32x32x16_bf16((a), (b), (c), 0, 0, 0)
; template <int TM, int TN>
; DI void gemm_mainloop(const u16* __restrict__ A, long lda, const u16* __restrict__ Bt, long ldb, int K, char* smem,
;                       f32x16 (&acc)[TM][TN]) {
;     ...
;   for (int kt = 0; kt < nk; kt++) {
;     const int buf = kt & 1;
;     const u16* cA = sA + buf * BM * LD + (wm * 32 * TM + r) * LD + h * 8;
;     const u16* cB = sB + buf * BN * LD + (wn * 32 * TN + r) * LD + h * 8;
;     bf16x8 af[TM], bfr[TN];
; #pragma unroll
;     for (int tm = 0; tm < TM; tm++) af[tm] = *(const bf16x8*)(cA + tm * 32 * LD);
; #pragma unroll
;     for (int tn = 0; tn < TN; tn++) bfr[tn] = *(const bf16x8*)(cB + tn * 32 * LD);
;     if (kt + 1 < nk) GEMM_SSTORE(buf ^ 1)
;     __builtin_amdgcn_sched_barrier(0);
;     __builtin_amdgcn_s_setprio(1);
; #pragma unroll
;     for (int tm = 0; tm < TM; tm++)
; #pragma unroll
;       for (int tn = 0; tn < TN; tn++) acc[tm][tn] = MFMA(af[tm], bfr[tn], acc[tm][tn]);
; #pragma unroll
;     for (int tm = 0; tm < TM; tm++) af[tm] = *(const bf16x8*)(cA + tm * 32 * LD + 16);
; #pragma unroll
;     for (int tn = 0; tn < TN; tn++) bfr[tn] = *(const bf16x8*)(cB + tn * 32 * LD + 16);
; #pragma unroll
;     for (int tm = 0; tm < TM; tm++)
; #pragma unroll
;       for (int tn = 0; tn < TN; tn++) acc[tm][tn] = MFMA(af[tm], bfr[tn], acc[tm][tn]);
;     __builtin_amdgcn_sched_group_barrier(0x8, 4, 0);
;     if (kt + 2 < nk) GEMM_GLOAD((kt + 2) * 64)
; #pragma unroll
;     for (int ks = 2; ks < 4; ks++) {
; #pragma unroll
;       for (int tm = 0; tm < TM; tm++) af[tm] = *(const bf16x8*)(cA + tm * 32 * LD + ks * 16);
; #pragma unroll
;       for (int tn = 0; tn < TN; tn++) bfr[tn] = *(const bf16x8*)(cB + tn * 32 * LD + ks * 16);
; #pragma unroll
;       for (int tm = 0; tm < TM; tm++)
; #pragma unroll
;         for (int tn = 0; tn < TN; tn++) acc[tm][tn] = MFMA(af[tm], bfr[tn], acc[tm][tn]);
;     }
;     __builtin_amdgcn_s_setprio(0);
;     __syncthreads();
;   }
	ds_read_b128 v[94:97], v68 offset:18432
	ds_read_b128 v[98:101], v68 offset:23040
	ds_read_b128 v[126:129], v1 offset:55296
	ds_read_b128 v[130:133], v1 offset:59904
	s_setprio 1
	ds_read_b128 v[86:89], v68 offset:18464
	s_waitcnt lgkmcnt(2)
	v_mfma_f32_32x32x16_bf16 v[34:49], v[94:97], v[126:129], v[34:49]
	ds_read_b128 v[90:93], v1 offset:55328
	s_waitcnt lgkmcnt(2)
	v_mfma_f32_32x32x16_bf16 v[50:65], v[94:97], v[130:133], v[50:65]
	ds_read_b128 v[94:97], v1 offset:59936
	s_waitcnt lgkmcnt(1)
	v_mfma_f32_32x32x16_bf16 v[34:49], v[86:89], v[90:93], v[34:49]
	s_waitcnt lgkmcnt(0)
	v_mfma_f32_32x32x16_bf16 v[50:65], v[86:89], v[94:97], v[50:65]
	s_waitcnt vmcnt(7)
	ds_write_b128 v66, v[140:143]
	s_waitcnt vmcnt(6)
	ds_write_b128 v66, v[102:105] offset:4608
	global_load_dwordx4 v[140:143], v[72:73], off offset:640
	global_load_dwordx4 v[102:105], v[70:71], off offset:640
	ds_read_b128 v[86:89], v68 offset:23072
	v_mfma_f32_32x32x16_bf16 v[2:17], v[98:101], v[126:129], v[2:17]
	v_mfma_f32_32x32x16_bf16 v[18:33], v[98:101], v[130:133], v[18:33]
	ds_read_b128 v[98:101], v68 offset:23136
	s_waitcnt lgkmcnt(1)
	v_mfma_f32_32x32x16_bf16 v[2:17], v[86:89], v[90:93], v[2:17]
	ds_read_b128 v[90:93], v1 offset:55360
	v_mfma_f32_32x32x16_bf16 v[18:33], v[86:89], v[94:97], v[18:33]
	s_waitcnt vmcnt(7)
	ds_write_b128 v66, v[106:109] offset:9216
	s_waitcnt vmcnt(6)
	ds_write_b128 v66, v[110:113] offset:13824
	global_load_dwordx4 v[106:109], v[74:75], off offset:640
	global_load_dwordx4 v[110:113], v[78:79], off offset:640
	ds_read_b128 v[86:89], v68 offset:18496
	ds_read_b128 v[94:97], v1 offset:59968
	s_waitcnt lgkmcnt(1)
	v_mfma_f32_32x32x16_bf16 v[34:49], v[86:89], v[90:93], v[34:49]
	s_waitcnt lgkmcnt(0)
	v_mfma_f32_32x32x16_bf16 v[50:65], v[86:89], v[94:97], v[50:65]
	ds_read_b128 v[86:89], v68 offset:23104
	s_waitcnt lgkmcnt(0)
	v_mfma_f32_32x32x16_bf16 v[2:17], v[86:89], v[90:93], v[2:17]
	ds_read_b128 v[90:93], v1 offset:55392
	v_mfma_f32_32x32x16_bf16 v[18:33], v[86:89], v[94:97], v[18:33]
	s_waitcnt vmcnt(7)
	ds_write_b128 v66, v[144:147] offset:36864
	s_waitcnt vmcnt(6)
	ds_write_b128 v66, v[122:125] offset:41472
	global_load_dwordx4 v[144:147], v[76:77], off offset:640
	global_load_dwordx4 v[122:125], v[80:81], off offset:640
	ds_read_b128 v[86:89], v68 offset:18528
	ds_read_b128 v[94:97], v1 offset:60000
	s_waitcnt lgkmcnt(1)
	v_mfma_f32_32x32x16_bf16 v[34:49], v[86:89], v[90:93], v[34:49]
	s_waitcnt lgkmcnt(0)
	v_mfma_f32_32x32x16_bf16 v[50:65], v[86:89], v[94:97], v[50:65]
	v_mfma_f32_32x32x16_bf16 v[2:17], v[98:101], v[90:93], v[2:17]
	v_mfma_f32_32x32x16_bf16 v[18:33], v[98:101], v[94:97], v[18:33]
	s_waitcnt vmcnt(7)
	ds_write_b128 v66, v[118:121] offset:46080
	s_waitcnt vmcnt(6)
	ds_write_b128 v66, v[114:117] offset:50688
	global_load_dwordx4 v[118:121], v[82:83], off offset:640
	global_load_dwordx4 v[114:117], v[84:85], off offset:640
	s_setprio 0
	s_waitcnt lgkmcnt(0)
	s_barrier
	ds_read_b128 v[94:97], v68
	ds_read_b128 v[98:101], v68 offset:4608
	ds_read_b128 v[126:129], v1 offset:36864
	ds_read_b128 v[130:133], v1 offset:41472
	s_setprio 1
	ds_read_b128 v[86:89], v68 offset:32
	s_waitcnt lgkmcnt(2)
	v_mfma_f32_32x32x16_bf16 v[34:49], v[94:97], v[126:129], v[34:49]
	ds_read_b128 v[90:93], v1 offset:36896
	s_waitcnt lgkmcnt(2)
	v_mfma_f32_32x32x16_bf16 v[50:65], v[94:97], v[130:133], v[50:65]
	ds_read_b128 v[94:97], v1 offset:41504
	s_waitcnt lgkmcnt(1)
	v_mfma_f32_32x32x16_bf16 v[34:49], v[86:89], v[90:93], v[34:49]
	s_waitcnt lgkmcnt(0)
	v_mfma_f32_32x32x16_bf16 v[50:65], v[86:89], v[94:97], v[50:65]
	s_waitcnt vmcnt(7)
	ds_write_b128 v66, v[140:143] offset:18432
	s_waitcnt vmcnt(6)
	ds_write_b128 v66, v[102:105] offset:23040
	global_load_dwordx4 v[140:143], v[72:73], off offset:768
	global_load_dwordx4 v[102:105], v[70:71], off offset:768
	ds_read_b128 v[86:89], v68 offset:4640
	v_mfma_f32_32x32x16_bf16 v[2:17], v[98:101], v[126:129], v[2:17]
	v_mfma_f32_32x32x16_bf16 v[18:33], v[98:101], v[130:133], v[18:33]
	ds_read_b128 v[98:101], v68 offset:4704
	s_waitcnt lgkmcnt(1)
	v_mfma_f32_32x32x16_bf16 v[2:17], v[86:89], v[90:93], v[2:17]
	ds_read_b128 v[90:93], v1 offset:36928
	v_mfma_f32_32x32x16_bf16 v[18:33], v[86:89], v[94:97], v[18:33]
	s_waitcnt vmcnt(7)
	ds_write_b128 v66, v[106:109] offset:27648
	s_waitcnt vmcnt(6)
	ds_write_b128 v66, v[110:113] offset:32256
	global_load_dwordx4 v[106:109], v[74:75], off offset:768
	global_load_dwordx4 v[110:113], v[78:79], off offset:768
	ds_read_b128 v[86:89], v68 offset:64
	ds_read_b128 v[94:97], v1 offset:41536
	s_waitcnt lgkmcnt(1)
	v_mfma_f32_32x32x16_bf16 v[34:49], v[86:89], v[90:93], v[34:49]
	s_waitcnt lgkmcnt(0)
	v_mfma_f32_32x32x16_bf16 v[50:65], v[86:89], v[94:97], v[50:65]
	ds_read_b128 v[86:89], v68 offset:4672
	s_waitcnt lgkmcnt(0)
	v_mfma_f32_32x32x16_bf16 v[2:17], v[86:89], v[90:93], v[2:17]
	ds_read_b128 v[90:93], v1 offset:36960
	v_mfma_f32_32x32x16_bf16 v[18:33], v[86:89], v[94:97], v[18:33]
	s_waitcnt vmcnt(7)
	ds_write_b128 v66, v[144:147] offset:55296
	s_waitcnt vmcnt(6)
	ds_write_b128 v66, v[122:125] offset:59904
	global_load_dwordx4 v[144:147], v[76:77], off offset:768
	global_load_dwordx4 v[122:125], v[80:81], off offset:768
	ds_read_b128 v[86:89], v68 offset:96
	ds_read_b128 v[94:97], v1 offset:41568
	s_waitcnt lgkmcnt(1)
	v_mfma_f32_32x32x16_bf16 v[34:49], v[86:89], v[90:93], v[34:49]
	s_waitcnt lgkmcnt(0)
	v_mfma_f32_32x32x16_bf16 v[50:65], v[86:89], v[94:97], v[50:65]
	v_mfma_f32_32x32x16_bf16 v[2:17], v[98:101], v[90:93], v[2:17]
	v_mfma_f32_32x32x16_bf16 v[18:33], v[98:101], v[94:97], v[18:33]
	s_waitcnt vmcnt(7)
	ds_write_b128 v66, v[118:121] offset:64512
	s_waitcnt vmcnt(6)
	ds_write_b128 v69, v[114:117] offset:32256
	global_load_dwordx4 v[118:121], v[82:83], off offset:768
	global_load_dwordx4 v[114:117], v[84:85], off offset:768
	s_setprio 0
	s_waitcnt lgkmcnt(0)
	s_barrier
; #define MFMA(a, b, c) __builtin_amdgcn_mfma_f32_32x32x16_bf16((a), (b), (c), 0, 0, 0)
; template <int TM, int TN>
; DI void gemm_mainloop(const u16* __restrict__ A, long lda, const u16* __restrict__ Bt, long ldb, int K, char* smem,
;                       f32x16 (&acc)[TM][TN]) {
;     ...
;   for (int kt = 0; kt < nk; kt++) {
;     const int buf = kt & 1;
;     const u16* cA = sA + buf * BM * LD + (wm * 32 * TM + r) * LD + h * 8;
;     const u16* cB = sB + buf * BN * LD + (wn * 32 * TN + r) * LD + h * 8;
;     bf16x8 af[TM], bfr[TN];
; #pragma unroll
;     for (int tm = 0; tm < TM; tm++) af[tm] = *(const bf16x8*)(cA + tm * 32 * LD);
; #pragma unroll
;     for (int tn = 0; tn < TN; tn++) bfr[tn] = *(const bf16x8*)(cB + tn * 32 * LD);
;     if (kt + 1 < nk) GEMM_SSTORE(buf ^ 1)
;     __builtin_amdgcn_sched_barrier(0);
;     __builtin_amdgcn_s_setprio(1);
; #pragma unroll
;     for (int tm = 0; tm < TM; tm++)
; #pragma unroll
;       for (int tn = 0; tn < TN; tn++) acc[tm][tn] = MFMA(af[tm], bfr[tn], acc[tm][tn]);
; #pragma unroll
;     for (int tm = 0; tm < TM; tm++) af[tm] = *(const bf16x8*)(cA + tm * 32 * LD + 16);
; #pragma unroll
;     for (int tn = 0; tn < TN; tn++) bfr[tn] = *(const bf16x8*)(cB + tn * 32 * LD + 16);
; #pragma unroll
;     for (int tm = 0; tm < TM; tm++)
; #pragma unroll
;       for (int tn = 0; tn < TN; tn++) acc[tm][tn] = MFMA(af[tm], bfr[tn], acc[tm][tn]);
;     __builtin_amdgcn_sched_group_barrier(0x8, 4, 0);
;     if (kt + 2 < nk) GEMM_GLOAD((kt + 2) * 64)
; #pragma unroll
;     for (int ks = 2; ks < 4; ks++) {
; #pragma unroll
;       for (int tm = 0; tm < TM; tm++) af[tm] = *(const bf16x8*)(cA + tm * 32 * LD + ks * 16);
; #pragma unroll
;       for (int tn = 0; tn < TN; tn++) bfr[tn] = *(const bf16x8*)(cB + tn * 32 * LD + ks * 16);
; #pragma unroll
;       for (int tm = 0; tm < TM; tm++)
; #pragma unroll
;         for (int tn = 0; tn < TN; tn++) acc[tm][tn] = MFMA(af[tm], bfr[tn], acc[tm][tn]);
;     }
;     __builtin_amdgcn_s_setprio(0);
;     __syncthreads();
;   }
	ds_read_b128 v[94:97], v68 offset:18432
	ds_read_b128 v[98:101], v68 offset:23040
	ds_read_b128 v[126:129], v1 offset:55296
	ds_read_b128 v[130:133], v1 offset:59904
	s_setprio 1
	ds_read_b128 v[86:89], v68 offset:18464
	s_waitcnt lgkmcnt(2)
	v_mfma_f32_32x32x16_bf16 v[34:49], v[94:97], v[126:129], v[34:49]
	ds_read_b128 v[90:93], v1 offset:55328
	s_waitcnt lgkmcnt(2)
	v_mfma_f32_32x32x16_bf16 v[50:65], v[94:97], v[130:133], v[50:65]
	ds_read_b128 v[94:97], v1 offset:59936
	s_waitcnt lgkmcnt(1)
	v_mfma_f32_32x32x16_bf16 v[34:49], v[86:89], v[90:93], v[34:49]
	s_waitcnt lgkmcnt(0)
	v_mfma_f32_32x32x16_bf16 v[50:65], v[86:89], v[94:97], v[50:65]
	s_waitcnt vmcnt(7)
	ds_write_b128 v66, v[140:143]
	s_waitcnt vmcnt(6)
	ds_write_b128 v66, v[102:105] offset:4608
	global_load_dwordx4 v[140:143], v[72:73], off offset:896
	global_load_dwordx4 v[102:105], v[70:71], off offset:896
	ds_read_b128 v[86:89], v68 offset:23072
	v_mfma_f32_32x32x16_bf16 v[2:17], v[98:101], v[126:129], v[2:17]
	v_mfma_f32_32x32x16_bf16 v[18:33], v[98:101], v[130:133], v[18:33]
	ds_read_b128 v[98:101], v68 offset:23136
	s_waitcnt lgkmcnt(1)
	v_mfma_f32_32x32x16_bf16 v[2:17], v[86:89], v[90:93], v[2:17]
	ds_read_b128 v[90:93], v1 offset:55360
	v_mfma_f32_32x32x16_bf16 v[18:33], v[86:89], v[94:97], v[18:33]
	s_waitcnt vmcnt(7)
	ds_write_b128 v66, v[106:109] offset:9216
	s_waitcnt vmcnt(6)
	ds_write_b128 v66, v[110:113] offset:13824
	global_load_dwordx4 v[106:109], v[74:75], off offset:896
	global_load_dwordx4 v[110:113], v[78:79], off offset:896
	ds_read_b128 v[86:89], v68 offset:18496
	ds_read_b128 v[94:97], v1 offset:59968
	s_waitcnt lgkmcnt(1)
	v_mfma_f32_32x32x16_bf16 v[34:49], v[86:89], v[90:93], v[34:49]
	s_waitcnt lgkmcnt(0)
	v_mfma_f32_32x32x16_bf16 v[50:65], v[86:89], v[94:97], v[50:65]
	ds_read_b128 v[86:89], v68 offset:23104
	s_waitcnt lgkmcnt(0)
	v_mfma_f32_32x32x16_bf16 v[2:17], v[86:89], v[90:93], v[2:17]
	ds_read_b128 v[90:93], v1 offset:55392
	v_mfma_f32_32x32x16_bf16 v[18:33], v[86:89], v[94:97], v[18:33]
	s_waitcnt vmcnt(7)
	ds_write_b128 v66, v[144:147] offset:36864
	s_waitcnt vmcnt(6)
	ds_write_b128 v66, v[122:125] offset:41472
	global_load_dwordx4 v[144:147], v[76:77], off offset:896
	global_load_dwordx4 v[122:125], v[80:81], off offset:896
	ds_read_b128 v[86:89], v68 offset:18528
	ds_read_b128 v[94:97], v1 offset:60000
	s_waitcnt lgkmcnt(1)
	v_mfma_f32_32x32x16_bf16 v[34:49], v[86:89], v[90:93], v[34:49]
	s_waitcnt lgkmcnt(0)
	v_mfma_f32_32x32x16_bf16 v[50:65], v[86:89], v[94:97], v[50:65]
	v_mfma_f32_32x32x16_bf16 v[2:17], v[98:101], v[90:93], v[2:17]
	v_mfma_f32_32x32x16_bf16 v[18:33], v[98:101], v[94:97], v[18:33]
	s_waitcnt vmcnt(7)
	ds_write_b128 v66, v[118:121] offset:46080
	s_waitcnt vmcnt(6)
	ds_write_b128 v66, v[114:117] offset:50688
	global_load_dwordx4 v[118:121], v[82:83], off offset:896
	global_load_dwordx4 v[114:117], v[84:85], off offset:896
	s_setprio 0
	s_waitcnt lgkmcnt(0)
	s_barrier
	ds_read_b128 v[94:97], v68
	ds_read_b128 v[98:101], v68 offset:4608
	ds_read_b128 v[126:129], v1 offset:36864
	ds_read_b128 v[130:133], v1 offset:41472
	s_setprio 1
	ds_read_b128 v[86:89], v68 offset:32
	s_waitcnt lgkmcnt(2)
	v_mfma_f32_32x32x16_bf16 v[34:49], v[94:97], v[126:129], v[34:49]
	ds_read_b128 v[90:93], v1 offset:36896
	s_waitcnt lgkmcnt(2)
	v_mfma_f32_32x32x16_bf16 v[50:65], v[94:97], v[130:133], v[50:65]
	ds_read_b128 v[94:97], v1 offset:41504
	s_waitcnt lgkmcnt(1)
	v_mfma_f32_32x32x16_bf16 v[34:49], v[86:89], v[90:93], v[34:49]
	s_waitcnt lgkmcnt(0)
	v_mfma_f32_32x32x16_bf16 v[50:65], v[86:89], v[94:97], v[50:65]
	s_waitcnt vmcnt(7)
	ds_write_b128 v66, v[140:143] offset:18432
	s_waitcnt vmcnt(6)
	ds_write_b128 v66, v[102:105] offset:23040
	global_load_dwordx4 v[140:143], v[72:73], off offset:1024
	global_load_dwordx4 v[102:105], v[70:71], off offset:1024
	ds_read_b128 v[86:89], v68 offset:4640
	v_mfma_f32_32x32x16_bf16 v[2:17], v[98:101], v[126:129], v[2:17]
	v_mfma_f32_32x32x16_bf16 v[18:33], v[98:101], v[130:133], v[18:33]
	ds_read_b128 v[98:101], v68 offset:4704
	s_waitcnt lgkmcnt(1)
	v_mfma_f32_32x32x16_bf16 v[2:17], v[86:89], v[90:93], v[2:17]
	ds_read_b128 v[90:93], v1 offset:36928
	v_mfma_f32_32x32x16_bf16 v[18:33], v[86:89], v[94:97], v[18:33]
	s_waitcnt vmcnt(7)
	ds_write_b128 v66, v[106:109] offset:27648
	s_waitcnt vmcnt(6)
	ds_write_b128 v66, v[110:113] offset:32256
	global_load_dwordx4 v[106:109], v[74:75], off offset:1024
	global_load_dwordx4 v[110:113], v[78:79], off offset:1024
	ds_read_b128 v[86:89], v68 offset:64
	ds_read_b128 v[94:97], v1 offset:41536
	s_waitcnt lgkmcnt(1)
	v_mfma_f32_32x32x16_bf16 v[34:49], v[86:89], v[90:93], v[34:49]
	s_waitcnt lgkmcnt(0)
	v_mfma_f32_32x32x16_bf16 v[50:65], v[86:89], v[94:97], v[50:65]
	ds_read_b128 v[86:89], v68 offset:4672
	s_waitcnt lgkmcnt(0)
	v_mfma_f32_32x32x16_bf16 v[2:17], v[86:89], v[90:93], v[2:17]
	ds_read_b128 v[90:93], v1 offset:36960
	v_mfma_f32_32x32x16_bf16 v[18:33], v[86:89], v[94:97], v[18:33]
	s_waitcnt vmcnt(7)
	ds_write_b128 v66, v[144:147] offset:55296
	s_waitcnt vmcnt(6)
	ds_write_b128 v66, v[122:125] offset:59904
	global_load_dwordx4 v[144:147], v[76:77], off offset:1024
	global_load_dwordx4 v[122:125], v[80:81], off offset:1024
	ds_read_b128 v[86:89], v68 offset:96
	ds_read_b128 v[94:97], v1 offset:41568
	s_waitcnt lgkmcnt(1)
	v_mfma_f32_32x32x16_bf16 v[34:49], v[86:89], v[90:93], v[34:49]
	s_waitcnt lgkmcnt(0)
	v_mfma_f32_32x32x16_bf16 v[50:65], v[86:89], v[94:97], v[50:65]
	v_mfma_f32_32x32x16_bf16 v[2:17], v[98:101], v[90:93], v[2:17]
	v_mfma_f32_32x32x16_bf16 v[18:33], v[98:101], v[94:97], v[18:33]
	s_waitcnt vmcnt(7)
	ds_write_b128 v66, v[118:121] offset:64512
	s_waitcnt vmcnt(6)
	ds_write_b128 v69, v[114:117] offset:32256
	global_load_dwordx4 v[118:121], v[82:83], off offset:1024
	global_load_dwordx4 v[114:117], v[84:85], off offset:1024
	s_setprio 0
	s_waitcnt lgkmcnt(0)
	s_barrier
; #define MFMA(a, b, c) __builtin_amdgcn_mfma_f32_32x32x16_bf16((a), (b), (c), 0, 0, 0)
; template <int TM, int TN>
; DI void gemm_mainloop(const u16* __restrict__ A, long lda, const u16* __restrict__ Bt, long ldb, int K, char* smem,
;                       f32x16 (&acc)[TM][TN]) {
;     ...
;   for (int kt = 0; kt < nk; kt++) {
;     const int buf = kt & 1;
;     const u16* cA = sA + buf * BM * LD + (wm * 32 * TM + r) * LD + h * 8;
;     const u16* cB = sB + buf * BN * LD + (wn * 32 * TN + r) * LD + h * 8;
;     bf16x8 af[TM], bfr[TN];
; #pragma unroll
;     for (int tm = 0; tm < TM; tm++) af[tm] = *(const bf16x8*)(cA + tm * 32 * LD);
; #pragma unroll
;     for (int tn = 0; tn < TN; tn++) bfr[tn] = *(const bf16x8*)(cB + tn * 32 * LD);
;     if (kt + 1 < nk) GEMM_SSTORE(buf ^ 1)
;     __builtin_amdgcn_sched_barrier(0);
;     __builtin_amdgcn_s_setprio(1);
; #pragma unroll
;     for (int tm = 0; tm < TM; tm++)
; #pragma unroll
;       for (int tn = 0; tn < TN; tn++) acc[tm][tn] = MFMA(af[tm], bfr[tn], acc[tm][tn]);
; #pragma unroll
;     for (int tm = 0; tm < TM; tm++) af[tm] = *(const bf16x8*)(cA + tm * 32 * LD + 16);
; #pragma unroll
;     for (int tn = 0; tn < TN; tn++) bfr[tn] = *(const bf16x8*)(cB + tn * 32 * LD + 16);
; #pragma unroll
;     for (int tm = 0; tm < TM; tm++)
; #pragma unroll
;       for (int tn = 0; tn < TN; tn++) acc[tm][tn] = MFMA(af[tm], bfr[tn], acc[tm][tn]);
;     __builtin_amdgcn_sched_group_barrier(0x8, 4, 0);
;     if (kt + 2 < nk) GEMM_GLOAD((kt + 2) * 64)
; #pragma unroll
;     for (int ks = 2; ks < 4; ks++) {
; #pragma unroll
;       for (int tm = 0; tm < TM; tm++) af[tm] = *(const bf16x8*)(cA + tm * 32 * LD + ks * 16);
; #pragma unroll
;       for (int tn = 0; tn < TN; tn++) bfr[tn] = *(const bf16x8*)(cB + tn * 32 * LD + ks * 16);
; #pragma unroll
;       for (int tm = 0; tm < TM; tm++)
; #pragma unroll
;         for (int tn = 0; tn < TN; tn++) acc[tm][tn] = MFMA(af[tm], bfr[tn], acc[tm][tn]);
;     }
;     __builtin_amdgcn_s_setprio(0);
;     __syncthreads();
;   }
	ds_read_b128 v[94:97], v68 offset:18432
	ds_read_b128 v[98:101], v68 offset:23040
	ds_read_b128 v[126:129], v1 offset:55296
	ds_read_b128 v[130:133], v1 offset:59904
	s_setprio 1
	ds_read_b128 v[86:89], v68 offset:18464
	s_waitcnt lgkmcnt(2)
	v_mfma_f32_32x32x16_bf16 v[34:49], v[94:97], v[126:129], v[34:49]
	ds_read_b128 v[90:93], v1 offset:55328
	s_waitcnt lgkmcnt(2)
	v_mfma_f32_32x32x16_bf16 v[50:65], v[94:97], v[130:133], v[50:65]
	ds_read_b128 v[94:97], v1 offset:59936
	s_waitcnt lgkmcnt(1)
	v_mfma_f32_32x32x16_bf16 v[34:49], v[86:89], v[90:93], v[34:49]
	s_waitcnt lgkmcnt(0)
	v_mfma_f32_32x32x16_bf16 v[50:65], v[86:89], v[94:97], v[50:65]
	s_waitcnt vmcnt(7)
	ds_write_b128 v66, v[140:143]
	s_waitcnt vmcnt(6)
	ds_write_b128 v66, v[102:105] offset:4608
	global_load_dwordx4 v[140:143], v[72:73], off offset:1152
	global_load_dwordx4 v[102:105], v[70:71], off offset:1152
	ds_read_b128 v[86:89], v68 offset:23072
	v_mfma_f32_32x32x16_bf16 v[2:17], v[98:101], v[126:129], v[2:17]
	v_mfma_f32_32x32x16_bf16 v[18:33], v[98:101], v[130:133], v[18:33]
	ds_read_b128 v[98:101], v68 offset:23136
	s_waitcnt lgkmcnt(1)
	v_mfma_f32_32x32x16_bf16 v[2:17], v[86:89], v[90:93], v[2:17]
	ds_read_b128 v[90:93], v1 offset:55360
	v_mfma_f32_32x32x16_bf16 v[18:33], v[86:89], v[94:97], v[18:33]
	s_waitcnt vmcnt(7)
	ds_write_b128 v66, v[106:109] offset:9216
	s_waitcnt vmcnt(6)
	ds_write_b128 v66, v[110:113] offset:13824
	global_load_dwordx4 v[106:109], v[74:75], off offset:1152
	global_load_dwordx4 v[110:113], v[78:79], off offset:1152
	ds_read_b128 v[86:89], v68 offset:18496
	ds_read_b128 v[94:97], v1 offset:59968
	s_waitcnt lgkmcnt(1)
	v_mfma_f32_32x32x16_bf16 v[34:49], v[86:89], v[90:93], v[34:49]
	s_waitcnt lgkmcnt(0)
	v_mfma_f32_32x32x16_bf16 v[50:65], v[86:89], v[94:97], v[50:65]
	ds_read_b128 v[86:89], v68 offset:23104
	s_waitcnt lgkmcnt(0)
	v_mfma_f32_32x32x16_bf16 v[2:17], v[86:89], v[90:93], v[2:17]
	ds_read_b128 v[90:93], v1 offset:55392
	v_mfma_f32_32x32x16_bf16 v[18:33], v[86:89], v[94:97], v[18:33]
	s_waitcnt vmcnt(7)
	ds_write_b128 v66, v[144:147] offset:36864
	s_waitcnt vmcnt(6)
	ds_write_b128 v66, v[122:125] offset:41472
	global_load_dwordx4 v[144:147], v[76:77], off offset:1152
	global_load_dwordx4 v[122:125], v[80:81], off offset:1152
	ds_read_b128 v[86:89], v68 offset:18528
	ds_read_b128 v[94:97], v1 offset:60000
	s_waitcnt lgkmcnt(1)
	v_mfma_f32_32x32x16_bf16 v[34:49], v[86:89], v[90:93], v[34:49]
	s_waitcnt lgkmcnt(0)
	v_mfma_f32_32x32x16_bf16 v[50:65], v[86:89], v[94:97], v[50:65]
	v_mfma_f32_32x32x16_bf16 v[2:17], v[98:101], v[90:93], v[2:17]
	v_mfma_f32_32x32x16_bf16 v[18:33], v[98:101], v[94:97], v[18:33]
	s_waitcnt vmcnt(7)
	ds_write_b128 v66, v[118:121] offset:46080
	s_waitcnt vmcnt(6)
	ds_write_b128 v66, v[114:117] offset:50688
	global_load_dwordx4 v[118:121], v[82:83], off offset:1152
	global_load_dwordx4 v[114:117], v[84:85], off offset:1152
	s_setprio 0
	s_waitcnt lgkmcnt(0)
	s_barrier
	ds_read_b128 v[94:97], v68
	ds_read_b128 v[98:101], v68 offset:4608
	ds_read_b128 v[126:129], v1 offset:36864
	ds_read_b128 v[130:133], v1 offset:41472
	s_setprio 1
	ds_read_b128 v[86:89], v68 offset:32
	s_waitcnt lgkmcnt(2)
	v_mfma_f32_32x32x16_bf16 v[34:49], v[94:97], v[126:129], v[34:49]
	ds_read_b128 v[90:93], v1 offset:36896
	s_waitcnt lgkmcnt(2)
	v_mfma_f32_32x32x16_bf16 v[50:65], v[94:97], v[130:133], v[50:65]
	ds_read_b128 v[94:97], v1 offset:41504
	s_waitcnt lgkmcnt(1)
	v_mfma_f32_32x32x16_bf16 v[34:49], v[86:89], v[90:93], v[34:49]
	s_waitcnt lgkmcnt(0)
	v_mfma_f32_32x32x16_bf16 v[50:65], v[86:89], v[94:97], v[50:65]
	s_waitcnt vmcnt(7)
	ds_write_b128 v66, v[140:143] offset:18432
	s_waitcnt vmcnt(6)
	ds_write_b128 v66, v[102:105] offset:23040
	global_load_dwordx4 v[140:143], v[72:73], off offset:1280
	global_load_dwordx4 v[102:105], v[70:71], off offset:1280
	ds_read_b128 v[86:89], v68 offset:4640
	v_mfma_f32_32x32x16_bf16 v[2:17], v[98:101], v[126:129], v[2:17]
	v_mfma_f32_32x32x16_bf16 v[18:33], v[98:101], v[130:133], v[18:33]
	ds_read_b128 v[98:101], v68 offset:4704
	s_waitcnt lgkmcnt(1)
	v_mfma_f32_32x32x16_bf16 v[2:17], v[86:89], v[90:93], v[2:17]
	ds_read_b128 v[90:93], v1 offset:36928
	v_mfma_f32_32x32x16_bf16 v[18:33], v[86:89], v[94:97], v[18:33]
	s_waitcnt vmcnt(7)
	ds_write_b128 v66, v[106:109] offset:27648
	s_waitcnt vmcnt(6)
	ds_write_b128 v66, v[110:113] offset:32256
	global_load_dwordx4 v[106:109], v[74:75], off offset:1280
	global_load_dwordx4 v[110:113], v[78:79], off offset:1280
	ds_read_b128 v[86:89], v68 offset:64
	ds_read_b128 v[94:97], v1 offset:41536
	s_waitcnt lgkmcnt(1)
	v_mfma_f32_32x32x16_bf16 v[34:49], v[86:89], v[90:93], v[34:49]
	s_waitcnt lgkmcnt(0)
	v_mfma_f32_32x32x16_bf16 v[50:65], v[86:89], v[94:97], v[50:65]
	ds_read_b128 v[86:89], v68 offset:4672
	s_waitcnt lgkmcnt(0)
	v_mfma_f32_32x32x16_bf16 v[2:17], v[86:89], v[90:93], v[2:17]
	ds_read_b128 v[90:93], v1 offset:36960
	v_mfma_f32_32x32x16_bf16 v[18:33], v[86:89], v[94:97], v[18:33]
	s_waitcnt vmcnt(7)
	ds_write_b128 v66, v[144:147] offset:55296
	s_waitcnt vmcnt(6)
	ds_write_b128 v66, v[122:125] offset:59904
	global_load_dwordx4 v[144:147], v[76:77], off offset:1280
	global_load_dwordx4 v[122:125], v[80:81], off offset:1280
	ds_read_b128 v[86:89], v68 offset:96
	ds_read_b128 v[94:97], v1 offset:41568
	s_waitcnt lgkmcnt(1)
	v_mfma_f32_32x32x16_bf16 v[34:49], v[86:89], v[90:93], v[34:49]
	s_waitcnt lgkmcnt(0)
	v_mfma_f32_32x32x16_bf16 v[50:65], v[86:89], v[94:97], v[50:65]
	v_mfma_f32_32x32x16_bf16 v[2:17], v[98:101], v[90:93], v[2:17]
	v_mfma_f32_32x32x16_bf16 v[18:33], v[98:101], v[94:97], v[18:33]
	s_waitcnt vmcnt(7)
	ds_write_b128 v66, v[118:121] offset:64512
	s_waitcnt vmcnt(6)
	ds_write_b128 v69, v[114:117] offset:32256
	global_load_dwordx4 v[118:121], v[82:83], off offset:1280
	global_load_dwordx4 v[114:117], v[84:85], off offset:1280
	s_setprio 0
	s_waitcnt lgkmcnt(0)
	s_barrier
; #define MFMA(a, b, c) __builtin_amdgcn_mfma_f32_32x32x16_bf16((a), (b), (c), 0, 0, 0)
; template <int TM, int TN>
; DI void gemm_mainloop(const u16* __restrict__ A, long lda, const u16* __restrict__ Bt, long ldb, int K, char* smem,
;                       f32x16 (&acc)[TM][TN]) {
;     ...
;   for (int kt = 0; kt < nk; kt++) {
;     const int buf = kt & 1;
;     const u16* cA = sA + buf * BM * LD + (wm * 32 * TM + r) * LD + h * 8;
;     const u16* cB = sB + buf * BN * LD + (wn * 32 * TN + r) * LD + h * 8;
;     bf16x8 af[TM], bfr[TN];
; #pragma unroll
;     for (int tm = 0; tm < TM; tm++) af[tm] = *(const bf16x8*)(cA + tm * 32 * LD);
; #pragma unroll
;     for (int tn = 0; tn < TN; tn++) bfr[tn] = *(const bf16x8*)(cB + tn * 32 * LD);
;     if (kt + 1 < nk) GEMM_SSTORE(buf ^ 1)
;     __builtin_amdgcn_sched_barrier(0);
;     __builtin_amdgcn_s_setprio(1);
; #pragma unroll
;     for (int tm = 0; tm < TM; tm++)
; #pragma unroll
;       for (int tn = 0; tn < TN; tn++) acc[tm][tn] = MFMA(af[tm], bfr[tn], acc[tm][tn]);
; #pragma unroll
;     for (int tm = 0; tm < TM; tm++) af[tm] = *(const bf16x8*)(cA + tm * 32 * LD + 16);
; #pragma unroll
;     for (int tn = 0; tn < TN; tn++) bfr[tn] = *(const bf16x8*)(cB + tn * 32 * LD + 16);
; #pragma unroll
;     for (int tm = 0; tm < TM; tm++)
; #pragma unroll
;       for (int tn = 0; tn < TN; tn++) acc[tm][tn] = MFMA(af[tm], bfr[tn], acc[tm][tn]);
;     __builtin_amdgcn_sched_group_barrier(0x8, 4, 0);
;     if (kt + 2 < nk) GEMM_GLOAD((kt + 2) * 64)
; #pragma unroll
;     for (int ks = 2; ks < 4; ks++) {
; #pragma unroll
;       for (int tm = 0; tm < TM; tm++) af[tm] = *(const bf16x8*)(cA + tm * 32 * LD + ks * 16);
; #pragma unroll
;       for (int tn = 0; tn < TN; tn++) bfr[tn] = *(const bf16x8*)(cB + tn * 32 * LD + ks * 16);
; #pragma unroll
;       for (int tm = 0; tm < TM; tm++)
; #pragma unroll
;         for (int tn = 0; tn < TN; tn++) acc[tm][tn] = MFMA(af[tm], bfr[tn], acc[tm][tn]);
;     }
;     __builtin_amdgcn_s_setprio(0);
;     __syncthreads();
;   }
	ds_read_b128 v[94:97], v68 offset:18432
	ds_read_b128 v[98:101], v68 offset:23040
	ds_read_b128 v[126:129], v1 offset:55296
	ds_read_b128 v[130:133], v1 offset:59904
	s_setprio 1
	ds_read_b128 v[86:89], v68 offset:18464
	s_waitcnt lgkmcnt(2)
	v_mfma_f32_32x32x16_bf16 v[34:49], v[94:97], v[126:129], v[34:49]
	ds_read_b128 v[90:93], v1 offset:55328
	s_waitcnt lgkmcnt(2)
	v_mfma_f32_32x32x16_bf16 v[50:65], v[94:97], v[130:133], v[50:65]
	ds_read_b128 v[94:97], v1 offset:59936
	s_waitcnt lgkmcnt(1)
	v_mfma_f32_32x32x16_bf16 v[34:49], v[86:89], v[90:93], v[34:49]
	s_waitcnt lgkmcnt(0)
	v_mfma_f32_32x32x16_bf16 v[50:65], v[86:89], v[94:97], v[50:65]
	s_waitcnt vmcnt(7)
	ds_write_b128 v66, v[140:143]
	s_waitcnt vmcnt(6)
	ds_write_b128 v66, v[102:105] offset:4608
	global_load_dwordx4 v[140:143], v[72:73], off offset:1408
	global_load_dwordx4 v[102:105], v[70:71], off offset:1408
	ds_read_b128 v[86:89], v68 offset:23072
	v_mfma_f32_32x32x16_bf16 v[2:17], v[98:101], v[126:129], v[2:17]
	v_mfma_f32_32x32x16_bf16 v[18:33], v[98:101], v[130:133], v[18:33]
	ds_read_b128 v[98:101], v68 offset:23136
	s_waitcnt lgkmcnt(1)
	v_mfma_f32_32x32x16_bf16 v[2:17], v[86:89], v[90:93], v[2:17]
	ds_read_b128 v[90:93], v1 offset:55360
	v_mfma_f32_32x32x16_bf16 v[18:33], v[86:89], v[94:97], v[18:33]
	s_waitcnt vmcnt(7)
	ds_write_b128 v66, v[106:109] offset:9216
	s_waitcnt vmcnt(6)
	ds_write_b128 v66, v[110:113] offset:13824
	global_load_dwordx4 v[106:109], v[74:75], off offset:1408
	global_load_dwordx4 v[110:113], v[78:79], off offset:1408
	ds_read_b128 v[86:89], v68 offset:18496
	ds_read_b128 v[94:97], v1 offset:59968
	s_waitcnt lgkmcnt(1)
	v_mfma_f32_32x32x16_bf16 v[34:49], v[86:89], v[90:93], v[34:49]
	s_waitcnt lgkmcnt(0)
	v_mfma_f32_32x32x16_bf16 v[50:65], v[86:89], v[94:97], v[50:65]
	ds_read_b128 v[86:89], v68 offset:23104
	s_waitcnt lgkmcnt(0)
	v_mfma_f32_32x32x16_bf16 v[2:17], v[86:89], v[90:93], v[2:17]
	ds_read_b128 v[90:93], v1 offset:55392
	v_mfma_f32_32x32x16_bf16 v[18:33], v[86:89], v[94:97], v[18:33]
	s_waitcnt vmcnt(7)
	ds_write_b128 v66, v[144:147] offset:36864
	s_waitcnt vmcnt(6)
	ds_write_b128 v66, v[122:125] offset:41472
	global_load_dwordx4 v[144:147], v[76:77], off offset:1408
	global_load_dwordx4 v[122:125], v[80:81], off offset:1408
	ds_read_b128 v[86:89], v68 offset:18528
	ds_read_b128 v[94:97], v1 offset:60000
	s_waitcnt lgkmcnt(1)
	v_mfma_f32_32x32x16_bf16 v[34:49], v[86:89], v[90:93], v[34:49]
	s_waitcnt lgkmcnt(0)
	v_mfma_f32_32x32x16_bf16 v[50:65], v[86:89], v[94:97], v[50:65]
	v_mfma_f32_32x32x16_bf16 v[2:17], v[98:101], v[90:93], v[2:17]
	v_mfma_f32_32x32x16_bf16 v[18:33], v[98:101], v[94:97], v[18:33]
	s_waitcnt vmcnt(7)
	ds_write_b128 v66, v[118:121] offset:46080
	s_waitcnt vmcnt(6)
	ds_write_b128 v66, v[114:117] offset:50688
	global_load_dwordx4 v[118:121], v[82:83], off offset:1408
	global_load_dwordx4 v[114:117], v[84:85], off offset:1408
	s_setprio 0
	s_waitcnt lgkmcnt(0)
	s_barrier
	ds_read_b128 v[94:97], v68
	ds_read_b128 v[98:101], v68 offset:4608
	ds_read_b128 v[126:129], v1 offset:36864
	ds_read_b128 v[130:133], v1 offset:41472
	s_setprio 1
	ds_read_b128 v[86:89], v68 offset:32
	s_waitcnt lgkmcnt(2)
	v_mfma_f32_32x32x16_bf16 v[34:49], v[94:97], v[126:129], v[34:49]
	ds_read_b128 v[90:93], v1 offset:36896
	s_waitcnt lgkmcnt(2)
	v_mfma_f32_32x32x16_bf16 v[50:65], v[94:97], v[130:133], v[50:65]
	ds_read_b128 v[94:97], v1 offset:41504
	s_waitcnt lgkmcnt(1)
	v_mfma_f32_32x32x16_bf16 v[34:49], v[86:89], v[90:93], v[34:49]
	s_waitcnt lgkmcnt(0)
	v_mfma_f32_32x32x16_bf16 v[50:65], v[86:89], v[94:97], v[50:65]
	s_waitcnt vmcnt(7)
	ds_write_b128 v66, v[140:143] offset:18432
	s_waitcnt vmcnt(6)
	ds_write_b128 v66, v[102:105] offset:23040
	global_load_dwordx4 v[140:143], v[72:73], off offset:1536
	global_load_dwordx4 v[102:105], v[70:71], off offset:1536
	ds_read_b128 v[86:89], v68 offset:4640
	v_mfma_f32_32x32x16_bf16 v[2:17], v[98:101], v[126:129], v[2:17]
	v_mfma_f32_32x32x16_bf16 v[18:33], v[98:101], v[130:133], v[18:33]
	ds_read_b128 v[98:101], v68 offset:4704
	s_waitcnt lgkmcnt(1)
	v_mfma_f32_32x32x16_bf16 v[2:17], v[86:89], v[90:93], v[2:17]
	ds_read_b128 v[90:93], v1 offset:36928
	v_mfma_f32_32x32x16_bf16 v[18:33], v[86:89], v[94:97], v[18:33]
	s_waitcnt vmcnt(7)
	ds_write_b128 v66, v[106:109] offset:27648
	s_waitcnt vmcnt(6)
	ds_write_b128 v66, v[110:113] offset:32256
	global_load_dwordx4 v[106:109], v[74:75], off offset:1536
	global_load_dwordx4 v[110:113], v[78:79], off offset:1536
	ds_read_b128 v[86:89], v68 offset:64
	ds_read_b128 v[94:97], v1 offset:41536
	s_waitcnt lgkmcnt(1)
	v_mfma_f32_32x32x16_bf16 v[34:49], v[86:89], v[90:93], v[34:49]
	s_waitcnt lgkmcnt(0)
	v_mfma_f32_32x32x16_bf16 v[50:65], v[86:89], v[94:97], v[50:65]
	ds_read_b128 v[86:89], v68 offset:4672
	s_waitcnt lgkmcnt(0)
	v_mfma_f32_32x32x16_bf16 v[2:17], v[86:89], v[90:93], v[2:17]
	ds_read_b128 v[90:93], v1 offset:36960
	v_mfma_f32_32x32x16_bf16 v[18:33], v[86:89], v[94:97], v[18:33]
	s_waitcnt vmcnt(7)
	ds_write_b128 v66, v[144:147] offset:55296
	s_waitcnt vmcnt(6)
	ds_write_b128 v66, v[122:125] offset:59904
	global_load_dwordx4 v[144:147], v[76:77], off offset:1536
	global_load_dwordx4 v[122:125], v[80:81], off offset:1536
	ds_read_b128 v[86:89], v68 offset:96
	ds_read_b128 v[94:97], v1 offset:41568
	s_waitcnt lgkmcnt(1)
	v_mfma_f32_32x32x16_bf16 v[34:49], v[86:89], v[90:93], v[34:49]
	s_waitcnt lgkmcnt(0)
	v_mfma_f32_32x32x16_bf16 v[50:65], v[86:89], v[94:97], v[50:65]
	v_mfma_f32_32x32x16_bf16 v[2:17], v[98:101], v[90:93], v[2:17]
	v_mfma_f32_32x32x16_bf16 v[18:33], v[98:101], v[94:97], v[18:33]
	s_waitcnt vmcnt(7)
	ds_write_b128 v66, v[118:121] offset:64512
	s_waitcnt vmcnt(6)
	ds_write_b128 v69, v[114:117] offset:32256
	global_load_dwordx4 v[118:121], v[82:83], off offset:1536
	global_load_dwordx4 v[114:117], v[84:85], off offset:1536
	s_setprio 0
	s_waitcnt lgkmcnt(0)
	s_barrier
; #define MFMA(a, b, c) __builtin_amdgcn_mfma_f32_32x32x16_bf16((a), (b), (c), 0, 0, 0)
; template <int TM, int TN>
; DI void gemm_mainloop(const u16* __restrict__ A, long lda, const u16* __restrict__ Bt, long ldb, int K, char* smem,
;                       f32x16 (&acc)[TM][TN]) {
;     ...
;   for (int kt = 0; kt < nk; kt++) {
;     const int buf = kt & 1;
;     const u16* cA = sA + buf * BM * LD + (wm * 32 * TM + r) * LD + h * 8;
;     const u16* cB = sB + buf * BN * LD + (wn * 32 * TN + r) * LD + h * 8;
;     bf16x8 af[TM], bfr[TN];
; #pragma unroll
;     for (int tm = 0; tm < TM; tm++) af[tm] = *(const bf16x8*)(cA + tm * 32 * LD);
; #pragma unroll
;     for (int tn = 0; tn < TN; tn++) bfr[tn] = *(const bf16x8*)(cB + tn * 32 * LD);
;     if (kt + 1 < nk) GEMM_SSTORE(buf ^ 1)
;     __builtin_amdgcn_sched_barrier(0);
;     __builtin_amdgcn_s_setprio(1);
; #pragma unroll
;     for (int tm = 0; tm < TM; tm++)
; #pragma unroll
;       for (int tn = 0; tn < TN; tn++) acc[tm][tn] = MFMA(af[tm], bfr[tn], acc[tm][tn]);
; #pragma unroll
;     for (int tm = 0; tm < TM; tm++) af[tm] = *(const bf16x8*)(cA + tm * 32 * LD + 16);
; #pragma unroll
;     for (int tn = 0; tn < TN; tn++) bfr[tn] = *(const bf16x8*)(cB + tn * 32 * LD + 16);
; #pragma unroll
;     for (int tm = 0; tm < TM; tm++)
; #pragma unroll
;       for (int tn = 0; tn < TN; tn++) acc[tm][tn] = MFMA(af[tm], bfr[tn], acc[tm][tn]);
;     __builtin_amdgcn_sched_group_barrier(0x8, 4, 0);
;     if (kt + 2 < nk) GEMM_GLOAD((kt + 2) * 64)
; #pragma unroll
;     for (int ks = 2; ks < 4; ks++) {
; #pragma unroll
;       for (int tm = 0; tm < TM; tm++) af[tm] = *(const bf16x8*)(cA + tm * 32 * LD + ks * 16);
; #pragma unroll
;       for (int tn = 0; tn < TN; tn++) bfr[tn] = *(const bf16x8*)(cB + tn * 32 * LD + ks * 16);
; #pragma unroll
;       for (int tm = 0; tm < TM; tm++)
; #pragma unroll
;         for (int tn = 0; tn < TN; tn++) acc[tm][tn] = MFMA(af[tm], bfr[tn], acc[tm][tn]);
;     }
;     __builtin_amdgcn_s_setprio(0);
;     __syncthreads();
;   }
	ds_read_b128 v[94:97], v68 offset:18432
	ds_read_b128 v[98:101], v68 offset:23040
	ds_read_b128 v[126:129], v1 offset:55296
	ds_read_b128 v[130:133], v1 offset:59904
	s_setprio 1
	ds_read_b128 v[86:89], v68 offset:18464
	s_waitcnt lgkmcnt(2)
	v_mfma_f32_32x32x16_bf16 v[34:49], v[94:97], v[126:129], v[34:49]
	ds_read_b128 v[90:93], v1 offset:55328
	s_waitcnt lgkmcnt(2)
	v_mfma_f32_32x32x16_bf16 v[50:65], v[94:97], v[130:133], v[50:65]
	ds_read_b128 v[94:97], v1 offset:59936
	s_waitcnt lgkmcnt(1)
	v_mfma_f32_32x32x16_bf16 v[34:49], v[86:89], v[90:93], v[34:49]
	s_waitcnt lgkmcnt(0)
	v_mfma_f32_32x32x16_bf16 v[50:65], v[86:89], v[94:97], v[50:65]
	s_waitcnt vmcnt(7)
	ds_write_b128 v66, v[140:143]
	s_waitcnt vmcnt(6)
	ds_write_b128 v66, v[102:105] offset:4608
	global_load_dwordx4 v[140:143], v[72:73], off offset:1664
	global_load_dwordx4 v[102:105], v[70:71], off offset:1664
	ds_read_b128 v[86:89], v68 offset:23072
	v_mfma_f32_32x32x16_bf16 v[2:17], v[98:101], v[126:129], v[2:17]
	v_mfma_f32_32x32x16_bf16 v[18:33], v[98:101], v[130:133], v[18:33]
	ds_read_b128 v[98:101], v68 offset:23136
	s_waitcnt lgkmcnt(1)
	v_mfma_f32_32x32x16_bf16 v[2:17], v[86:89], v[90:93], v[2:17]
	ds_read_b128 v[90:93], v1 offset:55360
	v_mfma_f32_32x32x16_bf16 v[18:33], v[86:89], v[94:97], v[18:33]
	s_waitcnt vmcnt(7)
	ds_write_b128 v66, v[106:109] offset:9216
	s_waitcnt vmcnt(6)
	ds_write_b128 v66, v[110:113] offset:13824
	global_load_dwordx4 v[106:109], v[74:75], off offset:1664
	global_load_dwordx4 v[110:113], v[78:79], off offset:1664
	ds_read_b128 v[86:89], v68 offset:18496
	ds_read_b128 v[94:97], v1 offset:59968
	s_waitcnt lgkmcnt(1)
	v_mfma_f32_32x32x16_bf16 v[34:49], v[86:89], v[90:93], v[34:49]
	s_waitcnt lgkmcnt(0)
	v_mfma_f32_32x32x16_bf16 v[50:65], v[86:89], v[94:97], v[50:65]
	ds_read_b128 v[86:89], v68 offset:23104
	s_waitcnt lgkmcnt(0)
	v_mfma_f32_32x32x16_bf16 v[2:17], v[86:89], v[90:93], v[2:17]
	ds_read_b128 v[90:93], v1 offset:55392
	v_mfma_f32_32x32x16_bf16 v[18:33], v[86:89], v[94:97], v[18:33]
	s_waitcnt vmcnt(7)
	ds_write_b128 v66, v[144:147] offset:36864
	s_waitcnt vmcnt(6)
	ds_write_b128 v66, v[122:125] offset:41472
	global_load_dwordx4 v[144:147], v[76:77], off offset:1664
	global_load_dwordx4 v[122:125], v[80:81], off offset:1664
	ds_read_b128 v[86:89], v68 offset:18528
	ds_read_b128 v[94:97], v1 offset:60000
	s_waitcnt lgkmcnt(1)
	v_mfma_f32_32x32x16_bf16 v[34:49], v[86:89], v[90:93], v[34:49]
	s_waitcnt lgkmcnt(0)
	v_mfma_f32_32x32x16_bf16 v[50:65], v[86:89], v[94:97], v[50:65]
	v_mfma_f32_32x32x16_bf16 v[2:17], v[98:101], v[90:93], v[2:17]
	v_mfma_f32_32x32x16_bf16 v[18:33], v[98:101], v[94:97], v[18:33]
	s_waitcnt vmcnt(7)
	ds_write_b128 v66, v[118:121] offset:46080
	s_waitcnt vmcnt(6)
	ds_write_b128 v66, v[114:117] offset:50688
	global_load_dwordx4 v[118:121], v[82:83], off offset:1664
	global_load_dwordx4 v[114:117], v[84:85], off offset:1664
	s_setprio 0
	s_waitcnt lgkmcnt(0)
	s_barrier
	ds_read_b128 v[94:97], v68
	ds_read_b128 v[98:101], v68 offset:4608
	ds_read_b128 v[126:129], v1 offset:36864
	ds_read_b128 v[130:133], v1 offset:41472
	s_setprio 1
	ds_read_b128 v[86:89], v68 offset:32
	s_waitcnt lgkmcnt(2)
	v_mfma_f32_32x32x16_bf16 v[34:49], v[94:97], v[126:129], v[34:49]
	ds_read_b128 v[90:93], v1 offset:36896
	s_waitcnt lgkmcnt(2)
	v_mfma_f32_32x32x16_bf16 v[50:65], v[94:97], v[130:133], v[50:65]
	ds_read_b128 v[94:97], v1 offset:41504
	s_waitcnt lgkmcnt(1)
	v_mfma_f32_32x32x16_bf16 v[34:49], v[86:89], v[90:93], v[34:49]
	s_waitcnt lgkmcnt(0)
	v_mfma_f32_32x32x16_bf16 v[50:65], v[86:89], v[94:97], v[50:65]
	s_waitcnt vmcnt(7)
	ds_write_b128 v66, v[140:143] offset:18432
	s_waitcnt vmcnt(6)
	ds_write_b128 v66, v[102:105] offset:23040
	global_load_dwordx4 v[140:143], v[72:73], off offset:1792
	global_load_dwordx4 v[102:105], v[70:71], off offset:1792
	ds_read_b128 v[86:89], v68 offset:4640
	v_mfma_f32_32x32x16_bf16 v[2:17], v[98:101], v[126:129], v[2:17]
	v_mfma_f32_32x32x16_bf16 v[18:33], v[98:101], v[130:133], v[18:33]
	ds_read_b128 v[98:101], v68 offset:4704
	s_waitcnt lgkmcnt(1)
	v_mfma_f32_32x32x16_bf16 v[2:17], v[86:89], v[90:93], v[2:17]
	ds_read_b128 v[90:93], v1 offset:36928
	v_mfma_f32_32x32x16_bf16 v[18:33], v[86:89], v[94:97], v[18:33]
	s_waitcnt vmcnt(7)
	ds_write_b128 v66, v[106:109] offset:27648
	s_waitcnt vmcnt(6)
	ds_write_b128 v66, v[110:113] offset:32256
	global_load_dwordx4 v[106:109], v[74:75], off offset:1792
	global_load_dwordx4 v[110:113], v[78:79], off offset:1792
	ds_read_b128 v[86:89], v68 offset:64
	ds_read_b128 v[94:97], v1 offset:41536
	s_waitcnt lgkmcnt(1)
	v_mfma_f32_32x32x16_bf16 v[34:49], v[86:89], v[90:93], v[34:49]
	s_waitcnt lgkmcnt(0)
	v_mfma_f32_32x32x16_bf16 v[50:65], v[86:89], v[94:97], v[50:65]
	ds_read_b128 v[86:89], v68 offset:4672
	s_waitcnt lgkmcnt(0)
	v_mfma_f32_32x32x16_bf16 v[2:17], v[86:89], v[90:93], v[2:17]
	ds_read_b128 v[90:93], v1 offset:36960
	v_mfma_f32_32x32x16_bf16 v[18:33], v[86:89], v[94:97], v[18:33]
	s_waitcnt vmcnt(7)
	ds_write_b128 v66, v[144:147] offset:55296
	s_waitcnt vmcnt(6)
	ds_write_b128 v66, v[122:125] offset:59904
	global_load_dwordx4 v[144:147], v[76:77], off offset:1792
	global_load_dwordx4 v[122:125], v[80:81], off offset:1792
	ds_read_b128 v[86:89], v68 offset:96
	ds_read_b128 v[94:97], v1 offset:41568
	s_waitcnt lgkmcnt(1)
	v_mfma_f32_32x32x16_bf16 v[34:49], v[86:89], v[90:93], v[34:49]
	s_waitcnt lgkmcnt(0)
	v_mfma_f32_32x32x16_bf16 v[50:65], v[86:89], v[94:97], v[50:65]
	v_mfma_f32_32x32x16_bf16 v[2:17], v[98:101], v[90:93], v[2:17]
	v_mfma_f32_32x32x16_bf16 v[18:33], v[98:101], v[94:97], v[18:33]
	s_waitcnt vmcnt(7)
	ds_write_b128 v66, v[118:121] offset:64512
	s_waitcnt vmcnt(6)
	ds_write_b128 v69, v[114:117] offset:32256
	global_load_dwordx4 v[118:121], v[82:83], off offset:1792
	global_load_dwordx4 v[114:117], v[84:85], off offset:1792
	s_setprio 0
	s_waitcnt lgkmcnt(0)
	s_barrier
; #define MFMA(a, b, c) __builtin_amdgcn_mfma_f32_32x32x16_bf16((a), (b), (c), 0, 0, 0)
; template <int TM, int TN>
; DI void gemm_mainloop(const u16* __restrict__ A, long lda, const u16* __restrict__ Bt, long ldb, int K, char* smem,
;                       f32x16 (&acc)[TM][TN]) {
;     ...
;   for (int kt = 0; kt < nk; kt++) {
;     const int buf = kt & 1;
;     const u16* cA = sA + buf * BM * LD + (wm * 32 * TM + r) * LD + h * 8;
;     const u16* cB = sB + buf * BN * LD + (wn * 32 * TN + r) * LD + h * 8;
;     bf16x8 af[TM], bfr[TN];
; #pragma unroll
;     for (int tm = 0; tm < TM; tm++) af[tm] = *(const bf16x8*)(cA + tm * 32 * LD);
; #pragma unroll
;     for (int tn = 0; tn < TN; tn++) bfr[tn] = *(const bf16x8*)(cB + tn * 32 * LD);
;     if (kt + 1 < nk) GEMM_SSTORE(buf ^ 1)
;     __builtin_amdgcn_sched_barrier(0);
;     __builtin_amdgcn_s_setprio(1);
; #pragma unroll
;     for (int tm = 0; tm < TM; tm++)
; #pragma unroll
;       for (int tn = 0; tn < TN; tn++) acc[tm][tn] = MFMA(af[tm], bfr[tn], acc[tm][tn]);
; #pragma unroll
;     for (int tm = 0; tm < TM; tm++) af[tm] = *(const bf16x8*)(cA + tm * 32 * LD + 16);
; #pragma unroll
;     for (int tn = 0; tn < TN; tn++) bfr[tn] = *(const bf16x8*)(cB + tn * 32 * LD + 16);
; #pragma unroll
;     for (int tm = 0; tm < TM; tm++)
; #pragma unroll
;       for (int tn = 0; tn < TN; tn++) acc[tm][tn] = MFMA(af[tm], bfr[tn], acc[tm][tn]);
;     __builtin_amdgcn_sched_group_barrier(0x8, 4, 0);
;     if (kt + 2 < nk) GEMM_GLOAD((kt + 2) * 64)
; #pragma unroll
;     for (int ks = 2; ks < 4; ks++) {
; #pragma unroll
;       for (int tm = 0; tm < TM; tm++) af[tm] = *(const bf16x8*)(cA + tm * 32 * LD + ks * 16);
; #pragma unroll
;       for (int tn = 0; tn < TN; tn++) bfr[tn] = *(const bf16x8*)(cB + tn * 32 * LD + ks * 16);
; #pragma unroll
;       for (int tm = 0; tm < TM; tm++)
; #pragma unroll
;         for (int tn = 0; tn < TN; tn++) acc[tm][tn] = MFMA(af[tm], bfr[tn], acc[tm][tn]);
;     }
;     __builtin_amdgcn_s_setprio(0);
;     __syncthreads();
;   }
	ds_read_b128 v[94:97], v68 offset:18432
	ds_read_b128 v[98:101], v68 offset:23040
	ds_read_b128 v[126:129], v1 offset:55296
	ds_read_b128 v[130:133], v1 offset:59904
	s_setprio 1
	ds_read_b128 v[86:89], v68 offset:18464
	s_waitcnt lgkmcnt(2)
	v_mfma_f32_32x32x16_bf16 v[34:49], v[94:97], v[126:129], v[34:49]
	ds_read_b128 v[90:93], v1 offset:55328
	s_waitcnt lgkmcnt(2)
	v_mfma_f32_32x32x16_bf16 v[50:65], v[94:97], v[130:133], v[50:65]
	ds_read_b128 v[94:97], v1 offset:59936
	s_waitcnt lgkmcnt(1)
	v_mfma_f32_32x32x16_bf16 v[34:49], v[86:89], v[90:93], v[34:49]
	s_waitcnt lgkmcnt(0)
	v_mfma_f32_32x32x16_bf16 v[50:65], v[86:89], v[94:97], v[50:65]
	s_waitcnt vmcnt(7)
	ds_write_b128 v66, v[140:143]
	s_waitcnt vmcnt(6)
	ds_write_b128 v66, v[102:105] offset:4608
	global_load_dwordx4 v[140:143], v[72:73], off offset:1920
	global_load_dwordx4 v[102:105], v[70:71], off offset:1920
	ds_read_b128 v[86:89], v68 offset:23072
	v_mfma_f32_32x32x16_bf16 v[2:17], v[98:101], v[126:129], v[2:17]
	v_mfma_f32_32x32x16_bf16 v[18:33], v[98:101], v[130:133], v[18:33]
	ds_read_b128 v[98:101], v68 offset:23136
	s_waitcnt lgkmcnt(1)
	v_mfma_f32_32x32x16_bf16 v[2:17], v[86:89], v[90:93], v[2:17]
	ds_read_b128 v[90:93], v1 offset:55360
	v_mfma_f32_32x32x16_bf16 v[18:33], v[86:89], v[94:97], v[18:33]
	s_waitcnt vmcnt(7)
	ds_write_b128 v66, v[106:109] offset:9216
	s_waitcnt vmcnt(6)
	ds_write_b128 v66, v[110:113] offset:13824
	global_load_dwordx4 v[106:109], v[74:75], off offset:1920
	global_load_dwordx4 v[110:113], v[78:79], off offset:1920
	ds_read_b128 v[86:89], v68 offset:18496
	ds_read_b128 v[94:97], v1 offset:59968
	s_waitcnt lgkmcnt(1)
	v_mfma_f32_32x32x16_bf16 v[34:49], v[86:89], v[90:93], v[34:49]
	s_waitcnt lgkmcnt(0)
	v_mfma_f32_32x32x16_bf16 v[50:65], v[86:89], v[94:97], v[50:65]
	ds_read_b128 v[86:89], v68 offset:23104
	s_waitcnt lgkmcnt(0)
	v_mfma_f32_32x32x16_bf16 v[2:17], v[86:89], v[90:93], v[2:17]
	ds_read_b128 v[90:93], v1 offset:55392
	v_mfma_f32_32x32x16_bf16 v[18:33], v[86:89], v[94:97], v[18:33]
	s_waitcnt vmcnt(7)
	ds_write_b128 v66, v[144:147] offset:36864
	s_waitcnt vmcnt(6)
	ds_write_b128 v66, v[122:125] offset:41472
	global_load_dwordx4 v[144:147], v[76:77], off offset:1920
	global_load_dwordx4 v[122:125], v[80:81], off offset:1920
	ds_read_b128 v[86:89], v68 offset:18528
	ds_read_b128 v[94:97], v1 offset:60000
	s_waitcnt lgkmcnt(1)
	v_mfma_f32_32x32x16_bf16 v[34:49], v[86:89], v[90:93], v[34:49]
	s_waitcnt lgkmcnt(0)
	v_mfma_f32_32x32x16_bf16 v[50:65], v[86:89], v[94:97], v[50:65]
	s_nop 0
	v_mfma_f32_32x32x16_bf16 v[2:17], v[98:101], v[90:93], v[2:17]
	v_mfma_f32_32x32x16_bf16 v[18:33], v[98:101], v[94:97], v[18:33]
	s_waitcnt vmcnt(7)
	ds_write_b128 v66, v[118:121] offset:46080
	s_waitcnt vmcnt(6)
	ds_write_b128 v66, v[114:117] offset:50688
	global_load_dwordx4 v[118:121], v[82:83], off offset:1920
	global_load_dwordx4 v[114:117], v[84:85], off offset:1920
	s_setprio 0
	s_waitcnt lgkmcnt(0)
	s_barrier
	ds_read_b128 v[74:77], v68
	ds_read_b128 v[78:81], v68 offset:4608
	ds_read_b128 v[82:85], v1 offset:36864
	ds_read_b128 v[90:93], v1 offset:41472
	s_setprio 1
	ds_read_b128 v[70:73], v68 offset:32
	s_waitcnt lgkmcnt(2)
	v_mfma_f32_32x32x16_bf16 v[34:49], v[74:77], v[82:85], v[34:49]
	s_waitcnt lgkmcnt(1)
	v_mfma_f32_32x32x16_bf16 v[50:65], v[74:77], v[90:93], v[50:65]
	ds_read_b128 v[74:77], v1 offset:36896
	v_mfma_f32_32x32x16_bf16 v[2:17], v[78:81], v[82:85], v[2:17]
	v_mfma_f32_32x32x16_bf16 v[18:33], v[78:81], v[90:93], v[18:33]
	s_waitcnt vmcnt(7)
	ds_write_b128 v66, v[140:143] offset:18432
	s_waitcnt vmcnt(6)
	ds_write_b128 v66, v[102:105] offset:23040
	ds_read_b128 v[78:81], v1 offset:41504
	s_waitcnt lgkmcnt(3)
	v_mfma_f32_32x32x16_bf16 v[34:49], v[70:73], v[74:77], v[34:49]
	s_waitcnt lgkmcnt(0)
	v_mfma_f32_32x32x16_bf16 v[50:65], v[70:73], v[78:81], v[50:65]
	ds_read_b128 v[70:73], v68 offset:4640
	s_waitcnt lgkmcnt(0)
	v_mfma_f32_32x32x16_bf16 v[2:17], v[70:73], v[74:77], v[2:17]
	ds_read_b128 v[74:77], v1 offset:36928
	v_mfma_f32_32x32x16_bf16 v[18:33], v[70:73], v[78:81], v[18:33]
	s_waitcnt vmcnt(5)
	ds_write_b128 v66, v[106:109] offset:27648
	s_waitcnt vmcnt(4)
	ds_write_b128 v66, v[110:113] offset:32256
	ds_read_b128 v[70:73], v68 offset:64
	ds_read_b128 v[78:81], v1 offset:41536
	s_waitcnt lgkmcnt(1)
	v_mfma_f32_32x32x16_bf16 v[34:49], v[70:73], v[74:77], v[34:49]
	s_waitcnt lgkmcnt(0)
	v_mfma_f32_32x32x16_bf16 v[50:65], v[70:73], v[78:81], v[50:65]
	ds_read_b128 v[70:73], v68 offset:4672
	s_waitcnt lgkmcnt(0)
	v_mfma_f32_32x32x16_bf16 v[2:17], v[70:73], v[74:77], v[2:17]
	ds_read_b128 v[74:77], v1 offset:36960
	v_mfma_f32_32x32x16_bf16 v[18:33], v[70:73], v[78:81], v[18:33]
	s_waitcnt vmcnt(3)
	ds_write_b128 v66, v[144:147] offset:55296
	s_waitcnt vmcnt(2)
	ds_write_b128 v66, v[122:125] offset:59904
	ds_read_b128 v[70:73], v68 offset:96
	ds_read_b128 v[78:81], v1 offset:41568
	s_waitcnt lgkmcnt(1)
	v_mfma_f32_32x32x16_bf16 v[34:49], v[70:73], v[74:77], v[34:49]
	s_waitcnt lgkmcnt(0)
	v_mfma_f32_32x32x16_bf16 v[50:65], v[70:73], v[78:81], v[50:65]
	ds_read_b128 v[70:73], v68 offset:4704
	s_waitcnt lgkmcnt(0)
	v_mfma_f32_32x32x16_bf16 v[2:17], v[70:73], v[74:77], v[2:17]
	v_mfma_f32_32x32x16_bf16 v[18:33], v[70:73], v[78:81], v[18:33]
	s_waitcnt vmcnt(1)
	ds_write_b128 v66, v[118:121] offset:64512
	s_waitcnt vmcnt(0)
	ds_write_b128 v69, v[114:117] offset:32256
	s_setprio 0
	s_waitcnt lgkmcnt(0)
	s_barrier
; #define MFMA(a, b, c) __builtin_amdgcn_mfma_f32_32x32x16_bf16((a), (b), (c), 0, 0, 0)
; DI int crow(int i, int h) { return (i & 3) + 8 * (i >> 2) + 4 * h; }
; template <int TM, int TN>
; DI void gemm_mainloop(const u16* __restrict__ A, long lda, const u16* __restrict__ Bt, long ldb, int K, char* smem,
;                       f32x16 (&acc)[TM][TN]) {
;     ...
;       for (int tm = 0; tm < TM; tm++)
; #pragma unroll
;         for (int tn = 0; tn < TN; tn++) acc[tm][tn] = MFMA(af[tm], bfr[tn], acc[tm][tn]);
;     }
;     __builtin_amdgcn_s_setprio(0);
;     __syncthreads();
;   }
; template <int TM, int TN, class Epi>
; DI void gemm_tile(const u16* A, long lda, const u16* Bt, long ldb, int K, int m0, int n0, char* smem, const Epi& epi) {
;     ...
; #pragma unroll
;   for (int tm = 0; tm < TM; tm++)
; #pragma unroll
;     for (int tn = 0; tn < TN; tn++)
; #pragma unroll
;       for (int i = 0; i < 16; i++)
;         Ct[(wm * 32 * TM + tm * 32 + crow(i, h)) * LDC + wn * 32 * TN + tn * 32 + r] = acc[tm][tn][i];
;   __syncthreads();
;   DI void operator()(const float* Ct, int ldc, int m0, int n0, int tid, int bm) const {
;     ...
;       int id = tid + 256 * it; int row = id >> 4, c8 = (id & 15) * 8;
;       const float* c = Ct + row * ldc + c8;
;       float* o = out + (long)(m0 + row) * ldo + n0 + c8;
;       *(float4*)o = *(const float4*)c; *(float4*)(o + 4) = *(const float4*)(c + 4);
	ds_read_b128 v[70:73], v68 offset:18432
	ds_read_b128 v[74:77], v68 offset:23040
	ds_read_b128 v[78:81], v1 offset:55296
	ds_read_b128 v[82:85], v1 offset:59904
	s_setprio 1
	s_waitcnt lgkmcnt(1)
	v_mfma_f32_32x32x16_bf16 v[34:49], v[70:73], v[78:81], v[34:49]
	s_waitcnt lgkmcnt(0)
	v_mfma_f32_32x32x16_bf16 v[50:65], v[70:73], v[82:85], v[50:65]
	ds_read_b128 v[70:73], v68 offset:18464
	v_mfma_f32_32x32x16_bf16 v[2:17], v[74:77], v[78:81], v[2:17]
	ds_read_b128 v[78:81], v1 offset:59936
	v_mfma_f32_32x32x16_bf16 v[18:33], v[74:77], v[82:85], v[18:33]
	ds_read_b128 v[74:77], v1 offset:55328
	s_waitcnt lgkmcnt(0)
	v_mfma_f32_32x32x16_bf16 v[34:49], v[70:73], v[74:77], v[34:49]
	v_mfma_f32_32x32x16_bf16 v[50:65], v[70:73], v[78:81], v[50:65]
	ds_read_b128 v[70:73], v68 offset:23072
	s_waitcnt lgkmcnt(0)
	v_mfma_f32_32x32x16_bf16 v[2:17], v[70:73], v[74:77], v[2:17]
	ds_read_b128 v[74:77], v1 offset:55360
	v_mfma_f32_32x32x16_bf16 v[18:33], v[70:73], v[78:81], v[18:33]
	ds_read_b128 v[70:73], v68 offset:18496
	ds_read_b128 v[78:81], v1 offset:59968
	s_waitcnt lgkmcnt(1)
	v_mfma_f32_32x32x16_bf16 v[34:49], v[70:73], v[74:77], v[34:49]
	s_waitcnt lgkmcnt(0)
	v_mfma_f32_32x32x16_bf16 v[50:65], v[70:73], v[78:81], v[50:65]
	ds_read_b128 v[70:73], v68 offset:23104
	s_waitcnt lgkmcnt(0)
	v_mfma_f32_32x32x16_bf16 v[2:17], v[70:73], v[74:77], v[2:17]
	ds_read_b128 v[74:77], v1 offset:55392
	v_mfma_f32_32x32x16_bf16 v[18:33], v[70:73], v[78:81], v[18:33]
	ds_read_b128 v[70:73], v68 offset:18528
	ds_read_b128 v[78:81], v1 offset:60000
	s_waitcnt lgkmcnt(1)
	v_mfma_f32_32x32x16_bf16 v[34:49], v[70:73], v[74:77], v[34:49]
	s_waitcnt lgkmcnt(0)
	v_mfma_f32_32x32x16_bf16 v[50:65], v[70:73], v[78:81], v[50:65]
	ds_read_b128 v[68:71], v68 offset:23136
	s_waitcnt lgkmcnt(0)
	v_mfma_f32_32x32x16_bf16 v[2:17], v[68:71], v[74:77], v[2:17]
	v_mfma_f32_32x32x16_bf16 v[18:33], v[68:71], v[78:81], v[18:33]
	s_setprio 0
	v_mov_b32_e32 v1, v0
	s_barrier
	s_lshl_b32 s25, s25, 2
	v_lshrrev_b32_e32 v66, 1, v1
	v_and_b32_e32 v66, 0xfffffc0, v66
	v_lshrrev_b32_e32 v68, 3, v1
	v_and_or_b32 v66, v68, 4, v66
	v_and_b32_e32 v68, 0x5f, v1
	v_mul_lo_u32 v66, v66, s20
	v_lshl_add_u32 v66, v68, 2, v66
	ds_write2_b32 v66, v34, v50 offset1:32
	v_add_u32_e32 v34, 0x400, v66
	ds_write2_b32 v34, v36, v52 offset0:8 offset1:40
	ds_write2_b32 v34, v37, v53 offset0:140 offset1:172
	v_add_u32_e32 v34, 0x1000, v66
	ds_write2_b32 v34, v38, v54 offset0:32 offset1:64
	ds_write2_b32 v34, v39, v55 offset0:164 offset1:196
	v_add_u32_e32 v34, 0x1400, v66
	ds_write2_b32 v34, v40, v56 offset0:40 offset1:72
	ds_write2_b32 v34, v41, v57 offset0:172 offset1:204
	v_add_u32_e32 v34, 0x2000, v66
	ds_write2_b32 v34, v42, v58 offset0:64 offset1:96
	ds_write2_b32 v34, v43, v59 offset0:196 offset1:228
	v_add_u32_e32 v34, 0x2400, v66
	ds_write2_b32 v34, v44, v60 offset0:72 offset1:104
	ds_write2_b32 v34, v45, v61 offset0:204 offset1:236
	v_add_u32_e32 v34, 0x3000, v66
	ds_write2_b32 v34, v46, v62 offset0:96 offset1:128
	v_add_u32_e32 v34, 0x3200, v66
	ds_write2_b32 v34, v47, v63 offset0:100 offset1:132
	v_add_u32_e32 v34, 0x3400, v66
	ds_write2_b32 v34, v48, v64 offset0:104 offset1:136
	v_add_u32_e32 v34, 0x3600, v66
	ds_write2_b32 v34, v49, v65 offset0:108 offset1:140
	v_add_u32_e32 v34, 0x4000, v66
	ds_write2_b32 v34, v2, v18 offset0:128 offset1:160
	v_add_u32_e32 v2, 0x4400, v66
	ds_write2_b32 v2, v3, v19 offset0:4 offset1:36
	ds_write2_b32 v2, v4, v20 offset0:136 offset1:168
	v_add_u32_e32 v2, 0x4800, v66
	ds_write2_b32 v2, v5, v21 offset0:12 offset1:44
	v_add_u32_e32 v2, 0x5000, v66
	ds_write2_b32 v2, v6, v22 offset0:160 offset1:192
	v_add_u32_e32 v2, 0x5400, v66
	ds_write2_b32 v2, v7, v23 offset0:36 offset1:68
	ds_write2_b32 v2, v8, v24 offset0:168 offset1:200
	v_add_u32_e32 v2, 0x5800, v66
	ds_write2_b32 v2, v9, v25 offset0:44 offset1:76
	v_add_u32_e32 v2, 0x6000, v66
	ds_write2_b32 v2, v10, v26 offset0:192 offset1:224
	v_add_u32_e32 v2, 0x6400, v66
	ds_write2_b32 v2, v11, v27 offset0:68 offset1:100
	ds_write2_b32 v2, v12, v28 offset0:200 offset1:232
	v_add_u32_e32 v2, 0x6800, v66
	ds_write2_b32 v2, v13, v29 offset0:76 offset1:108
	v_add_u32_e32 v2, 0x7200, v66
	ds_write2_b32 v2, v14, v30 offset0:96 offset1:128
	v_add_u32_e32 v2, 0x7400, v66
	ds_write2_b32 v2, v15, v31 offset0:100 offset1:132
	v_add_u32_e32 v2, 0x7600, v66
	ds_write2_b32 v2, v16, v32 offset0:104 offset1:136
	v_add_u32_e32 v2, 0x7800, v66
	ds_write2_b32 v2, v17, v33 offset0:108 offset1:140
	v_lshlrev_b32_e32 v2, 5, v1
	s_add_u32 s26, s23, s25
	ds_write2_b32 v66, v35, v51 offset0:132 offset1:164
	v_and_b32_e32 v66, 0x1e0, v2
	s_addc_u32 s27, s24, 0
	v_lshl_add_u64 v[2:3], s[26:27], 0, v[66:67]
	s_mov_b32 s23, 0
	s_waitcnt lgkmcnt(0)
	s_barrier

; #define MFMA(a, b, c) __builtin_amdgcn_mfma_f32_32x32x16_bf16((a), (b), (c), 0, 0, 0)
; template <int TM, int TN>
; DI void gemm_mainloop(const u16* __restrict__ A, long lda, const u16* __restrict__ Bt, long ldb, int K, char* smem,
;                       f32x16 (&acc)[TM][TN]) {
;     ...
;   const int nk = K / 64;
;   const int lrow = tid >> 3, lch = (tid & 7) * 8;
;   const u16* gA = A + (long)lrow * lda + lch;
;   const u16* gB = Bt + (long)lrow * ldb + lch;
;   const int soff = lrow * LD + lch;
;     ...
;   GEMM_GLOAD(0)
;   __syncthreads();
;   GEMM_SSTORE(0)
;   if (nk > 1) GEMM_GLOAD(64)
;   __syncthreads();
;   for (int kt = 0; kt < nk; kt++) {
;     const int buf = kt & 1;
;     const u16* cA = sA + buf * BM * LD + (wm * 32 * TM + r) * LD + h * 8;
;     const u16* cB = sB + buf * BN * LD + (wn * 32 * TN + r) * LD + h * 8;
;     bf16x8 af[TM], bfr[TN];
; #pragma unroll
;     for (int tm = 0; tm < TM; tm++) af[tm] = *(const bf16x8*)(cA + tm * 32 * LD);
; #pragma unroll
;     for (int tn = 0; tn < TN; tn++) bfr[tn] = *(const bf16x8*)(cB + tn * 32 * LD);
;     if (kt + 1 < nk) GEMM_SSTORE(buf ^ 1)
;     __builtin_amdgcn_sched_barrier(0);
;     __builtin_amdgcn_s_setprio(1);
; #pragma unroll
;     for (int tm = 0; tm < TM; tm++)
; #pragma unroll
;       for (int tn = 0; tn < TN; tn++) acc[tm][tn] = MFMA(af[tm], bfr[tn], acc[tm][tn]);
; #pragma unroll
;     for (int tm = 0; tm < TM; tm++) af[tm] = *(const bf16x8*)(cA + tm * 32 * LD + 16);
; #pragma unroll
;     for (int tn = 0; tn < TN; tn++) bfr[tn] = *(const bf16x8*)(cB + tn * 32 * LD + 16);
; #pragma unroll
;     for (int tm = 0; tm < TM; tm++)
; #pragma unroll
;       for (int tn = 0; tn < TN; tn++) acc[tm][tn] = MFMA(af[tm], bfr[tn], acc[tm][tn]);
;     __builtin_amdgcn_sched_group_barrier(0x8, 4, 0);
;     if (kt + 2 < nk) GEMM_GLOAD((kt + 2) * 64)
.LBB0_1072:
	s_lshl_b32 s27, s26, 10
	s_add_i32 s27, s27, s14
	s_mul_i32 s4, s27, 0x880
	s_mul_hi_i32 s5, s27, 0x880
	s_add_u32 s4, s8, s4
	v_mov_b32_e32 v1, v0
	s_addc_u32 s5, s9, s5
	s_nop 0
	v_lshlrev_b32_e32 v2, 3, v1
	v_ashrrev_i32_e32 v70, 3, v1
	v_and_b32_e32 v71, 56, v2
	v_mov_b64_e32 v[2:3], s[4:5]
	v_mad_i64_i32 v[2:3], s[4:5], v70, s17, v[2:3]
	v_lshlrev_b32_e32 v66, 1, v71
	v_lshl_add_u64 v[74:75], v[2:3], 0, v[66:67]
	v_add_co_u32_e32 v72, vcc, s19, v74
	v_mad_i64_i32 v[10:11], s[4:5], v70, s17, v[68:69]
	s_nop 0
	v_addc_co_u32_e32 v73, vcc, 0, v75, vcc
	v_add_co_u32_e32 v76, vcc, s20, v74
	v_lshl_add_u64 v[78:79], v[10:11], 0, v[66:67]
	s_nop 0
	v_addc_co_u32_e32 v77, vcc, 0, v75, vcc
	v_add_co_u32_e32 v80, vcc, s19, v78
	global_load_dwordx4 v[2:5], v[74:75], off
	s_nop 0
	v_addc_co_u32_e32 v81, vcc, 0, v79, vcc
	v_add_co_u32_e32 v82, vcc, s20, v78
	global_load_dwordx4 v[6:9], v[72:73], off
	s_nop 0
	v_addc_co_u32_e32 v83, vcc, 0, v79, vcc
	v_add_co_u32_e32 v84, vcc, s21, v78
	global_load_dwordx4 v[10:13], v[78:79], off
	s_nop 0
	v_addc_co_u32_e32 v85, vcc, 0, v79, vcc
	v_add_co_u32_e32 v86, vcc, s21, v74
	global_load_dwordx4 v[14:17], v[80:81], off
	s_nop 0
	v_addc_co_u32_e32 v87, vcc, 0, v75, vcc
	global_load_dwordx4 v[18:21], v[82:83], off
	global_load_dwordx4 v[22:25], v[84:85], off
	global_load_dwordx4 v[26:29], v[76:77], off
	global_load_dwordx4 v[30:33], v[86:87], off
	s_barrier
	global_load_dwordx4 v[34:37], v[74:75], off offset:128
	global_load_dwordx4 v[38:41], v[72:73], off offset:128
	global_load_dwordx4 v[42:45], v[76:77], off offset:128
	global_load_dwordx4 v[46:49], v[86:87], off offset:128
	global_load_dwordx4 v[50:53], v[78:79], off offset:128
	global_load_dwordx4 v[54:57], v[80:81], off offset:128
	global_load_dwordx4 v[58:61], v[82:83], off offset:128
	global_load_dwordx4 v[62:65], v[84:85], off offset:128
	v_and_b32_e32 v66, 31, v1
	v_lshrrev_b32_e32 v88, 1, v1
	v_mul_lo_u32 v70, v70, s18
	v_and_or_b32 v89, v88, s22, v66
	v_and_b32_e32 v88, 16, v88
	v_and_b32_e32 v1, 0x5f, v1
	v_add_lshl_u32 v66, v70, v71, 1
	v_mad_u64_u32 v[70:71], s[4:5], v89, s23, v[88:89]
	v_mad_u32_u24 v1, v1, s23, v88
	v_add_u32_e32 v71, 0x9000, v66
	s_waitcnt vmcnt(15)
	ds_write_b128 v66, v[2:5]
	s_waitcnt vmcnt(14)
	ds_write_b128 v66, v[6:9] offset:4608
	s_waitcnt vmcnt(13)
	ds_write_b128 v66, v[10:13] offset:36864
	s_waitcnt vmcnt(12)
	ds_write_b128 v66, v[14:17] offset:41472
	s_waitcnt vmcnt(11)
	ds_write_b128 v66, v[18:21] offset:46080
	s_waitcnt vmcnt(10)
	ds_write_b128 v66, v[22:25] offset:50688
	s_waitcnt vmcnt(9)
	ds_write_b128 v66, v[26:29] offset:9216
	s_waitcnt vmcnt(8)
	ds_write_b128 v66, v[30:33] offset:13824
	s_waitcnt lgkmcnt(0)
	s_barrier
	ds_read_b128 v[2:5], v70
	ds_read_b128 v[18:21], v70 offset:4608
	ds_read_b128 v[6:9], v1 offset:36864
	ds_read_b128 v[22:25], v1 offset:41472
	s_waitcnt vmcnt(7)
	ds_write_b128 v66, v[34:37] offset:18432
	s_waitcnt vmcnt(6)
	ds_write_b128 v66, v[38:41] offset:23040
	s_waitcnt vmcnt(5)
	ds_write_b128 v66, v[42:45] offset:27648
	s_waitcnt vmcnt(4)
	ds_write_b128 v66, v[46:49] offset:32256
	s_waitcnt vmcnt(3)
	ds_write_b128 v66, v[50:53] offset:55296
	s_waitcnt vmcnt(2)
	ds_write_b128 v66, v[54:57] offset:59904
	s_waitcnt vmcnt(1)
	ds_write_b128 v66, v[58:61] offset:64512
	s_waitcnt vmcnt(0)
	ds_write_b128 v71, v[62:65] offset:32256
	s_setprio 1
	ds_read_b128 v[88:91], v70 offset:32
	s_waitcnt lgkmcnt(10)
	v_mfma_f32_32x32x16_bf16 v[34:49], v[2:5], v[6:9], 0
	ds_read_b128 v[92:95], v1 offset:36896
	ds_read_b128 v[96:99], v1 offset:41504
	ds_read_b128 v[100:103], v70 offset:4704
	global_load_dwordx4 v[104:107], v[72:73], off offset:256
	global_load_dwordx4 v[108:111], v[76:77], off offset:256
	global_load_dwordx4 v[112:115], v[86:87], off offset:256
	global_load_dwordx4 v[116:119], v[84:85], off offset:256
	s_waitcnt lgkmcnt(12)
	v_mfma_f32_32x32x16_bf16 v[50:65], v[2:5], v[22:25], 0
	global_load_dwordx4 v[120:123], v[82:83], off offset:256
	global_load_dwordx4 v[124:127], v[80:81], off offset:256
	global_load_dwordx4 v[140:143], v[74:75], off offset:256
	global_load_dwordx4 v[144:147], v[78:79], off offset:256
	s_waitcnt lgkmcnt(2)
	v_mfma_f32_32x32x16_bf16 v[34:49], v[88:91], v[92:95], v[34:49]
	s_waitcnt lgkmcnt(1)
	v_mfma_f32_32x32x16_bf16 v[50:65], v[88:91], v[96:99], v[50:65]
	ds_read_b128 v[88:91], v70 offset:4640
	v_mfma_f32_32x32x16_bf16 v[2:17], v[18:21], v[6:9], 0
	v_mfma_f32_32x32x16_bf16 v[18:33], v[18:21], v[22:25], 0
	s_waitcnt lgkmcnt(0)
	v_mfma_f32_32x32x16_bf16 v[2:17], v[88:91], v[92:95], v[2:17]
	ds_read_b128 v[92:95], v1 offset:36928
	v_mfma_f32_32x32x16_bf16 v[18:33], v[88:91], v[96:99], v[18:33]
	ds_read_b128 v[88:91], v70 offset:64
	ds_read_b128 v[96:99], v1 offset:41536
	s_waitcnt lgkmcnt(1)
	v_mfma_f32_32x32x16_bf16 v[34:49], v[88:91], v[92:95], v[34:49]
	s_waitcnt lgkmcnt(0)
	v_mfma_f32_32x32x16_bf16 v[50:65], v[88:91], v[96:99], v[50:65]
	ds_read_b128 v[88:91], v70 offset:4672
	s_waitcnt lgkmcnt(0)
	v_mfma_f32_32x32x16_bf16 v[2:17], v[88:91], v[92:95], v[2:17]
	ds_read_b128 v[92:95], v1 offset:36960
	v_mfma_f32_32x32x16_bf16 v[18:33], v[88:91], v[96:99], v[18:33]
	ds_read_b128 v[88:91], v70 offset:96
	ds_read_b128 v[96:99], v1 offset:41568
	s_waitcnt lgkmcnt(1)
	v_mfma_f32_32x32x16_bf16 v[34:49], v[88:91], v[92:95], v[34:49]
	s_waitcnt lgkmcnt(0)
	v_mfma_f32_32x32x16_bf16 v[50:65], v[88:91], v[96:99], v[50:65]
	v_mfma_f32_32x32x16_bf16 v[2:17], v[100:103], v[92:95], v[2:17]
	v_mfma_f32_32x32x16_bf16 v[18:33], v[100:103], v[96:99], v[18:33]
	s_setprio 0
	s_barrier
; #define MFMA(a, b, c) __builtin_amdgcn_mfma_f32_32x32x16_bf16((a), (b), (c), 0, 0, 0)
; template <int TM, int TN>
; DI void gemm_mainloop(const u16* __restrict__ A, long lda, const u16* __restrict__ Bt, long ldb, int K, char* smem,
;                       f32x16 (&acc)[TM][TN]) {
;     ...
;   for (int kt = 0; kt < nk; kt++) {
;     const int buf = kt & 1;
;     const u16* cA = sA + buf * BM * LD + (wm * 32 * TM + r) * LD + h * 8;
;     const u16* cB = sB + buf * BN * LD + (wn * 32 * TN + r) * LD + h * 8;
;     bf16x8 af[TM], bfr[TN];
; #pragma unroll
;     for (int tm = 0; tm < TM; tm++) af[tm] = *(const bf16x8*)(cA + tm * 32 * LD);
; #pragma unroll
;     for (int tn = 0; tn < TN; tn++) bfr[tn] = *(const bf16x8*)(cB + tn * 32 * LD);
;     if (kt + 1 < nk) GEMM_SSTORE(buf ^ 1)
;     __builtin_amdgcn_sched_barrier(0);
;     __builtin_amdgcn_s_setprio(1);
; #pragma unroll
;     for (int tm = 0; tm < TM; tm++)
; #pragma unroll
;       for (int tn = 0; tn < TN; tn++) acc[tm][tn] = MFMA(af[tm], bfr[tn], acc[tm][tn]);
; #pragma unroll
;     for (int tm = 0; tm < TM; tm++) af[tm] = *(const bf16x8*)(cA + tm * 32 * LD + 16);
; #pragma unroll
;     for (int tn = 0; tn < TN; tn++) bfr[tn] = *(const bf16x8*)(cB + tn * 32 * LD + 16);
; #pragma unroll
;     for (int tm = 0; tm < TM; tm++)
; #pragma unroll
;       for (int tn = 0; tn < TN; tn++) acc[tm][tn] = MFMA(af[tm], bfr[tn], acc[tm][tn]);
;     __builtin_amdgcn_sched_group_barrier(0x8, 4, 0);
;     if (kt + 2 < nk) GEMM_GLOAD((kt + 2) * 64)
; #pragma unroll
;     for (int ks = 2; ks < 4; ks++) {
; #pragma unroll
;       for (int tm = 0; tm < TM; tm++) af[tm] = *(const bf16x8*)(cA + tm * 32 * LD + ks * 16);
; #pragma unroll
;       for (int tn = 0; tn < TN; tn++) bfr[tn] = *(const bf16x8*)(cB + tn * 32 * LD + ks * 16);
; #pragma unroll
;       for (int tm = 0; tm < TM; tm++)
; #pragma unroll
;         for (int tn = 0; tn < TN; tn++) acc[tm][tn] = MFMA(af[tm], bfr[tn], acc[tm][tn]);
;     }
;     __builtin_amdgcn_s_setprio(0);
;     __syncthreads();
;   }
	ds_read_b128 v[96:99], v70 offset:18432
	ds_read_b128 v[100:103], v70 offset:23040
	ds_read_b128 v[128:131], v1 offset:55296
	ds_read_b128 v[132:135], v1 offset:59904
	s_setprio 1
	ds_read_b128 v[88:91], v70 offset:18464
	s_waitcnt lgkmcnt(2)
	v_mfma_f32_32x32x16_bf16 v[34:49], v[96:99], v[128:131], v[34:49]
	ds_read_b128 v[92:95], v1 offset:55328
	s_waitcnt lgkmcnt(2)
	v_mfma_f32_32x32x16_bf16 v[50:65], v[96:99], v[132:135], v[50:65]
	ds_read_b128 v[96:99], v1 offset:59936
	s_waitcnt lgkmcnt(1)
	v_mfma_f32_32x32x16_bf16 v[34:49], v[88:91], v[92:95], v[34:49]
	s_waitcnt lgkmcnt(0)
	v_mfma_f32_32x32x16_bf16 v[50:65], v[88:91], v[96:99], v[50:65]
	s_waitcnt vmcnt(1)
	ds_write_b128 v66, v[140:143]
	ds_write_b128 v66, v[104:107] offset:4608
	global_load_dwordx4 v[140:143], v[74:75], off offset:384
	global_load_dwordx4 v[104:107], v[72:73], off offset:384
	ds_read_b128 v[88:91], v70 offset:23072
	v_mfma_f32_32x32x16_bf16 v[2:17], v[100:103], v[128:131], v[2:17]
	v_mfma_f32_32x32x16_bf16 v[18:33], v[100:103], v[132:135], v[18:33]
	ds_read_b128 v[100:103], v70 offset:23136
	s_waitcnt lgkmcnt(1)
	v_mfma_f32_32x32x16_bf16 v[2:17], v[88:91], v[92:95], v[2:17]
	ds_read_b128 v[92:95], v1 offset:55360
	v_mfma_f32_32x32x16_bf16 v[18:33], v[88:91], v[96:99], v[18:33]
	ds_write_b128 v66, v[108:111] offset:9216
	ds_write_b128 v66, v[112:115] offset:13824
	global_load_dwordx4 v[108:111], v[76:77], off offset:384
	global_load_dwordx4 v[112:115], v[86:87], off offset:384
	ds_read_b128 v[88:91], v70 offset:18496
	ds_read_b128 v[96:99], v1 offset:59968
	s_waitcnt lgkmcnt(1)
	v_mfma_f32_32x32x16_bf16 v[34:49], v[88:91], v[92:95], v[34:49]
	s_waitcnt lgkmcnt(0)
	v_mfma_f32_32x32x16_bf16 v[50:65], v[88:91], v[96:99], v[50:65]
	ds_read_b128 v[88:91], v70 offset:23104
	s_waitcnt lgkmcnt(0)
	v_mfma_f32_32x32x16_bf16 v[2:17], v[88:91], v[92:95], v[2:17]
	ds_read_b128 v[92:95], v1 offset:55392
	v_mfma_f32_32x32x16_bf16 v[18:33], v[88:91], v[96:99], v[18:33]
	s_waitcnt vmcnt(4)
	ds_write_b128 v66, v[144:147] offset:36864
	ds_write_b128 v66, v[124:127] offset:41472
	global_load_dwordx4 v[144:147], v[78:79], off offset:384
	global_load_dwordx4 v[124:127], v[80:81], off offset:384
	ds_read_b128 v[88:91], v70 offset:18528
	ds_read_b128 v[96:99], v1 offset:60000
	s_waitcnt lgkmcnt(1)
	v_mfma_f32_32x32x16_bf16 v[34:49], v[88:91], v[92:95], v[34:49]
	s_waitcnt lgkmcnt(0)
	v_mfma_f32_32x32x16_bf16 v[50:65], v[88:91], v[96:99], v[50:65]
	v_mfma_f32_32x32x16_bf16 v[2:17], v[100:103], v[92:95], v[2:17]
	v_mfma_f32_32x32x16_bf16 v[18:33], v[100:103], v[96:99], v[18:33]
	ds_write_b128 v66, v[120:123] offset:46080
	ds_write_b128 v66, v[116:119] offset:50688
	global_load_dwordx4 v[120:123], v[82:83], off offset:384
	global_load_dwordx4 v[116:119], v[84:85], off offset:384
	s_setprio 0
	s_waitcnt lgkmcnt(0)
	s_barrier
	ds_read_b128 v[96:99], v70
	ds_read_b128 v[100:103], v70 offset:4608
	ds_read_b128 v[128:131], v1 offset:36864
	ds_read_b128 v[132:135], v1 offset:41472
	s_setprio 1
	ds_read_b128 v[88:91], v70 offset:32
	s_waitcnt lgkmcnt(2)
	v_mfma_f32_32x32x16_bf16 v[34:49], v[96:99], v[128:131], v[34:49]
	ds_read_b128 v[92:95], v1 offset:36896
	s_waitcnt lgkmcnt(2)
	v_mfma_f32_32x32x16_bf16 v[50:65], v[96:99], v[132:135], v[50:65]
	ds_read_b128 v[96:99], v1 offset:41504
	s_waitcnt lgkmcnt(1)
	v_mfma_f32_32x32x16_bf16 v[34:49], v[88:91], v[92:95], v[34:49]
	s_waitcnt lgkmcnt(0)
	v_mfma_f32_32x32x16_bf16 v[50:65], v[88:91], v[96:99], v[50:65]
	s_waitcnt vmcnt(7)
	ds_write_b128 v66, v[140:143] offset:18432
	s_waitcnt vmcnt(6)
	ds_write_b128 v66, v[104:107] offset:23040
	global_load_dwordx4 v[140:143], v[74:75], off offset:512
	global_load_dwordx4 v[104:107], v[72:73], off offset:512
	ds_read_b128 v[88:91], v70 offset:4640
	v_mfma_f32_32x32x16_bf16 v[2:17], v[100:103], v[128:131], v[2:17]
	v_mfma_f32_32x32x16_bf16 v[18:33], v[100:103], v[132:135], v[18:33]
	ds_read_b128 v[100:103], v70 offset:4704
	s_waitcnt lgkmcnt(1)
	v_mfma_f32_32x32x16_bf16 v[2:17], v[88:91], v[92:95], v[2:17]
	ds_read_b128 v[92:95], v1 offset:36928
	v_mfma_f32_32x32x16_bf16 v[18:33], v[88:91], v[96:99], v[18:33]
	s_waitcnt vmcnt(7)
	ds_write_b128 v66, v[108:111] offset:27648
	s_waitcnt vmcnt(6)
	ds_write_b128 v66, v[112:115] offset:32256
	global_load_dwordx4 v[108:111], v[76:77], off offset:512
	global_load_dwordx4 v[112:115], v[86:87], off offset:512
	ds_read_b128 v[88:91], v70 offset:64
	ds_read_b128 v[96:99], v1 offset:41536
	s_waitcnt lgkmcnt(1)
	v_mfma_f32_32x32x16_bf16 v[34:49], v[88:91], v[92:95], v[34:49]
	s_waitcnt lgkmcnt(0)
	v_mfma_f32_32x32x16_bf16 v[50:65], v[88:91], v[96:99], v[50:65]
	ds_read_b128 v[88:91], v70 offset:4672
	s_waitcnt lgkmcnt(0)
	v_mfma_f32_32x32x16_bf16 v[2:17], v[88:91], v[92:95], v[2:17]
	ds_read_b128 v[92:95], v1 offset:36960
	v_mfma_f32_32x32x16_bf16 v[18:33], v[88:91], v[96:99], v[18:33]
	s_waitcnt vmcnt(7)
	ds_write_b128 v66, v[144:147] offset:55296
	s_waitcnt vmcnt(6)
	ds_write_b128 v66, v[124:127] offset:59904
	global_load_dwordx4 v[144:147], v[78:79], off offset:512
	global_load_dwordx4 v[124:127], v[80:81], off offset:512
	ds_read_b128 v[88:91], v70 offset:96
	ds_read_b128 v[96:99], v1 offset:41568
	s_waitcnt lgkmcnt(1)
	v_mfma_f32_32x32x16_bf16 v[34:49], v[88:91], v[92:95], v[34:49]
	s_waitcnt lgkmcnt(0)
	v_mfma_f32_32x32x16_bf16 v[50:65], v[88:91], v[96:99], v[50:65]
	v_mfma_f32_32x32x16_bf16 v[2:17], v[100:103], v[92:95], v[2:17]
	v_mfma_f32_32x32x16_bf16 v[18:33], v[100:103], v[96:99], v[18:33]
	s_waitcnt vmcnt(7)
	ds_write_b128 v66, v[120:123] offset:64512
	s_waitcnt vmcnt(6)
	ds_write_b128 v71, v[116:119] offset:32256
	global_load_dwordx4 v[120:123], v[82:83], off offset:512
	global_load_dwordx4 v[116:119], v[84:85], off offset:512
	s_setprio 0
	s_waitcnt lgkmcnt(0)
	s_barrier
; #define MFMA(a, b, c) __builtin_amdgcn_mfma_f32_32x32x16_bf16((a), (b), (c), 0, 0, 0)
; template <int TM, int TN>
; DI void gemm_mainloop(const u16* __restrict__ A, long lda, const u16* __restrict__ Bt, long ldb, int K, char* smem,
;                       f32x16 (&acc)[TM][TN]) {
;     ...
;   for (int kt = 0; kt < nk; kt++) {
;     const int buf = kt & 1;
;     const u16* cA = sA + buf * BM * LD + (wm * 32 * TM + r) * LD + h * 8;
;     const u16* cB = sB + buf * BN * LD + (wn * 32 * TN + r) * LD + h * 8;
;     bf16x8 af[TM], bfr[TN];
; #pragma unroll
;     for (int tm = 0; tm < TM; tm++) af[tm] = *(const bf16x8*)(cA + tm * 32 * LD);
; #pragma unroll
;     for (int tn = 0; tn < TN; tn++) bfr[tn] = *(const bf16x8*)(cB + tn * 32 * LD);
;     if (kt + 1 < nk) GEMM_SSTORE(buf ^ 1)
;     __builtin_amdgcn_sched_barrier(0);
;     __builtin_amdgcn_s_setprio(1);
; #pragma unroll
;     for (int tm = 0; tm < TM; tm++)
; #pragma unroll
;       for (int tn = 0; tn < TN; tn++) acc[tm][tn] = MFMA(af[tm], bfr[tn], acc[tm][tn]);
; #pragma unroll
;     for (int tm = 0; tm < TM; tm++) af[tm] = *(const bf16x8*)(cA + tm * 32 * LD + 16);
; #pragma unroll
;     for (int tn = 0; tn < TN; tn++) bfr[tn] = *(const bf16x8*)(cB + tn * 32 * LD + 16);
; #pragma unroll
;     for (int tm = 0; tm < TM; tm++)
; #pragma unroll
;       for (int tn = 0; tn < TN; tn++) acc[tm][tn] = MFMA(af[tm], bfr[tn], acc[tm][tn]);
;     __builtin_amdgcn_sched_group_barrier(0x8, 4, 0);
;     if (kt + 2 < nk) GEMM_GLOAD((kt + 2) * 64)
; #pragma unroll
;     for (int ks = 2; ks < 4; ks++) {
; #pragma unroll
;       for (int tm = 0; tm < TM; tm++) af[tm] = *(const bf16x8*)(cA + tm * 32 * LD + ks * 16);
; #pragma unroll
;       for (int tn = 0; tn < TN; tn++) bfr[tn] = *(const bf16x8*)(cB + tn * 32 * LD + ks * 16);
; #pragma unroll
;       for (int tm = 0; tm < TM; tm++)
; #pragma unroll
;         for (int tn = 0; tn < TN; tn++) acc[tm][tn] = MFMA(af[tm], bfr[tn], acc[tm][tn]);
;     }
;     __builtin_amdgcn_s_setprio(0);
;     __syncthreads();
;   }
	ds_read_b128 v[96:99], v70 offset:18432
	ds_read_b128 v[100:103], v70 offset:23040
	ds_read_b128 v[128:131], v1 offset:55296
	ds_read_b128 v[132:135], v1 offset:59904
	s_setprio 1
	ds_read_b128 v[88:91], v70 offset:18464
	s_waitcnt lgkmcnt(2)
	v_mfma_f32_32x32x16_bf16 v[34:49], v[96:99], v[128:131], v[34:49]
	ds_read_b128 v[92:95], v1 offset:55328
	s_waitcnt lgkmcnt(2)
	v_mfma_f32_32x32x16_bf16 v[50:65], v[96:99], v[132:135], v[50:65]
	ds_read_b128 v[96:99], v1 offset:59936
	s_waitcnt lgkmcnt(1)
	v_mfma_f32_32x32x16_bf16 v[34:49], v[88:91], v[92:95], v[34:49]
	s_waitcnt lgkmcnt(0)
	v_mfma_f32_32x32x16_bf16 v[50:65], v[88:91], v[96:99], v[50:65]
	s_waitcnt vmcnt(7)
	ds_write_b128 v66, v[140:143]
	s_waitcnt vmcnt(6)
	ds_write_b128 v66, v[104:107] offset:4608
	global_load_dwordx4 v[140:143], v[74:75], off offset:640
	global_load_dwordx4 v[104:107], v[72:73], off offset:640
	ds_read_b128 v[88:91], v70 offset:23072
	v_mfma_f32_32x32x16_bf16 v[2:17], v[100:103], v[128:131], v[2:17]
	v_mfma_f32_32x32x16_bf16 v[18:33], v[100:103], v[132:135], v[18:33]
	ds_read_b128 v[100:103], v70 offset:23136
	s_waitcnt lgkmcnt(1)
	v_mfma_f32_32x32x16_bf16 v[2:17], v[88:91], v[92:95], v[2:17]
	ds_read_b128 v[92:95], v1 offset:55360
	v_mfma_f32_32x32x16_bf16 v[18:33], v[88:91], v[96:99], v[18:33]
	s_waitcnt vmcnt(7)
	ds_write_b128 v66, v[108:111] offset:9216
	s_waitcnt vmcnt(6)
	ds_write_b128 v66, v[112:115] offset:13824
	global_load_dwordx4 v[108:111], v[76:77], off offset:640
	global_load_dwordx4 v[112:115], v[86:87], off offset:640
	ds_read_b128 v[88:91], v70 offset:18496
	ds_read_b128 v[96:99], v1 offset:59968
	s_waitcnt lgkmcnt(1)
	v_mfma_f32_32x32x16_bf16 v[34:49], v[88:91], v[92:95], v[34:49]
	s_waitcnt lgkmcnt(0)
	v_mfma_f32_32x32x16_bf16 v[50:65], v[88:91], v[96:99], v[50:65]
	ds_read_b128 v[88:91], v70 offset:23104
	s_waitcnt lgkmcnt(0)
	v_mfma_f32_32x32x16_bf16 v[2:17], v[88:91], v[92:95], v[2:17]
	ds_read_b128 v[92:95], v1 offset:55392
	v_mfma_f32_32x32x16_bf16 v[18:33], v[88:91], v[96:99], v[18:33]
	s_waitcnt vmcnt(7)
	ds_write_b128 v66, v[144:147] offset:36864
	s_waitcnt vmcnt(6)
	ds_write_b128 v66, v[124:127] offset:41472
	global_load_dwordx4 v[144:147], v[78:79], off offset:640
	global_load_dwordx4 v[124:127], v[80:81], off offset:640
	ds_read_b128 v[88:91], v70 offset:18528
	ds_read_b128 v[96:99], v1 offset:60000
	s_waitcnt lgkmcnt(1)
	v_mfma_f32_32x32x16_bf16 v[34:49], v[88:91], v[92:95], v[34:49]
	s_waitcnt lgkmcnt(0)
	v_mfma_f32_32x32x16_bf16 v[50:65], v[88:91], v[96:99], v[50:65]
	v_mfma_f32_32x32x16_bf16 v[2:17], v[100:103], v[92:95], v[2:17]
	v_mfma_f32_32x32x16_bf16 v[18:33], v[100:103], v[96:99], v[18:33]
	s_waitcnt vmcnt(7)
	ds_write_b128 v66, v[120:123] offset:46080
	s_waitcnt vmcnt(6)
	ds_write_b128 v66, v[116:119] offset:50688
	global_load_dwordx4 v[120:123], v[82:83], off offset:640
	global_load_dwordx4 v[116:119], v[84:85], off offset:640
	s_setprio 0
	s_waitcnt lgkmcnt(0)
	s_barrier
	ds_read_b128 v[96:99], v70
	ds_read_b128 v[100:103], v70 offset:4608
	ds_read_b128 v[128:131], v1 offset:36864
	ds_read_b128 v[132:135], v1 offset:41472
	s_setprio 1
	ds_read_b128 v[88:91], v70 offset:32
	s_waitcnt lgkmcnt(2)
	v_mfma_f32_32x32x16_bf16 v[34:49], v[96:99], v[128:131], v[34:49]
	ds_read_b128 v[92:95], v1 offset:36896
	s_waitcnt lgkmcnt(2)
	v_mfma_f32_32x32x16_bf16 v[50:65], v[96:99], v[132:135], v[50:65]
	ds_read_b128 v[96:99], v1 offset:41504
	s_waitcnt lgkmcnt(1)
	v_mfma_f32_32x32x16_bf16 v[34:49], v[88:91], v[92:95], v[34:49]
	s_waitcnt lgkmcnt(0)
	v_mfma_f32_32x32x16_bf16 v[50:65], v[88:91], v[96:99], v[50:65]
	s_waitcnt vmcnt(7)
	ds_write_b128 v66, v[140:143] offset:18432
	s_waitcnt vmcnt(6)
	ds_write_b128 v66, v[104:107] offset:23040
	global_load_dwordx4 v[140:143], v[74:75], off offset:768
	global_load_dwordx4 v[104:107], v[72:73], off offset:768
	ds_read_b128 v[88:91], v70 offset:4640
	v_mfma_f32_32x32x16_bf16 v[2:17], v[100:103], v[128:131], v[2:17]
	v_mfma_f32_32x32x16_bf16 v[18:33], v[100:103], v[132:135], v[18:33]
	ds_read_b128 v[100:103], v70 offset:4704
	s_waitcnt lgkmcnt(1)
	v_mfma_f32_32x32x16_bf16 v[2:17], v[88:91], v[92:95], v[2:17]
	ds_read_b128 v[92:95], v1 offset:36928
	v_mfma_f32_32x32x16_bf16 v[18:33], v[88:91], v[96:99], v[18:33]
	s_waitcnt vmcnt(7)
	ds_write_b128 v66, v[108:111] offset:27648
	s_waitcnt vmcnt(6)
	ds_write_b128 v66, v[112:115] offset:32256
	global_load_dwordx4 v[108:111], v[76:77], off offset:768
	global_load_dwordx4 v[112:115], v[86:87], off offset:768
	ds_read_b128 v[88:91], v70 offset:64
	ds_read_b128 v[96:99], v1 offset:41536
	s_waitcnt lgkmcnt(1)
	v_mfma_f32_32x32x16_bf16 v[34:49], v[88:91], v[92:95], v[34:49]
	s_waitcnt lgkmcnt(0)
	v_mfma_f32_32x32x16_bf16 v[50:65], v[88:91], v[96:99], v[50:65]
	ds_read_b128 v[88:91], v70 offset:4672
	s_waitcnt lgkmcnt(0)
	v_mfma_f32_32x32x16_bf16 v[2:17], v[88:91], v[92:95], v[2:17]
	ds_read_b128 v[92:95], v1 offset:36960
	v_mfma_f32_32x32x16_bf16 v[18:33], v[88:91], v[96:99], v[18:33]
	s_waitcnt vmcnt(7)
	ds_write_b128 v66, v[144:147] offset:55296
	s_waitcnt vmcnt(6)
	ds_write_b128 v66, v[124:127] offset:59904
	global_load_dwordx4 v[144:147], v[78:79], off offset:768
	global_load_dwordx4 v[124:127], v[80:81], off offset:768
	ds_read_b128 v[88:91], v70 offset:96
	ds_read_b128 v[96:99], v1 offset:41568
	s_waitcnt lgkmcnt(1)
	v_mfma_f32_32x32x16_bf16 v[34:49], v[88:91], v[92:95], v[34:49]
	s_waitcnt lgkmcnt(0)
	v_mfma_f32_32x32x16_bf16 v[50:65], v[88:91], v[96:99], v[50:65]
	v_mfma_f32_32x32x16_bf16 v[2:17], v[100:103], v[92:95], v[2:17]
	v_mfma_f32_32x32x16_bf16 v[18:33], v[100:103], v[96:99], v[18:33]
	s_waitcnt vmcnt(7)
	ds_write_b128 v66, v[120:123] offset:64512
	s_waitcnt vmcnt(6)
	ds_write_b128 v71, v[116:119] offset:32256
	global_load_dwordx4 v[120:123], v[82:83], off offset:768
	global_load_dwordx4 v[116:119], v[84:85], off offset:768
	s_setprio 0
	s_waitcnt lgkmcnt(0)
	s_barrier
; #define MFMA(a, b, c) __builtin_amdgcn_mfma_f32_32x32x16_bf16((a), (b), (c), 0, 0, 0)
; template <int TM, int TN>
; DI void gemm_mainloop(const u16* __restrict__ A, long lda, const u16* __restrict__ Bt, long ldb, int K, char* smem,
;                       f32x16 (&acc)[TM][TN]) {
;     ...
;   for (int kt = 0; kt < nk; kt++) {
;     const int buf = kt & 1;
;     const u16* cA = sA + buf * BM * LD + (wm * 32 * TM + r) * LD + h * 8;
;     const u16* cB = sB + buf * BN * LD + (wn * 32 * TN + r) * LD + h * 8;
;     bf16x8 af[TM], bfr[TN];
; #pragma unroll
;     for (int tm = 0; tm < TM; tm++) af[tm] = *(const bf16x8*)(cA + tm * 32 * LD);
; #pragma unroll
;     for (int tn = 0; tn < TN; tn++) bfr[tn] = *(const bf16x8*)(cB + tn * 32 * LD);
;     if (kt + 1 < nk) GEMM_SSTORE(buf ^ 1)
;     __builtin_amdgcn_sched_barrier(0);
;     __builtin_amdgcn_s_setprio(1);
; #pragma unroll
;     for (int tm = 0; tm < TM; tm++)
; #pragma unroll
;       for (int tn = 0; tn < TN; tn++) acc[tm][tn] = MFMA(af[tm], bfr[tn], acc[tm][tn]);
; #pragma unroll
;     for (int tm = 0; tm < TM; tm++) af[tm] = *(const bf16x8*)(cA + tm * 32 * LD + 16);
; #pragma unroll
;     for (int tn = 0; tn < TN; tn++) bfr[tn] = *(const bf16x8*)(cB + tn * 32 * LD + 16);
; #pragma unroll
;     for (int tm = 0; tm < TM; tm++)
; #pragma unroll
;       for (int tn = 0; tn < TN; tn++) acc[tm][tn] = MFMA(af[tm], bfr[tn], acc[tm][tn]);
;     __builtin_amdgcn_sched_group_barrier(0x8, 4, 0);
;     if (kt + 2 < nk) GEMM_GLOAD((kt + 2) * 64)
; #pragma unroll
;     for (int ks = 2; ks < 4; ks++) {
; #pragma unroll
;       for (int tm = 0; tm < TM; tm++) af[tm] = *(const bf16x8*)(cA + tm * 32 * LD + ks * 16);
; #pragma unroll
;       for (int tn = 0; tn < TN; tn++) bfr[tn] = *(const bf16x8*)(cB + tn * 32 * LD + ks * 16);
; #pragma unroll
;       for (int tm = 0; tm < TM; tm++)
; #pragma unroll
;         for (int tn = 0; tn < TN; tn++) acc[tm][tn] = MFMA(af[tm], bfr[tn], acc[tm][tn]);
;     }
;     __builtin_amdgcn_s_setprio(0);
;     __syncthreads();
;   }
	ds_read_b128 v[96:99], v70 offset:18432
	ds_read_b128 v[100:103], v70 offset:23040
	ds_read_b128 v[128:131], v1 offset:55296
	ds_read_b128 v[132:135], v1 offset:59904
	s_setprio 1
	ds_read_b128 v[88:91], v70 offset:18464
	s_waitcnt lgkmcnt(2)
	v_mfma_f32_32x32x16_bf16 v[34:49], v[96:99], v[128:131], v[34:49]
	ds_read_b128 v[92:95], v1 offset:55328
	s_waitcnt lgkmcnt(2)
	v_mfma_f32_32x32x16_bf16 v[50:65], v[96:99], v[132:135], v[50:65]
	ds_read_b128 v[96:99], v1 offset:59936
	s_waitcnt lgkmcnt(1)
	v_mfma_f32_32x32x16_bf16 v[34:49], v[88:91], v[92:95], v[34:49]
	s_waitcnt lgkmcnt(0)
	v_mfma_f32_32x32x16_bf16 v[50:65], v[88:91], v[96:99], v[50:65]
	s_waitcnt vmcnt(7)
	ds_write_b128 v66, v[140:143]
	s_waitcnt vmcnt(6)
	ds_write_b128 v66, v[104:107] offset:4608
	global_load_dwordx4 v[140:143], v[74:75], off offset:896
	global_load_dwordx4 v[104:107], v[72:73], off offset:896
	ds_read_b128 v[88:91], v70 offset:23072
	v_mfma_f32_32x32x16_bf16 v[2:17], v[100:103], v[128:131], v[2:17]
	v_mfma_f32_32x32x16_bf16 v[18:33], v[100:103], v[132:135], v[18:33]
	ds_read_b128 v[100:103], v70 offset:23136
	s_waitcnt lgkmcnt(1)
	v_mfma_f32_32x32x16_bf16 v[2:17], v[88:91], v[92:95], v[2:17]
	ds_read_b128 v[92:95], v1 offset:55360
	v_mfma_f32_32x32x16_bf16 v[18:33], v[88:91], v[96:99], v[18:33]
	s_waitcnt vmcnt(7)
	ds_write_b128 v66, v[108:111] offset:9216
	s_waitcnt vmcnt(6)
	ds_write_b128 v66, v[112:115] offset:13824
	global_load_dwordx4 v[108:111], v[76:77], off offset:896
	global_load_dwordx4 v[112:115], v[86:87], off offset:896
	ds_read_b128 v[88:91], v70 offset:18496
	ds_read_b128 v[96:99], v1 offset:59968
	s_waitcnt lgkmcnt(1)
	v_mfma_f32_32x32x16_bf16 v[34:49], v[88:91], v[92:95], v[34:49]
	s_waitcnt lgkmcnt(0)
	v_mfma_f32_32x32x16_bf16 v[50:65], v[88:91], v[96:99], v[50:65]
	ds_read_b128 v[88:91], v70 offset:23104
	s_waitcnt lgkmcnt(0)
	v_mfma_f32_32x32x16_bf16 v[2:17], v[88:91], v[92:95], v[2:17]
	ds_read_b128 v[92:95], v1 offset:55392
	v_mfma_f32_32x32x16_bf16 v[18:33], v[88:91], v[96:99], v[18:33]
	s_waitcnt vmcnt(7)
	ds_write_b128 v66, v[144:147] offset:36864
	s_waitcnt vmcnt(6)
	ds_write_b128 v66, v[124:127] offset:41472
	global_load_dwordx4 v[144:147], v[78:79], off offset:896
	global_load_dwordx4 v[124:127], v[80:81], off offset:896
	ds_read_b128 v[88:91], v70 offset:18528
	ds_read_b128 v[96:99], v1 offset:60000
	s_waitcnt lgkmcnt(1)
	v_mfma_f32_32x32x16_bf16 v[34:49], v[88:91], v[92:95], v[34:49]
	s_waitcnt lgkmcnt(0)
	v_mfma_f32_32x32x16_bf16 v[50:65], v[88:91], v[96:99], v[50:65]
	v_mfma_f32_32x32x16_bf16 v[2:17], v[100:103], v[92:95], v[2:17]
	v_mfma_f32_32x32x16_bf16 v[18:33], v[100:103], v[96:99], v[18:33]
	s_waitcnt vmcnt(7)
	ds_write_b128 v66, v[120:123] offset:46080
	s_waitcnt vmcnt(6)
	ds_write_b128 v66, v[116:119] offset:50688
	global_load_dwordx4 v[120:123], v[82:83], off offset:896
	global_load_dwordx4 v[116:119], v[84:85], off offset:896
	s_setprio 0
	s_waitcnt lgkmcnt(0)
	s_barrier
	ds_read_b128 v[96:99], v70
	ds_read_b128 v[100:103], v70 offset:4608
	ds_read_b128 v[128:131], v1 offset:36864
	ds_read_b128 v[132:135], v1 offset:41472
	s_setprio 1
	ds_read_b128 v[88:91], v70 offset:32
	s_waitcnt lgkmcnt(2)
	v_mfma_f32_32x32x16_bf16 v[34:49], v[96:99], v[128:131], v[34:49]
	ds_read_b128 v[92:95], v1 offset:36896
	s_waitcnt lgkmcnt(2)
	v_mfma_f32_32x32x16_bf16 v[50:65], v[96:99], v[132:135], v[50:65]
	ds_read_b128 v[96:99], v1 offset:41504
	s_waitcnt lgkmcnt(1)
	v_mfma_f32_32x32x16_bf16 v[34:49], v[88:91], v[92:95], v[34:49]
	s_waitcnt lgkmcnt(0)
	v_mfma_f32_32x32x16_bf16 v[50:65], v[88:91], v[96:99], v[50:65]
	s_waitcnt vmcnt(7)
	ds_write_b128 v66, v[140:143] offset:18432
	s_waitcnt vmcnt(6)
	ds_write_b128 v66, v[104:107] offset:23040
	global_load_dwordx4 v[140:143], v[74:75], off offset:1024
	global_load_dwordx4 v[104:107], v[72:73], off offset:1024
	ds_read_b128 v[88:91], v70 offset:4640
	v_mfma_f32_32x32x16_bf16 v[2:17], v[100:103], v[128:131], v[2:17]
	v_mfma_f32_32x32x16_bf16 v[18:33], v[100:103], v[132:135], v[18:33]
	ds_read_b128 v[100:103], v70 offset:4704
	s_waitcnt lgkmcnt(1)
	v_mfma_f32_32x32x16_bf16 v[2:17], v[88:91], v[92:95], v[2:17]
	ds_read_b128 v[92:95], v1 offset:36928
	v_mfma_f32_32x32x16_bf16 v[18:33], v[88:91], v[96:99], v[18:33]
	s_waitcnt vmcnt(7)
	ds_write_b128 v66, v[108:111] offset:27648
	s_waitcnt vmcnt(6)
	ds_write_b128 v66, v[112:115] offset:32256
	global_load_dwordx4 v[108:111], v[76:77], off offset:1024
	global_load_dwordx4 v[112:115], v[86:87], off offset:1024
	ds_read_b128 v[88:91], v70 offset:64
	ds_read_b128 v[96:99], v1 offset:41536
	s_waitcnt lgkmcnt(1)
	v_mfma_f32_32x32x16_bf16 v[34:49], v[88:91], v[92:95], v[34:49]
	s_waitcnt lgkmcnt(0)
	v_mfma_f32_32x32x16_bf16 v[50:65], v[88:91], v[96:99], v[50:65]
	ds_read_b128 v[88:91], v70 offset:4672
	s_waitcnt lgkmcnt(0)
	v_mfma_f32_32x32x16_bf16 v[2:17], v[88:91], v[92:95], v[2:17]
	ds_read_b128 v[92:95], v1 offset:36960
	v_mfma_f32_32x32x16_bf16 v[18:33], v[88:91], v[96:99], v[18:33]
	s_waitcnt vmcnt(7)
	ds_write_b128 v66, v[144:147] offset:55296
	s_waitcnt vmcnt(6)
	ds_write_b128 v66, v[124:127] offset:59904
	global_load_dwordx4 v[144:147], v[78:79], off offset:1024
	global_load_dwordx4 v[124:127], v[80:81], off offset:1024
	ds_read_b128 v[88:91], v70 offset:96
	ds_read_b128 v[96:99], v1 offset:41568
	s_waitcnt lgkmcnt(1)
	v_mfma_f32_32x32x16_bf16 v[34:49], v[88:91], v[92:95], v[34:49]
	s_waitcnt lgkmcnt(0)
	v_mfma_f32_32x32x16_bf16 v[50:65], v[88:91], v[96:99], v[50:65]
	v_mfma_f32_32x32x16_bf16 v[2:17], v[100:103], v[92:95], v[2:17]
	v_mfma_f32_32x32x16_bf16 v[18:33], v[100:103], v[96:99], v[18:33]
	s_waitcnt vmcnt(7)
	ds_write_b128 v66, v[120:123] offset:64512
	s_waitcnt vmcnt(6)
	ds_write_b128 v71, v[116:119] offset:32256
	global_load_dwordx4 v[120:123], v[82:83], off offset:1024
	global_load_dwordx4 v[116:119], v[84:85], off offset:1024
	s_setprio 0
	s_waitcnt lgkmcnt(0)
	s_barrier
; #define MFMA(a, b, c) __builtin_amdgcn_mfma_f32_32x32x16_bf16((a), (b), (c), 0, 0, 0)
; template <int TM, int TN>
; DI void gemm_mainloop(const u16* __restrict__ A, long lda, const u16* __restrict__ Bt, long ldb, int K, char* smem,
;                       f32x16 (&acc)[TM][TN]) {
;     ...
;   for (int kt = 0; kt < nk; kt++) {
;     const int buf = kt & 1;
;     const u16* cA = sA + buf * BM * LD + (wm * 32 * TM + r) * LD + h * 8;
;     const u16* cB = sB + buf * BN * LD + (wn * 32 * TN + r) * LD + h * 8;
;     bf16x8 af[TM], bfr[TN];
; #pragma unroll
;     for (int tm = 0; tm < TM; tm++) af[tm] = *(const bf16x8*)(cA + tm * 32 * LD);
; #pragma unroll
;     for (int tn = 0; tn < TN; tn++) bfr[tn] = *(const bf16x8*)(cB + tn * 32 * LD);
;     if (kt + 1 < nk) GEMM_SSTORE(buf ^ 1)
;     __builtin_amdgcn_sched_barrier(0);
;     __builtin_amdgcn_s_setprio(1);
; #pragma unroll
;     for (int tm = 0; tm < TM; tm++)
; #pragma unroll
;       for (int tn = 0; tn < TN; tn++) acc[tm][tn] = MFMA(af[tm], bfr[tn], acc[tm][tn]);
; #pragma unroll
;     for (int tm = 0; tm < TM; tm++) af[tm] = *(const bf16x8*)(cA + tm * 32 * LD + 16);
; #pragma unroll
;     for (int tn = 0; tn < TN; tn++) bfr[tn] = *(const bf16x8*)(cB + tn * 32 * LD + 16);
; #pragma unroll
;     for (int tm = 0; tm < TM; tm++)
; #pragma unroll
;       for (int tn = 0; tn < TN; tn++) acc[tm][tn] = MFMA(af[tm], bfr[tn], acc[tm][tn]);
;     __builtin_amdgcn_sched_group_barrier(0x8, 4, 0);
;     if (kt + 2 < nk) GEMM_GLOAD((kt + 2) * 64)
; #pragma unroll
;     for (int ks = 2; ks < 4; ks++) {
; #pragma unroll
;       for (int tm = 0; tm < TM; tm++) af[tm] = *(const bf16x8*)(cA + tm * 32 * LD + ks * 16);
; #pragma unroll
;       for (int tn = 0; tn < TN; tn++) bfr[tn] = *(const bf16x8*)(cB + tn * 32 * LD + ks * 16);
; #pragma unroll
;       for (int tm = 0; tm < TM; tm++)
; #pragma unroll
;         for (int tn = 0; tn < TN; tn++) acc[tm][tn] = MFMA(af[tm], bfr[tn], acc[tm][tn]);
;     }
;     __builtin_amdgcn_s_setprio(0);
;     __syncthreads();
;   }
	ds_read_b128 v[96:99], v70 offset:18432
	ds_read_b128 v[100:103], v70 offset:23040
	ds_read_b128 v[128:131], v1 offset:55296
	ds_read_b128 v[132:135], v1 offset:59904
	s_setprio 1
	ds_read_b128 v[88:91], v70 offset:18464
	s_waitcnt lgkmcnt(2)
	v_mfma_f32_32x32x16_bf16 v[34:49], v[96:99], v[128:131], v[34:49]
	ds_read_b128 v[92:95], v1 offset:55328
	s_waitcnt lgkmcnt(2)
	v_mfma_f32_32x32x16_bf16 v[50:65], v[96:99], v[132:135], v[50:65]
	ds_read_b128 v[96:99], v1 offset:59936
	s_waitcnt lgkmcnt(1)
	v_mfma_f32_32x32x16_bf16 v[34:49], v[88:91], v[92:95], v[34:49]
	s_waitcnt lgkmcnt(0)
	v_mfma_f32_32x32x16_bf16 v[50:65], v[88:91], v[96:99], v[50:65]
	s_waitcnt vmcnt(7)
	ds_write_b128 v66, v[140:143]
	s_waitcnt vmcnt(6)
	ds_write_b128 v66, v[104:107] offset:4608
	global_load_dwordx4 v[140:143], v[74:75], off offset:1152
	global_load_dwordx4 v[104:107], v[72:73], off offset:1152
	ds_read_b128 v[88:91], v70 offset:23072
	v_mfma_f32_32x32x16_bf16 v[2:17], v[100:103], v[128:131], v[2:17]
	v_mfma_f32_32x32x16_bf16 v[18:33], v[100:103], v[132:135], v[18:33]
	ds_read_b128 v[100:103], v70 offset:23136
	s_waitcnt lgkmcnt(1)
	v_mfma_f32_32x32x16_bf16 v[2:17], v[88:91], v[92:95], v[2:17]
	ds_read_b128 v[92:95], v1 offset:55360
	v_mfma_f32_32x32x16_bf16 v[18:33], v[88:91], v[96:99], v[18:33]
	s_waitcnt vmcnt(7)
	ds_write_b128 v66, v[108:111] offset:9216
	s_waitcnt vmcnt(6)
	ds_write_b128 v66, v[112:115] offset:13824
	global_load_dwordx4 v[108:111], v[76:77], off offset:1152
	global_load_dwordx4 v[112:115], v[86:87], off offset:1152
	ds_read_b128 v[88:91], v70 offset:18496
	ds_read_b128 v[96:99], v1 offset:59968
	s_waitcnt lgkmcnt(1)
	v_mfma_f32_32x32x16_bf16 v[34:49], v[88:91], v[92:95], v[34:49]
	s_waitcnt lgkmcnt(0)
	v_mfma_f32_32x32x16_bf16 v[50:65], v[88:91], v[96:99], v[50:65]
	ds_read_b128 v[88:91], v70 offset:23104
	s_waitcnt lgkmcnt(0)
	v_mfma_f32_32x32x16_bf16 v[2:17], v[88:91], v[92:95], v[2:17]
	ds_read_b128 v[92:95], v1 offset:55392
	v_mfma_f32_32x32x16_bf16 v[18:33], v[88:91], v[96:99], v[18:33]
	s_waitcnt vmcnt(7)
	ds_write_b128 v66, v[144:147] offset:36864
	s_waitcnt vmcnt(6)
	ds_write_b128 v66, v[124:127] offset:41472
	global_load_dwordx4 v[144:147], v[78:79], off offset:1152
	global_load_dwordx4 v[124:127], v[80:81], off offset:1152
	ds_read_b128 v[88:91], v70 offset:18528
	ds_read_b128 v[96:99], v1 offset:60000
	s_waitcnt lgkmcnt(1)
	v_mfma_f32_32x32x16_bf16 v[34:49], v[88:91], v[92:95], v[34:49]
	s_waitcnt lgkmcnt(0)
	v_mfma_f32_32x32x16_bf16 v[50:65], v[88:91], v[96:99], v[50:65]
	v_mfma_f32_32x32x16_bf16 v[2:17], v[100:103], v[92:95], v[2:17]
	v_mfma_f32_32x32x16_bf16 v[18:33], v[100:103], v[96:99], v[18:33]
	s_waitcnt vmcnt(7)
	ds_write_b128 v66, v[120:123] offset:46080
	s_waitcnt vmcnt(6)
	ds_write_b128 v66, v[116:119] offset:50688
	global_load_dwordx4 v[120:123], v[82:83], off offset:1152
	global_load_dwordx4 v[116:119], v[84:85], off offset:1152
	s_setprio 0
	s_waitcnt lgkmcnt(0)
	s_barrier
	ds_read_b128 v[96:99], v70
	ds_read_b128 v[100:103], v70 offset:4608
	ds_read_b128 v[128:131], v1 offset:36864
	ds_read_b128 v[132:135], v1 offset:41472
	s_setprio 1
	ds_read_b128 v[88:91], v70 offset:32
	s_waitcnt lgkmcnt(2)
	v_mfma_f32_32x32x16_bf16 v[34:49], v[96:99], v[128:131], v[34:49]
	ds_read_b128 v[92:95], v1 offset:36896
	s_waitcnt lgkmcnt(2)
	v_mfma_f32_32x32x16_bf16 v[50:65], v[96:99], v[132:135], v[50:65]
	ds_read_b128 v[96:99], v1 offset:41504
	s_waitcnt lgkmcnt(1)
	v_mfma_f32_32x32x16_bf16 v[34:49], v[88:91], v[92:95], v[34:49]
	s_waitcnt lgkmcnt(0)
	v_mfma_f32_32x32x16_bf16 v[50:65], v[88:91], v[96:99], v[50:65]
	s_waitcnt vmcnt(7)
	ds_write_b128 v66, v[140:143] offset:18432
	s_waitcnt vmcnt(6)
	ds_write_b128 v66, v[104:107] offset:23040
	global_load_dwordx4 v[140:143], v[74:75], off offset:1280
	global_load_dwordx4 v[104:107], v[72:73], off offset:1280
	ds_read_b128 v[88:91], v70 offset:4640
	v_mfma_f32_32x32x16_bf16 v[2:17], v[100:103], v[128:131], v[2:17]
	v_mfma_f32_32x32x16_bf16 v[18:33], v[100:103], v[132:135], v[18:33]
	ds_read_b128 v[100:103], v70 offset:4704
	s_waitcnt lgkmcnt(1)
	v_mfma_f32_32x32x16_bf16 v[2:17], v[88:91], v[92:95], v[2:17]
	ds_read_b128 v[92:95], v1 offset:36928
	v_mfma_f32_32x32x16_bf16 v[18:33], v[88:91], v[96:99], v[18:33]
	s_waitcnt vmcnt(7)
	ds_write_b128 v66, v[108:111] offset:27648
	s_waitcnt vmcnt(6)
	ds_write_b128 v66, v[112:115] offset:32256
	global_load_dwordx4 v[108:111], v[76:77], off offset:1280
	global_load_dwordx4 v[112:115], v[86:87], off offset:1280
	ds_read_b128 v[88:91], v70 offset:64
	ds_read_b128 v[96:99], v1 offset:41536
	s_waitcnt lgkmcnt(1)
	v_mfma_f32_32x32x16_bf16 v[34:49], v[88:91], v[92:95], v[34:49]
	s_waitcnt lgkmcnt(0)
	v_mfma_f32_32x32x16_bf16 v[50:65], v[88:91], v[96:99], v[50:65]
	ds_read_b128 v[88:91], v70 offset:4672
	s_waitcnt lgkmcnt(0)
	v_mfma_f32_32x32x16_bf16 v[2:17], v[88:91], v[92:95], v[2:17]
	ds_read_b128 v[92:95], v1 offset:36960
	v_mfma_f32_32x32x16_bf16 v[18:33], v[88:91], v[96:99], v[18:33]
	s_waitcnt vmcnt(7)
	ds_write_b128 v66, v[144:147] offset:55296
	s_waitcnt vmcnt(6)
	ds_write_b128 v66, v[124:127] offset:59904
	global_load_dwordx4 v[144:147], v[78:79], off offset:1280
	global_load_dwordx4 v[124:127], v[80:81], off offset:1280
	ds_read_b128 v[88:91], v70 offset:96
	ds_read_b128 v[96:99], v1 offset:41568
	s_waitcnt lgkmcnt(1)
	v_mfma_f32_32x32x16_bf16 v[34:49], v[88:91], v[92:95], v[34:49]
	s_waitcnt lgkmcnt(0)
	v_mfma_f32_32x32x16_bf16 v[50:65], v[88:91], v[96:99], v[50:65]
	v_mfma_f32_32x32x16_bf16 v[2:17], v[100:103], v[92:95], v[2:17]
	v_mfma_f32_32x32x16_bf16 v[18:33], v[100:103], v[96:99], v[18:33]
	s_waitcnt vmcnt(7)
	ds_write_b128 v66, v[120:123] offset:64512
	s_waitcnt vmcnt(6)
	ds_write_b128 v71, v[116:119] offset:32256
	global_load_dwordx4 v[120:123], v[82:83], off offset:1280
	global_load_dwordx4 v[116:119], v[84:85], off offset:1280
	s_setprio 0
	s_waitcnt lgkmcnt(0)
	s_barrier
; #define MFMA(a, b, c) __builtin_amdgcn_mfma_f32_32x32x16_bf16((a), (b), (c), 0, 0, 0)
; template <int TM, int TN>
; DI void gemm_mainloop(const u16* __restrict__ A, long lda, const u16* __restrict__ Bt, long ldb, int K, char* smem,
;                       f32x16 (&acc)[TM][TN]) {
;     ...
;   for (int kt = 0; kt < nk; kt++) {
;     const int buf = kt & 1;
;     const u16* cA = sA + buf * BM * LD + (wm * 32 * TM + r) * LD + h * 8;
;     const u16* cB = sB + buf * BN * LD + (wn * 32 * TN + r) * LD + h * 8;
;     bf16x8 af[TM], bfr[TN];
; #pragma unroll
;     for (int tm = 0; tm < TM; tm++) af[tm] = *(const bf16x8*)(cA + tm * 32 * LD);
; #pragma unroll
;     for (int tn = 0; tn < TN; tn++) bfr[tn] = *(const bf16x8*)(cB + tn * 32 * LD);
;     if (kt + 1 < nk) GEMM_SSTORE(buf ^ 1)
;     __builtin_amdgcn_sched_barrier(0);
;     __builtin_amdgcn_s_setprio(1);
; #pragma unroll
;     for (int tm = 0; tm < TM; tm++)
; #pragma unroll
;       for (int tn = 0; tn < TN; tn++) acc[tm][tn] = MFMA(af[tm], bfr[tn], acc[tm][tn]);
; #pragma unroll
;     for (int tm = 0; tm < TM; tm++) af[tm] = *(const bf16x8*)(cA + tm * 32 * LD + 16);
; #pragma unroll
;     for (int tn = 0; tn < TN; tn++) bfr[tn] = *(const bf16x8*)(cB + tn * 32 * LD + 16);
; #pragma unroll
;     for (int tm = 0; tm < TM; tm++)
; #pragma unroll
;       for (int tn = 0; tn < TN; tn++) acc[tm][tn] = MFMA(af[tm], bfr[tn], acc[tm][tn]);
;     __builtin_amdgcn_sched_group_barrier(0x8, 4, 0);
;     if (kt + 2 < nk) GEMM_GLOAD((kt + 2) * 64)
; #pragma unroll
;     for (int ks = 2; ks < 4; ks++) {
; #pragma unroll
;       for (int tm = 0; tm < TM; tm++) af[tm] = *(const bf16x8*)(cA + tm * 32 * LD + ks * 16);
; #pragma unroll
;       for (int tn = 0; tn < TN; tn++) bfr[tn] = *(const bf16x8*)(cB + tn * 32 * LD + ks * 16);
; #pragma unroll
;       for (int tm = 0; tm < TM; tm++)
; #pragma unroll
;         for (int tn = 0; tn < TN; tn++) acc[tm][tn] = MFMA(af[tm], bfr[tn], acc[tm][tn]);
;     }
;     __builtin_amdgcn_s_setprio(0);
;     __syncthreads();
;   }
	ds_read_b128 v[96:99], v70 offset:18432
	ds_read_b128 v[100:103], v70 offset:23040
	ds_read_b128 v[128:131], v1 offset:55296
	ds_read_b128 v[132:135], v1 offset:59904
	s_setprio 1
	ds_read_b128 v[88:91], v70 offset:18464
	s_waitcnt lgkmcnt(2)
	v_mfma_f32_32x32x16_bf16 v[34:49], v[96:99], v[128:131], v[34:49]
	ds_read_b128 v[92:95], v1 offset:55328
	s_waitcnt lgkmcnt(2)
	v_mfma_f32_32x32x16_bf16 v[50:65], v[96:99], v[132:135], v[50:65]
	ds_read_b128 v[96:99], v1 offset:59936
	s_waitcnt lgkmcnt(1)
	v_mfma_f32_32x32x16_bf16 v[34:49], v[88:91], v[92:95], v[34:49]
	s_waitcnt lgkmcnt(0)
	v_mfma_f32_32x32x16_bf16 v[50:65], v[88:91], v[96:99], v[50:65]
	s_waitcnt vmcnt(7)
	ds_write_b128 v66, v[140:143]
	s_waitcnt vmcnt(6)
	ds_write_b128 v66, v[104:107] offset:4608
	global_load_dwordx4 v[140:143], v[74:75], off offset:1408
	global_load_dwordx4 v[104:107], v[72:73], off offset:1408
	ds_read_b128 v[88:91], v70 offset:23072
	v_mfma_f32_32x32x16_bf16 v[2:17], v[100:103], v[128:131], v[2:17]
	v_mfma_f32_32x32x16_bf16 v[18:33], v[100:103], v[132:135], v[18:33]
	ds_read_b128 v[100:103], v70 offset:23136
	s_waitcnt lgkmcnt(1)
	v_mfma_f32_32x32x16_bf16 v[2:17], v[88:91], v[92:95], v[2:17]
	ds_read_b128 v[92:95], v1 offset:55360
	v_mfma_f32_32x32x16_bf16 v[18:33], v[88:91], v[96:99], v[18:33]
	s_waitcnt vmcnt(7)
	ds_write_b128 v66, v[108:111] offset:9216
	s_waitcnt vmcnt(6)
	ds_write_b128 v66, v[112:115] offset:13824
	global_load_dwordx4 v[108:111], v[76:77], off offset:1408
	global_load_dwordx4 v[112:115], v[86:87], off offset:1408
	ds_read_b128 v[88:91], v70 offset:18496
	ds_read_b128 v[96:99], v1 offset:59968
	s_waitcnt lgkmcnt(1)
	v_mfma_f32_32x32x16_bf16 v[34:49], v[88:91], v[92:95], v[34:49]
	s_waitcnt lgkmcnt(0)
	v_mfma_f32_32x32x16_bf16 v[50:65], v[88:91], v[96:99], v[50:65]
	ds_read_b128 v[88:91], v70 offset:23104
	s_waitcnt lgkmcnt(0)
	v_mfma_f32_32x32x16_bf16 v[2:17], v[88:91], v[92:95], v[2:17]
	ds_read_b128 v[92:95], v1 offset:55392
	v_mfma_f32_32x32x16_bf16 v[18:33], v[88:91], v[96:99], v[18:33]
	s_waitcnt vmcnt(7)
	ds_write_b128 v66, v[144:147] offset:36864
	s_waitcnt vmcnt(6)
	ds_write_b128 v66, v[124:127] offset:41472
	global_load_dwordx4 v[144:147], v[78:79], off offset:1408
	global_load_dwordx4 v[124:127], v[80:81], off offset:1408
	ds_read_b128 v[88:91], v70 offset:18528
	ds_read_b128 v[96:99], v1 offset:60000
	s_waitcnt lgkmcnt(1)
	v_mfma_f32_32x32x16_bf16 v[34:49], v[88:91], v[92:95], v[34:49]
	s_waitcnt lgkmcnt(0)
	v_mfma_f32_32x32x16_bf16 v[50:65], v[88:91], v[96:99], v[50:65]
	v_mfma_f32_32x32x16_bf16 v[2:17], v[100:103], v[92:95], v[2:17]
	v_mfma_f32_32x32x16_bf16 v[18:33], v[100:103], v[96:99], v[18:33]
	s_waitcnt vmcnt(7)
	ds_write_b128 v66, v[120:123] offset:46080
	s_waitcnt vmcnt(6)
	ds_write_b128 v66, v[116:119] offset:50688
	global_load_dwordx4 v[120:123], v[82:83], off offset:1408
	global_load_dwordx4 v[116:119], v[84:85], off offset:1408
	s_setprio 0
	s_waitcnt lgkmcnt(0)
	s_barrier
	ds_read_b128 v[96:99], v70
	ds_read_b128 v[100:103], v70 offset:4608
	ds_read_b128 v[128:131], v1 offset:36864
	ds_read_b128 v[132:135], v1 offset:41472
	s_setprio 1
	ds_read_b128 v[88:91], v70 offset:32
	s_waitcnt lgkmcnt(2)
	v_mfma_f32_32x32x16_bf16 v[34:49], v[96:99], v[128:131], v[34:49]
	ds_read_b128 v[92:95], v1 offset:36896
	s_waitcnt lgkmcnt(2)
	v_mfma_f32_32x32x16_bf16 v[50:65], v[96:99], v[132:135], v[50:65]
	ds_read_b128 v[96:99], v1 offset:41504
	s_waitcnt lgkmcnt(1)
	v_mfma_f32_32x32x16_bf16 v[34:49], v[88:91], v[92:95], v[34:49]
	s_waitcnt lgkmcnt(0)
	v_mfma_f32_32x32x16_bf16 v[50:65], v[88:91], v[96:99], v[50:65]
	s_waitcnt vmcnt(7)
	ds_write_b128 v66, v[140:143] offset:18432
	s_waitcnt vmcnt(6)
	ds_write_b128 v66, v[104:107] offset:23040
	global_load_dwordx4 v[140:143], v[74:75], off offset:1536
	global_load_dwordx4 v[104:107], v[72:73], off offset:1536
	ds_read_b128 v[88:91], v70 offset:4640
	v_mfma_f32_32x32x16_bf16 v[2:17], v[100:103], v[128:131], v[2:17]
	v_mfma_f32_32x32x16_bf16 v[18:33], v[100:103], v[132:135], v[18:33]
	ds_read_b128 v[100:103], v70 offset:4704
	s_waitcnt lgkmcnt(1)
	v_mfma_f32_32x32x16_bf16 v[2:17], v[88:91], v[92:95], v[2:17]
	ds_read_b128 v[92:95], v1 offset:36928
	v_mfma_f32_32x32x16_bf16 v[18:33], v[88:91], v[96:99], v[18:33]
	s_waitcnt vmcnt(7)
	ds_write_b128 v66, v[108:111] offset:27648
	s_waitcnt vmcnt(6)
	ds_write_b128 v66, v[112:115] offset:32256
	global_load_dwordx4 v[108:111], v[76:77], off offset:1536
	global_load_dwordx4 v[112:115], v[86:87], off offset:1536
	ds_read_b128 v[88:91], v70 offset:64
	ds_read_b128 v[96:99], v1 offset:41536
	s_waitcnt lgkmcnt(1)
	v_mfma_f32_32x32x16_bf16 v[34:49], v[88:91], v[92:95], v[34:49]
	s_waitcnt lgkmcnt(0)
	v_mfma_f32_32x32x16_bf16 v[50:65], v[88:91], v[96:99], v[50:65]
	ds_read_b128 v[88:91], v70 offset:4672
	s_waitcnt lgkmcnt(0)
	v_mfma_f32_32x32x16_bf16 v[2:17], v[88:91], v[92:95], v[2:17]
	ds_read_b128 v[92:95], v1 offset:36960
	v_mfma_f32_32x32x16_bf16 v[18:33], v[88:91], v[96:99], v[18:33]
	s_waitcnt vmcnt(7)
	ds_write_b128 v66, v[144:147] offset:55296
	s_waitcnt vmcnt(6)
	ds_write_b128 v66, v[124:127] offset:59904
	global_load_dwordx4 v[144:147], v[78:79], off offset:1536
	global_load_dwordx4 v[124:127], v[80:81], off offset:1536
	ds_read_b128 v[88:91], v70 offset:96
	ds_read_b128 v[96:99], v1 offset:41568
	s_waitcnt lgkmcnt(1)
	v_mfma_f32_32x32x16_bf16 v[34:49], v[88:91], v[92:95], v[34:49]
	s_waitcnt lgkmcnt(0)
	v_mfma_f32_32x32x16_bf16 v[50:65], v[88:91], v[96:99], v[50:65]
	v_mfma_f32_32x32x16_bf16 v[2:17], v[100:103], v[92:95], v[2:17]
	v_mfma_f32_32x32x16_bf16 v[18:33], v[100:103], v[96:99], v[18:33]
	s_waitcnt vmcnt(7)
	ds_write_b128 v66, v[120:123] offset:64512
	s_waitcnt vmcnt(6)
	ds_write_b128 v71, v[116:119] offset:32256
	global_load_dwordx4 v[120:123], v[82:83], off offset:1536
	global_load_dwordx4 v[116:119], v[84:85], off offset:1536
	s_setprio 0
	s_waitcnt lgkmcnt(0)
	s_barrier
; #define MFMA(a, b, c) __builtin_amdgcn_mfma_f32_32x32x16_bf16((a), (b), (c), 0, 0, 0)
; template <int TM, int TN>
; DI void gemm_mainloop(const u16* __restrict__ A, long lda, const u16* __restrict__ Bt, long ldb, int K, char* smem,
;                       f32x16 (&acc)[TM][TN]) {
;     ...
;   for (int kt = 0; kt < nk; kt++) {
;     const int buf = kt & 1;
;     const u16* cA = sA + buf * BM * LD + (wm * 32 * TM + r) * LD + h * 8;
;     const u16* cB = sB + buf * BN * LD + (wn * 32 * TN + r) * LD + h * 8;
;     bf16x8 af[TM], bfr[TN];
; #pragma unroll
;     for (int tm = 0; tm < TM; tm++) af[tm] = *(const bf16x8*)(cA + tm * 32 * LD);
; #pragma unroll
;     for (int tn = 0; tn < TN; tn++) bfr[tn] = *(const bf16x8*)(cB + tn * 32 * LD);
;     if (kt + 1 < nk) GEMM_SSTORE(buf ^ 1)
;     __builtin_amdgcn_sched_barrier(0);
;     __builtin_amdgcn_s_setprio(1);
; #pragma unroll
;     for (int tm = 0; tm < TM; tm++)
; #pragma unroll
;       for (int tn = 0; tn < TN; tn++) acc[tm][tn] = MFMA(af[tm], bfr[tn], acc[tm][tn]);
; #pragma unroll
;     for (int tm = 0; tm < TM; tm++) af[tm] = *(const bf16x8*)(cA + tm * 32 * LD + 16);
; #pragma unroll
;     for (int tn = 0; tn < TN; tn++) bfr[tn] = *(const bf16x8*)(cB + tn * 32 * LD + 16);
; #pragma unroll
;     for (int tm = 0; tm < TM; tm++)
; #pragma unroll
;       for (int tn = 0; tn < TN; tn++) acc[tm][tn] = MFMA(af[tm], bfr[tn], acc[tm][tn]);
;     __builtin_amdgcn_sched_group_barrier(0x8, 4, 0);
;     if (kt + 2 < nk) GEMM_GLOAD((kt + 2) * 64)
; #pragma unroll
;     for (int ks = 2; ks < 4; ks++) {
; #pragma unroll
;       for (int tm = 0; tm < TM; tm++) af[tm] = *(const bf16x8*)(cA + tm * 32 * LD + ks * 16);
; #pragma unroll
;       for (int tn = 0; tn < TN; tn++) bfr[tn] = *(const bf16x8*)(cB + tn * 32 * LD + ks * 16);
; #pragma unroll
;       for (int tm = 0; tm < TM; tm++)
; #pragma unroll
;         for (int tn = 0; tn < TN; tn++) acc[tm][tn] = MFMA(af[tm], bfr[tn], acc[tm][tn]);
;     }
;     __builtin_amdgcn_s_setprio(0);
;     __syncthreads();
;   }
	ds_read_b128 v[96:99], v70 offset:18432
	ds_read_b128 v[100:103], v70 offset:23040
	ds_read_b128 v[128:131], v1 offset:55296
	ds_read_b128 v[132:135], v1 offset:59904
	s_setprio 1
	ds_read_b128 v[88:91], v70 offset:18464
	s_waitcnt lgkmcnt(2)
	v_mfma_f32_32x32x16_bf16 v[34:49], v[96:99], v[128:131], v[34:49]
	ds_read_b128 v[92:95], v1 offset:55328
	s_waitcnt lgkmcnt(2)
	v_mfma_f32_32x32x16_bf16 v[50:65], v[96:99], v[132:135], v[50:65]
	ds_read_b128 v[96:99], v1 offset:59936
	s_waitcnt lgkmcnt(1)
	v_mfma_f32_32x32x16_bf16 v[34:49], v[88:91], v[92:95], v[34:49]
	s_waitcnt lgkmcnt(0)
	v_mfma_f32_32x32x16_bf16 v[50:65], v[88:91], v[96:99], v[50:65]
	s_waitcnt vmcnt(7)
	ds_write_b128 v66, v[140:143]
	s_waitcnt vmcnt(6)
	ds_write_b128 v66, v[104:107] offset:4608
	global_load_dwordx4 v[140:143], v[74:75], off offset:1664
	global_load_dwordx4 v[104:107], v[72:73], off offset:1664
	ds_read_b128 v[88:91], v70 offset:23072
	v_mfma_f32_32x32x16_bf16 v[2:17], v[100:103], v[128:131], v[2:17]
	v_mfma_f32_32x32x16_bf16 v[18:33], v[100:103], v[132:135], v[18:33]
	ds_read_b128 v[100:103], v70 offset:23136
	s_waitcnt lgkmcnt(1)
	v_mfma_f32_32x32x16_bf16 v[2:17], v[88:91], v[92:95], v[2:17]
	ds_read_b128 v[92:95], v1 offset:55360
	v_mfma_f32_32x32x16_bf16 v[18:33], v[88:91], v[96:99], v[18:33]
	s_waitcnt vmcnt(7)
	ds_write_b128 v66, v[108:111] offset:9216
	s_waitcnt vmcnt(6)
	ds_write_b128 v66, v[112:115] offset:13824
	global_load_dwordx4 v[108:111], v[76:77], off offset:1664
	global_load_dwordx4 v[112:115], v[86:87], off offset:1664
	ds_read_b128 v[88:91], v70 offset:18496
	ds_read_b128 v[96:99], v1 offset:59968
	s_waitcnt lgkmcnt(1)
	v_mfma_f32_32x32x16_bf16 v[34:49], v[88:91], v[92:95], v[34:49]
	s_waitcnt lgkmcnt(0)
	v_mfma_f32_32x32x16_bf16 v[50:65], v[88:91], v[96:99], v[50:65]
	ds_read_b128 v[88:91], v70 offset:23104
	s_waitcnt lgkmcnt(0)
	v_mfma_f32_32x32x16_bf16 v[2:17], v[88:91], v[92:95], v[2:17]
	ds_read_b128 v[92:95], v1 offset:55392
	v_mfma_f32_32x32x16_bf16 v[18:33], v[88:91], v[96:99], v[18:33]
	s_waitcnt vmcnt(7)
	ds_write_b128 v66, v[144:147] offset:36864
	s_waitcnt vmcnt(6)
	ds_write_b128 v66, v[124:127] offset:41472
	global_load_dwordx4 v[144:147], v[78:79], off offset:1664
	global_load_dwordx4 v[124:127], v[80:81], off offset:1664
	ds_read_b128 v[88:91], v70 offset:18528
	ds_read_b128 v[96:99], v1 offset:60000
	s_waitcnt lgkmcnt(1)
	v_mfma_f32_32x32x16_bf16 v[34:49], v[88:91], v[92:95], v[34:49]
	s_waitcnt lgkmcnt(0)
	v_mfma_f32_32x32x16_bf16 v[50:65], v[88:91], v[96:99], v[50:65]
	v_mfma_f32_32x32x16_bf16 v[2:17], v[100:103], v[92:95], v[2:17]
	v_mfma_f32_32x32x16_bf16 v[18:33], v[100:103], v[96:99], v[18:33]
	s_waitcnt vmcnt(7)
	ds_write_b128 v66, v[120:123] offset:46080
	s_waitcnt vmcnt(6)
	ds_write_b128 v66, v[116:119] offset:50688
	global_load_dwordx4 v[120:123], v[82:83], off offset:1664
	global_load_dwordx4 v[116:119], v[84:85], off offset:1664
	s_setprio 0
	s_waitcnt lgkmcnt(0)
	s_barrier
	ds_read_b128 v[96:99], v70
	ds_read_b128 v[100:103], v70 offset:4608
	ds_read_b128 v[128:131], v1 offset:36864
	ds_read_b128 v[132:135], v1 offset:41472
	s_setprio 1
	ds_read_b128 v[88:91], v70 offset:32
	s_waitcnt lgkmcnt(2)
	v_mfma_f32_32x32x16_bf16 v[34:49], v[96:99], v[128:131], v[34:49]
	ds_read_b128 v[92:95], v1 offset:36896
	s_waitcnt lgkmcnt(2)
	v_mfma_f32_32x32x16_bf16 v[50:65], v[96:99], v[132:135], v[50:65]
	ds_read_b128 v[96:99], v1 offset:41504
	s_waitcnt lgkmcnt(1)
	v_mfma_f32_32x32x16_bf16 v[34:49], v[88:91], v[92:95], v[34:49]
	s_waitcnt lgkmcnt(0)
	v_mfma_f32_32x32x16_bf16 v[50:65], v[88:91], v[96:99], v[50:65]
	s_waitcnt vmcnt(7)
	ds_write_b128 v66, v[140:143] offset:18432
	s_waitcnt vmcnt(6)
	ds_write_b128 v66, v[104:107] offset:23040
	global_load_dwordx4 v[140:143], v[74:75], off offset:1792
	global_load_dwordx4 v[104:107], v[72:73], off offset:1792
	ds_read_b128 v[88:91], v70 offset:4640
	v_mfma_f32_32x32x16_bf16 v[2:17], v[100:103], v[128:131], v[2:17]
	v_mfma_f32_32x32x16_bf16 v[18:33], v[100:103], v[132:135], v[18:33]
	ds_read_b128 v[100:103], v70 offset:4704
	s_waitcnt lgkmcnt(1)
	v_mfma_f32_32x32x16_bf16 v[2:17], v[88:91], v[92:95], v[2:17]
	ds_read_b128 v[92:95], v1 offset:36928
	v_mfma_f32_32x32x16_bf16 v[18:33], v[88:91], v[96:99], v[18:33]
	s_waitcnt vmcnt(7)
	ds_write_b128 v66, v[108:111] offset:27648
	s_waitcnt vmcnt(6)
	ds_write_b128 v66, v[112:115] offset:32256
	global_load_dwordx4 v[108:111], v[76:77], off offset:1792
	global_load_dwordx4 v[112:115], v[86:87], off offset:1792
	ds_read_b128 v[88:91], v70 offset:64
	ds_read_b128 v[96:99], v1 offset:41536
	s_waitcnt lgkmcnt(1)
	v_mfma_f32_32x32x16_bf16 v[34:49], v[88:91], v[92:95], v[34:49]
	s_waitcnt lgkmcnt(0)
	v_mfma_f32_32x32x16_bf16 v[50:65], v[88:91], v[96:99], v[50:65]
	ds_read_b128 v[88:91], v70 offset:4672
	s_waitcnt lgkmcnt(0)
	v_mfma_f32_32x32x16_bf16 v[2:17], v[88:91], v[92:95], v[2:17]
	ds_read_b128 v[92:95], v1 offset:36960
	v_mfma_f32_32x32x16_bf16 v[18:33], v[88:91], v[96:99], v[18:33]
	s_waitcnt vmcnt(7)
	ds_write_b128 v66, v[144:147] offset:55296
	s_waitcnt vmcnt(6)
	ds_write_b128 v66, v[124:127] offset:59904
	global_load_dwordx4 v[144:147], v[78:79], off offset:1792
	global_load_dwordx4 v[124:127], v[80:81], off offset:1792
	ds_read_b128 v[88:91], v70 offset:96
	ds_read_b128 v[96:99], v1 offset:41568
	s_waitcnt lgkmcnt(1)
	v_mfma_f32_32x32x16_bf16 v[34:49], v[88:91], v[92:95], v[34:49]
	s_waitcnt lgkmcnt(0)
	v_mfma_f32_32x32x16_bf16 v[50:65], v[88:91], v[96:99], v[50:65]
	v_mfma_f32_32x32x16_bf16 v[2:17], v[100:103], v[92:95], v[2:17]
	v_mfma_f32_32x32x16_bf16 v[18:33], v[100:103], v[96:99], v[18:33]
	s_waitcnt vmcnt(7)
	ds_write_b128 v66, v[120:123] offset:64512
	s_waitcnt vmcnt(6)
	ds_write_b128 v71, v[116:119] offset:32256
	global_load_dwordx4 v[120:123], v[82:83], off offset:1792
	global_load_dwordx4 v[116:119], v[84:85], off offset:1792
	s_setprio 0
	s_waitcnt lgkmcnt(0)
	s_barrier
; #define MFMA(a, b, c) __builtin_amdgcn_mfma_f32_32x32x16_bf16((a), (b), (c), 0, 0, 0)
; template <int TM, int TN>
; DI void gemm_mainloop(const u16* __restrict__ A, long lda, const u16* __restrict__ Bt, long ldb, int K, char* smem,
;                       f32x16 (&acc)[TM][TN]) {
;     ...
;   for (int kt = 0; kt < nk; kt++) {
;     const int buf = kt & 1;
;     const u16* cA = sA + buf * BM * LD + (wm * 32 * TM + r) * LD + h * 8;
;     const u16* cB = sB + buf * BN * LD + (wn * 32 * TN + r) * LD + h * 8;
;     bf16x8 af[TM], bfr[TN];
; #pragma unroll
;     for (int tm = 0; tm < TM; tm++) af[tm] = *(const bf16x8*)(cA + tm * 32 * LD);
; #pragma unroll
;     for (int tn = 0; tn < TN; tn++) bfr[tn] = *(const bf16x8*)(cB + tn * 32 * LD);
;     if (kt + 1 < nk) GEMM_SSTORE(buf ^ 1)
;     __builtin_amdgcn_sched_barrier(0);
;     __builtin_amdgcn_s_setprio(1);
; #pragma unroll
;     for (int tm = 0; tm < TM; tm++)
; #pragma unroll
;       for (int tn = 0; tn < TN; tn++) acc[tm][tn] = MFMA(af[tm], bfr[tn], acc[tm][tn]);
; #pragma unroll
;     for (int tm = 0; tm < TM; tm++) af[tm] = *(const bf16x8*)(cA + tm * 32 * LD + 16);
; #pragma unroll
;     for (int tn = 0; tn < TN; tn++) bfr[tn] = *(const bf16x8*)(cB + tn * 32 * LD + 16);
; #pragma unroll
;     for (int tm = 0; tm < TM; tm++)
; #pragma unroll
;       for (int tn = 0; tn < TN; tn++) acc[tm][tn] = MFMA(af[tm], bfr[tn], acc[tm][tn]);
;     __builtin_amdgcn_sched_group_barrier(0x8, 4, 0);
;     if (kt + 2 < nk) GEMM_GLOAD((kt + 2) * 64)
; #pragma unroll
;     for (int ks = 2; ks < 4; ks++) {
; #pragma unroll
;       for (int tm = 0; tm < TM; tm++) af[tm] = *(const bf16x8*)(cA + tm * 32 * LD + ks * 16);
; #pragma unroll
;       for (int tn = 0; tn < TN; tn++) bfr[tn] = *(const bf16x8*)(cB + tn * 32 * LD + ks * 16);
; #pragma unroll
;       for (int tm = 0; tm < TM; tm++)
; #pragma unroll
;         for (int tn = 0; tn < TN; tn++) acc[tm][tn] = MFMA(af[tm], bfr[tn], acc[tm][tn]);
;     }
;     __builtin_amdgcn_s_setprio(0);
;     __syncthreads();
;   }
	ds_read_b128 v[96:99], v70 offset:18432
	ds_read_b128 v[100:103], v70 offset:23040
	ds_read_b128 v[128:131], v1 offset:55296
	ds_read_b128 v[132:135], v1 offset:59904
	s_setprio 1
	ds_read_b128 v[88:91], v70 offset:18464
	s_waitcnt lgkmcnt(2)
	v_mfma_f32_32x32x16_bf16 v[34:49], v[96:99], v[128:131], v[34:49]
	ds_read_b128 v[92:95], v1 offset:55328
	s_waitcnt lgkmcnt(2)
	v_mfma_f32_32x32x16_bf16 v[50:65], v[96:99], v[132:135], v[50:65]
	ds_read_b128 v[96:99], v1 offset:59936
	s_waitcnt lgkmcnt(1)
	v_mfma_f32_32x32x16_bf16 v[34:49], v[88:91], v[92:95], v[34:49]
	s_waitcnt lgkmcnt(0)
	v_mfma_f32_32x32x16_bf16 v[50:65], v[88:91], v[96:99], v[50:65]
	s_waitcnt vmcnt(7)
	ds_write_b128 v66, v[140:143]
	s_waitcnt vmcnt(6)
	ds_write_b128 v66, v[104:107] offset:4608
	global_load_dwordx4 v[140:143], v[74:75], off offset:1920
	global_load_dwordx4 v[104:107], v[72:73], off offset:1920
	ds_read_b128 v[88:91], v70 offset:23072
	v_mfma_f32_32x32x16_bf16 v[2:17], v[100:103], v[128:131], v[2:17]
	v_mfma_f32_32x32x16_bf16 v[18:33], v[100:103], v[132:135], v[18:33]
	ds_read_b128 v[100:103], v70 offset:23136
	s_waitcnt lgkmcnt(1)
	v_mfma_f32_32x32x16_bf16 v[2:17], v[88:91], v[92:95], v[2:17]
	ds_read_b128 v[92:95], v1 offset:55360
	v_mfma_f32_32x32x16_bf16 v[18:33], v[88:91], v[96:99], v[18:33]
	s_waitcnt vmcnt(7)
	ds_write_b128 v66, v[108:111] offset:9216
	s_waitcnt vmcnt(6)
	ds_write_b128 v66, v[112:115] offset:13824
	global_load_dwordx4 v[108:111], v[76:77], off offset:1920
	global_load_dwordx4 v[112:115], v[86:87], off offset:1920
	ds_read_b128 v[88:91], v70 offset:18496
	ds_read_b128 v[96:99], v1 offset:59968
	s_waitcnt lgkmcnt(1)
	v_mfma_f32_32x32x16_bf16 v[34:49], v[88:91], v[92:95], v[34:49]
	s_waitcnt lgkmcnt(0)
	v_mfma_f32_32x32x16_bf16 v[50:65], v[88:91], v[96:99], v[50:65]
	ds_read_b128 v[88:91], v70 offset:23104
	s_waitcnt lgkmcnt(0)
	v_mfma_f32_32x32x16_bf16 v[2:17], v[88:91], v[92:95], v[2:17]
	ds_read_b128 v[92:95], v1 offset:55392
	v_mfma_f32_32x32x16_bf16 v[18:33], v[88:91], v[96:99], v[18:33]
	s_waitcnt vmcnt(7)
	ds_write_b128 v66, v[144:147] offset:36864
	s_waitcnt vmcnt(6)
	ds_write_b128 v66, v[124:127] offset:41472
	global_load_dwordx4 v[144:147], v[78:79], off offset:1920
	global_load_dwordx4 v[124:127], v[80:81], off offset:1920
	ds_read_b128 v[88:91], v70 offset:18528
	ds_read_b128 v[96:99], v1 offset:60000
	s_waitcnt lgkmcnt(1)
	v_mfma_f32_32x32x16_bf16 v[34:49], v[88:91], v[92:95], v[34:49]
	s_waitcnt lgkmcnt(0)
	v_mfma_f32_32x32x16_bf16 v[50:65], v[88:91], v[96:99], v[50:65]
	s_nop 0
	v_mfma_f32_32x32x16_bf16 v[2:17], v[100:103], v[92:95], v[2:17]
	v_mfma_f32_32x32x16_bf16 v[18:33], v[100:103], v[96:99], v[18:33]
	s_waitcnt vmcnt(7)
	ds_write_b128 v66, v[120:123] offset:46080
	s_waitcnt vmcnt(6)
	ds_write_b128 v66, v[116:119] offset:50688
	global_load_dwordx4 v[120:123], v[82:83], off offset:1920
	global_load_dwordx4 v[116:119], v[84:85], off offset:1920
	s_setprio 0
	s_waitcnt lgkmcnt(0)
	s_barrier
	ds_read_b128 v[76:79], v70
	ds_read_b128 v[80:83], v70 offset:4608
	ds_read_b128 v[84:87], v1 offset:36864
	ds_read_b128 v[92:95], v1 offset:41472
	s_setprio 1
	ds_read_b128 v[72:75], v70 offset:32
	s_waitcnt lgkmcnt(2)
	v_mfma_f32_32x32x16_bf16 v[34:49], v[76:79], v[84:87], v[34:49]
	s_waitcnt lgkmcnt(1)
	v_mfma_f32_32x32x16_bf16 v[50:65], v[76:79], v[92:95], v[50:65]
	ds_read_b128 v[76:79], v1 offset:36896
	v_mfma_f32_32x32x16_bf16 v[2:17], v[80:83], v[84:87], v[2:17]
	v_mfma_f32_32x32x16_bf16 v[18:33], v[80:83], v[92:95], v[18:33]
	s_waitcnt vmcnt(7)
	ds_write_b128 v66, v[140:143] offset:18432
	s_waitcnt vmcnt(6)
	ds_write_b128 v66, v[104:107] offset:23040
	ds_read_b128 v[80:83], v1 offset:41504
	s_waitcnt lgkmcnt(3)
	v_mfma_f32_32x32x16_bf16 v[34:49], v[72:75], v[76:79], v[34:49]
	s_waitcnt lgkmcnt(0)
	v_mfma_f32_32x32x16_bf16 v[50:65], v[72:75], v[80:83], v[50:65]
	ds_read_b128 v[72:75], v70 offset:4640
	s_waitcnt lgkmcnt(0)
	v_mfma_f32_32x32x16_bf16 v[2:17], v[72:75], v[76:79], v[2:17]
	ds_read_b128 v[76:79], v1 offset:36928
	v_mfma_f32_32x32x16_bf16 v[18:33], v[72:75], v[80:83], v[18:33]
	s_waitcnt vmcnt(5)
	ds_write_b128 v66, v[108:111] offset:27648
	s_waitcnt vmcnt(4)
	ds_write_b128 v66, v[112:115] offset:32256
	ds_read_b128 v[72:75], v70 offset:64
	ds_read_b128 v[80:83], v1 offset:41536
	s_waitcnt lgkmcnt(1)
	v_mfma_f32_32x32x16_bf16 v[34:49], v[72:75], v[76:79], v[34:49]
	s_waitcnt lgkmcnt(0)
	v_mfma_f32_32x32x16_bf16 v[50:65], v[72:75], v[80:83], v[50:65]
	ds_read_b128 v[72:75], v70 offset:4672
	s_waitcnt lgkmcnt(0)
	v_mfma_f32_32x32x16_bf16 v[2:17], v[72:75], v[76:79], v[2:17]
	ds_read_b128 v[76:79], v1 offset:36960
	v_mfma_f32_32x32x16_bf16 v[18:33], v[72:75], v[80:83], v[18:33]
	s_waitcnt vmcnt(3)
	ds_write_b128 v66, v[144:147] offset:55296
	s_waitcnt vmcnt(2)
	ds_write_b128 v66, v[124:127] offset:59904
	ds_read_b128 v[72:75], v70 offset:96
	ds_read_b128 v[80:83], v1 offset:41568
	s_waitcnt lgkmcnt(1)
	v_mfma_f32_32x32x16_bf16 v[34:49], v[72:75], v[76:79], v[34:49]
	s_waitcnt lgkmcnt(0)
	v_mfma_f32_32x32x16_bf16 v[50:65], v[72:75], v[80:83], v[50:65]
	ds_read_b128 v[72:75], v70 offset:4704
	s_waitcnt lgkmcnt(0)
	v_mfma_f32_32x32x16_bf16 v[2:17], v[72:75], v[76:79], v[2:17]
	v_mfma_f32_32x32x16_bf16 v[18:33], v[72:75], v[80:83], v[18:33]
	s_waitcnt vmcnt(1)
	ds_write_b128 v66, v[120:123] offset:64512
	s_waitcnt vmcnt(0)
	ds_write_b128 v71, v[116:119] offset:32256
	s_setprio 0
	s_waitcnt lgkmcnt(0)
	s_barrier
; #define MFMA(a, b, c) __builtin_amdgcn_mfma_f32_32x32x16_bf16((a), (b), (c), 0, 0, 0)
; DI int crow(int i, int h) { return (i & 3) + 8 * (i >> 2) + 4 * h; }
; template <int TM, int TN>
; DI void gemm_mainloop(const u16* __restrict__ A, long lda, const u16* __restrict__ Bt, long ldb, int K, char* smem,
;                       f32x16 (&acc)[TM][TN]) {
;     ...
;     for (int tm = 0; tm < TM; tm++)
; #pragma unroll
;       for (int tn = 0; tn < TN; tn++) acc[tm][tn] = MFMA(af[tm], bfr[tn], acc[tm][tn]);
;     __builtin_amdgcn_sched_group_barrier(0x8, 4, 0);
;     if (kt + 2 < nk) GEMM_GLOAD((kt + 2) * 64)
; #pragma unroll
;     for (int ks = 2; ks < 4; ks++) {
; #pragma unroll
;       for (int tm = 0; tm < TM; tm++) af[tm] = *(const bf16x8*)(cA + tm * 32 * LD + ks * 16);
; #pragma unroll
;       for (int tn = 0; tn < TN; tn++) bfr[tn] = *(const bf16x8*)(cB + tn * 32 * LD + ks * 16);
; #pragma unroll
;       for (int tm = 0; tm < TM; tm++)
; #pragma unroll
;         for (int tn = 0; tn < TN; tn++) acc[tm][tn] = MFMA(af[tm], bfr[tn], acc[tm][tn]);
;     }
;     __builtin_amdgcn_s_setprio(0);
;     __syncthreads();
; template <int TM, int TN, class Epi>
; DI void gemm_tile(const u16* A, long lda, const u16* Bt, long ldb, int K, int m0, int n0, char* smem, const Epi& epi) {
;     ...
; #pragma unroll
;   for (int tm = 0; tm < TM; tm++)
; #pragma unroll
;     for (int tn = 0; tn < TN; tn++)
; #pragma unroll
;       for (int i = 0; i < 16; i++)
;         Ct[(wm * 32 * TM + tm * 32 + crow(i, h)) * LDC + wn * 32 * TN + tn * 32 + r] = acc[tm][tn][i];
;   __syncthreads();
;   epi(Ct, LDC, m0, n0, tid, BM);
;   __syncthreads();
;   (void)BM;
; }
;   DI void operator()(const float* Ct, int ldc, int m0, int n0, int tid, int bm) const {
; #pragma unroll 4
;     for (int it = 0; it < bm / 16; it++) {
;       int id = tid + 256 * it; int row = id >> 4, c8 = (id & 15) * 8;
;       int n = n0 + c8;
;       if (n < nmax) {
	ds_read_b128 v[72:75], v70 offset:18432
	ds_read_b128 v[76:79], v70 offset:23040
	ds_read_b128 v[80:83], v1 offset:55296
	ds_read_b128 v[84:87], v1 offset:59904
	s_setprio 1
	s_waitcnt lgkmcnt(1)
	v_mfma_f32_32x32x16_bf16 v[34:49], v[72:75], v[80:83], v[34:49]
	s_waitcnt lgkmcnt(0)
	v_mfma_f32_32x32x16_bf16 v[50:65], v[72:75], v[84:87], v[50:65]
	ds_read_b128 v[72:75], v70 offset:18464
	v_mfma_f32_32x32x16_bf16 v[2:17], v[76:79], v[80:83], v[2:17]
	ds_read_b128 v[80:83], v1 offset:59936
	v_mfma_f32_32x32x16_bf16 v[18:33], v[76:79], v[84:87], v[18:33]
	ds_read_b128 v[76:79], v1 offset:55328
	s_waitcnt lgkmcnt(0)
	v_mfma_f32_32x32x16_bf16 v[34:49], v[72:75], v[76:79], v[34:49]
	v_mfma_f32_32x32x16_bf16 v[50:65], v[72:75], v[80:83], v[50:65]
	ds_read_b128 v[72:75], v70 offset:23072
	s_waitcnt lgkmcnt(0)
	v_mfma_f32_32x32x16_bf16 v[2:17], v[72:75], v[76:79], v[2:17]
	ds_read_b128 v[76:79], v1 offset:55360
	v_mfma_f32_32x32x16_bf16 v[18:33], v[72:75], v[80:83], v[18:33]
	ds_read_b128 v[72:75], v70 offset:18496
	ds_read_b128 v[80:83], v1 offset:59968
	s_waitcnt lgkmcnt(1)
	v_mfma_f32_32x32x16_bf16 v[34:49], v[72:75], v[76:79], v[34:49]
	s_waitcnt lgkmcnt(0)
	v_mfma_f32_32x32x16_bf16 v[50:65], v[72:75], v[80:83], v[50:65]
	ds_read_b128 v[72:75], v70 offset:23104
	s_waitcnt lgkmcnt(0)
	v_mfma_f32_32x32x16_bf16 v[2:17], v[72:75], v[76:79], v[2:17]
	ds_read_b128 v[76:79], v1 offset:55392
	v_mfma_f32_32x32x16_bf16 v[18:33], v[72:75], v[80:83], v[18:33]
	ds_read_b128 v[72:75], v70 offset:18528
	ds_read_b128 v[80:83], v1 offset:60000
	s_waitcnt lgkmcnt(1)
	v_mfma_f32_32x32x16_bf16 v[34:49], v[72:75], v[76:79], v[34:49]
	s_waitcnt lgkmcnt(0)
	v_mfma_f32_32x32x16_bf16 v[50:65], v[72:75], v[80:83], v[50:65]
	ds_read_b128 v[70:73], v70 offset:23136
	s_waitcnt lgkmcnt(0)
	v_mfma_f32_32x32x16_bf16 v[2:17], v[70:73], v[76:79], v[2:17]
	v_mfma_f32_32x32x16_bf16 v[18:33], v[70:73], v[80:83], v[18:33]
	s_setprio 0
	v_mov_b32_e32 v1, v0
	s_barrier
	s_mov_b32 s4, 0
	v_lshrrev_b32_e32 v66, 1, v1
	v_and_b32_e32 v66, 0xfffffc0, v66
	v_lshrrev_b32_e32 v70, 3, v1
	v_and_or_b32 v66, v70, 4, v66
	v_and_b32_e32 v70, 0x5f, v1
	v_mul_lo_u32 v66, v66, s24
	v_lshl_add_u32 v66, v70, 2, v66
	ds_write2_b32 v66, v34, v50 offset1:32
	v_add_u32_e32 v34, 0x400, v66
	ds_write2_b32 v34, v36, v52 offset0:8 offset1:40
	ds_write2_b32 v34, v37, v53 offset0:140 offset1:172
	v_add_u32_e32 v34, 0x1000, v66
	ds_write2_b32 v34, v38, v54 offset0:32 offset1:64
	ds_write2_b32 v34, v39, v55 offset0:164 offset1:196
	v_add_u32_e32 v34, 0x1400, v66
	ds_write2_b32 v34, v40, v56 offset0:40 offset1:72
	ds_write2_b32 v34, v41, v57 offset0:172 offset1:204
	v_add_u32_e32 v34, 0x2000, v66
	ds_write2_b32 v34, v42, v58 offset0:64 offset1:96
	ds_write2_b32 v34, v43, v59 offset0:196 offset1:228
	v_add_u32_e32 v34, 0x2400, v66
	ds_write2_b32 v34, v44, v60 offset0:72 offset1:104
	ds_write2_b32 v34, v45, v61 offset0:204 offset1:236
	v_add_u32_e32 v34, 0x3000, v66
	ds_write2_b32 v34, v46, v62 offset0:96 offset1:128
	v_add_u32_e32 v34, 0x3200, v66
	ds_write2_b32 v34, v47, v63 offset0:100 offset1:132
	v_add_u32_e32 v34, 0x3400, v66
	ds_write2_b32 v34, v48, v64 offset0:104 offset1:136
	v_add_u32_e32 v34, 0x3600, v66
	ds_write2_b32 v34, v49, v65 offset0:108 offset1:140
	v_add_u32_e32 v34, 0x4000, v66
	ds_write2_b32 v34, v2, v18 offset0:128 offset1:160
	v_add_u32_e32 v2, 0x4400, v66
	ds_write2_b32 v2, v3, v19 offset0:4 offset1:36
	ds_write2_b32 v2, v4, v20 offset0:136 offset1:168
	v_add_u32_e32 v2, 0x4800, v66
	ds_write2_b32 v2, v5, v21 offset0:12 offset1:44
	v_add_u32_e32 v2, 0x5000, v66
	ds_write2_b32 v2, v6, v22 offset0:160 offset1:192
	v_add_u32_e32 v2, 0x5400, v66
	ds_write2_b32 v2, v7, v23 offset0:36 offset1:68
	ds_write2_b32 v2, v8, v24 offset0:168 offset1:200
	v_add_u32_e32 v2, 0x5800, v66
	ds_write2_b32 v2, v9, v25 offset0:44 offset1:76
	v_add_u32_e32 v2, 0x6000, v66
	ds_write2_b32 v2, v10, v26 offset0:192 offset1:224
	v_add_u32_e32 v2, 0x6400, v66
	ds_write2_b32 v2, v11, v27 offset0:68 offset1:100
	ds_write2_b32 v2, v12, v28 offset0:200 offset1:232
	v_add_u32_e32 v2, 0x6800, v66
	ds_write2_b32 v2, v13, v29 offset0:76 offset1:108
	v_add_u32_e32 v2, 0x7200, v66
	ds_write2_b32 v2, v14, v30 offset0:96 offset1:128
	v_add_u32_e32 v2, 0x7400, v66
	ds_write2_b32 v2, v15, v31 offset0:100 offset1:132
	v_add_u32_e32 v2, 0x7600, v66
	ds_write2_b32 v2, v16, v32 offset0:104 offset1:136
	v_add_u32_e32 v2, 0x7800, v66
	ds_write2_b32 v2, v17, v33 offset0:108 offset1:140
	v_lshlrev_b32_e32 v2, 3, v1
	v_and_b32_e32 v2, 0x78, v2
	v_or_b32_e32 v4, s15, v2
	v_ashrrev_i32_e32 v5, 31, v4
	v_lshlrev_b32_e32 v2, 2, v2
	v_cmp_gt_i32_e32 vcc, s25, v4
	v_lshl_add_u64 v[4:5], v[4:5], 1, s[6:7]
	ds_write2_b32 v66, v35, v51 offset0:132 offset1:164
	s_waitcnt lgkmcnt(0)
	s_barrier
	s_branch .LBB0_1074

; template <int TM, int TN>
; DI void gemm_mainloop(const u16* __restrict__ A, long lda, const u16* __restrict__ Bt, long ldb, int K, char* smem,
;                       f32x16 (&acc)[TM][TN]) {
;     ...
;   const int nk = K / 64;
;   const int lrow = tid >> 3, lch = (tid & 7) * 8;
;   const u16* gA = A + (long)lrow * lda + lch;
;   const u16* gB = Bt + (long)lrow * ldb + lch;
;   const int soff = lrow * LD + lch;
;     ...
;   GEMM_GLOAD(0)
;   __syncthreads();
;   GEMM_SSTORE(0)
;   if (nk > 1) GEMM_GLOAD(64)
;   __syncthreads();
;   for (int kt = 0; kt < nk; kt++) {
;     const int buf = kt & 1;
;     const u16* cA = sA + buf * BM * LD + (wm * 32 * TM + r) * LD + h * 8;
;     const u16* cB = sB + buf * BN * LD + (wn * 32 * TN + r) * LD + h * 8;
;     bf16x8 af[TM], bfr[TN];
; #pragma unroll
;     for (int tm = 0; tm < TM; tm++) af[tm] = *(const bf16x8*)(cA + tm * 32 * LD);
; #pragma unroll
;     for (int tn = 0; tn < TN; tn++) bfr[tn] = *(const bf16x8*)(cB + tn * 32 * LD);
;     if (kt + 1 < nk) GEMM_SSTORE(buf ^ 1)
;     __builtin_amdgcn_sched_barrier(0);
;     __builtin_amdgcn_s_setprio(1);
; #pragma unroll
;     for (int tm = 0; tm < TM; tm++)
; #pragma unroll
;       for (int tn = 0; tn < TN; tn++) acc[tm][tn] = MFMA(af[tm], bfr[tn], acc[tm][tn]);
; #pragma unroll
;     for (int tm = 0; tm < TM; tm++) af[tm] = *(const bf16x8*)(cA + tm * 32 * LD + 16);
; #pragma unroll
;     for (int tn = 0; tn < TN; tn++) bfr[tn] = *(const bf16x8*)(cB + tn * 32 * LD + 16);
; #pragma unroll
;     for (int tm = 0; tm < TM; tm++)
; #pragma unroll
;       for (int tn = 0; tn < TN; tn++) acc[tm][tn] = MFMA(af[tm], bfr[tn], acc[tm][tn]);
;     __builtin_amdgcn_sched_group_barrier(0x8, 4, 0);
;     if (kt + 2 < nk) GEMM_GLOAD((kt + 2) * 64)
; #pragma unroll
;     for (int ks = 2; ks < 4; ks++) {
; #pragma unroll
;       for (int tm = 0; tm < TM; tm++) af[tm] = *(const bf16x8*)(cA + tm * 32 * LD + ks * 16);
; #pragma unroll
; template <class Epi>
; DI void phase_gemm128(const Sched& sc, const u16* A, long lda, const u16* Bt, long ldb, int K, int MT, int NT, int SN, char* smem, const Epi& epi) {
;     ...
;     for (int st = xg; st < nfull; st += 8) {
;       int sm = st / sng, sn = st % sng;
;       int mt = sm * SM + xi / SN, nt = sn * SN + xi % SN;
;       gemm_tile<2, 2>(A, lda, Bt, ldb, K, mt * 128, nt * 128, smem, epi);
.LBB0_1343:
	s_lshl_b32 s4, s26, 8
	s_and_b32 s27, s4, 0xfffffe00
	s_lshl_b32 s4, s26, 11
	s_add_i32 s27, s27, s15
	s_and_b32 s4, s4, 0x800
	s_add_i32 s6, s4, s16
	s_mul_i32 s4, s27, 0x880
	s_mul_hi_i32 s5, s27, 0x880
	s_add_u32 s4, s8, s4
	v_mov_b32_e32 v1, v0
	s_addc_u32 s5, s9, s5
	s_ashr_i32 s7, s6, 31
	v_lshlrev_b32_e32 v2, 3, v1
	v_ashrrev_i32_e32 v68, 3, v1
	v_and_b32_e32 v69, 56, v2
	v_mov_b64_e32 v[2:3], s[4:5]
	v_mad_i64_i32 v[2:3], s[4:5], v68, s17, v[2:3]
	v_lshlrev_b32_e32 v66, 1, v69
	v_lshl_add_u64 v[72:73], v[2:3], 0, v[66:67]
	s_mul_i32 s28, s6, 0x880
	v_add_co_u32_e32 v70, vcc, s19, v72
	s_mul_hi_i32 s29, s6, 0x880
	s_add_u32 s28, s10, s28
	v_addc_co_u32_e32 v71, vcc, 0, v73, vcc
	s_addc_u32 s29, s11, s29
	v_add_co_u32_e32 v74, vcc, s20, v72
	v_mov_b64_e32 v[2:3], s[28:29]
	s_nop 0
	v_addc_co_u32_e32 v75, vcc, 0, v73, vcc
	v_mad_i64_i32 v[18:19], s[4:5], v68, s17, v[2:3]
	v_add_co_u32_e32 v78, vcc, s21, v72
	v_lshl_add_u64 v[76:77], v[18:19], 0, v[66:67]
	s_nop 0
	v_addc_co_u32_e32 v79, vcc, 0, v73, vcc
	v_add_co_u32_e32 v80, vcc, s19, v76
	global_load_dwordx4 v[2:5], v[72:73], off
	s_nop 0
	v_addc_co_u32_e32 v81, vcc, 0, v77, vcc
	v_add_co_u32_e32 v82, vcc, s20, v76
	global_load_dwordx4 v[6:9], v[70:71], off
	s_nop 0
	v_addc_co_u32_e32 v83, vcc, 0, v77, vcc
	v_add_co_u32_e32 v84, vcc, s21, v76
	global_load_dwordx4 v[10:13], v[74:75], off
	s_nop 0
	v_addc_co_u32_e32 v85, vcc, 0, v77, vcc
	global_load_dwordx4 v[14:17], v[78:79], off
	global_load_dwordx4 v[18:21], v[76:77], off
	global_load_dwordx4 v[22:25], v[80:81], off
	global_load_dwordx4 v[26:29], v[82:83], off
	global_load_dwordx4 v[30:33], v[84:85], off
	s_barrier
	global_load_dwordx4 v[34:37], v[72:73], off offset:128
	global_load_dwordx4 v[38:41], v[70:71], off offset:128
	global_load_dwordx4 v[42:45], v[74:75], off offset:128
	global_load_dwordx4 v[46:49], v[78:79], off offset:128
	global_load_dwordx4 v[50:53], v[76:77], off offset:128
	global_load_dwordx4 v[54:57], v[80:81], off offset:128
	global_load_dwordx4 v[58:61], v[82:83], off offset:128
	global_load_dwordx4 v[62:65], v[84:85], off offset:128
	v_and_b32_e32 v66, 31, v1
	v_lshrrev_b32_e32 v86, 1, v1
	v_mul_lo_u32 v68, v68, s18
	v_and_or_b32 v87, v86, s22, v66
	v_and_b32_e32 v86, 16, v86
	v_and_b32_e32 v1, 0x5f, v1
	v_add_lshl_u32 v66, v68, v69, 1
	v_mad_u64_u32 v[68:69], s[4:5], v87, s23, v[86:87]
	v_mad_u32_u24 v1, v1, s23, v86
	v_add_u32_e32 v69, 0x9000, v66
	s_waitcnt vmcnt(15)
	ds_write_b128 v66, v[2:5]
	s_waitcnt vmcnt(14)
	ds_write_b128 v66, v[6:9] offset:4608
	s_waitcnt vmcnt(13)
	ds_write_b128 v66, v[10:13] offset:9216
	s_waitcnt vmcnt(12)
	ds_write_b128 v66, v[14:17] offset:13824
	s_waitcnt vmcnt(11)
	ds_write_b128 v66, v[18:21] offset:36864
	s_waitcnt vmcnt(10)
	ds_write_b128 v66, v[22:25] offset:41472
	s_waitcnt vmcnt(9)
	ds_write_b128 v66, v[26:29] offset:46080
	s_waitcnt vmcnt(8)
	ds_write_b128 v66, v[30:33] offset:50688
	s_waitcnt lgkmcnt(0)
	s_barrier
	ds_read_b128 v[2:5], v68
	ds_read_b128 v[18:21], v68 offset:4608
	ds_read_b128 v[6:9], v1 offset:36864
	ds_read_b128 v[22:25], v1 offset:41472
	s_waitcnt vmcnt(7)
	ds_write_b128 v66, v[34:37] offset:18432
	s_waitcnt vmcnt(6)
	ds_write_b128 v66, v[38:41] offset:23040
	s_waitcnt vmcnt(5)
	ds_write_b128 v66, v[42:45] offset:27648
	s_waitcnt vmcnt(4)
	ds_write_b128 v66, v[46:49] offset:32256
	s_waitcnt vmcnt(3)
	ds_write_b128 v66, v[50:53] offset:55296
	s_waitcnt vmcnt(2)
	ds_write_b128 v66, v[54:57] offset:59904
	s_waitcnt vmcnt(1)
	ds_write_b128 v66, v[58:61] offset:64512
	s_waitcnt vmcnt(0)
	ds_write_b128 v69, v[62:65] offset:32256
	s_setprio 1
	ds_read_b128 v[86:89], v68 offset:32
	s_waitcnt lgkmcnt(10)
	v_mfma_f32_32x32x16_bf16 v[34:49], v[2:5], v[6:9], 0
	ds_read_b128 v[90:93], v1 offset:36896
	ds_read_b128 v[94:97], v1 offset:41504
	ds_read_b128 v[98:101], v68 offset:4704
	global_load_dwordx4 v[102:105], v[70:71], off offset:256
	global_load_dwordx4 v[106:109], v[74:75], off offset:256
	global_load_dwordx4 v[110:113], v[78:79], off offset:256
	global_load_dwordx4 v[114:117], v[84:85], off offset:256
	s_waitcnt lgkmcnt(12)
	v_mfma_f32_32x32x16_bf16 v[50:65], v[2:5], v[22:25], 0
	global_load_dwordx4 v[118:121], v[82:83], off offset:256
	global_load_dwordx4 v[122:125], v[80:81], off offset:256
	global_load_dwordx4 v[140:143], v[72:73], off offset:256
	global_load_dwordx4 v[144:147], v[76:77], off offset:256
	s_waitcnt lgkmcnt(2)
	v_mfma_f32_32x32x16_bf16 v[34:49], v[86:89], v[90:93], v[34:49]
	s_waitcnt lgkmcnt(1)
	v_mfma_f32_32x32x16_bf16 v[50:65], v[86:89], v[94:97], v[50:65]
	ds_read_b128 v[86:89], v68 offset:4640
	v_mfma_f32_32x32x16_bf16 v[2:17], v[18:21], v[6:9], 0
	v_mfma_f32_32x32x16_bf16 v[18:33], v[18:21], v[22:25], 0
	s_waitcnt lgkmcnt(0)
	v_mfma_f32_32x32x16_bf16 v[2:17], v[86:89], v[90:93], v[2:17]
	ds_read_b128 v[90:93], v1 offset:36928
	v_mfma_f32_32x32x16_bf16 v[18:33], v[86:89], v[94:97], v[18:33]
	ds_read_b128 v[86:89], v68 offset:64
	ds_read_b128 v[94:97], v1 offset:41536
	s_waitcnt lgkmcnt(1)
	v_mfma_f32_32x32x16_bf16 v[34:49], v[86:89], v[90:93], v[34:49]
	s_waitcnt lgkmcnt(0)
	v_mfma_f32_32x32x16_bf16 v[50:65], v[86:89], v[94:97], v[50:65]
	ds_read_b128 v[86:89], v68 offset:4672
	s_waitcnt lgkmcnt(0)
	v_mfma_f32_32x32x16_bf16 v[2:17], v[86:89], v[90:93], v[2:17]
	ds_read_b128 v[90:93], v1 offset:36960
	v_mfma_f32_32x32x16_bf16 v[18:33], v[86:89], v[94:97], v[18:33]
	ds_read_b128 v[86:89], v68 offset:96
	ds_read_b128 v[94:97], v1 offset:41568
	s_waitcnt lgkmcnt(1)
	v_mfma_f32_32x32x16_bf16 v[34:49], v[86:89], v[90:93], v[34:49]
	s_waitcnt lgkmcnt(0)
	v_mfma_f32_32x32x16_bf16 v[50:65], v[86:89], v[94:97], v[50:65]
	v_mfma_f32_32x32x16_bf16 v[2:17], v[98:101], v[90:93], v[2:17]
	v_mfma_f32_32x32x16_bf16 v[18:33], v[98:101], v[94:97], v[18:33]
	s_setprio 0
	s_barrier
; #define MFMA(a, b, c) __builtin_amdgcn_mfma_f32_32x32x16_bf16((a), (b), (c), 0, 0, 0)
; template <int TM, int TN>
; DI void gemm_mainloop(const u16* __restrict__ A, long lda, const u16* __restrict__ Bt, long ldb, int K, char* smem,
;                       f32x16 (&acc)[TM][TN]) {
;     ...
;   for (int kt = 0; kt < nk; kt++) {
;     const int buf = kt & 1;
;     const u16* cA = sA + buf * BM * LD + (wm * 32 * TM + r) * LD + h * 8;
;     const u16* cB = sB + buf * BN * LD + (wn * 32 * TN + r) * LD + h * 8;
;     bf16x8 af[TM], bfr[TN];
; #pragma unroll
;     for (int tm = 0; tm < TM; tm++) af[tm] = *(const bf16x8*)(cA + tm * 32 * LD);
; #pragma unroll
;     for (int tn = 0; tn < TN; tn++) bfr[tn] = *(const bf16x8*)(cB + tn * 32 * LD);
;     if (kt + 1 < nk) GEMM_SSTORE(buf ^ 1)
;     __builtin_amdgcn_sched_barrier(0);
;     __builtin_amdgcn_s_setprio(1);
; #pragma unroll
;     for (int tm = 0; tm < TM; tm++)
; #pragma unroll
;       for (int tn = 0; tn < TN; tn++) acc[tm][tn] = MFMA(af[tm], bfr[tn], acc[tm][tn]);
; #pragma unroll
;     for (int tm = 0; tm < TM; tm++) af[tm] = *(const bf16x8*)(cA + tm * 32 * LD + 16);
; #pragma unroll
;     for (int tn = 0; tn < TN; tn++) bfr[tn] = *(const bf16x8*)(cB + tn * 32 * LD + 16);
; #pragma unroll
;     for (int tm = 0; tm < TM; tm++)
; #pragma unroll
;       for (int tn = 0; tn < TN; tn++) acc[tm][tn] = MFMA(af[tm], bfr[tn], acc[tm][tn]);
;     __builtin_amdgcn_sched_group_barrier(0x8, 4, 0);
;     if (kt + 2 < nk) GEMM_GLOAD((kt + 2) * 64)
; #pragma unroll
;     for (int ks = 2; ks < 4; ks++) {
; #pragma unroll
;       for (int tm = 0; tm < TM; tm++) af[tm] = *(const bf16x8*)(cA + tm * 32 * LD + ks * 16);
; #pragma unroll
;       for (int tn = 0; tn < TN; tn++) bfr[tn] = *(const bf16x8*)(cB + tn * 32 * LD + ks * 16);
; #pragma unroll
;       for (int tm = 0; tm < TM; tm++)
; #pragma unroll
;         for (int tn = 0; tn < TN; tn++) acc[tm][tn] = MFMA(af[tm], bfr[tn], acc[tm][tn]);
;     }
;     __builtin_amdgcn_s_setprio(0);
;     __syncthreads();
;   }
	ds_read_b128 v[94:97], v68 offset:18432
	ds_read_b128 v[98:101], v68 offset:23040
	ds_read_b128 v[126:129], v1 offset:55296
	ds_read_b128 v[130:133], v1 offset:59904
	s_setprio 1
	ds_read_b128 v[86:89], v68 offset:18464
	s_waitcnt lgkmcnt(2)
	v_mfma_f32_32x32x16_bf16 v[34:49], v[94:97], v[126:129], v[34:49]
	ds_read_b128 v[90:93], v1 offset:55328
	s_waitcnt lgkmcnt(2)
	v_mfma_f32_32x32x16_bf16 v[50:65], v[94:97], v[130:133], v[50:65]
	ds_read_b128 v[94:97], v1 offset:59936
	s_waitcnt lgkmcnt(1)
	v_mfma_f32_32x32x16_bf16 v[34:49], v[86:89], v[90:93], v[34:49]
	s_waitcnt lgkmcnt(0)
	v_mfma_f32_32x32x16_bf16 v[50:65], v[86:89], v[94:97], v[50:65]
	s_waitcnt vmcnt(1)
	ds_write_b128 v66, v[140:143]
	ds_write_b128 v66, v[102:105] offset:4608
	global_load_dwordx4 v[140:143], v[72:73], off offset:384
	global_load_dwordx4 v[102:105], v[70:71], off offset:384
	ds_read_b128 v[86:89], v68 offset:23072
	v_mfma_f32_32x32x16_bf16 v[2:17], v[98:101], v[126:129], v[2:17]
	v_mfma_f32_32x32x16_bf16 v[18:33], v[98:101], v[130:133], v[18:33]
	ds_read_b128 v[98:101], v68 offset:23136
	s_waitcnt lgkmcnt(1)
	v_mfma_f32_32x32x16_bf16 v[2:17], v[86:89], v[90:93], v[2:17]
	ds_read_b128 v[90:93], v1 offset:55360
	v_mfma_f32_32x32x16_bf16 v[18:33], v[86:89], v[94:97], v[18:33]
	ds_write_b128 v66, v[106:109] offset:9216
	ds_write_b128 v66, v[110:113] offset:13824
	global_load_dwordx4 v[106:109], v[74:75], off offset:384
	global_load_dwordx4 v[110:113], v[78:79], off offset:384
	ds_read_b128 v[86:89], v68 offset:18496
	ds_read_b128 v[94:97], v1 offset:59968
	s_waitcnt lgkmcnt(1)
	v_mfma_f32_32x32x16_bf16 v[34:49], v[86:89], v[90:93], v[34:49]
	s_waitcnt lgkmcnt(0)
	v_mfma_f32_32x32x16_bf16 v[50:65], v[86:89], v[94:97], v[50:65]
	ds_read_b128 v[86:89], v68 offset:23104
	s_waitcnt lgkmcnt(0)
	v_mfma_f32_32x32x16_bf16 v[2:17], v[86:89], v[90:93], v[2:17]
	ds_read_b128 v[90:93], v1 offset:55392
	v_mfma_f32_32x32x16_bf16 v[18:33], v[86:89], v[94:97], v[18:33]
	s_waitcnt vmcnt(4)
	ds_write_b128 v66, v[144:147] offset:36864
	ds_write_b128 v66, v[122:125] offset:41472
	global_load_dwordx4 v[144:147], v[76:77], off offset:384
	global_load_dwordx4 v[122:125], v[80:81], off offset:384
	ds_read_b128 v[86:89], v68 offset:18528
	ds_read_b128 v[94:97], v1 offset:60000
	s_waitcnt lgkmcnt(1)
	v_mfma_f32_32x32x16_bf16 v[34:49], v[86:89], v[90:93], v[34:49]
	s_waitcnt lgkmcnt(0)
	v_mfma_f32_32x32x16_bf16 v[50:65], v[86:89], v[94:97], v[50:65]
	v_mfma_f32_32x32x16_bf16 v[2:17], v[98:101], v[90:93], v[2:17]
	v_mfma_f32_32x32x16_bf16 v[18:33], v[98:101], v[94:97], v[18:33]
	ds_write_b128 v66, v[118:121] offset:46080
	ds_write_b128 v66, v[114:117] offset:50688
	global_load_dwordx4 v[118:121], v[82:83], off offset:384
	global_load_dwordx4 v[114:117], v[84:85], off offset:384
	s_setprio 0
	s_waitcnt lgkmcnt(0)
	s_barrier
	ds_read_b128 v[94:97], v68
	ds_read_b128 v[98:101], v68 offset:4608
	ds_read_b128 v[126:129], v1 offset:36864
	ds_read_b128 v[130:133], v1 offset:41472
	s_setprio 1
	ds_read_b128 v[86:89], v68 offset:32
	s_waitcnt lgkmcnt(2)
	v_mfma_f32_32x32x16_bf16 v[34:49], v[94:97], v[126:129], v[34:49]
	ds_read_b128 v[90:93], v1 offset:36896
	s_waitcnt lgkmcnt(2)
	v_mfma_f32_32x32x16_bf16 v[50:65], v[94:97], v[130:133], v[50:65]
	ds_read_b128 v[94:97], v1 offset:41504
	s_waitcnt lgkmcnt(1)
	v_mfma_f32_32x32x16_bf16 v[34:49], v[86:89], v[90:93], v[34:49]
	s_waitcnt lgkmcnt(0)
	v_mfma_f32_32x32x16_bf16 v[50:65], v[86:89], v[94:97], v[50:65]
	s_waitcnt vmcnt(7)
	ds_write_b128 v66, v[140:143] offset:18432
	s_waitcnt vmcnt(6)
	ds_write_b128 v66, v[102:105] offset:23040
	global_load_dwordx4 v[140:143], v[72:73], off offset:512
	global_load_dwordx4 v[102:105], v[70:71], off offset:512
	ds_read_b128 v[86:89], v68 offset:4640
	v_mfma_f32_32x32x16_bf16 v[2:17], v[98:101], v[126:129], v[2:17]
	v_mfma_f32_32x32x16_bf16 v[18:33], v[98:101], v[130:133], v[18:33]
	ds_read_b128 v[98:101], v68 offset:4704
	s_waitcnt lgkmcnt(1)
	v_mfma_f32_32x32x16_bf16 v[2:17], v[86:89], v[90:93], v[2:17]
	ds_read_b128 v[90:93], v1 offset:36928
	v_mfma_f32_32x32x16_bf16 v[18:33], v[86:89], v[94:97], v[18:33]
	s_waitcnt vmcnt(7)
	ds_write_b128 v66, v[106:109] offset:27648
	s_waitcnt vmcnt(6)
	ds_write_b128 v66, v[110:113] offset:32256
	global_load_dwordx4 v[106:109], v[74:75], off offset:512
	global_load_dwordx4 v[110:113], v[78:79], off offset:512
	ds_read_b128 v[86:89], v68 offset:64
	ds_read_b128 v[94:97], v1 offset:41536
	s_waitcnt lgkmcnt(1)
	v_mfma_f32_32x32x16_bf16 v[34:49], v[86:89], v[90:93], v[34:49]
	s_waitcnt lgkmcnt(0)
	v_mfma_f32_32x32x16_bf16 v[50:65], v[86:89], v[94:97], v[50:65]
	ds_read_b128 v[86:89], v68 offset:4672
	s_waitcnt lgkmcnt(0)
	v_mfma_f32_32x32x16_bf16 v[2:17], v[86:89], v[90:93], v[2:17]
	ds_read_b128 v[90:93], v1 offset:36960
	v_mfma_f32_32x32x16_bf16 v[18:33], v[86:89], v[94:97], v[18:33]
	s_waitcnt vmcnt(7)
	ds_write_b128 v66, v[144:147] offset:55296
	s_waitcnt vmcnt(6)
	ds_write_b128 v66, v[122:125] offset:59904
	global_load_dwordx4 v[144:147], v[76:77], off offset:512
	global_load_dwordx4 v[122:125], v[80:81], off offset:512
	ds_read_b128 v[86:89], v68 offset:96
	ds_read_b128 v[94:97], v1 offset:41568
	s_waitcnt lgkmcnt(1)
	v_mfma_f32_32x32x16_bf16 v[34:49], v[86:89], v[90:93], v[34:49]
	s_waitcnt lgkmcnt(0)
	v_mfma_f32_32x32x16_bf16 v[50:65], v[86:89], v[94:97], v[50:65]
	v_mfma_f32_32x32x16_bf16 v[2:17], v[98:101], v[90:93], v[2:17]
	v_mfma_f32_32x32x16_bf16 v[18:33], v[98:101], v[94:97], v[18:33]
	s_waitcnt vmcnt(7)
	ds_write_b128 v66, v[118:121] offset:64512
	s_waitcnt vmcnt(6)
	ds_write_b128 v69, v[114:117] offset:32256
	global_load_dwordx4 v[118:121], v[82:83], off offset:512
	global_load_dwordx4 v[114:117], v[84:85], off offset:512
	s_setprio 0
	s_waitcnt lgkmcnt(0)
	s_barrier
; #define MFMA(a, b, c) __builtin_amdgcn_mfma_f32_32x32x16_bf16((a), (b), (c), 0, 0, 0)
; template <int TM, int TN>
; DI void gemm_mainloop(const u16* __restrict__ A, long lda, const u16* __restrict__ Bt, long ldb, int K, char* smem,
;                       f32x16 (&acc)[TM][TN]) {
;     ...
;   for (int kt = 0; kt < nk; kt++) {
;     const int buf = kt & 1;
;     const u16* cA = sA + buf * BM * LD + (wm * 32 * TM + r) * LD + h * 8;
;     const u16* cB = sB + buf * BN * LD + (wn * 32 * TN + r) * LD + h * 8;
;     bf16x8 af[TM], bfr[TN];
; #pragma unroll
;     for (int tm = 0; tm < TM; tm++) af[tm] = *(const bf16x8*)(cA + tm * 32 * LD);
; #pragma unroll
;     for (int tn = 0; tn < TN; tn++) bfr[tn] = *(const bf16x8*)(cB + tn * 32 * LD);
;     if (kt + 1 < nk) GEMM_SSTORE(buf ^ 1)
;     __builtin_amdgcn_sched_barrier(0);
;     __builtin_amdgcn_s_setprio(1);
; #pragma unroll
;     for (int tm = 0; tm < TM; tm++)
; #pragma unroll
;       for (int tn = 0; tn < TN; tn++) acc[tm][tn] = MFMA(af[tm], bfr[tn], acc[tm][tn]);
; #pragma unroll
;     for (int tm = 0; tm < TM; tm++) af[tm] = *(const bf16x8*)(cA + tm * 32 * LD + 16);
; #pragma unroll
;     for (int tn = 0; tn < TN; tn++) bfr[tn] = *(const bf16x8*)(cB + tn * 32 * LD + 16);
; #pragma unroll
;     for (int tm = 0; tm < TM; tm++)
; #pragma unroll
;       for (int tn = 0; tn < TN; tn++) acc[tm][tn] = MFMA(af[tm], bfr[tn], acc[tm][tn]);
;     __builtin_amdgcn_sched_group_barrier(0x8, 4, 0);
;     if (kt + 2 < nk) GEMM_GLOAD((kt + 2) * 64)
; #pragma unroll
;     for (int ks = 2; ks < 4; ks++) {
; #pragma unroll
;       for (int tm = 0; tm < TM; tm++) af[tm] = *(const bf16x8*)(cA + tm * 32 * LD + ks * 16);
; #pragma unroll
;       for (int tn = 0; tn < TN; tn++) bfr[tn] = *(const bf16x8*)(cB + tn * 32 * LD + ks * 16);
; #pragma unroll
;       for (int tm = 0; tm < TM; tm++)
; #pragma unroll
;         for (int tn = 0; tn < TN; tn++) acc[tm][tn] = MFMA(af[tm], bfr[tn], acc[tm][tn]);
;     }
;     __builtin_amdgcn_s_setprio(0);
;     __syncthreads();
;   }
	ds_read_b128 v[94:97], v68 offset:18432
	ds_read_b128 v[98:101], v68 offset:23040
	ds_read_b128 v[126:129], v1 offset:55296
	ds_read_b128 v[130:133], v1 offset:59904
	s_setprio 1
	ds_read_b128 v[86:89], v68 offset:18464
	s_waitcnt lgkmcnt(2)
	v_mfma_f32_32x32x16_bf16 v[34:49], v[94:97], v[126:129], v[34:49]
	ds_read_b128 v[90:93], v1 offset:55328
	s_waitcnt lgkmcnt(2)
	v_mfma_f32_32x32x16_bf16 v[50:65], v[94:97], v[130:133], v[50:65]
	ds_read_b128 v[94:97], v1 offset:59936
	s_waitcnt lgkmcnt(1)
	v_mfma_f32_32x32x16_bf16 v[34:49], v[86:89], v[90:93], v[34:49]
	s_waitcnt lgkmcnt(0)
	v_mfma_f32_32x32x16_bf16 v[50:65], v[86:89], v[94:97], v[50:65]
	s_waitcnt vmcnt(7)
	ds_write_b128 v66, v[140:143]
	s_waitcnt vmcnt(6)
	ds_write_b128 v66, v[102:105] offset:4608
	global_load_dwordx4 v[140:143], v[72:73], off offset:640
	global_load_dwordx4 v[102:105], v[70:71], off offset:640
	ds_read_b128 v[86:89], v68 offset:23072
	v_mfma_f32_32x32x16_bf16 v[2:17], v[98:101], v[126:129], v[2:17]
	v_mfma_f32_32x32x16_bf16 v[18:33], v[98:101], v[130:133], v[18:33]
	ds_read_b128 v[98:101], v68 offset:23136
	s_waitcnt lgkmcnt(1)
	v_mfma_f32_32x32x16_bf16 v[2:17], v[86:89], v[90:93], v[2:17]
	ds_read_b128 v[90:93], v1 offset:55360
	v_mfma_f32_32x32x16_bf16 v[18:33], v[86:89], v[94:97], v[18:33]
	s_waitcnt vmcnt(7)
	ds_write_b128 v66, v[106:109] offset:9216
	s_waitcnt vmcnt(6)
	ds_write_b128 v66, v[110:113] offset:13824
	global_load_dwordx4 v[106:109], v[74:75], off offset:640
	global_load_dwordx4 v[110:113], v[78:79], off offset:640
	ds_read_b128 v[86:89], v68 offset:18496
	ds_read_b128 v[94:97], v1 offset:59968
	s_waitcnt lgkmcnt(1)
	v_mfma_f32_32x32x16_bf16 v[34:49], v[86:89], v[90:93], v[34:49]
	s_waitcnt lgkmcnt(0)
	v_mfma_f32_32x32x16_bf16 v[50:65], v[86:89], v[94:97], v[50:65]
	ds_read_b128 v[86:89], v68 offset:23104
	s_waitcnt lgkmcnt(0)
	v_mfma_f32_32x32x16_bf16 v[2:17], v[86:89], v[90:93], v[2:17]
	ds_read_b128 v[90:93], v1 offset:55392
	v_mfma_f32_32x32x16_bf16 v[18:33], v[86:89], v[94:97], v[18:33]
	s_waitcnt vmcnt(7)
	ds_write_b128 v66, v[144:147] offset:36864
	s_waitcnt vmcnt(6)
	ds_write_b128 v66, v[122:125] offset:41472
	global_load_dwordx4 v[144:147], v[76:77], off offset:640
	global_load_dwordx4 v[122:125], v[80:81], off offset:640
	ds_read_b128 v[86:89], v68 offset:18528
	ds_read_b128 v[94:97], v1 offset:60000
	s_waitcnt lgkmcnt(1)
	v_mfma_f32_32x32x16_bf16 v[34:49], v[86:89], v[90:93], v[34:49]
	s_waitcnt lgkmcnt(0)
	v_mfma_f32_32x32x16_bf16 v[50:65], v[86:89], v[94:97], v[50:65]
	v_mfma_f32_32x32x16_bf16 v[2:17], v[98:101], v[90:93], v[2:17]
	v_mfma_f32_32x32x16_bf16 v[18:33], v[98:101], v[94:97], v[18:33]
	s_waitcnt vmcnt(7)
	ds_write_b128 v66, v[118:121] offset:46080
	s_waitcnt vmcnt(6)
	ds_write_b128 v66, v[114:117] offset:50688
	global_load_dwordx4 v[118:121], v[82:83], off offset:640
	global_load_dwordx4 v[114:117], v[84:85], off offset:640
	s_setprio 0
	s_waitcnt lgkmcnt(0)
	s_barrier
	ds_read_b128 v[94:97], v68
	ds_read_b128 v[98:101], v68 offset:4608
	ds_read_b128 v[126:129], v1 offset:36864
	ds_read_b128 v[130:133], v1 offset:41472
	s_setprio 1
	ds_read_b128 v[86:89], v68 offset:32
	s_waitcnt lgkmcnt(2)
	v_mfma_f32_32x32x16_bf16 v[34:49], v[94:97], v[126:129], v[34:49]
	ds_read_b128 v[90:93], v1 offset:36896
	s_waitcnt lgkmcnt(2)
	v_mfma_f32_32x32x16_bf16 v[50:65], v[94:97], v[130:133], v[50:65]
	ds_read_b128 v[94:97], v1 offset:41504
	s_waitcnt lgkmcnt(1)
	v_mfma_f32_32x32x16_bf16 v[34:49], v[86:89], v[90:93], v[34:49]
	s_waitcnt lgkmcnt(0)
	v_mfma_f32_32x32x16_bf16 v[50:65], v[86:89], v[94:97], v[50:65]
	s_waitcnt vmcnt(7)
	ds_write_b128 v66, v[140:143] offset:18432
	s_waitcnt vmcnt(6)
	ds_write_b128 v66, v[102:105] offset:23040
	global_load_dwordx4 v[140:143], v[72:73], off offset:768
	global_load_dwordx4 v[102:105], v[70:71], off offset:768
	ds_read_b128 v[86:89], v68 offset:4640
	v_mfma_f32_32x32x16_bf16 v[2:17], v[98:101], v[126:129], v[2:17]
	v_mfma_f32_32x32x16_bf16 v[18:33], v[98:101], v[130:133], v[18:33]
	ds_read_b128 v[98:101], v68 offset:4704
	s_waitcnt lgkmcnt(1)
	v_mfma_f32_32x32x16_bf16 v[2:17], v[86:89], v[90:93], v[2:17]
	ds_read_b128 v[90:93], v1 offset:36928
	v_mfma_f32_32x32x16_bf16 v[18:33], v[86:89], v[94:97], v[18:33]
	s_waitcnt vmcnt(7)
	ds_write_b128 v66, v[106:109] offset:27648
	s_waitcnt vmcnt(6)
	ds_write_b128 v66, v[110:113] offset:32256
	global_load_dwordx4 v[106:109], v[74:75], off offset:768
	global_load_dwordx4 v[110:113], v[78:79], off offset:768
	ds_read_b128 v[86:89], v68 offset:64
	ds_read_b128 v[94:97], v1 offset:41536
	s_waitcnt lgkmcnt(1)
	v_mfma_f32_32x32x16_bf16 v[34:49], v[86:89], v[90:93], v[34:49]
	s_waitcnt lgkmcnt(0)
	v_mfma_f32_32x32x16_bf16 v[50:65], v[86:89], v[94:97], v[50:65]
	ds_read_b128 v[86:89], v68 offset:4672
	s_waitcnt lgkmcnt(0)
	v_mfma_f32_32x32x16_bf16 v[2:17], v[86:89], v[90:93], v[2:17]
	ds_read_b128 v[90:93], v1 offset:36960
	v_mfma_f32_32x32x16_bf16 v[18:33], v[86:89], v[94:97], v[18:33]
	s_waitcnt vmcnt(7)
	ds_write_b128 v66, v[144:147] offset:55296
	s_waitcnt vmcnt(6)
	ds_write_b128 v66, v[122:125] offset:59904
	global_load_dwordx4 v[144:147], v[76:77], off offset:768
	global_load_dwordx4 v[122:125], v[80:81], off offset:768
	ds_read_b128 v[86:89], v68 offset:96
	ds_read_b128 v[94:97], v1 offset:41568
	s_waitcnt lgkmcnt(1)
	v_mfma_f32_32x32x16_bf16 v[34:49], v[86:89], v[90:93], v[34:49]
	s_waitcnt lgkmcnt(0)
	v_mfma_f32_32x32x16_bf16 v[50:65], v[86:89], v[94:97], v[50:65]
	v_mfma_f32_32x32x16_bf16 v[2:17], v[98:101], v[90:93], v[2:17]
	v_mfma_f32_32x32x16_bf16 v[18:33], v[98:101], v[94:97], v[18:33]
	s_waitcnt vmcnt(7)
	ds_write_b128 v66, v[118:121] offset:64512
	s_waitcnt vmcnt(6)
	ds_write_b128 v69, v[114:117] offset:32256
	global_load_dwordx4 v[118:121], v[82:83], off offset:768
	global_load_dwordx4 v[114:117], v[84:85], off offset:768
	s_setprio 0
	s_waitcnt lgkmcnt(0)
	s_barrier
; #define MFMA(a, b, c) __builtin_amdgcn_mfma_f32_32x32x16_bf16((a), (b), (c), 0, 0, 0)
; template <int TM, int TN>
; DI void gemm_mainloop(const u16* __restrict__ A, long lda, const u16* __restrict__ Bt, long ldb, int K, char* smem,
;                       f32x16 (&acc)[TM][TN]) {
;     ...
;   for (int kt = 0; kt < nk; kt++) {
;     const int buf = kt & 1;
;     const u16* cA = sA + buf * BM * LD + (wm * 32 * TM + r) * LD + h * 8;
;     const u16* cB = sB + buf * BN * LD + (wn * 32 * TN + r) * LD + h * 8;
;     bf16x8 af[TM], bfr[TN];
; #pragma unroll
;     for (int tm = 0; tm < TM; tm++) af[tm] = *(const bf16x8*)(cA + tm * 32 * LD);
; #pragma unroll
;     for (int tn = 0; tn < TN; tn++) bfr[tn] = *(const bf16x8*)(cB + tn * 32 * LD);
;     if (kt + 1 < nk) GEMM_SSTORE(buf ^ 1)
;     __builtin_amdgcn_sched_barrier(0);
;     __builtin_amdgcn_s_setprio(1);
; #pragma unroll
;     for (int tm = 0; tm < TM; tm++)
; #pragma unroll
;       for (int tn = 0; tn < TN; tn++) acc[tm][tn] = MFMA(af[tm], bfr[tn], acc[tm][tn]);
; #pragma unroll
;     for (int tm = 0; tm < TM; tm++) af[tm] = *(const bf16x8*)(cA + tm * 32 * LD + 16);
; #pragma unroll
;     for (int tn = 0; tn < TN; tn++) bfr[tn] = *(const bf16x8*)(cB + tn * 32 * LD + 16);
; #pragma unroll
;     for (int tm = 0; tm < TM; tm++)
; #pragma unroll
;       for (int tn = 0; tn < TN; tn++) acc[tm][tn] = MFMA(af[tm], bfr[tn], acc[tm][tn]);
;     __builtin_amdgcn_sched_group_barrier(0x8, 4, 0);
;     if (kt + 2 < nk) GEMM_GLOAD((kt + 2) * 64)
; #pragma unroll
;     for (int ks = 2; ks < 4; ks++) {
; #pragma unroll
;       for (int tm = 0; tm < TM; tm++) af[tm] = *(const bf16x8*)(cA + tm * 32 * LD + ks * 16);
; #pragma unroll
;       for (int tn = 0; tn < TN; tn++) bfr[tn] = *(const bf16x8*)(cB + tn * 32 * LD + ks * 16);
; #pragma unroll
;       for (int tm = 0; tm < TM; tm++)
; #pragma unroll
;         for (int tn = 0; tn < TN; tn++) acc[tm][tn] = MFMA(af[tm], bfr[tn], acc[tm][tn]);
;     }
;     __builtin_amdgcn_s_setprio(0);
;     __syncthreads();
;   }
	ds_read_b128 v[94:97], v68 offset:18432
	ds_read_b128 v[98:101], v68 offset:23040
	ds_read_b128 v[126:129], v1 offset:55296
	ds_read_b128 v[130:133], v1 offset:59904
	s_setprio 1
	ds_read_b128 v[86:89], v68 offset:18464
	s_waitcnt lgkmcnt(2)
	v_mfma_f32_32x32x16_bf16 v[34:49], v[94:97], v[126:129], v[34:49]
	ds_read_b128 v[90:93], v1 offset:55328
	s_waitcnt lgkmcnt(2)
	v_mfma_f32_32x32x16_bf16 v[50:65], v[94:97], v[130:133], v[50:65]
	ds_read_b128 v[94:97], v1 offset:59936
	s_waitcnt lgkmcnt(1)
	v_mfma_f32_32x32x16_bf16 v[34:49], v[86:89], v[90:93], v[34:49]
	s_waitcnt lgkmcnt(0)
	v_mfma_f32_32x32x16_bf16 v[50:65], v[86:89], v[94:97], v[50:65]
	s_waitcnt vmcnt(7)
	ds_write_b128 v66, v[140:143]
	s_waitcnt vmcnt(6)
	ds_write_b128 v66, v[102:105] offset:4608
	global_load_dwordx4 v[140:143], v[72:73], off offset:896
	global_load_dwordx4 v[102:105], v[70:71], off offset:896
	ds_read_b128 v[86:89], v68 offset:23072
	v_mfma_f32_32x32x16_bf16 v[2:17], v[98:101], v[126:129], v[2:17]
	v_mfma_f32_32x32x16_bf16 v[18:33], v[98:101], v[130:133], v[18:33]
	ds_read_b128 v[98:101], v68 offset:23136
	s_waitcnt lgkmcnt(1)
	v_mfma_f32_32x32x16_bf16 v[2:17], v[86:89], v[90:93], v[2:17]
	ds_read_b128 v[90:93], v1 offset:55360
	v_mfma_f32_32x32x16_bf16 v[18:33], v[86:89], v[94:97], v[18:33]
	s_waitcnt vmcnt(7)
	ds_write_b128 v66, v[106:109] offset:9216
	s_waitcnt vmcnt(6)
	ds_write_b128 v66, v[110:113] offset:13824
	global_load_dwordx4 v[106:109], v[74:75], off offset:896
	global_load_dwordx4 v[110:113], v[78:79], off offset:896
	ds_read_b128 v[86:89], v68 offset:18496
	ds_read_b128 v[94:97], v1 offset:59968
	s_waitcnt lgkmcnt(1)
	v_mfma_f32_32x32x16_bf16 v[34:49], v[86:89], v[90:93], v[34:49]
	s_waitcnt lgkmcnt(0)
	v_mfma_f32_32x32x16_bf16 v[50:65], v[86:89], v[94:97], v[50:65]
	ds_read_b128 v[86:89], v68 offset:23104
	s_waitcnt lgkmcnt(0)
	v_mfma_f32_32x32x16_bf16 v[2:17], v[86:89], v[90:93], v[2:17]
	ds_read_b128 v[90:93], v1 offset:55392
	v_mfma_f32_32x32x16_bf16 v[18:33], v[86:89], v[94:97], v[18:33]
	s_waitcnt vmcnt(7)
	ds_write_b128 v66, v[144:147] offset:36864
	s_waitcnt vmcnt(6)
	ds_write_b128 v66, v[122:125] offset:41472
	global_load_dwordx4 v[144:147], v[76:77], off offset:896
	global_load_dwordx4 v[122:125], v[80:81], off offset:896
	ds_read_b128 v[86:89], v68 offset:18528
	ds_read_b128 v[94:97], v1 offset:60000
	s_waitcnt lgkmcnt(1)
	v_mfma_f32_32x32x16_bf16 v[34:49], v[86:89], v[90:93], v[34:49]
	s_waitcnt lgkmcnt(0)
	v_mfma_f32_32x32x16_bf16 v[50:65], v[86:89], v[94:97], v[50:65]
	v_mfma_f32_32x32x16_bf16 v[2:17], v[98:101], v[90:93], v[2:17]
	v_mfma_f32_32x32x16_bf16 v[18:33], v[98:101], v[94:97], v[18:33]
	s_waitcnt vmcnt(7)
	ds_write_b128 v66, v[118:121] offset:46080
	s_waitcnt vmcnt(6)
	ds_write_b128 v66, v[114:117] offset:50688
	global_load_dwordx4 v[118:121], v[82:83], off offset:896
	global_load_dwordx4 v[114:117], v[84:85], off offset:896
	s_setprio 0
	s_waitcnt lgkmcnt(0)
	s_barrier
	ds_read_b128 v[94:97], v68
	ds_read_b128 v[98:101], v68 offset:4608
	ds_read_b128 v[126:129], v1 offset:36864
	ds_read_b128 v[130:133], v1 offset:41472
	s_setprio 1
	ds_read_b128 v[86:89], v68 offset:32
	s_waitcnt lgkmcnt(2)
	v_mfma_f32_32x32x16_bf16 v[34:49], v[94:97], v[126:129], v[34:49]
	ds_read_b128 v[90:93], v1 offset:36896
	s_waitcnt lgkmcnt(2)
	v_mfma_f32_32x32x16_bf16 v[50:65], v[94:97], v[130:133], v[50:65]
	ds_read_b128 v[94:97], v1 offset:41504
	s_waitcnt lgkmcnt(1)
	v_mfma_f32_32x32x16_bf16 v[34:49], v[86:89], v[90:93], v[34:49]
	s_waitcnt lgkmcnt(0)
	v_mfma_f32_32x32x16_bf16 v[50:65], v[86:89], v[94:97], v[50:65]
	s_waitcnt vmcnt(7)
	ds_write_b128 v66, v[140:143] offset:18432
	s_waitcnt vmcnt(6)
	ds_write_b128 v66, v[102:105] offset:23040
	global_load_dwordx4 v[140:143], v[72:73], off offset:1024
	global_load_dwordx4 v[102:105], v[70:71], off offset:1024
	ds_read_b128 v[86:89], v68 offset:4640
	v_mfma_f32_32x32x16_bf16 v[2:17], v[98:101], v[126:129], v[2:17]
	v_mfma_f32_32x32x16_bf16 v[18:33], v[98:101], v[130:133], v[18:33]
	ds_read_b128 v[98:101], v68 offset:4704
	s_waitcnt lgkmcnt(1)
	v_mfma_f32_32x32x16_bf16 v[2:17], v[86:89], v[90:93], v[2:17]
	ds_read_b128 v[90:93], v1 offset:36928
	v_mfma_f32_32x32x16_bf16 v[18:33], v[86:89], v[94:97], v[18:33]
	s_waitcnt vmcnt(7)
	ds_write_b128 v66, v[106:109] offset:27648
	s_waitcnt vmcnt(6)
	ds_write_b128 v66, v[110:113] offset:32256
	global_load_dwordx4 v[106:109], v[74:75], off offset:1024
	global_load_dwordx4 v[110:113], v[78:79], off offset:1024
	ds_read_b128 v[86:89], v68 offset:64
	ds_read_b128 v[94:97], v1 offset:41536
	s_waitcnt lgkmcnt(1)
	v_mfma_f32_32x32x16_bf16 v[34:49], v[86:89], v[90:93], v[34:49]
	s_waitcnt lgkmcnt(0)
	v_mfma_f32_32x32x16_bf16 v[50:65], v[86:89], v[94:97], v[50:65]
	ds_read_b128 v[86:89], v68 offset:4672
	s_waitcnt lgkmcnt(0)
	v_mfma_f32_32x32x16_bf16 v[2:17], v[86:89], v[90:93], v[2:17]
	ds_read_b128 v[90:93], v1 offset:36960
	v_mfma_f32_32x32x16_bf16 v[18:33], v[86:89], v[94:97], v[18:33]
	s_waitcnt vmcnt(7)
	ds_write_b128 v66, v[144:147] offset:55296
	s_waitcnt vmcnt(6)
	ds_write_b128 v66, v[122:125] offset:59904
	global_load_dwordx4 v[144:147], v[76:77], off offset:1024
	global_load_dwordx4 v[122:125], v[80:81], off offset:1024
	ds_read_b128 v[86:89], v68 offset:96
	ds_read_b128 v[94:97], v1 offset:41568
	s_waitcnt lgkmcnt(1)
	v_mfma_f32_32x32x16_bf16 v[34:49], v[86:89], v[90:93], v[34:49]
	s_waitcnt lgkmcnt(0)
	v_mfma_f32_32x32x16_bf16 v[50:65], v[86:89], v[94:97], v[50:65]
	v_mfma_f32_32x32x16_bf16 v[2:17], v[98:101], v[90:93], v[2:17]
	v_mfma_f32_32x32x16_bf16 v[18:33], v[98:101], v[94:97], v[18:33]
	s_waitcnt vmcnt(7)
	ds_write_b128 v66, v[118:121] offset:64512
	s_waitcnt vmcnt(6)
	ds_write_b128 v69, v[114:117] offset:32256
	global_load_dwordx4 v[118:121], v[82:83], off offset:1024
	global_load_dwordx4 v[114:117], v[84:85], off offset:1024
	s_setprio 0
	s_waitcnt lgkmcnt(0)
	s_barrier
; #define MFMA(a, b, c) __builtin_amdgcn_mfma_f32_32x32x16_bf16((a), (b), (c), 0, 0, 0)
; template <int TM, int TN>
; DI void gemm_mainloop(const u16* __restrict__ A, long lda, const u16* __restrict__ Bt, long ldb, int K, char* smem,
;                       f32x16 (&acc)[TM][TN]) {
;     ...
;   for (int kt = 0; kt < nk; kt++) {
;     const int buf = kt & 1;
;     const u16* cA = sA + buf * BM * LD + (wm * 32 * TM + r) * LD + h * 8;
;     const u16* cB = sB + buf * BN * LD + (wn * 32 * TN + r) * LD + h * 8;
;     bf16x8 af[TM], bfr[TN];
; #pragma unroll
;     for (int tm = 0; tm < TM; tm++) af[tm] = *(const bf16x8*)(cA + tm * 32 * LD);
; #pragma unroll
;     for (int tn = 0; tn < TN; tn++) bfr[tn] = *(const bf16x8*)(cB + tn * 32 * LD);
;     if (kt + 1 < nk) GEMM_SSTORE(buf ^ 1)
;     __builtin_amdgcn_sched_barrier(0);
;     __builtin_amdgcn_s_setprio(1);
; #pragma unroll
;     for (int tm = 0; tm < TM; tm++)
; #pragma unroll
;       for (int tn = 0; tn < TN; tn++) acc[tm][tn] = MFMA(af[tm], bfr[tn], acc[tm][tn]);
; #pragma unroll
;     for (int tm = 0; tm < TM; tm++) af[tm] = *(const bf16x8*)(cA + tm * 32 * LD + 16);
; #pragma unroll
;     for (int tn = 0; tn < TN; tn++) bfr[tn] = *(const bf16x8*)(cB + tn * 32 * LD + 16);
; #pragma unroll
;     for (int tm = 0; tm < TM; tm++)
; #pragma unroll
;       for (int tn = 0; tn < TN; tn++) acc[tm][tn] = MFMA(af[tm], bfr[tn], acc[tm][tn]);
;     __builtin_amdgcn_sched_group_barrier(0x8, 4, 0);
;     if (kt + 2 < nk) GEMM_GLOAD((kt + 2) * 64)
; #pragma unroll
;     for (int ks = 2; ks < 4; ks++) {
; #pragma unroll
;       for (int tm = 0; tm < TM; tm++) af[tm] = *(const bf16x8*)(cA + tm * 32 * LD + ks * 16);
; #pragma unroll
;       for (int tn = 0; tn < TN; tn++) bfr[tn] = *(const bf16x8*)(cB + tn * 32 * LD + ks * 16);
; #pragma unroll
;       for (int tm = 0; tm < TM; tm++)
; #pragma unroll
;         for (int tn = 0; tn < TN; tn++) acc[tm][tn] = MFMA(af[tm], bfr[tn], acc[tm][tn]);
;     }
;     __builtin_amdgcn_s_setprio(0);
;     __syncthreads();
;   }
	ds_read_b128 v[94:97], v68 offset:18432
	ds_read_b128 v[98:101], v68 offset:23040
	ds_read_b128 v[126:129], v1 offset:55296
	ds_read_b128 v[130:133], v1 offset:59904
	s_setprio 1
	ds_read_b128 v[86:89], v68 offset:18464
	s_waitcnt lgkmcnt(2)
	v_mfma_f32_32x32x16_bf16 v[34:49], v[94:97], v[126:129], v[34:49]
	ds_read_b128 v[90:93], v1 offset:55328
	s_waitcnt lgkmcnt(2)
	v_mfma_f32_32x32x16_bf16 v[50:65], v[94:97], v[130:133], v[50:65]
	ds_read_b128 v[94:97], v1 offset:59936
	s_waitcnt lgkmcnt(1)
	v_mfma_f32_32x32x16_bf16 v[34:49], v[86:89], v[90:93], v[34:49]
	s_waitcnt lgkmcnt(0)
	v_mfma_f32_32x32x16_bf16 v[50:65], v[86:89], v[94:97], v[50:65]
	s_waitcnt vmcnt(7)
	ds_write_b128 v66, v[140:143]
	s_waitcnt vmcnt(6)
	ds_write_b128 v66, v[102:105] offset:4608
	global_load_dwordx4 v[140:143], v[72:73], off offset:1152
	global_load_dwordx4 v[102:105], v[70:71], off offset:1152
	ds_read_b128 v[86:89], v68 offset:23072
	v_mfma_f32_32x32x16_bf16 v[2:17], v[98:101], v[126:129], v[2:17]
	v_mfma_f32_32x32x16_bf16 v[18:33], v[98:101], v[130:133], v[18:33]
	ds_read_b128 v[98:101], v68 offset:23136
	s_waitcnt lgkmcnt(1)
	v_mfma_f32_32x32x16_bf16 v[2:17], v[86:89], v[90:93], v[2:17]
	ds_read_b128 v[90:93], v1 offset:55360
	v_mfma_f32_32x32x16_bf16 v[18:33], v[86:89], v[94:97], v[18:33]
	s_waitcnt vmcnt(7)
	ds_write_b128 v66, v[106:109] offset:9216
	s_waitcnt vmcnt(6)
	ds_write_b128 v66, v[110:113] offset:13824
	global_load_dwordx4 v[106:109], v[74:75], off offset:1152
	global_load_dwordx4 v[110:113], v[78:79], off offset:1152
	ds_read_b128 v[86:89], v68 offset:18496
	ds_read_b128 v[94:97], v1 offset:59968
	s_waitcnt lgkmcnt(1)
	v_mfma_f32_32x32x16_bf16 v[34:49], v[86:89], v[90:93], v[34:49]
	s_waitcnt lgkmcnt(0)
	v_mfma_f32_32x32x16_bf16 v[50:65], v[86:89], v[94:97], v[50:65]
	ds_read_b128 v[86:89], v68 offset:23104
	s_waitcnt lgkmcnt(0)
	v_mfma_f32_32x32x16_bf16 v[2:17], v[86:89], v[90:93], v[2:17]
	ds_read_b128 v[90:93], v1 offset:55392
	v_mfma_f32_32x32x16_bf16 v[18:33], v[86:89], v[94:97], v[18:33]
	s_waitcnt vmcnt(7)
	ds_write_b128 v66, v[144:147] offset:36864
	s_waitcnt vmcnt(6)
	ds_write_b128 v66, v[122:125] offset:41472
	global_load_dwordx4 v[144:147], v[76:77], off offset:1152
	global_load_dwordx4 v[122:125], v[80:81], off offset:1152
	ds_read_b128 v[86:89], v68 offset:18528
	ds_read_b128 v[94:97], v1 offset:60000
	s_waitcnt lgkmcnt(1)
	v_mfma_f32_32x32x16_bf16 v[34:49], v[86:89], v[90:93], v[34:49]
	s_waitcnt lgkmcnt(0)
	v_mfma_f32_32x32x16_bf16 v[50:65], v[86:89], v[94:97], v[50:65]
	v_mfma_f32_32x32x16_bf16 v[2:17], v[98:101], v[90:93], v[2:17]
	v_mfma_f32_32x32x16_bf16 v[18:33], v[98:101], v[94:97], v[18:33]
	s_waitcnt vmcnt(7)
	ds_write_b128 v66, v[118:121] offset:46080
	s_waitcnt vmcnt(6)
	ds_write_b128 v66, v[114:117] offset:50688
	global_load_dwordx4 v[118:121], v[82:83], off offset:1152
	global_load_dwordx4 v[114:117], v[84:85], off offset:1152
	s_setprio 0
	s_waitcnt lgkmcnt(0)
	s_barrier
	ds_read_b128 v[94:97], v68
	ds_read_b128 v[98:101], v68 offset:4608
	ds_read_b128 v[126:129], v1 offset:36864
	ds_read_b128 v[130:133], v1 offset:41472
	s_setprio 1
	ds_read_b128 v[86:89], v68 offset:32
	s_waitcnt lgkmcnt(2)
	v_mfma_f32_32x32x16_bf16 v[34:49], v[94:97], v[126:129], v[34:49]
	ds_read_b128 v[90:93], v1 offset:36896
	s_waitcnt lgkmcnt(2)
	v_mfma_f32_32x32x16_bf16 v[50:65], v[94:97], v[130:133], v[50:65]
	ds_read_b128 v[94:97], v1 offset:41504
	s_waitcnt lgkmcnt(1)
	v_mfma_f32_32x32x16_bf16 v[34:49], v[86:89], v[90:93], v[34:49]
	s_waitcnt lgkmcnt(0)
	v_mfma_f32_32x32x16_bf16 v[50:65], v[86:89], v[94:97], v[50:65]
	s_waitcnt vmcnt(7)
	ds_write_b128 v66, v[140:143] offset:18432
	s_waitcnt vmcnt(6)
	ds_write_b128 v66, v[102:105] offset:23040
	global_load_dwordx4 v[140:143], v[72:73], off offset:1280
	global_load_dwordx4 v[102:105], v[70:71], off offset:1280
	ds_read_b128 v[86:89], v68 offset:4640
	v_mfma_f32_32x32x16_bf16 v[2:17], v[98:101], v[126:129], v[2:17]
	v_mfma_f32_32x32x16_bf16 v[18:33], v[98:101], v[130:133], v[18:33]
	ds_read_b128 v[98:101], v68 offset:4704
	s_waitcnt lgkmcnt(1)
	v_mfma_f32_32x32x16_bf16 v[2:17], v[86:89], v[90:93], v[2:17]
	ds_read_b128 v[90:93], v1 offset:36928
	v_mfma_f32_32x32x16_bf16 v[18:33], v[86:89], v[94:97], v[18:33]
	s_waitcnt vmcnt(7)
	ds_write_b128 v66, v[106:109] offset:27648
	s_waitcnt vmcnt(6)
	ds_write_b128 v66, v[110:113] offset:32256
	global_load_dwordx4 v[106:109], v[74:75], off offset:1280
	global_load_dwordx4 v[110:113], v[78:79], off offset:1280
	ds_read_b128 v[86:89], v68 offset:64
	ds_read_b128 v[94:97], v1 offset:41536
	s_waitcnt lgkmcnt(1)
	v_mfma_f32_32x32x16_bf16 v[34:49], v[86:89], v[90:93], v[34:49]
	s_waitcnt lgkmcnt(0)
	v_mfma_f32_32x32x16_bf16 v[50:65], v[86:89], v[94:97], v[50:65]
	ds_read_b128 v[86:89], v68 offset:4672
	s_waitcnt lgkmcnt(0)
	v_mfma_f32_32x32x16_bf16 v[2:17], v[86:89], v[90:93], v[2:17]
	ds_read_b128 v[90:93], v1 offset:36960
	v_mfma_f32_32x32x16_bf16 v[18:33], v[86:89], v[94:97], v[18:33]
	s_waitcnt vmcnt(7)
	ds_write_b128 v66, v[144:147] offset:55296
	s_waitcnt vmcnt(6)
	ds_write_b128 v66, v[122:125] offset:59904
	global_load_dwordx4 v[144:147], v[76:77], off offset:1280
	global_load_dwordx4 v[122:125], v[80:81], off offset:1280
	ds_read_b128 v[86:89], v68 offset:96
	ds_read_b128 v[94:97], v1 offset:41568
	s_waitcnt lgkmcnt(1)
	v_mfma_f32_32x32x16_bf16 v[34:49], v[86:89], v[90:93], v[34:49]
	s_waitcnt lgkmcnt(0)
	v_mfma_f32_32x32x16_bf16 v[50:65], v[86:89], v[94:97], v[50:65]
	v_mfma_f32_32x32x16_bf16 v[2:17], v[98:101], v[90:93], v[2:17]
	v_mfma_f32_32x32x16_bf16 v[18:33], v[98:101], v[94:97], v[18:33]
	s_waitcnt vmcnt(7)
	ds_write_b128 v66, v[118:121] offset:64512
	s_waitcnt vmcnt(6)
	ds_write_b128 v69, v[114:117] offset:32256
	global_load_dwordx4 v[118:121], v[82:83], off offset:1280
	global_load_dwordx4 v[114:117], v[84:85], off offset:1280
	s_setprio 0
	s_waitcnt lgkmcnt(0)
	s_barrier
; #define MFMA(a, b, c) __builtin_amdgcn_mfma_f32_32x32x16_bf16((a), (b), (c), 0, 0, 0)
; template <int TM, int TN>
; DI void gemm_mainloop(const u16* __restrict__ A, long lda, const u16* __restrict__ Bt, long ldb, int K, char* smem,
;                       f32x16 (&acc)[TM][TN]) {
;     ...
;   for (int kt = 0; kt < nk; kt++) {
;     const int buf = kt & 1;
;     const u16* cA = sA + buf * BM * LD + (wm * 32 * TM + r) * LD + h * 8;
;     const u16* cB = sB + buf * BN * LD + (wn * 32 * TN + r) * LD + h * 8;
;     bf16x8 af[TM], bfr[TN];
; #pragma unroll
;     for (int tm = 0; tm < TM; tm++) af[tm] = *(const bf16x8*)(cA + tm * 32 * LD);
; #pragma unroll
;     for (int tn = 0; tn < TN; tn++) bfr[tn] = *(const bf16x8*)(cB + tn * 32 * LD);
;     if (kt + 1 < nk) GEMM_SSTORE(buf ^ 1)
;     __builtin_amdgcn_sched_barrier(0);
;     __builtin_amdgcn_s_setprio(1);
; #pragma unroll
;     for (int tm = 0; tm < TM; tm++)
; #pragma unroll
;       for (int tn = 0; tn < TN; tn++) acc[tm][tn] = MFMA(af[tm], bfr[tn], acc[tm][tn]);
; #pragma unroll
;     for (int tm = 0; tm < TM; tm++) af[tm] = *(const bf16x8*)(cA + tm * 32 * LD + 16);
; #pragma unroll
;     for (int tn = 0; tn < TN; tn++) bfr[tn] = *(const bf16x8*)(cB + tn * 32 * LD + 16);
; #pragma unroll
;     for (int tm = 0; tm < TM; tm++)
; #pragma unroll
;       for (int tn = 0; tn < TN; tn++) acc[tm][tn] = MFMA(af[tm], bfr[tn], acc[tm][tn]);
;     __builtin_amdgcn_sched_group_barrier(0x8, 4, 0);
;     if (kt + 2 < nk) GEMM_GLOAD((kt + 2) * 64)
; #pragma unroll
;     for (int ks = 2; ks < 4; ks++) {
; #pragma unroll
;       for (int tm = 0; tm < TM; tm++) af[tm] = *(const bf16x8*)(cA + tm * 32 * LD + ks * 16);
; #pragma unroll
;       for (int tn = 0; tn < TN; tn++) bfr[tn] = *(const bf16x8*)(cB + tn * 32 * LD + ks * 16);
; #pragma unroll
;       for (int tm = 0; tm < TM; tm++)
; #pragma unroll
;         for (int tn = 0; tn < TN; tn++) acc[tm][tn] = MFMA(af[tm], bfr[tn], acc[tm][tn]);
;     }
;     __builtin_amdgcn_s_setprio(0);
;     __syncthreads();
;   }
	ds_read_b128 v[94:97], v68 offset:18432
	ds_read_b128 v[98:101], v68 offset:23040
	ds_read_b128 v[126:129], v1 offset:55296
	ds_read_b128 v[130:133], v1 offset:59904
	s_setprio 1
	ds_read_b128 v[86:89], v68 offset:18464
	s_waitcnt lgkmcnt(2)
	v_mfma_f32_32x32x16_bf16 v[34:49], v[94:97], v[126:129], v[34:49]
	ds_read_b128 v[90:93], v1 offset:55328
	s_waitcnt lgkmcnt(2)
	v_mfma_f32_32x32x16_bf16 v[50:65], v[94:97], v[130:133], v[50:65]
	ds_read_b128 v[94:97], v1 offset:59936
	s_waitcnt lgkmcnt(1)
	v_mfma_f32_32x32x16_bf16 v[34:49], v[86:89], v[90:93], v[34:49]
	s_waitcnt lgkmcnt(0)
	v_mfma_f32_32x32x16_bf16 v[50:65], v[86:89], v[94:97], v[50:65]
	s_waitcnt vmcnt(7)
	ds_write_b128 v66, v[140:143]
	s_waitcnt vmcnt(6)
	ds_write_b128 v66, v[102:105] offset:4608
	global_load_dwordx4 v[140:143], v[72:73], off offset:1408
	global_load_dwordx4 v[102:105], v[70:71], off offset:1408
	ds_read_b128 v[86:89], v68 offset:23072
	v_mfma_f32_32x32x16_bf16 v[2:17], v[98:101], v[126:129], v[2:17]
	v_mfma_f32_32x32x16_bf16 v[18:33], v[98:101], v[130:133], v[18:33]
	ds_read_b128 v[98:101], v68 offset:23136
	s_waitcnt lgkmcnt(1)
	v_mfma_f32_32x32x16_bf16 v[2:17], v[86:89], v[90:93], v[2:17]
	ds_read_b128 v[90:93], v1 offset:55360
	v_mfma_f32_32x32x16_bf16 v[18:33], v[86:89], v[94:97], v[18:33]
	s_waitcnt vmcnt(7)
	ds_write_b128 v66, v[106:109] offset:9216
	s_waitcnt vmcnt(6)
	ds_write_b128 v66, v[110:113] offset:13824
	global_load_dwordx4 v[106:109], v[74:75], off offset:1408
	global_load_dwordx4 v[110:113], v[78:79], off offset:1408
	ds_read_b128 v[86:89], v68 offset:18496
	ds_read_b128 v[94:97], v1 offset:59968
	s_waitcnt lgkmcnt(1)
	v_mfma_f32_32x32x16_bf16 v[34:49], v[86:89], v[90:93], v[34:49]
	s_waitcnt lgkmcnt(0)
	v_mfma_f32_32x32x16_bf16 v[50:65], v[86:89], v[94:97], v[50:65]
	ds_read_b128 v[86:89], v68 offset:23104
	s_waitcnt lgkmcnt(0)
	v_mfma_f32_32x32x16_bf16 v[2:17], v[86:89], v[90:93], v[2:17]
	ds_read_b128 v[90:93], v1 offset:55392
	v_mfma_f32_32x32x16_bf16 v[18:33], v[86:89], v[94:97], v[18:33]
	s_waitcnt vmcnt(7)
	ds_write_b128 v66, v[144:147] offset:36864
	s_waitcnt vmcnt(6)
	ds_write_b128 v66, v[122:125] offset:41472
	global_load_dwordx4 v[144:147], v[76:77], off offset:1408
	global_load_dwordx4 v[122:125], v[80:81], off offset:1408
	ds_read_b128 v[86:89], v68 offset:18528
	ds_read_b128 v[94:97], v1 offset:60000
	s_waitcnt lgkmcnt(1)
	v_mfma_f32_32x32x16_bf16 v[34:49], v[86:89], v[90:93], v[34:49]
	s_waitcnt lgkmcnt(0)
	v_mfma_f32_32x32x16_bf16 v[50:65], v[86:89], v[94:97], v[50:65]
	v_mfma_f32_32x32x16_bf16 v[2:17], v[98:101], v[90:93], v[2:17]
	v_mfma_f32_32x32x16_bf16 v[18:33], v[98:101], v[94:97], v[18:33]
	s_waitcnt vmcnt(7)
	ds_write_b128 v66, v[118:121] offset:46080
	s_waitcnt vmcnt(6)
	ds_write_b128 v66, v[114:117] offset:50688
	global_load_dwordx4 v[118:121], v[82:83], off offset:1408
	global_load_dwordx4 v[114:117], v[84:85], off offset:1408
	s_setprio 0
	s_waitcnt lgkmcnt(0)
	s_barrier
	ds_read_b128 v[94:97], v68
	ds_read_b128 v[98:101], v68 offset:4608
	ds_read_b128 v[126:129], v1 offset:36864
	ds_read_b128 v[130:133], v1 offset:41472
	s_setprio 1
	ds_read_b128 v[86:89], v68 offset:32
	s_waitcnt lgkmcnt(2)
	v_mfma_f32_32x32x16_bf16 v[34:49], v[94:97], v[126:129], v[34:49]
	ds_read_b128 v[90:93], v1 offset:36896
	s_waitcnt lgkmcnt(2)
	v_mfma_f32_32x32x16_bf16 v[50:65], v[94:97], v[130:133], v[50:65]
	ds_read_b128 v[94:97], v1 offset:41504
	s_waitcnt lgkmcnt(1)
	v_mfma_f32_32x32x16_bf16 v[34:49], v[86:89], v[90:93], v[34:49]
	s_waitcnt lgkmcnt(0)
	v_mfma_f32_32x32x16_bf16 v[50:65], v[86:89], v[94:97], v[50:65]
	s_waitcnt vmcnt(7)
	ds_write_b128 v66, v[140:143] offset:18432
	s_waitcnt vmcnt(6)
	ds_write_b128 v66, v[102:105] offset:23040
	global_load_dwordx4 v[140:143], v[72:73], off offset:1536
	global_load_dwordx4 v[102:105], v[70:71], off offset:1536
	ds_read_b128 v[86:89], v68 offset:4640
	v_mfma_f32_32x32x16_bf16 v[2:17], v[98:101], v[126:129], v[2:17]
	v_mfma_f32_32x32x16_bf16 v[18:33], v[98:101], v[130:133], v[18:33]
	ds_read_b128 v[98:101], v68 offset:4704
	s_waitcnt lgkmcnt(1)
	v_mfma_f32_32x32x16_bf16 v[2:17], v[86:89], v[90:93], v[2:17]
	ds_read_b128 v[90:93], v1 offset:36928
	v_mfma_f32_32x32x16_bf16 v[18:33], v[86:89], v[94:97], v[18:33]
	s_waitcnt vmcnt(7)
	ds_write_b128 v66, v[106:109] offset:27648
	s_waitcnt vmcnt(6)
	ds_write_b128 v66, v[110:113] offset:32256
	global_load_dwordx4 v[106:109], v[74:75], off offset:1536
	global_load_dwordx4 v[110:113], v[78:79], off offset:1536
	ds_read_b128 v[86:89], v68 offset:64
	ds_read_b128 v[94:97], v1 offset:41536
	s_waitcnt lgkmcnt(1)
	v_mfma_f32_32x32x16_bf16 v[34:49], v[86:89], v[90:93], v[34:49]
	s_waitcnt lgkmcnt(0)
	v_mfma_f32_32x32x16_bf16 v[50:65], v[86:89], v[94:97], v[50:65]
	ds_read_b128 v[86:89], v68 offset:4672
	s_waitcnt lgkmcnt(0)
	v_mfma_f32_32x32x16_bf16 v[2:17], v[86:89], v[90:93], v[2:17]
	ds_read_b128 v[90:93], v1 offset:36960
	v_mfma_f32_32x32x16_bf16 v[18:33], v[86:89], v[94:97], v[18:33]
	s_waitcnt vmcnt(7)
	ds_write_b128 v66, v[144:147] offset:55296
	s_waitcnt vmcnt(6)
	ds_write_b128 v66, v[122:125] offset:59904
	global_load_dwordx4 v[144:147], v[76:77], off offset:1536
	global_load_dwordx4 v[122:125], v[80:81], off offset:1536
	ds_read_b128 v[86:89], v68 offset:96
	ds_read_b128 v[94:97], v1 offset:41568
	s_waitcnt lgkmcnt(1)
	v_mfma_f32_32x32x16_bf16 v[34:49], v[86:89], v[90:93], v[34:49]
	s_waitcnt lgkmcnt(0)
	v_mfma_f32_32x32x16_bf16 v[50:65], v[86:89], v[94:97], v[50:65]
	v_mfma_f32_32x32x16_bf16 v[2:17], v[98:101], v[90:93], v[2:17]
	v_mfma_f32_32x32x16_bf16 v[18:33], v[98:101], v[94:97], v[18:33]
	s_waitcnt vmcnt(7)
	ds_write_b128 v66, v[118:121] offset:64512
	s_waitcnt vmcnt(6)
	ds_write_b128 v69, v[114:117] offset:32256
	global_load_dwordx4 v[118:121], v[82:83], off offset:1536
	global_load_dwordx4 v[114:117], v[84:85], off offset:1536
	s_setprio 0
	s_waitcnt lgkmcnt(0)
	s_barrier
; #define MFMA(a, b, c) __builtin_amdgcn_mfma_f32_32x32x16_bf16((a), (b), (c), 0, 0, 0)
; template <int TM, int TN>
; DI void gemm_mainloop(const u16* __restrict__ A, long lda, const u16* __restrict__ Bt, long ldb, int K, char* smem,
;                       f32x16 (&acc)[TM][TN]) {
;     ...
;   for (int kt = 0; kt < nk; kt++) {
;     const int buf = kt & 1;
;     const u16* cA = sA + buf * BM * LD + (wm * 32 * TM + r) * LD + h * 8;
;     const u16* cB = sB + buf * BN * LD + (wn * 32 * TN + r) * LD + h * 8;
;     bf16x8 af[TM], bfr[TN];
; #pragma unroll
;     for (int tm = 0; tm < TM; tm++) af[tm] = *(const bf16x8*)(cA + tm * 32 * LD);
; #pragma unroll
;     for (int tn = 0; tn < TN; tn++) bfr[tn] = *(const bf16x8*)(cB + tn * 32 * LD);
;     if (kt + 1 < nk) GEMM_SSTORE(buf ^ 1)
;     __builtin_amdgcn_sched_barrier(0);
;     __builtin_amdgcn_s_setprio(1);
; #pragma unroll
;     for (int tm = 0; tm < TM; tm++)
; #pragma unroll
;       for (int tn = 0; tn < TN; tn++) acc[tm][tn] = MFMA(af[tm], bfr[tn], acc[tm][tn]);
; #pragma unroll
;     for (int tm = 0; tm < TM; tm++) af[tm] = *(const bf16x8*)(cA + tm * 32 * LD + 16);
; #pragma unroll
;     for (int tn = 0; tn < TN; tn++) bfr[tn] = *(const bf16x8*)(cB + tn * 32 * LD + 16);
; #pragma unroll
;     for (int tm = 0; tm < TM; tm++)
; #pragma unroll
;       for (int tn = 0; tn < TN; tn++) acc[tm][tn] = MFMA(af[tm], bfr[tn], acc[tm][tn]);
;     __builtin_amdgcn_sched_group_barrier(0x8, 4, 0);
;     if (kt + 2 < nk) GEMM_GLOAD((kt + 2) * 64)
; #pragma unroll
;     for (int ks = 2; ks < 4; ks++) {
; #pragma unroll
;       for (int tm = 0; tm < TM; tm++) af[tm] = *(const bf16x8*)(cA + tm * 32 * LD + ks * 16);
; #pragma unroll
;       for (int tn = 0; tn < TN; tn++) bfr[tn] = *(const bf16x8*)(cB + tn * 32 * LD + ks * 16);
; #pragma unroll
;       for (int tm = 0; tm < TM; tm++)
; #pragma unroll
;         for (int tn = 0; tn < TN; tn++) acc[tm][tn] = MFMA(af[tm], bfr[tn], acc[tm][tn]);
;     }
;     __builtin_amdgcn_s_setprio(0);
;     __syncthreads();
;   }
	ds_read_b128 v[94:97], v68 offset:18432
	ds_read_b128 v[98:101], v68 offset:23040
	ds_read_b128 v[126:129], v1 offset:55296
	ds_read_b128 v[130:133], v1 offset:59904
	s_setprio 1
	ds_read_b128 v[86:89], v68 offset:18464
	s_waitcnt lgkmcnt(2)
	v_mfma_f32_32x32x16_bf16 v[34:49], v[94:97], v[126:129], v[34:49]
	ds_read_b128 v[90:93], v1 offset:55328
	s_waitcnt lgkmcnt(2)
	v_mfma_f32_32x32x16_bf16 v[50:65], v[94:97], v[130:133], v[50:65]
	ds_read_b128 v[94:97], v1 offset:59936
	s_waitcnt lgkmcnt(1)
	v_mfma_f32_32x32x16_bf16 v[34:49], v[86:89], v[90:93], v[34:49]
	s_waitcnt lgkmcnt(0)
	v_mfma_f32_32x32x16_bf16 v[50:65], v[86:89], v[94:97], v[50:65]
	s_waitcnt vmcnt(7)
	ds_write_b128 v66, v[140:143]
	s_waitcnt vmcnt(6)
	ds_write_b128 v66, v[102:105] offset:4608
	global_load_dwordx4 v[140:143], v[72:73], off offset:1664
	global_load_dwordx4 v[102:105], v[70:71], off offset:1664
	ds_read_b128 v[86:89], v68 offset:23072
	v_mfma_f32_32x32x16_bf16 v[2:17], v[98:101], v[126:129], v[2:17]
	v_mfma_f32_32x32x16_bf16 v[18:33], v[98:101], v[130:133], v[18:33]
	ds_read_b128 v[98:101], v68 offset:23136
	s_waitcnt lgkmcnt(1)
	v_mfma_f32_32x32x16_bf16 v[2:17], v[86:89], v[90:93], v[2:17]
	ds_read_b128 v[90:93], v1 offset:55360
	v_mfma_f32_32x32x16_bf16 v[18:33], v[86:89], v[94:97], v[18:33]
	s_waitcnt vmcnt(7)
	ds_write_b128 v66, v[106:109] offset:9216
	s_waitcnt vmcnt(6)
	ds_write_b128 v66, v[110:113] offset:13824
	global_load_dwordx4 v[106:109], v[74:75], off offset:1664
	global_load_dwordx4 v[110:113], v[78:79], off offset:1664
	ds_read_b128 v[86:89], v68 offset:18496
	ds_read_b128 v[94:97], v1 offset:59968
	s_waitcnt lgkmcnt(1)
	v_mfma_f32_32x32x16_bf16 v[34:49], v[86:89], v[90:93], v[34:49]
	s_waitcnt lgkmcnt(0)
	v_mfma_f32_32x32x16_bf16 v[50:65], v[86:89], v[94:97], v[50:65]
	ds_read_b128 v[86:89], v68 offset:23104
	s_waitcnt lgkmcnt(0)
	v_mfma_f32_32x32x16_bf16 v[2:17], v[86:89], v[90:93], v[2:17]
	ds_read_b128 v[90:93], v1 offset:55392
	v_mfma_f32_32x32x16_bf16 v[18:33], v[86:89], v[94:97], v[18:33]
	s_waitcnt vmcnt(7)
	ds_write_b128 v66, v[144:147] offset:36864
	s_waitcnt vmcnt(6)
	ds_write_b128 v66, v[122:125] offset:41472
	global_load_dwordx4 v[144:147], v[76:77], off offset:1664
	global_load_dwordx4 v[122:125], v[80:81], off offset:1664
	ds_read_b128 v[86:89], v68 offset:18528
	ds_read_b128 v[94:97], v1 offset:60000
	s_waitcnt lgkmcnt(1)
	v_mfma_f32_32x32x16_bf16 v[34:49], v[86:89], v[90:93], v[34:49]
	s_waitcnt lgkmcnt(0)
	v_mfma_f32_32x32x16_bf16 v[50:65], v[86:89], v[94:97], v[50:65]
	v_mfma_f32_32x32x16_bf16 v[2:17], v[98:101], v[90:93], v[2:17]
	v_mfma_f32_32x32x16_bf16 v[18:33], v[98:101], v[94:97], v[18:33]
	s_waitcnt vmcnt(7)
	ds_write_b128 v66, v[118:121] offset:46080
	s_waitcnt vmcnt(6)
	ds_write_b128 v66, v[114:117] offset:50688
	global_load_dwordx4 v[118:121], v[82:83], off offset:1664
	global_load_dwordx4 v[114:117], v[84:85], off offset:1664
	s_setprio 0
	s_waitcnt lgkmcnt(0)
	s_barrier
	ds_read_b128 v[94:97], v68
	ds_read_b128 v[98:101], v68 offset:4608
	ds_read_b128 v[126:129], v1 offset:36864
	ds_read_b128 v[130:133], v1 offset:41472
	s_setprio 1
	ds_read_b128 v[86:89], v68 offset:32
	s_waitcnt lgkmcnt(2)
	v_mfma_f32_32x32x16_bf16 v[34:49], v[94:97], v[126:129], v[34:49]
	ds_read_b128 v[90:93], v1 offset:36896
	s_waitcnt lgkmcnt(2)
	v_mfma_f32_32x32x16_bf16 v[50:65], v[94:97], v[130:133], v[50:65]
	ds_read_b128 v[94:97], v1 offset:41504
	s_waitcnt lgkmcnt(1)
	v_mfma_f32_32x32x16_bf16 v[34:49], v[86:89], v[90:93], v[34:49]
	s_waitcnt lgkmcnt(0)
	v_mfma_f32_32x32x16_bf16 v[50:65], v[86:89], v[94:97], v[50:65]
	s_waitcnt vmcnt(7)
	ds_write_b128 v66, v[140:143] offset:18432
	s_waitcnt vmcnt(6)
	ds_write_b128 v66, v[102:105] offset:23040
	global_load_dwordx4 v[140:143], v[72:73], off offset:1792
	global_load_dwordx4 v[102:105], v[70:71], off offset:1792
	ds_read_b128 v[86:89], v68 offset:4640
	v_mfma_f32_32x32x16_bf16 v[2:17], v[98:101], v[126:129], v[2:17]
	v_mfma_f32_32x32x16_bf16 v[18:33], v[98:101], v[130:133], v[18:33]
	ds_read_b128 v[98:101], v68 offset:4704
	s_waitcnt lgkmcnt(1)
	v_mfma_f32_32x32x16_bf16 v[2:17], v[86:89], v[90:93], v[2:17]
	ds_read_b128 v[90:93], v1 offset:36928
	v_mfma_f32_32x32x16_bf16 v[18:33], v[86:89], v[94:97], v[18:33]
	s_waitcnt vmcnt(7)
	ds_write_b128 v66, v[106:109] offset:27648
	s_waitcnt vmcnt(6)
	ds_write_b128 v66, v[110:113] offset:32256
	global_load_dwordx4 v[106:109], v[74:75], off offset:1792
	global_load_dwordx4 v[110:113], v[78:79], off offset:1792
	ds_read_b128 v[86:89], v68 offset:64
	ds_read_b128 v[94:97], v1 offset:41536
	s_waitcnt lgkmcnt(1)
	v_mfma_f32_32x32x16_bf16 v[34:49], v[86:89], v[90:93], v[34:49]
	s_waitcnt lgkmcnt(0)
	v_mfma_f32_32x32x16_bf16 v[50:65], v[86:89], v[94:97], v[50:65]
	ds_read_b128 v[86:89], v68 offset:4672
	s_waitcnt lgkmcnt(0)
	v_mfma_f32_32x32x16_bf16 v[2:17], v[86:89], v[90:93], v[2:17]
	ds_read_b128 v[90:93], v1 offset:36960
	v_mfma_f32_32x32x16_bf16 v[18:33], v[86:89], v[94:97], v[18:33]
	s_waitcnt vmcnt(7)
	ds_write_b128 v66, v[144:147] offset:55296
	s_waitcnt vmcnt(6)
	ds_write_b128 v66, v[122:125] offset:59904
	global_load_dwordx4 v[144:147], v[76:77], off offset:1792
	global_load_dwordx4 v[122:125], v[80:81], off offset:1792
	ds_read_b128 v[86:89], v68 offset:96
	ds_read_b128 v[94:97], v1 offset:41568
	s_waitcnt lgkmcnt(1)
	v_mfma_f32_32x32x16_bf16 v[34:49], v[86:89], v[90:93], v[34:49]
	s_waitcnt lgkmcnt(0)
	v_mfma_f32_32x32x16_bf16 v[50:65], v[86:89], v[94:97], v[50:65]
	v_mfma_f32_32x32x16_bf16 v[2:17], v[98:101], v[90:93], v[2:17]
	v_mfma_f32_32x32x16_bf16 v[18:33], v[98:101], v[94:97], v[18:33]
	s_waitcnt vmcnt(7)
	ds_write_b128 v66, v[118:121] offset:64512
	s_waitcnt vmcnt(6)
	ds_write_b128 v69, v[114:117] offset:32256
	global_load_dwordx4 v[118:121], v[82:83], off offset:1792
	global_load_dwordx4 v[114:117], v[84:85], off offset:1792
	s_setprio 0
	s_waitcnt lgkmcnt(0)
	s_barrier
; #define MFMA(a, b, c) __builtin_amdgcn_mfma_f32_32x32x16_bf16((a), (b), (c), 0, 0, 0)
; template <int TM, int TN>
; DI void gemm_mainloop(const u16* __restrict__ A, long lda, const u16* __restrict__ Bt, long ldb, int K, char* smem,
;                       f32x16 (&acc)[TM][TN]) {
;     ...
;   for (int kt = 0; kt < nk; kt++) {
;     const int buf = kt & 1;
;     const u16* cA = sA + buf * BM * LD + (wm * 32 * TM + r) * LD + h * 8;
;     const u16* cB = sB + buf * BN * LD + (wn * 32 * TN + r) * LD + h * 8;
;     bf16x8 af[TM], bfr[TN];
; #pragma unroll
;     for (int tm = 0; tm < TM; tm++) af[tm] = *(const bf16x8*)(cA + tm * 32 * LD);
; #pragma unroll
;     for (int tn = 0; tn < TN; tn++) bfr[tn] = *(const bf16x8*)(cB + tn * 32 * LD);
;     if (kt + 1 < nk) GEMM_SSTORE(buf ^ 1)
;     __builtin_amdgcn_sched_barrier(0);
;     __builtin_amdgcn_s_setprio(1);
; #pragma unroll
;     for (int tm = 0; tm < TM; tm++)
; #pragma unroll
;       for (int tn = 0; tn < TN; tn++) acc[tm][tn] = MFMA(af[tm], bfr[tn], acc[tm][tn]);
; #pragma unroll
;     for (int tm = 0; tm < TM; tm++) af[tm] = *(const bf16x8*)(cA + tm * 32 * LD + 16);
; #pragma unroll
;     for (int tn = 0; tn < TN; tn++) bfr[tn] = *(const bf16x8*)(cB + tn * 32 * LD + 16);
; #pragma unroll
;     for (int tm = 0; tm < TM; tm++)
; #pragma unroll
;       for (int tn = 0; tn < TN; tn++) acc[tm][tn] = MFMA(af[tm], bfr[tn], acc[tm][tn]);
;     __builtin_amdgcn_sched_group_barrier(0x8, 4, 0);
;     if (kt + 2 < nk) GEMM_GLOAD((kt + 2) * 64)
; #pragma unroll
;     for (int ks = 2; ks < 4; ks++) {
; #pragma unroll
;       for (int tm = 0; tm < TM; tm++) af[tm] = *(const bf16x8*)(cA + tm * 32 * LD + ks * 16);
; #pragma unroll
;       for (int tn = 0; tn < TN; tn++) bfr[tn] = *(const bf16x8*)(cB + tn * 32 * LD + ks * 16);
; #pragma unroll
;       for (int tm = 0; tm < TM; tm++)
; #pragma unroll
;         for (int tn = 0; tn < TN; tn++) acc[tm][tn] = MFMA(af[tm], bfr[tn], acc[tm][tn]);
;     }
;     __builtin_amdgcn_s_setprio(0);
;     __syncthreads();
;   }
	ds_read_b128 v[94:97], v68 offset:18432
	ds_read_b128 v[98:101], v68 offset:23040
	ds_read_b128 v[126:129], v1 offset:55296
	ds_read_b128 v[130:133], v1 offset:59904
	s_setprio 1
	ds_read_b128 v[86:89], v68 offset:18464
	s_waitcnt lgkmcnt(2)
	v_mfma_f32_32x32x16_bf16 v[34:49], v[94:97], v[126:129], v[34:49]
	ds_read_b128 v[90:93], v1 offset:55328
	s_waitcnt lgkmcnt(2)
	v_mfma_f32_32x32x16_bf16 v[50:65], v[94:97], v[130:133], v[50:65]
	ds_read_b128 v[94:97], v1 offset:59936
	s_waitcnt lgkmcnt(1)
	v_mfma_f32_32x32x16_bf16 v[34:49], v[86:89], v[90:93], v[34:49]
	s_waitcnt lgkmcnt(0)
	v_mfma_f32_32x32x16_bf16 v[50:65], v[86:89], v[94:97], v[50:65]
	s_waitcnt vmcnt(7)
	ds_write_b128 v66, v[140:143]
	s_waitcnt vmcnt(6)
	ds_write_b128 v66, v[102:105] offset:4608
	global_load_dwordx4 v[140:143], v[72:73], off offset:1920
	global_load_dwordx4 v[102:105], v[70:71], off offset:1920
	ds_read_b128 v[86:89], v68 offset:23072
	v_mfma_f32_32x32x16_bf16 v[2:17], v[98:101], v[126:129], v[2:17]
	v_mfma_f32_32x32x16_bf16 v[18:33], v[98:101], v[130:133], v[18:33]
	ds_read_b128 v[98:101], v68 offset:23136
	s_waitcnt lgkmcnt(1)
	v_mfma_f32_32x32x16_bf16 v[2:17], v[86:89], v[90:93], v[2:17]
	ds_read_b128 v[90:93], v1 offset:55360
	v_mfma_f32_32x32x16_bf16 v[18:33], v[86:89], v[94:97], v[18:33]
	s_waitcnt vmcnt(7)
	ds_write_b128 v66, v[106:109] offset:9216
	s_waitcnt vmcnt(6)
	ds_write_b128 v66, v[110:113] offset:13824
	global_load_dwordx4 v[106:109], v[74:75], off offset:1920
	global_load_dwordx4 v[110:113], v[78:79], off offset:1920
	ds_read_b128 v[86:89], v68 offset:18496
	ds_read_b128 v[94:97], v1 offset:59968
	s_waitcnt lgkmcnt(1)
	v_mfma_f32_32x32x16_bf16 v[34:49], v[86:89], v[90:93], v[34:49]
	s_waitcnt lgkmcnt(0)
	v_mfma_f32_32x32x16_bf16 v[50:65], v[86:89], v[94:97], v[50:65]
	ds_read_b128 v[86:89], v68 offset:23104
	s_waitcnt lgkmcnt(0)
	v_mfma_f32_32x32x16_bf16 v[2:17], v[86:89], v[90:93], v[2:17]
	ds_read_b128 v[90:93], v1 offset:55392
	v_mfma_f32_32x32x16_bf16 v[18:33], v[86:89], v[94:97], v[18:33]
	s_waitcnt vmcnt(7)
	ds_write_b128 v66, v[144:147] offset:36864
	s_waitcnt vmcnt(6)
	ds_write_b128 v66, v[122:125] offset:41472
	global_load_dwordx4 v[144:147], v[76:77], off offset:1920
	global_load_dwordx4 v[122:125], v[80:81], off offset:1920
	ds_read_b128 v[86:89], v68 offset:18528
	ds_read_b128 v[94:97], v1 offset:60000
	s_waitcnt lgkmcnt(1)
	v_mfma_f32_32x32x16_bf16 v[34:49], v[86:89], v[90:93], v[34:49]
	s_waitcnt lgkmcnt(0)
	v_mfma_f32_32x32x16_bf16 v[50:65], v[86:89], v[94:97], v[50:65]
	s_nop 0
	v_mfma_f32_32x32x16_bf16 v[2:17], v[98:101], v[90:93], v[2:17]
	v_mfma_f32_32x32x16_bf16 v[18:33], v[98:101], v[94:97], v[18:33]
	s_waitcnt vmcnt(7)
	ds_write_b128 v66, v[118:121] offset:46080
	s_waitcnt vmcnt(6)
	ds_write_b128 v66, v[114:117] offset:50688
	global_load_dwordx4 v[118:121], v[82:83], off offset:1920
	global_load_dwordx4 v[114:117], v[84:85], off offset:1920
	s_setprio 0
	s_waitcnt lgkmcnt(0)
	s_barrier
	ds_read_b128 v[74:77], v68
	ds_read_b128 v[78:81], v68 offset:4608
	ds_read_b128 v[82:85], v1 offset:36864
	ds_read_b128 v[90:93], v1 offset:41472
	s_setprio 1
	ds_read_b128 v[70:73], v68 offset:32
	s_waitcnt lgkmcnt(2)
	v_mfma_f32_32x32x16_bf16 v[34:49], v[74:77], v[82:85], v[34:49]
	s_waitcnt lgkmcnt(1)
	v_mfma_f32_32x32x16_bf16 v[50:65], v[74:77], v[90:93], v[50:65]
	ds_read_b128 v[74:77], v1 offset:36896
	v_mfma_f32_32x32x16_bf16 v[2:17], v[78:81], v[82:85], v[2:17]
	v_mfma_f32_32x32x16_bf16 v[18:33], v[78:81], v[90:93], v[18:33]
	s_waitcnt vmcnt(7)
	ds_write_b128 v66, v[140:143] offset:18432
	s_waitcnt vmcnt(6)
	ds_write_b128 v66, v[102:105] offset:23040
	ds_read_b128 v[78:81], v1 offset:41504
	s_waitcnt lgkmcnt(3)
	v_mfma_f32_32x32x16_bf16 v[34:49], v[70:73], v[74:77], v[34:49]
	s_waitcnt lgkmcnt(0)
	v_mfma_f32_32x32x16_bf16 v[50:65], v[70:73], v[78:81], v[50:65]
	ds_read_b128 v[70:73], v68 offset:4640
	s_waitcnt lgkmcnt(0)
	v_mfma_f32_32x32x16_bf16 v[2:17], v[70:73], v[74:77], v[2:17]
	ds_read_b128 v[74:77], v1 offset:36928
	v_mfma_f32_32x32x16_bf16 v[18:33], v[70:73], v[78:81], v[18:33]
	s_waitcnt vmcnt(5)
	ds_write_b128 v66, v[106:109] offset:27648
	s_waitcnt vmcnt(4)
	ds_write_b128 v66, v[110:113] offset:32256
	ds_read_b128 v[70:73], v68 offset:64
	ds_read_b128 v[78:81], v1 offset:41536
	s_waitcnt lgkmcnt(1)
	v_mfma_f32_32x32x16_bf16 v[34:49], v[70:73], v[74:77], v[34:49]
	s_waitcnt lgkmcnt(0)
	v_mfma_f32_32x32x16_bf16 v[50:65], v[70:73], v[78:81], v[50:65]
	ds_read_b128 v[70:73], v68 offset:4672
	s_waitcnt lgkmcnt(0)
	v_mfma_f32_32x32x16_bf16 v[2:17], v[70:73], v[74:77], v[2:17]
	ds_read_b128 v[74:77], v1 offset:36960
	v_mfma_f32_32x32x16_bf16 v[18:33], v[70:73], v[78:81], v[18:33]
	s_waitcnt vmcnt(3)
	ds_write_b128 v66, v[144:147] offset:55296
	s_waitcnt vmcnt(2)
	ds_write_b128 v66, v[122:125] offset:59904
	ds_read_b128 v[70:73], v68 offset:96
	ds_read_b128 v[78:81], v1 offset:41568
	s_waitcnt lgkmcnt(1)
	v_mfma_f32_32x32x16_bf16 v[34:49], v[70:73], v[74:77], v[34:49]
	s_waitcnt lgkmcnt(0)
	v_mfma_f32_32x32x16_bf16 v[50:65], v[70:73], v[78:81], v[50:65]
	ds_read_b128 v[70:73], v68 offset:4704
	s_waitcnt lgkmcnt(0)
	v_mfma_f32_32x32x16_bf16 v[2:17], v[70:73], v[74:77], v[2:17]
	v_mfma_f32_32x32x16_bf16 v[18:33], v[70:73], v[78:81], v[18:33]
	s_waitcnt vmcnt(1)
	ds_write_b128 v66, v[118:121] offset:64512
	s_waitcnt vmcnt(0)
	ds_write_b128 v69, v[114:117] offset:32256
	s_setprio 0
	s_waitcnt lgkmcnt(0)
	s_barrier
; template <int TM, int TN>
; DI void gemm_mainloop(const u16* __restrict__ A, long lda, const u16* __restrict__ Bt, long ldb, int K, char* smem,
;                       f32x16 (&acc)[TM][TN]) {
;     ...
;     for (int tm = 0; tm < TM; tm++)
; #pragma unroll
;       for (int tn = 0; tn < TN; tn++) acc[tm][tn] = MFMA(af[tm], bfr[tn], acc[tm][tn]);
;     __builtin_amdgcn_sched_group_barrier(0x8, 4, 0);
;     if (kt + 2 < nk) GEMM_GLOAD((kt + 2) * 64)
; #pragma unroll
;     for (int ks = 2; ks < 4; ks++) {
; #pragma unroll
;       for (int tm = 0; tm < TM; tm++) af[tm] = *(const bf16x8*)(cA + tm * 32 * LD + ks * 16);
; #pragma unroll
;       for (int tn = 0; tn < TN; tn++) bfr[tn] = *(const bf16x8*)(cB + tn * 32 * LD + ks * 16);
; #pragma unroll
;       for (int tm = 0; tm < TM; tm++)
; #pragma unroll
;         for (int tn = 0; tn < TN; tn++) acc[tm][tn] = MFMA(af[tm], bfr[tn], acc[tm][tn]);
;     }
;     __builtin_amdgcn_s_setprio(0);
;     __syncthreads();
; template <int TM, int TN, class Epi>
; DI void gemm_tile(const u16* A, long lda, const u16* Bt, long ldb, int K, int m0, int n0, char* smem, const Epi& epi) {
;     ...
; #pragma unroll
;   for (int tm = 0; tm < TM; tm++)
; #pragma unroll
;     for (int tn = 0; tn < TN; tn++)
; #pragma unroll
;       for (int i = 0; i < 16; i++)
;         Ct[(wm * 32 * TM + tm * 32 + crow(i, h)) * LDC + wn * 32 * TN + tn * 32 + r] = acc[tm][tn][i];
;   __syncthreads();
;   epi(Ct, LDC, m0, n0, tid, BM);
;   __syncthreads();
;   (void)BM;
; }
;   DI void operator()(const float* Ct, int ldc, int m0, int n0, int tid, int bm) const {
; #pragma unroll 4
;     for (int it = 0; it < bm / 16; it++) {
;       int id = tid + 256 * it; int row = id >> 4, c8 = (id & 15) * 8;
;       int n = n0 + c8;
;       if (n < nmax) {
;         const float* c = Ct + row * ldc + c8;
;         float4 a = *(const float4*)c, b = *(const float4*)(c + 4);
;         uint4 v; v.x = pk2(a.x, a.y); v.y = pk2(a.z, a.w); v.z = pk2(b.x, b.y); v.w = pk2(b.z, b.w);
;         *(uint4*)(out + (long)(m0 + row) * ldo + n) = v;
;         if (gates != nullptr && n == 1952) {
;           float* g = gates + (long)(m0 + row) * 8;
;           *(float4*)g = a; *(float4*)(g + 4) = b;
;         }
;       }
;     }
;   }
;   DI void operator()(const float* Ct, int ldc, int m0, int n0, int tid, int bm) const {
; #pragma unroll 4
;     for (int it = 0; it < bm / 16; it++) {
	ds_read_b128 v[70:73], v68 offset:18432
	ds_read_b128 v[74:77], v68 offset:23040
	ds_read_b128 v[78:81], v1 offset:55296
	ds_read_b128 v[82:85], v1 offset:59904
	s_setprio 1
	s_waitcnt lgkmcnt(1)
	v_mfma_f32_32x32x16_bf16 v[34:49], v[70:73], v[78:81], v[34:49]
	s_waitcnt lgkmcnt(0)
	v_mfma_f32_32x32x16_bf16 v[50:65], v[70:73], v[82:85], v[50:65]
	ds_read_b128 v[70:73], v68 offset:18464
	v_mfma_f32_32x32x16_bf16 v[2:17], v[74:77], v[78:81], v[2:17]
	ds_read_b128 v[78:81], v1 offset:59936
	v_mfma_f32_32x32x16_bf16 v[18:33], v[74:77], v[82:85], v[18:33]
	ds_read_b128 v[74:77], v1 offset:55328
	s_waitcnt lgkmcnt(0)
	v_mfma_f32_32x32x16_bf16 v[34:49], v[70:73], v[74:77], v[34:49]
	v_mfma_f32_32x32x16_bf16 v[50:65], v[70:73], v[78:81], v[50:65]
	ds_read_b128 v[70:73], v68 offset:23072
	s_waitcnt lgkmcnt(0)
	v_mfma_f32_32x32x16_bf16 v[2:17], v[70:73], v[74:77], v[2:17]
	ds_read_b128 v[74:77], v1 offset:55360
	v_mfma_f32_32x32x16_bf16 v[18:33], v[70:73], v[78:81], v[18:33]
	ds_read_b128 v[70:73], v68 offset:18496
	ds_read_b128 v[78:81], v1 offset:59968
	s_waitcnt lgkmcnt(1)
	v_mfma_f32_32x32x16_bf16 v[34:49], v[70:73], v[74:77], v[34:49]
	s_waitcnt lgkmcnt(0)
	v_mfma_f32_32x32x16_bf16 v[50:65], v[70:73], v[78:81], v[50:65]
	ds_read_b128 v[70:73], v68 offset:23104
	s_waitcnt lgkmcnt(0)
	v_mfma_f32_32x32x16_bf16 v[2:17], v[70:73], v[74:77], v[2:17]
	ds_read_b128 v[74:77], v1 offset:55392
	v_mfma_f32_32x32x16_bf16 v[18:33], v[70:73], v[78:81], v[18:33]
	ds_read_b128 v[70:73], v68 offset:18528
	ds_read_b128 v[78:81], v1 offset:60000
	s_waitcnt lgkmcnt(1)
	v_mfma_f32_32x32x16_bf16 v[34:49], v[70:73], v[74:77], v[34:49]
	s_waitcnt lgkmcnt(0)
	v_mfma_f32_32x32x16_bf16 v[50:65], v[70:73], v[78:81], v[50:65]
	ds_read_b128 v[68:71], v68 offset:23136
	s_waitcnt lgkmcnt(0)
	v_mfma_f32_32x32x16_bf16 v[2:17], v[68:71], v[74:77], v[2:17]
	v_mfma_f32_32x32x16_bf16 v[18:33], v[68:71], v[78:81], v[18:33]
	s_setprio 0
	v_mov_b32_e32 v1, v0
	s_barrier
	s_lshl_b64 s[4:5], s[6:7], 1
	v_lshrrev_b32_e32 v66, 1, v1
	v_and_b32_e32 v66, 0xfffffc0, v66
	v_lshrrev_b32_e32 v68, 3, v1
	v_and_or_b32 v66, v68, 4, v66
	v_and_b32_e32 v68, 0x5f, v1
	v_mul_lo_u32 v66, v66, s24
	v_lshl_add_u32 v66, v68, 2, v66
	ds_write2_b32 v66, v34, v50 offset1:32
	v_add_u32_e32 v34, 0x400, v66
	ds_write2_b32 v34, v36, v52 offset0:8 offset1:40
	ds_write2_b32 v34, v37, v53 offset0:140 offset1:172
	v_add_u32_e32 v34, 0x1000, v66
	ds_write2_b32 v34, v38, v54 offset0:32 offset1:64
	ds_write2_b32 v34, v39, v55 offset0:164 offset1:196
	v_add_u32_e32 v34, 0x1400, v66
	ds_write2_b32 v34, v40, v56 offset0:40 offset1:72
	ds_write2_b32 v34, v41, v57 offset0:172 offset1:204
	v_add_u32_e32 v34, 0x2000, v66
	ds_write2_b32 v34, v42, v58 offset0:64 offset1:96
	ds_write2_b32 v34, v43, v59 offset0:196 offset1:228
	v_add_u32_e32 v34, 0x2400, v66
	ds_write2_b32 v34, v44, v60 offset0:72 offset1:104
	ds_write2_b32 v34, v45, v61 offset0:204 offset1:236
	v_add_u32_e32 v34, 0x3000, v66
	ds_write2_b32 v34, v46, v62 offset0:96 offset1:128
	v_add_u32_e32 v34, 0x3200, v66
	ds_write2_b32 v34, v47, v63 offset0:100 offset1:132
	v_add_u32_e32 v34, 0x3400, v66
	ds_write2_b32 v34, v48, v64 offset0:104 offset1:136
	v_add_u32_e32 v34, 0x3600, v66
	ds_write2_b32 v34, v49, v65 offset0:108 offset1:140
	v_add_u32_e32 v34, 0x4000, v66
	ds_write2_b32 v34, v2, v18 offset0:128 offset1:160
	v_add_u32_e32 v2, 0x4400, v66
	ds_write2_b32 v2, v3, v19 offset0:4 offset1:36
	ds_write2_b32 v2, v4, v20 offset0:136 offset1:168
	v_add_u32_e32 v2, 0x4800, v66
	ds_write2_b32 v2, v5, v21 offset0:12 offset1:44
	v_add_u32_e32 v2, 0x5000, v66
	ds_write2_b32 v2, v6, v22 offset0:160 offset1:192
	v_add_u32_e32 v2, 0x5400, v66
	ds_write2_b32 v2, v7, v23 offset0:36 offset1:68
	ds_write2_b32 v2, v8, v24 offset0:168 offset1:200
	v_add_u32_e32 v2, 0x5800, v66
	ds_write2_b32 v2, v9, v25 offset0:44 offset1:76
	v_add_u32_e32 v2, 0x6000, v66
	ds_write2_b32 v2, v10, v26 offset0:192 offset1:224
	v_add_u32_e32 v2, 0x6400, v66
	ds_write2_b32 v2, v11, v27 offset0:68 offset1:100
	ds_write2_b32 v2, v12, v28 offset0:200 offset1:232
	v_add_u32_e32 v2, 0x6800, v66
	ds_write2_b32 v2, v13, v29 offset0:76 offset1:108
	v_add_u32_e32 v2, 0x7200, v66
	ds_write2_b32 v2, v14, v30 offset0:96 offset1:128
	v_add_u32_e32 v2, 0x7400, v66
	ds_write2_b32 v2, v15, v31 offset0:100 offset1:132
	v_add_u32_e32 v2, 0x7600, v66
	ds_write2_b32 v2, v16, v32 offset0:104 offset1:136
	v_add_u32_e32 v2, 0x7800, v66
	ds_write2_b32 v2, v17, v33 offset0:108 offset1:140
	v_lshlrev_b32_e32 v2, 3, v1
	v_and_b32_e32 v3, 0x78, v2
	s_add_u32 s4, s3, s4
	ds_write2_b32 v66, v35, v51 offset0:132 offset1:164
	s_addc_u32 s5, s14, s5
	v_lshlrev_b32_e32 v66, 1, v3
	v_lshlrev_b32_e32 v2, 2, v3
	v_lshl_add_u64 v[4:5], s[4:5], 0, v[66:67]
	s_mov_b32 s4, 0
	s_waitcnt lgkmcnt(0)
	s_barrier

; template <int TM, int TN>
; DI void gemm_mainloop(const u16* __restrict__ A, long lda, const u16* __restrict__ Bt, long ldb, int K, char* smem,
;                       f32x16 (&acc)[TM][TN]) {
;     ...
;   const int nk = K / 64;
;   const int lrow = tid >> 3, lch = (tid & 7) * 8;
;   const u16* gA = A + (long)lrow * lda + lch;
;   const u16* gB = Bt + (long)lrow * ldb + lch;
;   const int soff = lrow * LD + lch;
;     ...
;   GEMM_GLOAD(0)
;   __syncthreads();
;   GEMM_SSTORE(0)
;   if (nk > 1) GEMM_GLOAD(64)
;   __syncthreads();
;   for (int kt = 0; kt < nk; kt++) {
;     const int buf = kt & 1;
;     const u16* cA = sA + buf * BM * LD + (wm * 32 * TM + r) * LD + h * 8;
;     const u16* cB = sB + buf * BN * LD + (wn * 32 * TN + r) * LD + h * 8;
;     bf16x8 af[TM], bfr[TN];
; #pragma unroll
;     for (int tm = 0; tm < TM; tm++) af[tm] = *(const bf16x8*)(cA + tm * 32 * LD);
; #pragma unroll
;     for (int tn = 0; tn < TN; tn++) bfr[tn] = *(const bf16x8*)(cB + tn * 32 * LD);
;     if (kt + 1 < nk) GEMM_SSTORE(buf ^ 1)
;     __builtin_amdgcn_sched_barrier(0);
;     __builtin_amdgcn_s_setprio(1);
; #pragma unroll
;     for (int tm = 0; tm < TM; tm++)
; #pragma unroll
;       for (int tn = 0; tn < TN; tn++) acc[tm][tn] = MFMA(af[tm], bfr[tn], acc[tm][tn]);
; #pragma unroll
;     for (int tm = 0; tm < TM; tm++) af[tm] = *(const bf16x8*)(cA + tm * 32 * LD + 16);
; #pragma unroll
;     for (int tn = 0; tn < TN; tn++) bfr[tn] = *(const bf16x8*)(cB + tn * 32 * LD + 16);
; #pragma unroll
;     for (int tm = 0; tm < TM; tm++)
; #pragma unroll
;       for (int tn = 0; tn < TN; tn++) acc[tm][tn] = MFMA(af[tm], bfr[tn], acc[tm][tn]);
;     __builtin_amdgcn_sched_group_barrier(0x8, 4, 0);
;     if (kt + 2 < nk) GEMM_GLOAD((kt + 2) * 64)
; #pragma unroll
;     for (int ks = 2; ks < 4; ks++) {
; #pragma unroll
;       for (int tm = 0; tm < TM; tm++) af[tm] = *(const bf16x8*)(cA + tm * 32 * LD + ks * 16);
; #pragma unroll
; template <class Epi>
; DI void phase_gemm128(const Sched& sc, const u16* A, long lda, const u16* Bt, long ldb, int K, int MT, int NT, int SN, char* smem, const Epi& epi) {
;     ...
;     for (int st = xg; st < nfull; st += 8) {
;       int sm = st / sng, sn = st % sng;
;       int mt = sm * SM + xi / SN, nt = sn * SN + xi % SN;
;       gemm_tile<2, 2>(A, lda, Bt, ldb, K, mt * 128, nt * 128, smem, epi);
.LBB0_1553:
	s_mul_hi_u32 s4, s38, 0xcccccccd
	s_lshr_b32 s4, s4, 2
	s_mul_i32 s5, s4, 5
	s_sub_i32 s5, s38, s5
	s_lshl_b32 s39, s4, 11
	s_add_i32 s39, s39, s21
	s_lshl_b32 s6, s5, 9
	s_add_i32 s6, s6, s22
	s_mul_i32 s4, s39, 0x880
	s_mul_hi_i32 s5, s39, 0x880
	s_add_u32 s4, s8, s4
	v_mov_b32_e32 v1, v0
	s_addc_u32 s5, s9, s5
	s_mul_i32 s7, s6, 0x880
	v_lshlrev_b32_e32 v2, 3, v1
	v_ashrrev_i32_e32 v68, 3, v1
	v_and_b32_e32 v69, 56, v2
	v_mov_b64_e32 v[2:3], s[4:5]
	v_mad_i64_i32 v[2:3], s[4:5], v68, s23, v[2:3]
	v_lshlrev_b32_e32 v66, 1, v69
	v_lshl_add_u64 v[72:73], v[2:3], 0, v[66:67]
	s_ashr_i32 s17, s7, 31
	v_add_co_u32_e32 v70, vcc, s25, v72
	s_add_u32 s16, s3, s7
	s_nop 0
	v_addc_co_u32_e32 v71, vcc, 0, v73, vcc
	s_addc_u32 s17, s20, s17
	v_add_co_u32_e32 v74, vcc, s26, v72
	v_mov_b64_e32 v[2:3], s[16:17]
	s_nop 0
	v_addc_co_u32_e32 v75, vcc, 0, v73, vcc
	v_mad_i64_i32 v[18:19], s[4:5], v68, s23, v[2:3]
	v_add_co_u32_e32 v76, vcc, s27, v72
	v_lshl_add_u64 v[78:79], v[18:19], 0, v[66:67]
	s_nop 0
	v_addc_co_u32_e32 v77, vcc, 0, v73, vcc
	v_add_co_u32_e32 v80, vcc, s25, v78
	global_load_dwordx4 v[2:5], v[72:73], off
	s_nop 0
	v_addc_co_u32_e32 v81, vcc, 0, v79, vcc
	v_add_co_u32_e32 v82, vcc, s26, v78
	global_load_dwordx4 v[6:9], v[70:71], off
	s_nop 0
	v_addc_co_u32_e32 v83, vcc, 0, v79, vcc
	v_add_co_u32_e32 v84, vcc, s27, v78
	global_load_dwordx4 v[10:13], v[74:75], off
	s_nop 0
	v_addc_co_u32_e32 v85, vcc, 0, v79, vcc
	global_load_dwordx4 v[14:17], v[76:77], off
	global_load_dwordx4 v[18:21], v[78:79], off
	global_load_dwordx4 v[22:25], v[80:81], off
	global_load_dwordx4 v[26:29], v[82:83], off
	global_load_dwordx4 v[30:33], v[84:85], off
	s_barrier
	global_load_dwordx4 v[34:37], v[72:73], off offset:128
	global_load_dwordx4 v[38:41], v[70:71], off offset:128
	global_load_dwordx4 v[42:45], v[74:75], off offset:128
	global_load_dwordx4 v[46:49], v[76:77], off offset:128
	global_load_dwordx4 v[50:53], v[78:79], off offset:128
	global_load_dwordx4 v[54:57], v[80:81], off offset:128
	global_load_dwordx4 v[58:61], v[82:83], off offset:128
	global_load_dwordx4 v[62:65], v[84:85], off offset:128
	v_and_b32_e32 v66, 31, v1
	v_lshrrev_b32_e32 v86, 1, v1
	v_and_b32_e32 v1, 0x5f, v1
	v_mul_lo_u32 v68, v68, s24
	v_and_or_b32 v87, v86, s28, v66
	v_and_b32_e32 v86, 16, v86
	v_add_lshl_u32 v66, v68, v69, 1
	v_mad_u64_u32 v[68:69], s[4:5], v87, s29, v[86:87]
	v_mad_u32_u24 v1, v1, s29, v86
	v_add_u32_e32 v69, 0x9000, v66
	s_waitcnt vmcnt(15)
	ds_write_b128 v66, v[2:5]
	s_waitcnt vmcnt(14)
	ds_write_b128 v66, v[6:9] offset:4608
	s_waitcnt vmcnt(13)
	ds_write_b128 v66, v[10:13] offset:9216
	s_waitcnt vmcnt(12)
	ds_write_b128 v66, v[14:17] offset:13824
	s_waitcnt vmcnt(11)
	ds_write_b128 v66, v[18:21] offset:36864
	s_waitcnt vmcnt(10)
	ds_write_b128 v66, v[22:25] offset:41472
	s_waitcnt vmcnt(9)
	ds_write_b128 v66, v[26:29] offset:46080
	s_waitcnt vmcnt(8)
	ds_write_b128 v66, v[30:33] offset:50688
	s_waitcnt lgkmcnt(0)
	s_barrier
	ds_read_b128 v[2:5], v68
	ds_read_b128 v[18:21], v68 offset:4608
	ds_read_b128 v[6:9], v1 offset:36864
	ds_read_b128 v[22:25], v1 offset:41472
	s_waitcnt vmcnt(7)
	ds_write_b128 v66, v[34:37] offset:18432
	s_waitcnt vmcnt(6)
	ds_write_b128 v66, v[38:41] offset:23040
	s_waitcnt vmcnt(5)
	ds_write_b128 v66, v[42:45] offset:27648
	s_waitcnt vmcnt(4)
	ds_write_b128 v66, v[46:49] offset:32256
	s_waitcnt vmcnt(3)
	ds_write_b128 v66, v[50:53] offset:55296
	s_waitcnt vmcnt(2)
	ds_write_b128 v66, v[54:57] offset:59904
	s_waitcnt vmcnt(1)
	ds_write_b128 v66, v[58:61] offset:64512
	s_waitcnt vmcnt(0)
	ds_write_b128 v69, v[62:65] offset:32256
	s_setprio 1
	ds_read_b128 v[86:89], v68 offset:32
	s_waitcnt lgkmcnt(10)
	v_mfma_f32_32x32x16_bf16 v[34:49], v[2:5], v[6:9], 0
	ds_read_b128 v[90:93], v1 offset:36896
	ds_read_b128 v[94:97], v1 offset:41504
	ds_read_b128 v[98:101], v68 offset:4704
	global_load_dwordx4 v[102:105], v[70:71], off offset:256
	global_load_dwordx4 v[106:109], v[74:75], off offset:256
	global_load_dwordx4 v[110:113], v[76:77], off offset:256
	global_load_dwordx4 v[114:117], v[84:85], off offset:256
	s_waitcnt lgkmcnt(12)
	v_mfma_f32_32x32x16_bf16 v[50:65], v[2:5], v[22:25], 0
	global_load_dwordx4 v[118:121], v[82:83], off offset:256
	global_load_dwordx4 v[122:125], v[80:81], off offset:256
	global_load_dwordx4 v[140:143], v[72:73], off offset:256
	global_load_dwordx4 v[144:147], v[78:79], off offset:256
	s_waitcnt lgkmcnt(2)
	v_mfma_f32_32x32x16_bf16 v[34:49], v[86:89], v[90:93], v[34:49]
	s_waitcnt lgkmcnt(1)
	v_mfma_f32_32x32x16_bf16 v[50:65], v[86:89], v[94:97], v[50:65]
	ds_read_b128 v[86:89], v68 offset:4640
	v_mfma_f32_32x32x16_bf16 v[2:17], v[18:21], v[6:9], 0
	v_mfma_f32_32x32x16_bf16 v[18:33], v[18:21], v[22:25], 0
	s_waitcnt lgkmcnt(0)
	v_mfma_f32_32x32x16_bf16 v[2:17], v[86:89], v[90:93], v[2:17]
	ds_read_b128 v[90:93], v1 offset:36928
	v_mfma_f32_32x32x16_bf16 v[18:33], v[86:89], v[94:97], v[18:33]
	ds_read_b128 v[86:89], v68 offset:64
	ds_read_b128 v[94:97], v1 offset:41536
	s_waitcnt lgkmcnt(1)
	v_mfma_f32_32x32x16_bf16 v[34:49], v[86:89], v[90:93], v[34:49]
	s_waitcnt lgkmcnt(0)
	v_mfma_f32_32x32x16_bf16 v[50:65], v[86:89], v[94:97], v[50:65]
	ds_read_b128 v[86:89], v68 offset:4672
	s_waitcnt lgkmcnt(0)
	v_mfma_f32_32x32x16_bf16 v[2:17], v[86:89], v[90:93], v[2:17]
	ds_read_b128 v[90:93], v1 offset:36960
	v_mfma_f32_32x32x16_bf16 v[18:33], v[86:89], v[94:97], v[18:33]
	ds_read_b128 v[86:89], v68 offset:96
	ds_read_b128 v[94:97], v1 offset:41568
	s_waitcnt lgkmcnt(1)
	v_mfma_f32_32x32x16_bf16 v[34:49], v[86:89], v[90:93], v[34:49]
	s_waitcnt lgkmcnt(0)
	v_mfma_f32_32x32x16_bf16 v[50:65], v[86:89], v[94:97], v[50:65]
	v_mfma_f32_32x32x16_bf16 v[2:17], v[98:101], v[90:93], v[2:17]
	v_mfma_f32_32x32x16_bf16 v[18:33], v[98:101], v[94:97], v[18:33]
	s_setprio 0
	s_barrier
; #define MFMA(a, b, c) __builtin_amdgcn_mfma_f32_32x32x16_bf16((a), (b), (c), 0, 0, 0)
; template <int TM, int TN>
; DI void gemm_mainloop(const u16* __restrict__ A, long lda, const u16* __restrict__ Bt, long ldb, int K, char* smem,
;                       f32x16 (&acc)[TM][TN]) {
;     ...
;   GEMM_GLOAD(0)
;   __syncthreads();
;   GEMM_SSTORE(0)
;   if (nk > 1) GEMM_GLOAD(64)
;   __syncthreads();
;   for (int kt = 0; kt < nk; kt++) {
;     const int buf = kt & 1;
;     const u16* cA = sA + buf * BM * LD + (wm * 32 * TM + r) * LD + h * 8;
;     const u16* cB = sB + buf * BN * LD + (wn * 32 * TN + r) * LD + h * 8;
;     bf16x8 af[TM], bfr[TN];
; #pragma unroll
;     for (int tm = 0; tm < TM; tm++) af[tm] = *(const bf16x8*)(cA + tm * 32 * LD);
; #pragma unroll
;     for (int tn = 0; tn < TN; tn++) bfr[tn] = *(const bf16x8*)(cB + tn * 32 * LD);
;     if (kt + 1 < nk) GEMM_SSTORE(buf ^ 1)
;     __builtin_amdgcn_sched_barrier(0);
;     __builtin_amdgcn_s_setprio(1);
; #pragma unroll
;     for (int tm = 0; tm < TM; tm++)
; #pragma unroll
;       for (int tn = 0; tn < TN; tn++) acc[tm][tn] = MFMA(af[tm], bfr[tn], acc[tm][tn]);
; #pragma unroll
;     for (int tm = 0; tm < TM; tm++) af[tm] = *(const bf16x8*)(cA + tm * 32 * LD + 16);
; #pragma unroll
;     for (int tn = 0; tn < TN; tn++) bfr[tn] = *(const bf16x8*)(cB + tn * 32 * LD + 16);
; #pragma unroll
;     for (int tm = 0; tm < TM; tm++)
; #pragma unroll
;       for (int tn = 0; tn < TN; tn++) acc[tm][tn] = MFMA(af[tm], bfr[tn], acc[tm][tn]);
;     __builtin_amdgcn_sched_group_barrier(0x8, 4, 0);
;     if (kt + 2 < nk) GEMM_GLOAD((kt + 2) * 64)
; #pragma unroll
;     for (int ks = 2; ks < 4; ks++) {
; #pragma unroll
;       for (int tm = 0; tm < TM; tm++) af[tm] = *(const bf16x8*)(cA + tm * 32 * LD + ks * 16);
; #pragma unroll
;       for (int tn = 0; tn < TN; tn++) bfr[tn] = *(const bf16x8*)(cB + tn * 32 * LD + ks * 16);
; #pragma unroll
;       for (int tm = 0; tm < TM; tm++)
; #pragma unroll
;         for (int tn = 0; tn < TN; tn++) acc[tm][tn] = MFMA(af[tm], bfr[tn], acc[tm][tn]);
;     }
;     __builtin_amdgcn_s_setprio(0);
;     __syncthreads();
;   }
	ds_read_b128 v[94:97], v68 offset:18432
	ds_read_b128 v[98:101], v68 offset:23040
	ds_read_b128 v[126:129], v1 offset:55296
	ds_read_b128 v[130:133], v1 offset:59904
	s_setprio 1
	ds_read_b128 v[86:89], v68 offset:18464
	s_waitcnt lgkmcnt(2)
	v_mfma_f32_32x32x16_bf16 v[34:49], v[94:97], v[126:129], v[34:49]
	ds_read_b128 v[90:93], v1 offset:55328
	s_waitcnt lgkmcnt(2)
	v_mfma_f32_32x32x16_bf16 v[50:65], v[94:97], v[130:133], v[50:65]
	ds_read_b128 v[94:97], v1 offset:59936
	s_waitcnt lgkmcnt(1)
	v_mfma_f32_32x32x16_bf16 v[34:49], v[86:89], v[90:93], v[34:49]
	s_waitcnt lgkmcnt(0)
	v_mfma_f32_32x32x16_bf16 v[50:65], v[86:89], v[94:97], v[50:65]
	s_waitcnt vmcnt(1)
	ds_write_b128 v66, v[140:143]
	ds_write_b128 v66, v[102:105] offset:4608
	global_load_dwordx4 v[140:143], v[72:73], off offset:384
	global_load_dwordx4 v[102:105], v[70:71], off offset:384
	ds_read_b128 v[86:89], v68 offset:23072
	v_mfma_f32_32x32x16_bf16 v[2:17], v[98:101], v[126:129], v[2:17]
	v_mfma_f32_32x32x16_bf16 v[18:33], v[98:101], v[130:133], v[18:33]
	ds_read_b128 v[98:101], v68 offset:23136
	s_waitcnt lgkmcnt(1)
	v_mfma_f32_32x32x16_bf16 v[2:17], v[86:89], v[90:93], v[2:17]
	ds_read_b128 v[90:93], v1 offset:55360
	v_mfma_f32_32x32x16_bf16 v[18:33], v[86:89], v[94:97], v[18:33]
	ds_write_b128 v66, v[106:109] offset:9216
	ds_write_b128 v66, v[110:113] offset:13824
	global_load_dwordx4 v[106:109], v[74:75], off offset:384
	global_load_dwordx4 v[110:113], v[76:77], off offset:384
	ds_read_b128 v[86:89], v68 offset:18496
	ds_read_b128 v[94:97], v1 offset:59968
	s_waitcnt lgkmcnt(1)
	v_mfma_f32_32x32x16_bf16 v[34:49], v[86:89], v[90:93], v[34:49]
	s_waitcnt lgkmcnt(0)
	v_mfma_f32_32x32x16_bf16 v[50:65], v[86:89], v[94:97], v[50:65]
	ds_read_b128 v[86:89], v68 offset:23104
	s_waitcnt lgkmcnt(0)
	v_mfma_f32_32x32x16_bf16 v[2:17], v[86:89], v[90:93], v[2:17]
	ds_read_b128 v[90:93], v1 offset:55392
	v_mfma_f32_32x32x16_bf16 v[18:33], v[86:89], v[94:97], v[18:33]
	s_waitcnt vmcnt(4)
	ds_write_b128 v66, v[144:147] offset:36864
	ds_write_b128 v66, v[122:125] offset:41472
	global_load_dwordx4 v[144:147], v[78:79], off offset:384
	global_load_dwordx4 v[122:125], v[80:81], off offset:384
	ds_read_b128 v[86:89], v68 offset:18528
	ds_read_b128 v[94:97], v1 offset:60000
	s_waitcnt lgkmcnt(1)
	v_mfma_f32_32x32x16_bf16 v[34:49], v[86:89], v[90:93], v[34:49]
	s_waitcnt lgkmcnt(0)
	v_mfma_f32_32x32x16_bf16 v[50:65], v[86:89], v[94:97], v[50:65]
	v_mfma_f32_32x32x16_bf16 v[2:17], v[98:101], v[90:93], v[2:17]
	v_mfma_f32_32x32x16_bf16 v[18:33], v[98:101], v[94:97], v[18:33]
	ds_write_b128 v66, v[118:121] offset:46080
	ds_write_b128 v66, v[114:117] offset:50688
	global_load_dwordx4 v[118:121], v[82:83], off offset:384
	global_load_dwordx4 v[114:117], v[84:85], off offset:384
	s_setprio 0
	s_waitcnt lgkmcnt(0)
	s_barrier
	ds_read_b128 v[94:97], v68
	ds_read_b128 v[98:101], v68 offset:4608
	ds_read_b128 v[126:129], v1 offset:36864
	ds_read_b128 v[130:133], v1 offset:41472
	s_setprio 1
	ds_read_b128 v[86:89], v68 offset:32
	s_waitcnt lgkmcnt(2)
	v_mfma_f32_32x32x16_bf16 v[34:49], v[94:97], v[126:129], v[34:49]
	ds_read_b128 v[90:93], v1 offset:36896
	s_waitcnt lgkmcnt(2)
	v_mfma_f32_32x32x16_bf16 v[50:65], v[94:97], v[130:133], v[50:65]
	ds_read_b128 v[94:97], v1 offset:41504
	s_waitcnt lgkmcnt(1)
	v_mfma_f32_32x32x16_bf16 v[34:49], v[86:89], v[90:93], v[34:49]
	s_waitcnt lgkmcnt(0)
	v_mfma_f32_32x32x16_bf16 v[50:65], v[86:89], v[94:97], v[50:65]
	s_waitcnt vmcnt(7)
	ds_write_b128 v66, v[140:143] offset:18432
	s_waitcnt vmcnt(6)
	ds_write_b128 v66, v[102:105] offset:23040
	global_load_dwordx4 v[140:143], v[72:73], off offset:512
	global_load_dwordx4 v[102:105], v[70:71], off offset:512
	ds_read_b128 v[86:89], v68 offset:4640
	v_mfma_f32_32x32x16_bf16 v[2:17], v[98:101], v[126:129], v[2:17]
	v_mfma_f32_32x32x16_bf16 v[18:33], v[98:101], v[130:133], v[18:33]
	ds_read_b128 v[98:101], v68 offset:4704
	s_waitcnt lgkmcnt(1)
	v_mfma_f32_32x32x16_bf16 v[2:17], v[86:89], v[90:93], v[2:17]
	ds_read_b128 v[90:93], v1 offset:36928
	v_mfma_f32_32x32x16_bf16 v[18:33], v[86:89], v[94:97], v[18:33]
	s_waitcnt vmcnt(7)
	ds_write_b128 v66, v[106:109] offset:27648
	s_waitcnt vmcnt(6)
	ds_write_b128 v66, v[110:113] offset:32256
	global_load_dwordx4 v[106:109], v[74:75], off offset:512
	global_load_dwordx4 v[110:113], v[76:77], off offset:512
	ds_read_b128 v[86:89], v68 offset:64
	ds_read_b128 v[94:97], v1 offset:41536
	s_waitcnt lgkmcnt(1)
	v_mfma_f32_32x32x16_bf16 v[34:49], v[86:89], v[90:93], v[34:49]
	s_waitcnt lgkmcnt(0)
	v_mfma_f32_32x32x16_bf16 v[50:65], v[86:89], v[94:97], v[50:65]
	ds_read_b128 v[86:89], v68 offset:4672
	s_waitcnt lgkmcnt(0)
	v_mfma_f32_32x32x16_bf16 v[2:17], v[86:89], v[90:93], v[2:17]
	ds_read_b128 v[90:93], v1 offset:36960
	v_mfma_f32_32x32x16_bf16 v[18:33], v[86:89], v[94:97], v[18:33]
	s_waitcnt vmcnt(7)
	ds_write_b128 v66, v[144:147] offset:55296
	s_waitcnt vmcnt(6)
	ds_write_b128 v66, v[122:125] offset:59904
	global_load_dwordx4 v[144:147], v[78:79], off offset:512
	global_load_dwordx4 v[122:125], v[80:81], off offset:512
	ds_read_b128 v[86:89], v68 offset:96
	ds_read_b128 v[94:97], v1 offset:41568
	s_waitcnt lgkmcnt(1)
	v_mfma_f32_32x32x16_bf16 v[34:49], v[86:89], v[90:93], v[34:49]
	s_waitcnt lgkmcnt(0)
	v_mfma_f32_32x32x16_bf16 v[50:65], v[86:89], v[94:97], v[50:65]
	v_mfma_f32_32x32x16_bf16 v[2:17], v[98:101], v[90:93], v[2:17]
	v_mfma_f32_32x32x16_bf16 v[18:33], v[98:101], v[94:97], v[18:33]
	s_waitcnt vmcnt(7)
	ds_write_b128 v66, v[118:121] offset:64512
	s_waitcnt vmcnt(6)
	ds_write_b128 v69, v[114:117] offset:32256
	global_load_dwordx4 v[118:121], v[82:83], off offset:512
	global_load_dwordx4 v[114:117], v[84:85], off offset:512
	s_setprio 0
	s_waitcnt lgkmcnt(0)
	s_barrier
; #define MFMA(a, b, c) __builtin_amdgcn_mfma_f32_32x32x16_bf16((a), (b), (c), 0, 0, 0)
; template <int TM, int TN>
; DI void gemm_mainloop(const u16* __restrict__ A, long lda, const u16* __restrict__ Bt, long ldb, int K, char* smem,
;                       f32x16 (&acc)[TM][TN]) {
;     ...
;   GEMM_GLOAD(0)
;   __syncthreads();
;   GEMM_SSTORE(0)
;   if (nk > 1) GEMM_GLOAD(64)
;   __syncthreads();
;   for (int kt = 0; kt < nk; kt++) {
;     const int buf = kt & 1;
;     const u16* cA = sA + buf * BM * LD + (wm * 32 * TM + r) * LD + h * 8;
;     const u16* cB = sB + buf * BN * LD + (wn * 32 * TN + r) * LD + h * 8;
;     bf16x8 af[TM], bfr[TN];
; #pragma unroll
;     for (int tm = 0; tm < TM; tm++) af[tm] = *(const bf16x8*)(cA + tm * 32 * LD);
; #pragma unroll
;     for (int tn = 0; tn < TN; tn++) bfr[tn] = *(const bf16x8*)(cB + tn * 32 * LD);
;     if (kt + 1 < nk) GEMM_SSTORE(buf ^ 1)
;     __builtin_amdgcn_sched_barrier(0);
;     __builtin_amdgcn_s_setprio(1);
; #pragma unroll
;     for (int tm = 0; tm < TM; tm++)
; #pragma unroll
;       for (int tn = 0; tn < TN; tn++) acc[tm][tn] = MFMA(af[tm], bfr[tn], acc[tm][tn]);
; #pragma unroll
;     for (int tm = 0; tm < TM; tm++) af[tm] = *(const bf16x8*)(cA + tm * 32 * LD + 16);
; #pragma unroll
;     for (int tn = 0; tn < TN; tn++) bfr[tn] = *(const bf16x8*)(cB + tn * 32 * LD + 16);
; #pragma unroll
;     for (int tm = 0; tm < TM; tm++)
; #pragma unroll
;       for (int tn = 0; tn < TN; tn++) acc[tm][tn] = MFMA(af[tm], bfr[tn], acc[tm][tn]);
;     __builtin_amdgcn_sched_group_barrier(0x8, 4, 0);
;     if (kt + 2 < nk) GEMM_GLOAD((kt + 2) * 64)
; #pragma unroll
;     for (int ks = 2; ks < 4; ks++) {
; #pragma unroll
;       for (int tm = 0; tm < TM; tm++) af[tm] = *(const bf16x8*)(cA + tm * 32 * LD + ks * 16);
; #pragma unroll
;       for (int tn = 0; tn < TN; tn++) bfr[tn] = *(const bf16x8*)(cB + tn * 32 * LD + ks * 16);
; #pragma unroll
;       for (int tm = 0; tm < TM; tm++)
; #pragma unroll
;         for (int tn = 0; tn < TN; tn++) acc[tm][tn] = MFMA(af[tm], bfr[tn], acc[tm][tn]);
;     }
;     __builtin_amdgcn_s_setprio(0);
;     __syncthreads();
;   }
	ds_read_b128 v[94:97], v68 offset:18432
	ds_read_b128 v[98:101], v68 offset:23040
	ds_read_b128 v[126:129], v1 offset:55296
	ds_read_b128 v[130:133], v1 offset:59904
	s_setprio 1
	ds_read_b128 v[86:89], v68 offset:18464
	s_waitcnt lgkmcnt(2)
	v_mfma_f32_32x32x16_bf16 v[34:49], v[94:97], v[126:129], v[34:49]
	ds_read_b128 v[90:93], v1 offset:55328
	s_waitcnt lgkmcnt(2)
	v_mfma_f32_32x32x16_bf16 v[50:65], v[94:97], v[130:133], v[50:65]
	ds_read_b128 v[94:97], v1 offset:59936
	s_waitcnt lgkmcnt(1)
	v_mfma_f32_32x32x16_bf16 v[34:49], v[86:89], v[90:93], v[34:49]
	s_waitcnt lgkmcnt(0)
	v_mfma_f32_32x32x16_bf16 v[50:65], v[86:89], v[94:97], v[50:65]
	s_waitcnt vmcnt(7)
	ds_write_b128 v66, v[140:143]
	s_waitcnt vmcnt(6)
	ds_write_b128 v66, v[102:105] offset:4608
	global_load_dwordx4 v[140:143], v[72:73], off offset:640
	global_load_dwordx4 v[102:105], v[70:71], off offset:640
	ds_read_b128 v[86:89], v68 offset:23072
	v_mfma_f32_32x32x16_bf16 v[2:17], v[98:101], v[126:129], v[2:17]
	v_mfma_f32_32x32x16_bf16 v[18:33], v[98:101], v[130:133], v[18:33]
	ds_read_b128 v[98:101], v68 offset:23136
	s_waitcnt lgkmcnt(1)
	v_mfma_f32_32x32x16_bf16 v[2:17], v[86:89], v[90:93], v[2:17]
	ds_read_b128 v[90:93], v1 offset:55360
	v_mfma_f32_32x32x16_bf16 v[18:33], v[86:89], v[94:97], v[18:33]
	s_waitcnt vmcnt(7)
	ds_write_b128 v66, v[106:109] offset:9216
	s_waitcnt vmcnt(6)
	ds_write_b128 v66, v[110:113] offset:13824
	global_load_dwordx4 v[106:109], v[74:75], off offset:640
	global_load_dwordx4 v[110:113], v[76:77], off offset:640
	ds_read_b128 v[86:89], v68 offset:18496
	ds_read_b128 v[94:97], v1 offset:59968
	s_waitcnt lgkmcnt(1)
	v_mfma_f32_32x32x16_bf16 v[34:49], v[86:89], v[90:93], v[34:49]
	s_waitcnt lgkmcnt(0)
	v_mfma_f32_32x32x16_bf16 v[50:65], v[86:89], v[94:97], v[50:65]
	ds_read_b128 v[86:89], v68 offset:23104
	s_waitcnt lgkmcnt(0)
	v_mfma_f32_32x32x16_bf16 v[2:17], v[86:89], v[90:93], v[2:17]
	ds_read_b128 v[90:93], v1 offset:55392
	v_mfma_f32_32x32x16_bf16 v[18:33], v[86:89], v[94:97], v[18:33]
	s_waitcnt vmcnt(7)
	ds_write_b128 v66, v[144:147] offset:36864
	s_waitcnt vmcnt(6)
	ds_write_b128 v66, v[122:125] offset:41472
	global_load_dwordx4 v[144:147], v[78:79], off offset:640
	global_load_dwordx4 v[122:125], v[80:81], off offset:640
	ds_read_b128 v[86:89], v68 offset:18528
	ds_read_b128 v[94:97], v1 offset:60000
	s_waitcnt lgkmcnt(1)
	v_mfma_f32_32x32x16_bf16 v[34:49], v[86:89], v[90:93], v[34:49]
	s_waitcnt lgkmcnt(0)
	v_mfma_f32_32x32x16_bf16 v[50:65], v[86:89], v[94:97], v[50:65]
	v_mfma_f32_32x32x16_bf16 v[2:17], v[98:101], v[90:93], v[2:17]
	v_mfma_f32_32x32x16_bf16 v[18:33], v[98:101], v[94:97], v[18:33]
	s_waitcnt vmcnt(7)
	ds_write_b128 v66, v[118:121] offset:46080
	s_waitcnt vmcnt(6)
	ds_write_b128 v66, v[114:117] offset:50688
	global_load_dwordx4 v[118:121], v[82:83], off offset:640
	global_load_dwordx4 v[114:117], v[84:85], off offset:640
	s_setprio 0
	s_waitcnt lgkmcnt(0)
	s_barrier
	ds_read_b128 v[94:97], v68
	ds_read_b128 v[98:101], v68 offset:4608
	ds_read_b128 v[126:129], v1 offset:36864
	ds_read_b128 v[130:133], v1 offset:41472
	s_setprio 1
	ds_read_b128 v[86:89], v68 offset:32
	s_waitcnt lgkmcnt(2)
	v_mfma_f32_32x32x16_bf16 v[34:49], v[94:97], v[126:129], v[34:49]
	ds_read_b128 v[90:93], v1 offset:36896
	s_waitcnt lgkmcnt(2)
	v_mfma_f32_32x32x16_bf16 v[50:65], v[94:97], v[130:133], v[50:65]
	ds_read_b128 v[94:97], v1 offset:41504
	s_waitcnt lgkmcnt(1)
	v_mfma_f32_32x32x16_bf16 v[34:49], v[86:89], v[90:93], v[34:49]
	s_waitcnt lgkmcnt(0)
	v_mfma_f32_32x32x16_bf16 v[50:65], v[86:89], v[94:97], v[50:65]
	s_waitcnt vmcnt(7)
	ds_write_b128 v66, v[140:143] offset:18432
	s_waitcnt vmcnt(6)
	ds_write_b128 v66, v[102:105] offset:23040
	global_load_dwordx4 v[140:143], v[72:73], off offset:768
	global_load_dwordx4 v[102:105], v[70:71], off offset:768
	ds_read_b128 v[86:89], v68 offset:4640
	v_mfma_f32_32x32x16_bf16 v[2:17], v[98:101], v[126:129], v[2:17]
	v_mfma_f32_32x32x16_bf16 v[18:33], v[98:101], v[130:133], v[18:33]
	ds_read_b128 v[98:101], v68 offset:4704
	s_waitcnt lgkmcnt(1)
	v_mfma_f32_32x32x16_bf16 v[2:17], v[86:89], v[90:93], v[2:17]
	ds_read_b128 v[90:93], v1 offset:36928
	v_mfma_f32_32x32x16_bf16 v[18:33], v[86:89], v[94:97], v[18:33]
	s_waitcnt vmcnt(7)
	ds_write_b128 v66, v[106:109] offset:27648
	s_waitcnt vmcnt(6)
	ds_write_b128 v66, v[110:113] offset:32256
	global_load_dwordx4 v[106:109], v[74:75], off offset:768
	global_load_dwordx4 v[110:113], v[76:77], off offset:768
	ds_read_b128 v[86:89], v68 offset:64
	ds_read_b128 v[94:97], v1 offset:41536
	s_waitcnt lgkmcnt(1)
	v_mfma_f32_32x32x16_bf16 v[34:49], v[86:89], v[90:93], v[34:49]
	s_waitcnt lgkmcnt(0)
	v_mfma_f32_32x32x16_bf16 v[50:65], v[86:89], v[94:97], v[50:65]
	ds_read_b128 v[86:89], v68 offset:4672
	s_waitcnt lgkmcnt(0)
	v_mfma_f32_32x32x16_bf16 v[2:17], v[86:89], v[90:93], v[2:17]
	ds_read_b128 v[90:93], v1 offset:36960
	v_mfma_f32_32x32x16_bf16 v[18:33], v[86:89], v[94:97], v[18:33]
	s_waitcnt vmcnt(7)
	ds_write_b128 v66, v[144:147] offset:55296
	s_waitcnt vmcnt(6)
	ds_write_b128 v66, v[122:125] offset:59904
	global_load_dwordx4 v[144:147], v[78:79], off offset:768
	global_load_dwordx4 v[122:125], v[80:81], off offset:768
	ds_read_b128 v[86:89], v68 offset:96
	ds_read_b128 v[94:97], v1 offset:41568
	s_waitcnt lgkmcnt(1)
	v_mfma_f32_32x32x16_bf16 v[34:49], v[86:89], v[90:93], v[34:49]
	s_waitcnt lgkmcnt(0)
	v_mfma_f32_32x32x16_bf16 v[50:65], v[86:89], v[94:97], v[50:65]
	v_mfma_f32_32x32x16_bf16 v[2:17], v[98:101], v[90:93], v[2:17]
	v_mfma_f32_32x32x16_bf16 v[18:33], v[98:101], v[94:97], v[18:33]
	s_waitcnt vmcnt(7)
	ds_write_b128 v66, v[118:121] offset:64512
	s_waitcnt vmcnt(6)
	ds_write_b128 v69, v[114:117] offset:32256
	global_load_dwordx4 v[118:121], v[82:83], off offset:768
	global_load_dwordx4 v[114:117], v[84:85], off offset:768
	s_setprio 0
	s_waitcnt lgkmcnt(0)
	s_barrier
; #define MFMA(a, b, c) __builtin_amdgcn_mfma_f32_32x32x16_bf16((a), (b), (c), 0, 0, 0)
; template <int TM, int TN>
; DI void gemm_mainloop(const u16* __restrict__ A, long lda, const u16* __restrict__ Bt, long ldb, int K, char* smem,
;                       f32x16 (&acc)[TM][TN]) {
;     ...
;   GEMM_GLOAD(0)
;   __syncthreads();
;   GEMM_SSTORE(0)
;   if (nk > 1) GEMM_GLOAD(64)
;   __syncthreads();
;   for (int kt = 0; kt < nk; kt++) {
;     const int buf = kt & 1;
;     const u16* cA = sA + buf * BM * LD + (wm * 32 * TM + r) * LD + h * 8;
;     const u16* cB = sB + buf * BN * LD + (wn * 32 * TN + r) * LD + h * 8;
;     bf16x8 af[TM], bfr[TN];
; #pragma unroll
;     for (int tm = 0; tm < TM; tm++) af[tm] = *(const bf16x8*)(cA + tm * 32 * LD);
; #pragma unroll
;     for (int tn = 0; tn < TN; tn++) bfr[tn] = *(const bf16x8*)(cB + tn * 32 * LD);
;     if (kt + 1 < nk) GEMM_SSTORE(buf ^ 1)
;     __builtin_amdgcn_sched_barrier(0);
;     __builtin_amdgcn_s_setprio(1);
; #pragma unroll
;     for (int tm = 0; tm < TM; tm++)
; #pragma unroll
;       for (int tn = 0; tn < TN; tn++) acc[tm][tn] = MFMA(af[tm], bfr[tn], acc[tm][tn]);
; #pragma unroll
;     for (int tm = 0; tm < TM; tm++) af[tm] = *(const bf16x8*)(cA + tm * 32 * LD + 16);
; #pragma unroll
;     for (int tn = 0; tn < TN; tn++) bfr[tn] = *(const bf16x8*)(cB + tn * 32 * LD + 16);
; #pragma unroll
;     for (int tm = 0; tm < TM; tm++)
; #pragma unroll
;       for (int tn = 0; tn < TN; tn++) acc[tm][tn] = MFMA(af[tm], bfr[tn], acc[tm][tn]);
;     __builtin_amdgcn_sched_group_barrier(0x8, 4, 0);
;     if (kt + 2 < nk) GEMM_GLOAD((kt + 2) * 64)
; #pragma unroll
;     for (int ks = 2; ks < 4; ks++) {
; #pragma unroll
;       for (int tm = 0; tm < TM; tm++) af[tm] = *(const bf16x8*)(cA + tm * 32 * LD + ks * 16);
; #pragma unroll
;       for (int tn = 0; tn < TN; tn++) bfr[tn] = *(const bf16x8*)(cB + tn * 32 * LD + ks * 16);
; #pragma unroll
;       for (int tm = 0; tm < TM; tm++)
; #pragma unroll
;         for (int tn = 0; tn < TN; tn++) acc[tm][tn] = MFMA(af[tm], bfr[tn], acc[tm][tn]);
;     }
;     __builtin_amdgcn_s_setprio(0);
;     __syncthreads();
;   }
	ds_read_b128 v[94:97], v68 offset:18432
	ds_read_b128 v[98:101], v68 offset:23040
	ds_read_b128 v[126:129], v1 offset:55296
	ds_read_b128 v[130:133], v1 offset:59904
	s_setprio 1
	ds_read_b128 v[86:89], v68 offset:18464
	s_waitcnt lgkmcnt(2)
	v_mfma_f32_32x32x16_bf16 v[34:49], v[94:97], v[126:129], v[34:49]
	ds_read_b128 v[90:93], v1 offset:55328
	s_waitcnt lgkmcnt(2)
	v_mfma_f32_32x32x16_bf16 v[50:65], v[94:97], v[130:133], v[50:65]
	ds_read_b128 v[94:97], v1 offset:59936
	s_waitcnt lgkmcnt(1)
	v_mfma_f32_32x32x16_bf16 v[34:49], v[86:89], v[90:93], v[34:49]
	s_waitcnt lgkmcnt(0)
	v_mfma_f32_32x32x16_bf16 v[50:65], v[86:89], v[94:97], v[50:65]
	s_waitcnt vmcnt(7)
	ds_write_b128 v66, v[140:143]
	s_waitcnt vmcnt(6)
	ds_write_b128 v66, v[102:105] offset:4608
	global_load_dwordx4 v[140:143], v[72:73], off offset:896
	global_load_dwordx4 v[102:105], v[70:71], off offset:896
	ds_read_b128 v[86:89], v68 offset:23072
	v_mfma_f32_32x32x16_bf16 v[2:17], v[98:101], v[126:129], v[2:17]
	v_mfma_f32_32x32x16_bf16 v[18:33], v[98:101], v[130:133], v[18:33]
	ds_read_b128 v[98:101], v68 offset:23136
	s_waitcnt lgkmcnt(1)
	v_mfma_f32_32x32x16_bf16 v[2:17], v[86:89], v[90:93], v[2:17]
	ds_read_b128 v[90:93], v1 offset:55360
	v_mfma_f32_32x32x16_bf16 v[18:33], v[86:89], v[94:97], v[18:33]
	s_waitcnt vmcnt(7)
	ds_write_b128 v66, v[106:109] offset:9216
	s_waitcnt vmcnt(6)
	ds_write_b128 v66, v[110:113] offset:13824
	global_load_dwordx4 v[106:109], v[74:75], off offset:896
	global_load_dwordx4 v[110:113], v[76:77], off offset:896
	ds_read_b128 v[86:89], v68 offset:18496
	ds_read_b128 v[94:97], v1 offset:59968
	s_waitcnt lgkmcnt(1)
	v_mfma_f32_32x32x16_bf16 v[34:49], v[86:89], v[90:93], v[34:49]
	s_waitcnt lgkmcnt(0)
	v_mfma_f32_32x32x16_bf16 v[50:65], v[86:89], v[94:97], v[50:65]
	ds_read_b128 v[86:89], v68 offset:23104
	s_waitcnt lgkmcnt(0)
	v_mfma_f32_32x32x16_bf16 v[2:17], v[86:89], v[90:93], v[2:17]
	ds_read_b128 v[90:93], v1 offset:55392
	v_mfma_f32_32x32x16_bf16 v[18:33], v[86:89], v[94:97], v[18:33]
	s_waitcnt vmcnt(7)
	ds_write_b128 v66, v[144:147] offset:36864
	s_waitcnt vmcnt(6)
	ds_write_b128 v66, v[122:125] offset:41472
	global_load_dwordx4 v[144:147], v[78:79], off offset:896
	global_load_dwordx4 v[122:125], v[80:81], off offset:896
	ds_read_b128 v[86:89], v68 offset:18528
	ds_read_b128 v[94:97], v1 offset:60000
	s_waitcnt lgkmcnt(1)
	v_mfma_f32_32x32x16_bf16 v[34:49], v[86:89], v[90:93], v[34:49]
	s_waitcnt lgkmcnt(0)
	v_mfma_f32_32x32x16_bf16 v[50:65], v[86:89], v[94:97], v[50:65]
	v_mfma_f32_32x32x16_bf16 v[2:17], v[98:101], v[90:93], v[2:17]
	v_mfma_f32_32x32x16_bf16 v[18:33], v[98:101], v[94:97], v[18:33]
	s_waitcnt vmcnt(7)
	ds_write_b128 v66, v[118:121] offset:46080
	s_waitcnt vmcnt(6)
	ds_write_b128 v66, v[114:117] offset:50688
	global_load_dwordx4 v[118:121], v[82:83], off offset:896
	global_load_dwordx4 v[114:117], v[84:85], off offset:896
	s_setprio 0
	s_waitcnt lgkmcnt(0)
	s_barrier
	ds_read_b128 v[94:97], v68
	ds_read_b128 v[98:101], v68 offset:4608
	ds_read_b128 v[126:129], v1 offset:36864
	ds_read_b128 v[130:133], v1 offset:41472
	s_setprio 1
	ds_read_b128 v[86:89], v68 offset:32
	s_waitcnt lgkmcnt(2)
	v_mfma_f32_32x32x16_bf16 v[34:49], v[94:97], v[126:129], v[34:49]
	ds_read_b128 v[90:93], v1 offset:36896
	s_waitcnt lgkmcnt(2)
	v_mfma_f32_32x32x16_bf16 v[50:65], v[94:97], v[130:133], v[50:65]
	ds_read_b128 v[94:97], v1 offset:41504
	s_waitcnt lgkmcnt(1)
	v_mfma_f32_32x32x16_bf16 v[34:49], v[86:89], v[90:93], v[34:49]
	s_waitcnt lgkmcnt(0)
	v_mfma_f32_32x32x16_bf16 v[50:65], v[86:89], v[94:97], v[50:65]
	s_waitcnt vmcnt(7)
	ds_write_b128 v66, v[140:143] offset:18432
	s_waitcnt vmcnt(6)
	ds_write_b128 v66, v[102:105] offset:23040
	global_load_dwordx4 v[140:143], v[72:73], off offset:1024
	global_load_dwordx4 v[102:105], v[70:71], off offset:1024
	ds_read_b128 v[86:89], v68 offset:4640
	v_mfma_f32_32x32x16_bf16 v[2:17], v[98:101], v[126:129], v[2:17]
	v_mfma_f32_32x32x16_bf16 v[18:33], v[98:101], v[130:133], v[18:33]
	ds_read_b128 v[98:101], v68 offset:4704
	s_waitcnt lgkmcnt(1)
	v_mfma_f32_32x32x16_bf16 v[2:17], v[86:89], v[90:93], v[2:17]
	ds_read_b128 v[90:93], v1 offset:36928
	v_mfma_f32_32x32x16_bf16 v[18:33], v[86:89], v[94:97], v[18:33]
	s_waitcnt vmcnt(7)
	ds_write_b128 v66, v[106:109] offset:27648
	s_waitcnt vmcnt(6)
	ds_write_b128 v66, v[110:113] offset:32256
	global_load_dwordx4 v[106:109], v[74:75], off offset:1024
	global_load_dwordx4 v[110:113], v[76:77], off offset:1024
	ds_read_b128 v[86:89], v68 offset:64
	ds_read_b128 v[94:97], v1 offset:41536
	s_waitcnt lgkmcnt(1)
	v_mfma_f32_32x32x16_bf16 v[34:49], v[86:89], v[90:93], v[34:49]
	s_waitcnt lgkmcnt(0)
	v_mfma_f32_32x32x16_bf16 v[50:65], v[86:89], v[94:97], v[50:65]
	ds_read_b128 v[86:89], v68 offset:4672
	s_waitcnt lgkmcnt(0)
	v_mfma_f32_32x32x16_bf16 v[2:17], v[86:89], v[90:93], v[2:17]
	ds_read_b128 v[90:93], v1 offset:36960
	v_mfma_f32_32x32x16_bf16 v[18:33], v[86:89], v[94:97], v[18:33]
	s_waitcnt vmcnt(7)
	ds_write_b128 v66, v[144:147] offset:55296
	s_waitcnt vmcnt(6)
	ds_write_b128 v66, v[122:125] offset:59904
	global_load_dwordx4 v[144:147], v[78:79], off offset:1024
	global_load_dwordx4 v[122:125], v[80:81], off offset:1024
	ds_read_b128 v[86:89], v68 offset:96
	ds_read_b128 v[94:97], v1 offset:41568
	s_waitcnt lgkmcnt(1)
	v_mfma_f32_32x32x16_bf16 v[34:49], v[86:89], v[90:93], v[34:49]
	s_waitcnt lgkmcnt(0)
	v_mfma_f32_32x32x16_bf16 v[50:65], v[86:89], v[94:97], v[50:65]
	v_mfma_f32_32x32x16_bf16 v[2:17], v[98:101], v[90:93], v[2:17]
	v_mfma_f32_32x32x16_bf16 v[18:33], v[98:101], v[94:97], v[18:33]
	s_waitcnt vmcnt(7)
	ds_write_b128 v66, v[118:121] offset:64512
	s_waitcnt vmcnt(6)
	ds_write_b128 v69, v[114:117] offset:32256
	global_load_dwordx4 v[118:121], v[82:83], off offset:1024
	global_load_dwordx4 v[114:117], v[84:85], off offset:1024
	s_setprio 0
	s_waitcnt lgkmcnt(0)
	s_barrier
; #define MFMA(a, b, c) __builtin_amdgcn_mfma_f32_32x32x16_bf16((a), (b), (c), 0, 0, 0)
; template <int TM, int TN>
; DI void gemm_mainloop(const u16* __restrict__ A, long lda, const u16* __restrict__ Bt, long ldb, int K, char* smem,
;                       f32x16 (&acc)[TM][TN]) {
;     ...
;   GEMM_GLOAD(0)
;   __syncthreads();
;   GEMM_SSTORE(0)
;   if (nk > 1) GEMM_GLOAD(64)
;   __syncthreads();
;   for (int kt = 0; kt < nk; kt++) {
;     const int buf = kt & 1;
;     const u16* cA = sA + buf * BM * LD + (wm * 32 * TM + r) * LD + h * 8;
;     const u16* cB = sB + buf * BN * LD + (wn * 32 * TN + r) * LD + h * 8;
;     bf16x8 af[TM], bfr[TN];
; #pragma unroll
;     for (int tm = 0; tm < TM; tm++) af[tm] = *(const bf16x8*)(cA + tm * 32 * LD);
; #pragma unroll
;     for (int tn = 0; tn < TN; tn++) bfr[tn] = *(const bf16x8*)(cB + tn * 32 * LD);
;     if (kt + 1 < nk) GEMM_SSTORE(buf ^ 1)
;     __builtin_amdgcn_sched_barrier(0);
;     __builtin_amdgcn_s_setprio(1);
; #pragma unroll
;     for (int tm = 0; tm < TM; tm++)
; #pragma unroll
;       for (int tn = 0; tn < TN; tn++) acc[tm][tn] = MFMA(af[tm], bfr[tn], acc[tm][tn]);
; #pragma unroll
;     for (int tm = 0; tm < TM; tm++) af[tm] = *(const bf16x8*)(cA + tm * 32 * LD + 16);
; #pragma unroll
;     for (int tn = 0; tn < TN; tn++) bfr[tn] = *(const bf16x8*)(cB + tn * 32 * LD + 16);
; #pragma unroll
;     for (int tm = 0; tm < TM; tm++)
; #pragma unroll
;       for (int tn = 0; tn < TN; tn++) acc[tm][tn] = MFMA(af[tm], bfr[tn], acc[tm][tn]);
;     __builtin_amdgcn_sched_group_barrier(0x8, 4, 0);
;     if (kt + 2 < nk) GEMM_GLOAD((kt + 2) * 64)
; #pragma unroll
;     for (int ks = 2; ks < 4; ks++) {
; #pragma unroll
;       for (int tm = 0; tm < TM; tm++) af[tm] = *(const bf16x8*)(cA + tm * 32 * LD + ks * 16);
; #pragma unroll
;       for (int tn = 0; tn < TN; tn++) bfr[tn] = *(const bf16x8*)(cB + tn * 32 * LD + ks * 16);
; #pragma unroll
;       for (int tm = 0; tm < TM; tm++)
; #pragma unroll
;         for (int tn = 0; tn < TN; tn++) acc[tm][tn] = MFMA(af[tm], bfr[tn], acc[tm][tn]);
;     }
;     __builtin_amdgcn_s_setprio(0);
;     __syncthreads();
;   }
	ds_read_b128 v[94:97], v68 offset:18432
	ds_read_b128 v[98:101], v68 offset:23040
	ds_read_b128 v[126:129], v1 offset:55296
	ds_read_b128 v[130:133], v1 offset:59904
	s_setprio 1
	ds_read_b128 v[86:89], v68 offset:18464
	s_waitcnt lgkmcnt(2)
	v_mfma_f32_32x32x16_bf16 v[34:49], v[94:97], v[126:129], v[34:49]
	ds_read_b128 v[90:93], v1 offset:55328
	s_waitcnt lgkmcnt(2)
	v_mfma_f32_32x32x16_bf16 v[50:65], v[94:97], v[130:133], v[50:65]
	ds_read_b128 v[94:97], v1 offset:59936
	s_waitcnt lgkmcnt(1)
	v_mfma_f32_32x32x16_bf16 v[34:49], v[86:89], v[90:93], v[34:49]
	s_waitcnt lgkmcnt(0)
	v_mfma_f32_32x32x16_bf16 v[50:65], v[86:89], v[94:97], v[50:65]
	s_waitcnt vmcnt(7)
	ds_write_b128 v66, v[140:143]
	s_waitcnt vmcnt(6)
	ds_write_b128 v66, v[102:105] offset:4608
	global_load_dwordx4 v[140:143], v[72:73], off offset:1152
	global_load_dwordx4 v[102:105], v[70:71], off offset:1152
	ds_read_b128 v[86:89], v68 offset:23072
	v_mfma_f32_32x32x16_bf16 v[2:17], v[98:101], v[126:129], v[2:17]
	v_mfma_f32_32x32x16_bf16 v[18:33], v[98:101], v[130:133], v[18:33]
	ds_read_b128 v[98:101], v68 offset:23136
	s_waitcnt lgkmcnt(1)
	v_mfma_f32_32x32x16_bf16 v[2:17], v[86:89], v[90:93], v[2:17]
	ds_read_b128 v[90:93], v1 offset:55360
	v_mfma_f32_32x32x16_bf16 v[18:33], v[86:89], v[94:97], v[18:33]
	s_waitcnt vmcnt(7)
	ds_write_b128 v66, v[106:109] offset:9216
	s_waitcnt vmcnt(6)
	ds_write_b128 v66, v[110:113] offset:13824
	global_load_dwordx4 v[106:109], v[74:75], off offset:1152
	global_load_dwordx4 v[110:113], v[76:77], off offset:1152
	ds_read_b128 v[86:89], v68 offset:18496
	ds_read_b128 v[94:97], v1 offset:59968
	s_waitcnt lgkmcnt(1)
	v_mfma_f32_32x32x16_bf16 v[34:49], v[86:89], v[90:93], v[34:49]
	s_waitcnt lgkmcnt(0)
	v_mfma_f32_32x32x16_bf16 v[50:65], v[86:89], v[94:97], v[50:65]
	ds_read_b128 v[86:89], v68 offset:23104
	s_waitcnt lgkmcnt(0)
	v_mfma_f32_32x32x16_bf16 v[2:17], v[86:89], v[90:93], v[2:17]
	ds_read_b128 v[90:93], v1 offset:55392
	v_mfma_f32_32x32x16_bf16 v[18:33], v[86:89], v[94:97], v[18:33]
	s_waitcnt vmcnt(7)
	ds_write_b128 v66, v[144:147] offset:36864
	s_waitcnt vmcnt(6)
	ds_write_b128 v66, v[122:125] offset:41472
	global_load_dwordx4 v[144:147], v[78:79], off offset:1152
	global_load_dwordx4 v[122:125], v[80:81], off offset:1152
	ds_read_b128 v[86:89], v68 offset:18528
	ds_read_b128 v[94:97], v1 offset:60000
	s_waitcnt lgkmcnt(1)
	v_mfma_f32_32x32x16_bf16 v[34:49], v[86:89], v[90:93], v[34:49]
	s_waitcnt lgkmcnt(0)
	v_mfma_f32_32x32x16_bf16 v[50:65], v[86:89], v[94:97], v[50:65]
	v_mfma_f32_32x32x16_bf16 v[2:17], v[98:101], v[90:93], v[2:17]
	v_mfma_f32_32x32x16_bf16 v[18:33], v[98:101], v[94:97], v[18:33]
	s_waitcnt vmcnt(7)
	ds_write_b128 v66, v[118:121] offset:46080
	s_waitcnt vmcnt(6)
	ds_write_b128 v66, v[114:117] offset:50688
	global_load_dwordx4 v[118:121], v[82:83], off offset:1152
	global_load_dwordx4 v[114:117], v[84:85], off offset:1152
	s_setprio 0
	s_waitcnt lgkmcnt(0)
	s_barrier
	ds_read_b128 v[94:97], v68
	ds_read_b128 v[98:101], v68 offset:4608
	ds_read_b128 v[126:129], v1 offset:36864
	ds_read_b128 v[130:133], v1 offset:41472
	s_setprio 1
	ds_read_b128 v[86:89], v68 offset:32
	s_waitcnt lgkmcnt(2)
	v_mfma_f32_32x32x16_bf16 v[34:49], v[94:97], v[126:129], v[34:49]
	ds_read_b128 v[90:93], v1 offset:36896
	s_waitcnt lgkmcnt(2)
	v_mfma_f32_32x32x16_bf16 v[50:65], v[94:97], v[130:133], v[50:65]
	ds_read_b128 v[94:97], v1 offset:41504
	s_waitcnt lgkmcnt(1)
	v_mfma_f32_32x32x16_bf16 v[34:49], v[86:89], v[90:93], v[34:49]
	s_waitcnt lgkmcnt(0)
	v_mfma_f32_32x32x16_bf16 v[50:65], v[86:89], v[94:97], v[50:65]
	s_waitcnt vmcnt(7)
	ds_write_b128 v66, v[140:143] offset:18432
	s_waitcnt vmcnt(6)
	ds_write_b128 v66, v[102:105] offset:23040
	global_load_dwordx4 v[140:143], v[72:73], off offset:1280
	global_load_dwordx4 v[102:105], v[70:71], off offset:1280
	ds_read_b128 v[86:89], v68 offset:4640
	v_mfma_f32_32x32x16_bf16 v[2:17], v[98:101], v[126:129], v[2:17]
	v_mfma_f32_32x32x16_bf16 v[18:33], v[98:101], v[130:133], v[18:33]
	ds_read_b128 v[98:101], v68 offset:4704
	s_waitcnt lgkmcnt(1)
	v_mfma_f32_32x32x16_bf16 v[2:17], v[86:89], v[90:93], v[2:17]
	ds_read_b128 v[90:93], v1 offset:36928
	v_mfma_f32_32x32x16_bf16 v[18:33], v[86:89], v[94:97], v[18:33]
	s_waitcnt vmcnt(7)
	ds_write_b128 v66, v[106:109] offset:27648
	s_waitcnt vmcnt(6)
	ds_write_b128 v66, v[110:113] offset:32256
	global_load_dwordx4 v[106:109], v[74:75], off offset:1280
	global_load_dwordx4 v[110:113], v[76:77], off offset:1280
	ds_read_b128 v[86:89], v68 offset:64
	ds_read_b128 v[94:97], v1 offset:41536
	s_waitcnt lgkmcnt(1)
	v_mfma_f32_32x32x16_bf16 v[34:49], v[86:89], v[90:93], v[34:49]
	s_waitcnt lgkmcnt(0)
	v_mfma_f32_32x32x16_bf16 v[50:65], v[86:89], v[94:97], v[50:65]
	ds_read_b128 v[86:89], v68 offset:4672
	s_waitcnt lgkmcnt(0)
	v_mfma_f32_32x32x16_bf16 v[2:17], v[86:89], v[90:93], v[2:17]
	ds_read_b128 v[90:93], v1 offset:36960
	v_mfma_f32_32x32x16_bf16 v[18:33], v[86:89], v[94:97], v[18:33]
	s_waitcnt vmcnt(7)
	ds_write_b128 v66, v[144:147] offset:55296
	s_waitcnt vmcnt(6)
	ds_write_b128 v66, v[122:125] offset:59904
	global_load_dwordx4 v[144:147], v[78:79], off offset:1280
	global_load_dwordx4 v[122:125], v[80:81], off offset:1280
	ds_read_b128 v[86:89], v68 offset:96
	ds_read_b128 v[94:97], v1 offset:41568
	s_waitcnt lgkmcnt(1)
	v_mfma_f32_32x32x16_bf16 v[34:49], v[86:89], v[90:93], v[34:49]
	s_waitcnt lgkmcnt(0)
	v_mfma_f32_32x32x16_bf16 v[50:65], v[86:89], v[94:97], v[50:65]
	v_mfma_f32_32x32x16_bf16 v[2:17], v[98:101], v[90:93], v[2:17]
	v_mfma_f32_32x32x16_bf16 v[18:33], v[98:101], v[94:97], v[18:33]
	s_waitcnt vmcnt(7)
	ds_write_b128 v66, v[118:121] offset:64512
	s_waitcnt vmcnt(6)
	ds_write_b128 v69, v[114:117] offset:32256
	global_load_dwordx4 v[118:121], v[82:83], off offset:1280
	global_load_dwordx4 v[114:117], v[84:85], off offset:1280
	s_setprio 0
	s_waitcnt lgkmcnt(0)
	s_barrier
; #define MFMA(a, b, c) __builtin_amdgcn_mfma_f32_32x32x16_bf16((a), (b), (c), 0, 0, 0)
; template <int TM, int TN>
; DI void gemm_mainloop(const u16* __restrict__ A, long lda, const u16* __restrict__ Bt, long ldb, int K, char* smem,
;                       f32x16 (&acc)[TM][TN]) {
;     ...
;   GEMM_GLOAD(0)
;   __syncthreads();
;   GEMM_SSTORE(0)
;   if (nk > 1) GEMM_GLOAD(64)
;   __syncthreads();
;   for (int kt = 0; kt < nk; kt++) {
;     const int buf = kt & 1;
;     const u16* cA = sA + buf * BM * LD + (wm * 32 * TM + r) * LD + h * 8;
;     const u16* cB = sB + buf * BN * LD + (wn * 32 * TN + r) * LD + h * 8;
;     bf16x8 af[TM], bfr[TN];
; #pragma unroll
;     for (int tm = 0; tm < TM; tm++) af[tm] = *(const bf16x8*)(cA + tm * 32 * LD);
; #pragma unroll
;     for (int tn = 0; tn < TN; tn++) bfr[tn] = *(const bf16x8*)(cB + tn * 32 * LD);
;     if (kt + 1 < nk) GEMM_SSTORE(buf ^ 1)
;     __builtin_amdgcn_sched_barrier(0);
;     __builtin_amdgcn_s_setprio(1);
; #pragma unroll
;     for (int tm = 0; tm < TM; tm++)
; #pragma unroll
;       for (int tn = 0; tn < TN; tn++) acc[tm][tn] = MFMA(af[tm], bfr[tn], acc[tm][tn]);
; #pragma unroll
;     for (int tm = 0; tm < TM; tm++) af[tm] = *(const bf16x8*)(cA + tm * 32 * LD + 16);
; #pragma unroll
;     for (int tn = 0; tn < TN; tn++) bfr[tn] = *(const bf16x8*)(cB + tn * 32 * LD + 16);
; #pragma unroll
;     for (int tm = 0; tm < TM; tm++)
; #pragma unroll
;       for (int tn = 0; tn < TN; tn++) acc[tm][tn] = MFMA(af[tm], bfr[tn], acc[tm][tn]);
;     __builtin_amdgcn_sched_group_barrier(0x8, 4, 0);
;     if (kt + 2 < nk) GEMM_GLOAD((kt + 2) * 64)
; #pragma unroll
;     for (int ks = 2; ks < 4; ks++) {
; #pragma unroll
;       for (int tm = 0; tm < TM; tm++) af[tm] = *(const bf16x8*)(cA + tm * 32 * LD + ks * 16);
; #pragma unroll
;       for (int tn = 0; tn < TN; tn++) bfr[tn] = *(const bf16x8*)(cB + tn * 32 * LD + ks * 16);
; #pragma unroll
;       for (int tm = 0; tm < TM; tm++)
; #pragma unroll
;         for (int tn = 0; tn < TN; tn++) acc[tm][tn] = MFMA(af[tm], bfr[tn], acc[tm][tn]);
;     }
;     __builtin_amdgcn_s_setprio(0);
;     __syncthreads();
;   }
	ds_read_b128 v[94:97], v68 offset:18432
	ds_read_b128 v[98:101], v68 offset:23040
	ds_read_b128 v[126:129], v1 offset:55296
	ds_read_b128 v[130:133], v1 offset:59904
	s_setprio 1
	ds_read_b128 v[86:89], v68 offset:18464
	s_waitcnt lgkmcnt(2)
	v_mfma_f32_32x32x16_bf16 v[34:49], v[94:97], v[126:129], v[34:49]
	ds_read_b128 v[90:93], v1 offset:55328
	s_waitcnt lgkmcnt(2)
	v_mfma_f32_32x32x16_bf16 v[50:65], v[94:97], v[130:133], v[50:65]
	ds_read_b128 v[94:97], v1 offset:59936
	s_waitcnt lgkmcnt(1)
	v_mfma_f32_32x32x16_bf16 v[34:49], v[86:89], v[90:93], v[34:49]
	s_waitcnt lgkmcnt(0)
	v_mfma_f32_32x32x16_bf16 v[50:65], v[86:89], v[94:97], v[50:65]
	s_waitcnt vmcnt(7)
	ds_write_b128 v66, v[140:143]
	s_waitcnt vmcnt(6)
	ds_write_b128 v66, v[102:105] offset:4608
	global_load_dwordx4 v[140:143], v[72:73], off offset:1408
	global_load_dwordx4 v[102:105], v[70:71], off offset:1408
	ds_read_b128 v[86:89], v68 offset:23072
	v_mfma_f32_32x32x16_bf16 v[2:17], v[98:101], v[126:129], v[2:17]
	v_mfma_f32_32x32x16_bf16 v[18:33], v[98:101], v[130:133], v[18:33]
	ds_read_b128 v[98:101], v68 offset:23136
	s_waitcnt lgkmcnt(1)
	v_mfma_f32_32x32x16_bf16 v[2:17], v[86:89], v[90:93], v[2:17]
	ds_read_b128 v[90:93], v1 offset:55360
	v_mfma_f32_32x32x16_bf16 v[18:33], v[86:89], v[94:97], v[18:33]
	s_waitcnt vmcnt(7)
	ds_write_b128 v66, v[106:109] offset:9216
	s_waitcnt vmcnt(6)
	ds_write_b128 v66, v[110:113] offset:13824
	global_load_dwordx4 v[106:109], v[74:75], off offset:1408
	global_load_dwordx4 v[110:113], v[76:77], off offset:1408
	ds_read_b128 v[86:89], v68 offset:18496
	ds_read_b128 v[94:97], v1 offset:59968
	s_waitcnt lgkmcnt(1)
	v_mfma_f32_32x32x16_bf16 v[34:49], v[86:89], v[90:93], v[34:49]
	s_waitcnt lgkmcnt(0)
	v_mfma_f32_32x32x16_bf16 v[50:65], v[86:89], v[94:97], v[50:65]
	ds_read_b128 v[86:89], v68 offset:23104
	s_waitcnt lgkmcnt(0)
	v_mfma_f32_32x32x16_bf16 v[2:17], v[86:89], v[90:93], v[2:17]
	ds_read_b128 v[90:93], v1 offset:55392
	v_mfma_f32_32x32x16_bf16 v[18:33], v[86:89], v[94:97], v[18:33]
	s_waitcnt vmcnt(7)
	ds_write_b128 v66, v[144:147] offset:36864
	s_waitcnt vmcnt(6)
	ds_write_b128 v66, v[122:125] offset:41472
	global_load_dwordx4 v[144:147], v[78:79], off offset:1408
	global_load_dwordx4 v[122:125], v[80:81], off offset:1408
	ds_read_b128 v[86:89], v68 offset:18528
	ds_read_b128 v[94:97], v1 offset:60000
	s_waitcnt lgkmcnt(1)
	v_mfma_f32_32x32x16_bf16 v[34:49], v[86:89], v[90:93], v[34:49]
	s_waitcnt lgkmcnt(0)
	v_mfma_f32_32x32x16_bf16 v[50:65], v[86:89], v[94:97], v[50:65]
	v_mfma_f32_32x32x16_bf16 v[2:17], v[98:101], v[90:93], v[2:17]
	v_mfma_f32_32x32x16_bf16 v[18:33], v[98:101], v[94:97], v[18:33]
	s_waitcnt vmcnt(7)
	ds_write_b128 v66, v[118:121] offset:46080
	s_waitcnt vmcnt(6)
	ds_write_b128 v66, v[114:117] offset:50688
	global_load_dwordx4 v[118:121], v[82:83], off offset:1408
	global_load_dwordx4 v[114:117], v[84:85], off offset:1408
	s_setprio 0
	s_waitcnt lgkmcnt(0)
	s_barrier
	ds_read_b128 v[94:97], v68
	ds_read_b128 v[98:101], v68 offset:4608
	ds_read_b128 v[126:129], v1 offset:36864
	ds_read_b128 v[130:133], v1 offset:41472
	s_setprio 1
	ds_read_b128 v[86:89], v68 offset:32
	s_waitcnt lgkmcnt(2)
	v_mfma_f32_32x32x16_bf16 v[34:49], v[94:97], v[126:129], v[34:49]
	ds_read_b128 v[90:93], v1 offset:36896
	s_waitcnt lgkmcnt(2)
	v_mfma_f32_32x32x16_bf16 v[50:65], v[94:97], v[130:133], v[50:65]
	ds_read_b128 v[94:97], v1 offset:41504
	s_waitcnt lgkmcnt(1)
	v_mfma_f32_32x32x16_bf16 v[34:49], v[86:89], v[90:93], v[34:49]
	s_waitcnt lgkmcnt(0)
	v_mfma_f32_32x32x16_bf16 v[50:65], v[86:89], v[94:97], v[50:65]
	s_waitcnt vmcnt(7)
	ds_write_b128 v66, v[140:143] offset:18432
	s_waitcnt vmcnt(6)
	ds_write_b128 v66, v[102:105] offset:23040
	global_load_dwordx4 v[140:143], v[72:73], off offset:1536
	global_load_dwordx4 v[102:105], v[70:71], off offset:1536
	ds_read_b128 v[86:89], v68 offset:4640
	v_mfma_f32_32x32x16_bf16 v[2:17], v[98:101], v[126:129], v[2:17]
	v_mfma_f32_32x32x16_bf16 v[18:33], v[98:101], v[130:133], v[18:33]
	ds_read_b128 v[98:101], v68 offset:4704
	s_waitcnt lgkmcnt(1)
	v_mfma_f32_32x32x16_bf16 v[2:17], v[86:89], v[90:93], v[2:17]
	ds_read_b128 v[90:93], v1 offset:36928
	v_mfma_f32_32x32x16_bf16 v[18:33], v[86:89], v[94:97], v[18:33]
	s_waitcnt vmcnt(7)
	ds_write_b128 v66, v[106:109] offset:27648
	s_waitcnt vmcnt(6)
	ds_write_b128 v66, v[110:113] offset:32256
	global_load_dwordx4 v[106:109], v[74:75], off offset:1536
	global_load_dwordx4 v[110:113], v[76:77], off offset:1536
	ds_read_b128 v[86:89], v68 offset:64
	ds_read_b128 v[94:97], v1 offset:41536
	s_waitcnt lgkmcnt(1)
	v_mfma_f32_32x32x16_bf16 v[34:49], v[86:89], v[90:93], v[34:49]
	s_waitcnt lgkmcnt(0)
	v_mfma_f32_32x32x16_bf16 v[50:65], v[86:89], v[94:97], v[50:65]
	ds_read_b128 v[86:89], v68 offset:4672
	s_waitcnt lgkmcnt(0)
	v_mfma_f32_32x32x16_bf16 v[2:17], v[86:89], v[90:93], v[2:17]
	ds_read_b128 v[90:93], v1 offset:36960
	v_mfma_f32_32x32x16_bf16 v[18:33], v[86:89], v[94:97], v[18:33]
	s_waitcnt vmcnt(7)
	ds_write_b128 v66, v[144:147] offset:55296
	s_waitcnt vmcnt(6)
	ds_write_b128 v66, v[122:125] offset:59904
	global_load_dwordx4 v[144:147], v[78:79], off offset:1536
	global_load_dwordx4 v[122:125], v[80:81], off offset:1536
	ds_read_b128 v[86:89], v68 offset:96
	ds_read_b128 v[94:97], v1 offset:41568
	s_waitcnt lgkmcnt(1)
	v_mfma_f32_32x32x16_bf16 v[34:49], v[86:89], v[90:93], v[34:49]
	s_waitcnt lgkmcnt(0)
	v_mfma_f32_32x32x16_bf16 v[50:65], v[86:89], v[94:97], v[50:65]
	v_mfma_f32_32x32x16_bf16 v[2:17], v[98:101], v[90:93], v[2:17]
	v_mfma_f32_32x32x16_bf16 v[18:33], v[98:101], v[94:97], v[18:33]
	s_waitcnt vmcnt(7)
	ds_write_b128 v66, v[118:121] offset:64512
	s_waitcnt vmcnt(6)
	ds_write_b128 v69, v[114:117] offset:32256
	global_load_dwordx4 v[118:121], v[82:83], off offset:1536
	global_load_dwordx4 v[114:117], v[84:85], off offset:1536
	s_setprio 0
	s_waitcnt lgkmcnt(0)
	s_barrier
; #define MFMA(a, b, c) __builtin_amdgcn_mfma_f32_32x32x16_bf16((a), (b), (c), 0, 0, 0)
; template <int TM, int TN>
; DI void gemm_mainloop(const u16* __restrict__ A, long lda, const u16* __restrict__ Bt, long ldb, int K, char* smem,
;                       f32x16 (&acc)[TM][TN]) {
;     ...
;   GEMM_GLOAD(0)
;   __syncthreads();
;   GEMM_SSTORE(0)
;   if (nk > 1) GEMM_GLOAD(64)
;   __syncthreads();
;   for (int kt = 0; kt < nk; kt++) {
;     const int buf = kt & 1;
;     const u16* cA = sA + buf * BM * LD + (wm * 32 * TM + r) * LD + h * 8;
;     const u16* cB = sB + buf * BN * LD + (wn * 32 * TN + r) * LD + h * 8;
;     bf16x8 af[TM], bfr[TN];
; #pragma unroll
;     for (int tm = 0; tm < TM; tm++) af[tm] = *(const bf16x8*)(cA + tm * 32 * LD);
; #pragma unroll
;     for (int tn = 0; tn < TN; tn++) bfr[tn] = *(const bf16x8*)(cB + tn * 32 * LD);
;     if (kt + 1 < nk) GEMM_SSTORE(buf ^ 1)
;     __builtin_amdgcn_sched_barrier(0);
;     __builtin_amdgcn_s_setprio(1);
; #pragma unroll
;     for (int tm = 0; tm < TM; tm++)
; #pragma unroll
;       for (int tn = 0; tn < TN; tn++) acc[tm][tn] = MFMA(af[tm], bfr[tn], acc[tm][tn]);
; #pragma unroll
;     for (int tm = 0; tm < TM; tm++) af[tm] = *(const bf16x8*)(cA + tm * 32 * LD + 16);
; #pragma unroll
;     for (int tn = 0; tn < TN; tn++) bfr[tn] = *(const bf16x8*)(cB + tn * 32 * LD + 16);
; #pragma unroll
;     for (int tm = 0; tm < TM; tm++)
; #pragma unroll
;       for (int tn = 0; tn < TN; tn++) acc[tm][tn] = MFMA(af[tm], bfr[tn], acc[tm][tn]);
;     __builtin_amdgcn_sched_group_barrier(0x8, 4, 0);
;     if (kt + 2 < nk) GEMM_GLOAD((kt + 2) * 64)
; #pragma unroll
;     for (int ks = 2; ks < 4; ks++) {
; #pragma unroll
;       for (int tm = 0; tm < TM; tm++) af[tm] = *(const bf16x8*)(cA + tm * 32 * LD + ks * 16);
; #pragma unroll
;       for (int tn = 0; tn < TN; tn++) bfr[tn] = *(const bf16x8*)(cB + tn * 32 * LD + ks * 16);
; #pragma unroll
;       for (int tm = 0; tm < TM; tm++)
; #pragma unroll
;         for (int tn = 0; tn < TN; tn++) acc[tm][tn] = MFMA(af[tm], bfr[tn], acc[tm][tn]);
;     }
;     __builtin_amdgcn_s_setprio(0);
;     __syncthreads();
;   }
	ds_read_b128 v[94:97], v68 offset:18432
	ds_read_b128 v[98:101], v68 offset:23040
	ds_read_b128 v[126:129], v1 offset:55296
	ds_read_b128 v[130:133], v1 offset:59904
	s_setprio 1
	ds_read_b128 v[86:89], v68 offset:18464
	s_waitcnt lgkmcnt(2)
	v_mfma_f32_32x32x16_bf16 v[34:49], v[94:97], v[126:129], v[34:49]
	ds_read_b128 v[90:93], v1 offset:55328
	s_waitcnt lgkmcnt(2)
	v_mfma_f32_32x32x16_bf16 v[50:65], v[94:97], v[130:133], v[50:65]
	ds_read_b128 v[94:97], v1 offset:59936
	s_waitcnt lgkmcnt(1)
	v_mfma_f32_32x32x16_bf16 v[34:49], v[86:89], v[90:93], v[34:49]
	s_waitcnt lgkmcnt(0)
	v_mfma_f32_32x32x16_bf16 v[50:65], v[86:89], v[94:97], v[50:65]
	s_waitcnt vmcnt(7)
	ds_write_b128 v66, v[140:143]
	s_waitcnt vmcnt(6)
	ds_write_b128 v66, v[102:105] offset:4608
	global_load_dwordx4 v[140:143], v[72:73], off offset:1664
	global_load_dwordx4 v[102:105], v[70:71], off offset:1664
	ds_read_b128 v[86:89], v68 offset:23072
	v_mfma_f32_32x32x16_bf16 v[2:17], v[98:101], v[126:129], v[2:17]
	v_mfma_f32_32x32x16_bf16 v[18:33], v[98:101], v[130:133], v[18:33]
	ds_read_b128 v[98:101], v68 offset:23136
	s_waitcnt lgkmcnt(1)
	v_mfma_f32_32x32x16_bf16 v[2:17], v[86:89], v[90:93], v[2:17]
	ds_read_b128 v[90:93], v1 offset:55360
	v_mfma_f32_32x32x16_bf16 v[18:33], v[86:89], v[94:97], v[18:33]
	s_waitcnt vmcnt(7)
	ds_write_b128 v66, v[106:109] offset:9216
	s_waitcnt vmcnt(6)
	ds_write_b128 v66, v[110:113] offset:13824
	global_load_dwordx4 v[106:109], v[74:75], off offset:1664
	global_load_dwordx4 v[110:113], v[76:77], off offset:1664
	ds_read_b128 v[86:89], v68 offset:18496
	ds_read_b128 v[94:97], v1 offset:59968
	s_waitcnt lgkmcnt(1)
	v_mfma_f32_32x32x16_bf16 v[34:49], v[86:89], v[90:93], v[34:49]
	s_waitcnt lgkmcnt(0)
	v_mfma_f32_32x32x16_bf16 v[50:65], v[86:89], v[94:97], v[50:65]
	ds_read_b128 v[86:89], v68 offset:23104
	s_waitcnt lgkmcnt(0)
	v_mfma_f32_32x32x16_bf16 v[2:17], v[86:89], v[90:93], v[2:17]
	ds_read_b128 v[90:93], v1 offset:55392
	v_mfma_f32_32x32x16_bf16 v[18:33], v[86:89], v[94:97], v[18:33]
	s_waitcnt vmcnt(7)
	ds_write_b128 v66, v[144:147] offset:36864
	s_waitcnt vmcnt(6)
	ds_write_b128 v66, v[122:125] offset:41472
	global_load_dwordx4 v[144:147], v[78:79], off offset:1664
	global_load_dwordx4 v[122:125], v[80:81], off offset:1664
	ds_read_b128 v[86:89], v68 offset:18528
	ds_read_b128 v[94:97], v1 offset:60000
	s_waitcnt lgkmcnt(1)
	v_mfma_f32_32x32x16_bf16 v[34:49], v[86:89], v[90:93], v[34:49]
	s_waitcnt lgkmcnt(0)
	v_mfma_f32_32x32x16_bf16 v[50:65], v[86:89], v[94:97], v[50:65]
	v_mfma_f32_32x32x16_bf16 v[2:17], v[98:101], v[90:93], v[2:17]
	v_mfma_f32_32x32x16_bf16 v[18:33], v[98:101], v[94:97], v[18:33]
	s_waitcnt vmcnt(7)
	ds_write_b128 v66, v[118:121] offset:46080
	s_waitcnt vmcnt(6)
	ds_write_b128 v66, v[114:117] offset:50688
	global_load_dwordx4 v[118:121], v[82:83], off offset:1664
	global_load_dwordx4 v[114:117], v[84:85], off offset:1664
	s_setprio 0
	s_waitcnt lgkmcnt(0)
	s_barrier
	ds_read_b128 v[94:97], v68
	ds_read_b128 v[98:101], v68 offset:4608
	ds_read_b128 v[126:129], v1 offset:36864
	ds_read_b128 v[130:133], v1 offset:41472
	s_setprio 1
	ds_read_b128 v[86:89], v68 offset:32
	s_waitcnt lgkmcnt(2)
	v_mfma_f32_32x32x16_bf16 v[34:49], v[94:97], v[126:129], v[34:49]
	ds_read_b128 v[90:93], v1 offset:36896
	s_waitcnt lgkmcnt(2)
	v_mfma_f32_32x32x16_bf16 v[50:65], v[94:97], v[130:133], v[50:65]
	ds_read_b128 v[94:97], v1 offset:41504
	s_waitcnt lgkmcnt(1)
	v_mfma_f32_32x32x16_bf16 v[34:49], v[86:89], v[90:93], v[34:49]
	s_waitcnt lgkmcnt(0)
	v_mfma_f32_32x32x16_bf16 v[50:65], v[86:89], v[94:97], v[50:65]
	s_waitcnt vmcnt(7)
	ds_write_b128 v66, v[140:143] offset:18432
	s_waitcnt vmcnt(6)
	ds_write_b128 v66, v[102:105] offset:23040
	global_load_dwordx4 v[140:143], v[72:73], off offset:1792
	global_load_dwordx4 v[102:105], v[70:71], off offset:1792
	ds_read_b128 v[86:89], v68 offset:4640
	v_mfma_f32_32x32x16_bf16 v[2:17], v[98:101], v[126:129], v[2:17]
	v_mfma_f32_32x32x16_bf16 v[18:33], v[98:101], v[130:133], v[18:33]
	ds_read_b128 v[98:101], v68 offset:4704
	s_waitcnt lgkmcnt(1)
	v_mfma_f32_32x32x16_bf16 v[2:17], v[86:89], v[90:93], v[2:17]
	ds_read_b128 v[90:93], v1 offset:36928
	v_mfma_f32_32x32x16_bf16 v[18:33], v[86:89], v[94:97], v[18:33]
	s_waitcnt vmcnt(7)
	ds_write_b128 v66, v[106:109] offset:27648
	s_waitcnt vmcnt(6)
	ds_write_b128 v66, v[110:113] offset:32256
	global_load_dwordx4 v[106:109], v[74:75], off offset:1792
	global_load_dwordx4 v[110:113], v[76:77], off offset:1792
	ds_read_b128 v[86:89], v68 offset:64
	ds_read_b128 v[94:97], v1 offset:41536
	s_waitcnt lgkmcnt(1)
	v_mfma_f32_32x32x16_bf16 v[34:49], v[86:89], v[90:93], v[34:49]
	s_waitcnt lgkmcnt(0)
	v_mfma_f32_32x32x16_bf16 v[50:65], v[86:89], v[94:97], v[50:65]
	ds_read_b128 v[86:89], v68 offset:4672
	s_waitcnt lgkmcnt(0)
	v_mfma_f32_32x32x16_bf16 v[2:17], v[86:89], v[90:93], v[2:17]
	ds_read_b128 v[90:93], v1 offset:36960
	v_mfma_f32_32x32x16_bf16 v[18:33], v[86:89], v[94:97], v[18:33]
	s_waitcnt vmcnt(7)
	ds_write_b128 v66, v[144:147] offset:55296
	s_waitcnt vmcnt(6)
	ds_write_b128 v66, v[122:125] offset:59904
	global_load_dwordx4 v[144:147], v[78:79], off offset:1792
	global_load_dwordx4 v[122:125], v[80:81], off offset:1792
	ds_read_b128 v[86:89], v68 offset:96
	ds_read_b128 v[94:97], v1 offset:41568
	s_waitcnt lgkmcnt(1)
	v_mfma_f32_32x32x16_bf16 v[34:49], v[86:89], v[90:93], v[34:49]
	s_waitcnt lgkmcnt(0)
	v_mfma_f32_32x32x16_bf16 v[50:65], v[86:89], v[94:97], v[50:65]
	v_mfma_f32_32x32x16_bf16 v[2:17], v[98:101], v[90:93], v[2:17]
	v_mfma_f32_32x32x16_bf16 v[18:33], v[98:101], v[94:97], v[18:33]
	s_waitcnt vmcnt(7)
	ds_write_b128 v66, v[118:121] offset:64512
	s_waitcnt vmcnt(6)
	ds_write_b128 v69, v[114:117] offset:32256
	global_load_dwordx4 v[118:121], v[82:83], off offset:1792
	global_load_dwordx4 v[114:117], v[84:85], off offset:1792
	s_setprio 0
	s_waitcnt lgkmcnt(0)
	s_barrier
; #define MFMA(a, b, c) __builtin_amdgcn_mfma_f32_32x32x16_bf16((a), (b), (c), 0, 0, 0)
; template <int TM, int TN>
; DI void gemm_mainloop(const u16* __restrict__ A, long lda, const u16* __restrict__ Bt, long ldb, int K, char* smem,
;                       f32x16 (&acc)[TM][TN]) {
;     ...
;   GEMM_GLOAD(0)
;   __syncthreads();
;   GEMM_SSTORE(0)
;   if (nk > 1) GEMM_GLOAD(64)
;   __syncthreads();
;   for (int kt = 0; kt < nk; kt++) {
;     const int buf = kt & 1;
;     const u16* cA = sA + buf * BM * LD + (wm * 32 * TM + r) * LD + h * 8;
;     const u16* cB = sB + buf * BN * LD + (wn * 32 * TN + r) * LD + h * 8;
;     bf16x8 af[TM], bfr[TN];
; #pragma unroll
;     for (int tm = 0; tm < TM; tm++) af[tm] = *(const bf16x8*)(cA + tm * 32 * LD);
; #pragma unroll
;     for (int tn = 0; tn < TN; tn++) bfr[tn] = *(const bf16x8*)(cB + tn * 32 * LD);
;     if (kt + 1 < nk) GEMM_SSTORE(buf ^ 1)
;     __builtin_amdgcn_sched_barrier(0);
;     __builtin_amdgcn_s_setprio(1);
; #pragma unroll
;     for (int tm = 0; tm < TM; tm++)
; #pragma unroll
;       for (int tn = 0; tn < TN; tn++) acc[tm][tn] = MFMA(af[tm], bfr[tn], acc[tm][tn]);
; #pragma unroll
;     for (int tm = 0; tm < TM; tm++) af[tm] = *(const bf16x8*)(cA + tm * 32 * LD + 16);
; #pragma unroll
;     for (int tn = 0; tn < TN; tn++) bfr[tn] = *(const bf16x8*)(cB + tn * 32 * LD + 16);
; #pragma unroll
;     for (int tm = 0; tm < TM; tm++)
; #pragma unroll
;       for (int tn = 0; tn < TN; tn++) acc[tm][tn] = MFMA(af[tm], bfr[tn], acc[tm][tn]);
;     __builtin_amdgcn_sched_group_barrier(0x8, 4, 0);
;     if (kt + 2 < nk) GEMM_GLOAD((kt + 2) * 64)
; #pragma unroll
;     for (int ks = 2; ks < 4; ks++) {
; #pragma unroll
;       for (int tm = 0; tm < TM; tm++) af[tm] = *(const bf16x8*)(cA + tm * 32 * LD + ks * 16);
; #pragma unroll
;       for (int tn = 0; tn < TN; tn++) bfr[tn] = *(const bf16x8*)(cB + tn * 32 * LD + ks * 16);
; #pragma unroll
;       for (int tm = 0; tm < TM; tm++)
; #pragma unroll
;         for (int tn = 0; tn < TN; tn++) acc[tm][tn] = MFMA(af[tm], bfr[tn], acc[tm][tn]);
;     }
;     __builtin_amdgcn_s_setprio(0);
;     __syncthreads();
;   }
	ds_read_b128 v[94:97], v68 offset:18432
	ds_read_b128 v[98:101], v68 offset:23040
	ds_read_b128 v[126:129], v1 offset:55296
	ds_read_b128 v[130:133], v1 offset:59904
	s_setprio 1
	ds_read_b128 v[86:89], v68 offset:18464
	s_waitcnt lgkmcnt(2)
	v_mfma_f32_32x32x16_bf16 v[34:49], v[94:97], v[126:129], v[34:49]
	ds_read_b128 v[90:93], v1 offset:55328
	s_waitcnt lgkmcnt(2)
	v_mfma_f32_32x32x16_bf16 v[50:65], v[94:97], v[130:133], v[50:65]
	ds_read_b128 v[94:97], v1 offset:59936
	s_waitcnt lgkmcnt(1)
	v_mfma_f32_32x32x16_bf16 v[34:49], v[86:89], v[90:93], v[34:49]
	s_waitcnt lgkmcnt(0)
	v_mfma_f32_32x32x16_bf16 v[50:65], v[86:89], v[94:97], v[50:65]
	s_waitcnt vmcnt(7)
	ds_write_b128 v66, v[140:143]
	s_waitcnt vmcnt(6)
	ds_write_b128 v66, v[102:105] offset:4608
	global_load_dwordx4 v[140:143], v[72:73], off offset:1920
	global_load_dwordx4 v[102:105], v[70:71], off offset:1920
	ds_read_b128 v[86:89], v68 offset:23072
	v_mfma_f32_32x32x16_bf16 v[2:17], v[98:101], v[126:129], v[2:17]
	v_mfma_f32_32x32x16_bf16 v[18:33], v[98:101], v[130:133], v[18:33]
	ds_read_b128 v[98:101], v68 offset:23136
	s_waitcnt lgkmcnt(1)
	v_mfma_f32_32x32x16_bf16 v[2:17], v[86:89], v[90:93], v[2:17]
	ds_read_b128 v[90:93], v1 offset:55360
	v_mfma_f32_32x32x16_bf16 v[18:33], v[86:89], v[94:97], v[18:33]
	s_waitcnt vmcnt(7)
	ds_write_b128 v66, v[106:109] offset:9216
	s_waitcnt vmcnt(6)
	ds_write_b128 v66, v[110:113] offset:13824
	global_load_dwordx4 v[106:109], v[74:75], off offset:1920
	global_load_dwordx4 v[110:113], v[76:77], off offset:1920
	ds_read_b128 v[86:89], v68 offset:18496
	ds_read_b128 v[94:97], v1 offset:59968
	s_waitcnt lgkmcnt(1)
	v_mfma_f32_32x32x16_bf16 v[34:49], v[86:89], v[90:93], v[34:49]
	s_waitcnt lgkmcnt(0)
	v_mfma_f32_32x32x16_bf16 v[50:65], v[86:89], v[94:97], v[50:65]
	ds_read_b128 v[86:89], v68 offset:23104
	s_waitcnt lgkmcnt(0)
	v_mfma_f32_32x32x16_bf16 v[2:17], v[86:89], v[90:93], v[2:17]
	ds_read_b128 v[90:93], v1 offset:55392
	v_mfma_f32_32x32x16_bf16 v[18:33], v[86:89], v[94:97], v[18:33]
	s_waitcnt vmcnt(7)
	ds_write_b128 v66, v[144:147] offset:36864
	s_waitcnt vmcnt(6)
	ds_write_b128 v66, v[122:125] offset:41472
	global_load_dwordx4 v[144:147], v[78:79], off offset:1920
	global_load_dwordx4 v[122:125], v[80:81], off offset:1920
	ds_read_b128 v[86:89], v68 offset:18528
	ds_read_b128 v[94:97], v1 offset:60000
	s_waitcnt lgkmcnt(1)
	v_mfma_f32_32x32x16_bf16 v[34:49], v[86:89], v[90:93], v[34:49]
	s_waitcnt lgkmcnt(0)
	v_mfma_f32_32x32x16_bf16 v[50:65], v[86:89], v[94:97], v[50:65]
	s_nop 0
	v_mfma_f32_32x32x16_bf16 v[2:17], v[98:101], v[90:93], v[2:17]
	v_mfma_f32_32x32x16_bf16 v[18:33], v[98:101], v[94:97], v[18:33]
	s_waitcnt vmcnt(7)
	ds_write_b128 v66, v[118:121] offset:46080
	s_waitcnt vmcnt(6)
	ds_write_b128 v66, v[114:117] offset:50688
	global_load_dwordx4 v[118:121], v[82:83], off offset:1920
	global_load_dwordx4 v[114:117], v[84:85], off offset:1920
	s_setprio 0
	s_waitcnt lgkmcnt(0)
	s_barrier
	ds_read_b128 v[74:77], v68
	ds_read_b128 v[78:81], v68 offset:4608
	ds_read_b128 v[82:85], v1 offset:36864
	ds_read_b128 v[90:93], v1 offset:41472
	s_setprio 1
	ds_read_b128 v[70:73], v68 offset:32
	s_waitcnt lgkmcnt(2)
	v_mfma_f32_32x32x16_bf16 v[34:49], v[74:77], v[82:85], v[34:49]
	s_waitcnt lgkmcnt(1)
	v_mfma_f32_32x32x16_bf16 v[50:65], v[74:77], v[90:93], v[50:65]
	ds_read_b128 v[74:77], v1 offset:36896
	v_mfma_f32_32x32x16_bf16 v[2:17], v[78:81], v[82:85], v[2:17]
	v_mfma_f32_32x32x16_bf16 v[18:33], v[78:81], v[90:93], v[18:33]
	s_waitcnt vmcnt(7)
	ds_write_b128 v66, v[140:143] offset:18432
	s_waitcnt vmcnt(6)
	ds_write_b128 v66, v[102:105] offset:23040
	ds_read_b128 v[78:81], v1 offset:41504
	s_waitcnt lgkmcnt(3)
	v_mfma_f32_32x32x16_bf16 v[34:49], v[70:73], v[74:77], v[34:49]
	s_waitcnt lgkmcnt(0)
	v_mfma_f32_32x32x16_bf16 v[50:65], v[70:73], v[78:81], v[50:65]
	ds_read_b128 v[70:73], v68 offset:4640
	s_waitcnt lgkmcnt(0)
	v_mfma_f32_32x32x16_bf16 v[2:17], v[70:73], v[74:77], v[2:17]
	ds_read_b128 v[74:77], v1 offset:36928
	v_mfma_f32_32x32x16_bf16 v[18:33], v[70:73], v[78:81], v[18:33]
	s_waitcnt vmcnt(5)
	ds_write_b128 v66, v[106:109] offset:27648
	s_waitcnt vmcnt(4)
	ds_write_b128 v66, v[110:113] offset:32256
	ds_read_b128 v[70:73], v68 offset:64
	ds_read_b128 v[78:81], v1 offset:41536
	s_waitcnt lgkmcnt(1)
	v_mfma_f32_32x32x16_bf16 v[34:49], v[70:73], v[74:77], v[34:49]
	s_waitcnt lgkmcnt(0)
	v_mfma_f32_32x32x16_bf16 v[50:65], v[70:73], v[78:81], v[50:65]
	ds_read_b128 v[70:73], v68 offset:4672
	s_waitcnt lgkmcnt(0)
	v_mfma_f32_32x32x16_bf16 v[2:17], v[70:73], v[74:77], v[2:17]
	ds_read_b128 v[74:77], v1 offset:36960
	v_mfma_f32_32x32x16_bf16 v[18:33], v[70:73], v[78:81], v[18:33]
	s_waitcnt vmcnt(3)
	ds_write_b128 v66, v[144:147] offset:55296
	s_waitcnt vmcnt(2)
	ds_write_b128 v66, v[122:125] offset:59904
	ds_read_b128 v[70:73], v68 offset:96
	ds_read_b128 v[78:81], v1 offset:41568
	s_waitcnt lgkmcnt(1)
	v_mfma_f32_32x32x16_bf16 v[34:49], v[70:73], v[74:77], v[34:49]
	s_waitcnt lgkmcnt(0)
	v_mfma_f32_32x32x16_bf16 v[50:65], v[70:73], v[78:81], v[50:65]
	ds_read_b128 v[70:73], v68 offset:4704
	s_waitcnt lgkmcnt(0)
	v_mfma_f32_32x32x16_bf16 v[2:17], v[70:73], v[74:77], v[2:17]
	v_mfma_f32_32x32x16_bf16 v[18:33], v[70:73], v[78:81], v[18:33]
	s_waitcnt vmcnt(1)
	ds_write_b128 v66, v[118:121] offset:64512
	s_waitcnt vmcnt(0)
	ds_write_b128 v69, v[114:117] offset:32256
	s_setprio 0
	s_waitcnt lgkmcnt(0)
	s_barrier
; #define MFMA(a, b, c) __builtin_amdgcn_mfma_f32_32x32x16_bf16((a), (b), (c), 0, 0, 0)
; DI unsigned pk2(float a, float b) { fv2 v = {a, b}; bfv2 r = __builtin_convertvector(v, bfv2); return __builtin_bit_cast(unsigned, r); }
; DI int crow(int i, int h) { return (i & 3) + 8 * (i >> 2) + 4 * h; }
; template <int TM, int TN>
; DI void gemm_mainloop(const u16* __restrict__ A, long lda, const u16* __restrict__ Bt, long ldb, int K, char* smem,
;                       f32x16 (&acc)[TM][TN]) {
;     ...
;     for (int ks = 2; ks < 4; ks++) {
; #pragma unroll
;       for (int tm = 0; tm < TM; tm++) af[tm] = *(const bf16x8*)(cA + tm * 32 * LD + ks * 16);
; #pragma unroll
;       for (int tn = 0; tn < TN; tn++) bfr[tn] = *(const bf16x8*)(cB + tn * 32 * LD + ks * 16);
; #pragma unroll
;       for (int tm = 0; tm < TM; tm++)
; #pragma unroll
;         for (int tn = 0; tn < TN; tn++) acc[tm][tn] = MFMA(af[tm], bfr[tn], acc[tm][tn]);
;     }
;     __builtin_amdgcn_s_setprio(0);
;     __syncthreads();
; template <int TM, int TN, class Epi>
; DI void gemm_tile(const u16* A, long lda, const u16* Bt, long ldb, int K, int m0, int n0, char* smem, const Epi& epi) {
;     ...
; #pragma unroll
;   for (int tm = 0; tm < TM; tm++)
; #pragma unroll
;     for (int tn = 0; tn < TN; tn++)
; #pragma unroll
;       for (int i = 0; i < 16; i++)
;         Ct[(wm * 32 * TM + tm * 32 + crow(i, h)) * LDC + wn * 32 * TN + tn * 32 + r] = acc[tm][tn][i];
;   __syncthreads();
;   epi(Ct, LDC, m0, n0, tid, BM);
;   __syncthreads();
;   (void)BM;
; }
;   DI void operator()(const float* Ct, int ldc, int m0, int n0, int tid, int bm) const {
; #pragma unroll 4
;     for (int it = 0; it < bm / 16; it++) {
;       int id = tid + 256 * it; int row = id >> 4, c8 = (id & 15) * 8;
;       int n = n0 + c8;
;       if (n < nmax) {
;         const float* c = Ct + row * ldc + c8;
;         float4 a = *(const float4*)c, b = *(const float4*)(c + 4);
;         uint4 v; v.x = pk2(a.x, a.y); v.y = pk2(a.z, a.w); v.z = pk2(b.x, b.y); v.w = pk2(b.z, b.w);
;         *(uint4*)(out + (long)(m0 + row) * ldo + n) = v;
;         if (gates != nullptr && n == 1952) {
	ds_read_b128 v[70:73], v68 offset:18432
	ds_read_b128 v[74:77], v68 offset:23040
	ds_read_b128 v[78:81], v1 offset:55296
	ds_read_b128 v[82:85], v1 offset:59904
	s_setprio 1
	s_waitcnt lgkmcnt(1)
	v_mfma_f32_32x32x16_bf16 v[34:49], v[70:73], v[78:81], v[34:49]
	s_waitcnt lgkmcnt(0)
	v_mfma_f32_32x32x16_bf16 v[50:65], v[70:73], v[82:85], v[50:65]
	ds_read_b128 v[70:73], v68 offset:18464
	v_mfma_f32_32x32x16_bf16 v[2:17], v[74:77], v[78:81], v[2:17]
	ds_read_b128 v[78:81], v1 offset:59936
	v_mfma_f32_32x32x16_bf16 v[18:33], v[74:77], v[82:85], v[18:33]
	ds_read_b128 v[74:77], v1 offset:55328
	s_waitcnt lgkmcnt(0)
	v_mfma_f32_32x32x16_bf16 v[34:49], v[70:73], v[74:77], v[34:49]
	v_mfma_f32_32x32x16_bf16 v[50:65], v[70:73], v[78:81], v[50:65]
	ds_read_b128 v[70:73], v68 offset:23072
	s_waitcnt lgkmcnt(0)
	v_mfma_f32_32x32x16_bf16 v[2:17], v[70:73], v[74:77], v[2:17]
	ds_read_b128 v[74:77], v1 offset:55360
	v_mfma_f32_32x32x16_bf16 v[18:33], v[70:73], v[78:81], v[18:33]
	ds_read_b128 v[70:73], v68 offset:18496
	ds_read_b128 v[78:81], v1 offset:59968
	s_waitcnt lgkmcnt(1)
	v_mfma_f32_32x32x16_bf16 v[34:49], v[70:73], v[74:77], v[34:49]
	s_waitcnt lgkmcnt(0)
	v_mfma_f32_32x32x16_bf16 v[50:65], v[70:73], v[78:81], v[50:65]
	ds_read_b128 v[70:73], v68 offset:23104
	s_waitcnt lgkmcnt(0)
	v_mfma_f32_32x32x16_bf16 v[2:17], v[70:73], v[74:77], v[2:17]
	ds_read_b128 v[74:77], v1 offset:55392
	v_mfma_f32_32x32x16_bf16 v[18:33], v[70:73], v[78:81], v[18:33]
	ds_read_b128 v[70:73], v68 offset:18528
	ds_read_b128 v[78:81], v1 offset:60000
	s_waitcnt lgkmcnt(1)
	v_mfma_f32_32x32x16_bf16 v[34:49], v[70:73], v[74:77], v[34:49]
	s_waitcnt lgkmcnt(0)
	v_mfma_f32_32x32x16_bf16 v[50:65], v[70:73], v[78:81], v[50:65]
	ds_read_b128 v[68:71], v68 offset:23136
	s_waitcnt lgkmcnt(0)
	v_mfma_f32_32x32x16_bf16 v[2:17], v[68:71], v[74:77], v[2:17]
	v_mfma_f32_32x32x16_bf16 v[18:33], v[68:71], v[78:81], v[18:33]
	s_setprio 0
	v_mov_b32_e32 v1, v0
	s_barrier
	s_mov_b32 s4, 0
	v_lshrrev_b32_e32 v66, 1, v1
	v_and_b32_e32 v66, 0xfffffc0, v66
	v_lshrrev_b32_e32 v68, 3, v1
	v_and_or_b32 v66, v68, 4, v66
	v_and_b32_e32 v68, 0x5f, v1
	v_mul_lo_u32 v66, v66, s30
	v_lshl_add_u32 v66, v68, 2, v66
	ds_write2_b32 v66, v34, v50 offset1:32
	v_add_u32_e32 v34, 0x400, v66
	ds_write2_b32 v34, v36, v52 offset0:8 offset1:40
	ds_write2_b32 v34, v37, v53 offset0:140 offset1:172
	v_add_u32_e32 v34, 0x1000, v66
	ds_write2_b32 v34, v38, v54 offset0:32 offset1:64
	ds_write2_b32 v34, v39, v55 offset0:164 offset1:196
	v_add_u32_e32 v34, 0x1400, v66
	ds_write2_b32 v34, v40, v56 offset0:40 offset1:72
	ds_write2_b32 v34, v41, v57 offset0:172 offset1:204
	v_add_u32_e32 v34, 0x2000, v66
	ds_write2_b32 v34, v42, v58 offset0:64 offset1:96
	ds_write2_b32 v34, v43, v59 offset0:196 offset1:228
	v_add_u32_e32 v34, 0x2400, v66
	ds_write2_b32 v34, v44, v60 offset0:72 offset1:104
	ds_write2_b32 v34, v45, v61 offset0:204 offset1:236
	v_add_u32_e32 v34, 0x3000, v66
	ds_write2_b32 v34, v46, v62 offset0:96 offset1:128
	v_add_u32_e32 v34, 0x3200, v66
	ds_write2_b32 v34, v47, v63 offset0:100 offset1:132
	v_add_u32_e32 v34, 0x3400, v66
	ds_write2_b32 v34, v48, v64 offset0:104 offset1:136
	v_add_u32_e32 v34, 0x3600, v66
	ds_write2_b32 v34, v49, v65 offset0:108 offset1:140
	v_add_u32_e32 v34, 0x4000, v66
	ds_write2_b32 v34, v2, v18 offset0:128 offset1:160
	v_add_u32_e32 v2, 0x4400, v66
	ds_write2_b32 v2, v3, v19 offset0:4 offset1:36
	ds_write2_b32 v2, v4, v20 offset0:136 offset1:168
	v_add_u32_e32 v2, 0x4800, v66
	ds_write2_b32 v2, v5, v21 offset0:12 offset1:44
	v_add_u32_e32 v2, 0x5000, v66
	ds_write2_b32 v2, v6, v22 offset0:160 offset1:192
	v_add_u32_e32 v2, 0x5400, v66
	ds_write2_b32 v2, v7, v23 offset0:36 offset1:68
	ds_write2_b32 v2, v8, v24 offset0:168 offset1:200
	v_add_u32_e32 v2, 0x5800, v66
	ds_write2_b32 v2, v9, v25 offset0:44 offset1:76
	v_add_u32_e32 v2, 0x6000, v66
	ds_write2_b32 v2, v10, v26 offset0:192 offset1:224
	v_add_u32_e32 v2, 0x6400, v66
	ds_write2_b32 v2, v11, v27 offset0:68 offset1:100
	ds_write2_b32 v2, v12, v28 offset0:200 offset1:232
	v_add_u32_e32 v2, 0x6800, v66
	ds_write2_b32 v2, v13, v29 offset0:76 offset1:108
	v_add_u32_e32 v2, 0x7200, v66
	ds_write2_b32 v2, v14, v30 offset0:96 offset1:128
	v_add_u32_e32 v2, 0x7400, v66
	ds_write2_b32 v2, v15, v31 offset0:100 offset1:132
	v_add_u32_e32 v2, 0x7600, v66
	ds_write2_b32 v2, v16, v32 offset0:104 offset1:136
	v_add_u32_e32 v2, 0x7800, v66
	ds_write2_b32 v2, v17, v33 offset0:108 offset1:140
	v_lshlrev_b32_e32 v2, 3, v1
	v_and_b32_e32 v3, 0x78, v2
	v_or_b32_e32 v2, s6, v3
	v_lshlrev_b32_e32 v10, 2, v3
	v_ashrrev_i32_e32 v3, 31, v2
	v_cmp_eq_u32_e32 vcc, s31, v2
	v_cmp_gt_i32_e64 s[6:7], s36, v2
	v_lshl_add_u64 v[12:13], v[2:3], 1, s[14:15]
	ds_write2_b32 v66, v35, v51 offset0:132 offset1:164
	s_waitcnt lgkmcnt(0)
	s_barrier
	s_branch .LBB0_1555

; #define MFMA(a, b, c) __builtin_amdgcn_mfma_f32_32x32x16_bf16((a), (b), (c), 0, 0, 0)
; template <int TM, int TN>
; DI void gemm_mainloop(const u16* __restrict__ A, long lda, const u16* __restrict__ Bt, long ldb, int K, char* smem,
;                       f32x16 (&acc)[TM][TN]) {
;     ...
;   const int nk = K / 64;
;   const int lrow = tid >> 3, lch = (tid & 7) * 8;
;   const u16* gA = A + (long)lrow * lda + lch;
;   const u16* gB = Bt + (long)lrow * ldb + lch;
;   const int soff = lrow * LD + lch;
;     ...
;   GEMM_GLOAD(0)
;   __syncthreads();
;   GEMM_SSTORE(0)
;   if (nk > 1) GEMM_GLOAD(64)
;   __syncthreads();
;   for (int kt = 0; kt < nk; kt++) {
;     const int buf = kt & 1;
;     const u16* cA = sA + buf * BM * LD + (wm * 32 * TM + r) * LD + h * 8;
;     const u16* cB = sB + buf * BN * LD + (wn * 32 * TN + r) * LD + h * 8;
;     bf16x8 af[TM], bfr[TN];
; #pragma unroll
;     for (int tm = 0; tm < TM; tm++) af[tm] = *(const bf16x8*)(cA + tm * 32 * LD);
; #pragma unroll
;     for (int tn = 0; tn < TN; tn++) bfr[tn] = *(const bf16x8*)(cB + tn * 32 * LD);
;     if (kt + 1 < nk) GEMM_SSTORE(buf ^ 1)
;     __builtin_amdgcn_sched_barrier(0);
;     __builtin_amdgcn_s_setprio(1);
; #pragma unroll
;     for (int tm = 0; tm < TM; tm++)
; #pragma unroll
;       for (int tn = 0; tn < TN; tn++) acc[tm][tn] = MFMA(af[tm], bfr[tn], acc[tm][tn]);
; #pragma unroll
;     for (int tm = 0; tm < TM; tm++) af[tm] = *(const bf16x8*)(cA + tm * 32 * LD + 16);
; #pragma unroll
;     for (int tn = 0; tn < TN; tn++) bfr[tn] = *(const bf16x8*)(cB + tn * 32 * LD + 16);
; #pragma unroll
;     for (int tm = 0; tm < TM; tm++)
; #pragma unroll
;       for (int tn = 0; tn < TN; tn++) acc[tm][tn] = MFMA(af[tm], bfr[tn], acc[tm][tn]);
;     __builtin_amdgcn_sched_group_barrier(0x8, 4, 0);
;     if (kt + 2 < nk) GEMM_GLOAD((kt + 2) * 64)
; #pragma unroll
;     for (int ks = 2; ks < 4; ks++) {
; #pragma unroll
;       for (int tm = 0; tm < TM; tm++) af[tm] = *(const bf16x8*)(cA + tm * 32 * LD + ks * 16);
; #pragma unroll
;       for (int tn = 0; tn < TN; tn++) bfr[tn] = *(const bf16x8*)(cB + tn * 32 * LD + ks * 16);
; #pragma unroll
;       for (int tm = 0; tm < TM; tm++)
; #pragma unroll
;         for (int tn = 0; tn < TN; tn++) acc[tm][tn] = MFMA(af[tm], bfr[tn], acc[tm][tn]);
;     }
;     __builtin_amdgcn_s_setprio(0);
;     __syncthreads();
;   }
.LBB0_2474:
	s_lshl_b32 s25, s24, 10
	s_add_i32 s25, s25, s10
	s_mul_i32 s6, s25, 0x880
	s_mul_hi_i32 s7, s25, 0x880
	s_add_u32 s6, s4, s6
	v_mov_b32_e32 v1, v0
	s_addc_u32 s7, s5, s7
	s_nop 0
	v_lshlrev_b32_e32 v2, 3, v1
	v_ashrrev_i32_e32 v70, 3, v1
	v_and_b32_e32 v71, 56, v2
	v_mov_b64_e32 v[2:3], s[6:7]
	v_mad_i64_i32 v[2:3], s[6:7], v70, s15, v[2:3]
	v_lshlrev_b32_e32 v66, 1, v71
	v_lshl_add_u64 v[74:75], v[2:3], 0, v[66:67]
	v_add_co_u32_e32 v72, vcc, s17, v74
	v_mad_i64_i32 v[10:11], s[6:7], v70, s15, v[68:69]
	s_nop 0
	v_addc_co_u32_e32 v73, vcc, 0, v75, vcc
	v_add_co_u32_e32 v76, vcc, s18, v74
	v_lshl_add_u64 v[78:79], v[10:11], 0, v[66:67]
	s_nop 0
	v_addc_co_u32_e32 v77, vcc, 0, v75, vcc
	v_add_co_u32_e32 v80, vcc, s17, v78
	global_load_dwordx4 v[2:5], v[74:75], off
	s_nop 0
	v_addc_co_u32_e32 v81, vcc, 0, v79, vcc
	v_add_co_u32_e32 v82, vcc, s18, v78
	global_load_dwordx4 v[6:9], v[72:73], off
	s_nop 0
	v_addc_co_u32_e32 v83, vcc, 0, v79, vcc
	v_add_co_u32_e32 v84, vcc, s19, v78
	global_load_dwordx4 v[10:13], v[78:79], off
	s_nop 0
	v_addc_co_u32_e32 v85, vcc, 0, v79, vcc
	v_add_co_u32_e32 v86, vcc, s19, v74
	global_load_dwordx4 v[14:17], v[80:81], off
	s_nop 0
	v_addc_co_u32_e32 v87, vcc, 0, v75, vcc
	global_load_dwordx4 v[18:21], v[82:83], off
	global_load_dwordx4 v[22:25], v[84:85], off
	global_load_dwordx4 v[26:29], v[76:77], off
	global_load_dwordx4 v[30:33], v[86:87], off
	s_barrier
	global_load_dwordx4 v[34:37], v[74:75], off offset:128
	global_load_dwordx4 v[38:41], v[72:73], off offset:128
	global_load_dwordx4 v[42:45], v[76:77], off offset:128
	global_load_dwordx4 v[46:49], v[86:87], off offset:128
	global_load_dwordx4 v[50:53], v[78:79], off offset:128
	global_load_dwordx4 v[54:57], v[80:81], off offset:128
	global_load_dwordx4 v[58:61], v[82:83], off offset:128
	global_load_dwordx4 v[62:65], v[84:85], off offset:128
	v_and_b32_e32 v66, 31, v1
	v_lshrrev_b32_e32 v88, 1, v1
	v_mul_lo_u32 v70, v70, s16
	v_and_or_b32 v89, v88, s20, v66
	v_and_b32_e32 v88, 16, v88
	v_and_b32_e32 v1, 0x5f, v1
	v_add_lshl_u32 v66, v70, v71, 1
	v_mad_u64_u32 v[70:71], s[6:7], v89, s21, v[88:89]
	v_mad_u32_u24 v1, v1, s21, v88
	v_add_u32_e32 v71, 0x9000, v66
	s_waitcnt vmcnt(15)
	ds_write_b128 v66, v[2:5]
	s_waitcnt vmcnt(14)
	ds_write_b128 v66, v[6:9] offset:4608
	s_waitcnt vmcnt(13)
	ds_write_b128 v66, v[10:13] offset:36864
	s_waitcnt vmcnt(12)
	ds_write_b128 v66, v[14:17] offset:41472
	s_waitcnt vmcnt(11)
	ds_write_b128 v66, v[18:21] offset:46080
	s_waitcnt vmcnt(10)
	ds_write_b128 v66, v[22:25] offset:50688
	s_waitcnt vmcnt(9)
	ds_write_b128 v66, v[26:29] offset:9216
	s_waitcnt vmcnt(8)
	ds_write_b128 v66, v[30:33] offset:13824
	s_waitcnt lgkmcnt(0)
	s_barrier
	ds_read_b128 v[2:5], v70
	ds_read_b128 v[18:21], v70 offset:4608
	ds_read_b128 v[6:9], v1 offset:36864
	ds_read_b128 v[22:25], v1 offset:41472
	s_waitcnt vmcnt(7)
	ds_write_b128 v66, v[34:37] offset:18432
	s_waitcnt vmcnt(6)
	ds_write_b128 v66, v[38:41] offset:23040
	s_waitcnt vmcnt(5)
	ds_write_b128 v66, v[42:45] offset:27648
	s_waitcnt vmcnt(4)
	ds_write_b128 v66, v[46:49] offset:32256
	s_waitcnt vmcnt(3)
	ds_write_b128 v66, v[50:53] offset:55296
	s_waitcnt vmcnt(2)
	ds_write_b128 v66, v[54:57] offset:59904
	s_waitcnt vmcnt(1)
	ds_write_b128 v66, v[58:61] offset:64512
	s_waitcnt vmcnt(0)
	ds_write_b128 v71, v[62:65] offset:32256
	s_setprio 1
	ds_read_b128 v[88:91], v70 offset:32
	s_waitcnt lgkmcnt(10)
	v_mfma_f32_32x32x16_bf16 v[34:49], v[2:5], v[6:9], 0
	ds_read_b128 v[92:95], v1 offset:36896
	ds_read_b128 v[96:99], v1 offset:41504
	ds_read_b128 v[100:103], v70 offset:4704
	global_load_dwordx4 v[104:107], v[72:73], off offset:256
	global_load_dwordx4 v[108:111], v[76:77], off offset:256
	global_load_dwordx4 v[112:115], v[86:87], off offset:256
	global_load_dwordx4 v[116:119], v[84:85], off offset:256
	s_waitcnt lgkmcnt(12)
	v_mfma_f32_32x32x16_bf16 v[50:65], v[2:5], v[22:25], 0
	global_load_dwordx4 v[120:123], v[82:83], off offset:256
	global_load_dwordx4 v[124:127], v[80:81], off offset:256
	global_load_dwordx4 v[140:143], v[74:75], off offset:256
	global_load_dwordx4 v[144:147], v[78:79], off offset:256
	s_waitcnt lgkmcnt(2)
	v_mfma_f32_32x32x16_bf16 v[34:49], v[88:91], v[92:95], v[34:49]
	s_waitcnt lgkmcnt(1)
	v_mfma_f32_32x32x16_bf16 v[50:65], v[88:91], v[96:99], v[50:65]
	ds_read_b128 v[88:91], v70 offset:4640
	v_mfma_f32_32x32x16_bf16 v[2:17], v[18:21], v[6:9], 0
	v_mfma_f32_32x32x16_bf16 v[18:33], v[18:21], v[22:25], 0
	s_waitcnt lgkmcnt(0)
	v_mfma_f32_32x32x16_bf16 v[2:17], v[88:91], v[92:95], v[2:17]
	ds_read_b128 v[92:95], v1 offset:36928
	v_mfma_f32_32x32x16_bf16 v[18:33], v[88:91], v[96:99], v[18:33]
	ds_read_b128 v[88:91], v70 offset:64
	ds_read_b128 v[96:99], v1 offset:41536
	s_waitcnt lgkmcnt(1)
	v_mfma_f32_32x32x16_bf16 v[34:49], v[88:91], v[92:95], v[34:49]
	s_waitcnt lgkmcnt(0)
	v_mfma_f32_32x32x16_bf16 v[50:65], v[88:91], v[96:99], v[50:65]
	ds_read_b128 v[88:91], v70 offset:4672
	s_waitcnt lgkmcnt(0)
	v_mfma_f32_32x32x16_bf16 v[2:17], v[88:91], v[92:95], v[2:17]
	ds_read_b128 v[92:95], v1 offset:36960
	v_mfma_f32_32x32x16_bf16 v[18:33], v[88:91], v[96:99], v[18:33]
	ds_read_b128 v[88:91], v70 offset:96
	ds_read_b128 v[96:99], v1 offset:41568
	s_waitcnt lgkmcnt(1)
	v_mfma_f32_32x32x16_bf16 v[34:49], v[88:91], v[92:95], v[34:49]
	s_waitcnt lgkmcnt(0)
	v_mfma_f32_32x32x16_bf16 v[50:65], v[88:91], v[96:99], v[50:65]
	v_mfma_f32_32x32x16_bf16 v[2:17], v[100:103], v[92:95], v[2:17]
	v_mfma_f32_32x32x16_bf16 v[18:33], v[100:103], v[96:99], v[18:33]
	s_setprio 0
	s_barrier
; #define MFMA(a, b, c) __builtin_amdgcn_mfma_f32_32x32x16_bf16((a), (b), (c), 0, 0, 0)
; template <int TM, int TN>
; DI void gemm_mainloop(const u16* __restrict__ A, long lda, const u16* __restrict__ Bt, long ldb, int K, char* smem,
;                       f32x16 (&acc)[TM][TN]) {
;     ...
;   GEMM_GLOAD(0)
;   __syncthreads();
;   GEMM_SSTORE(0)
;   if (nk > 1) GEMM_GLOAD(64)
;   __syncthreads();
;   for (int kt = 0; kt < nk; kt++) {
;     const int buf = kt & 1;
;     const u16* cA = sA + buf * BM * LD + (wm * 32 * TM + r) * LD + h * 8;
;     const u16* cB = sB + buf * BN * LD + (wn * 32 * TN + r) * LD + h * 8;
;     bf16x8 af[TM], bfr[TN];
; #pragma unroll
;     for (int tm = 0; tm < TM; tm++) af[tm] = *(const bf16x8*)(cA + tm * 32 * LD);
; #pragma unroll
;     for (int tn = 0; tn < TN; tn++) bfr[tn] = *(const bf16x8*)(cB + tn * 32 * LD);
;     if (kt + 1 < nk) GEMM_SSTORE(buf ^ 1)
;     __builtin_amdgcn_sched_barrier(0);
;     __builtin_amdgcn_s_setprio(1);
; #pragma unroll
;     for (int tm = 0; tm < TM; tm++)
; #pragma unroll
;       for (int tn = 0; tn < TN; tn++) acc[tm][tn] = MFMA(af[tm], bfr[tn], acc[tm][tn]);
; #pragma unroll
;     for (int tm = 0; tm < TM; tm++) af[tm] = *(const bf16x8*)(cA + tm * 32 * LD + 16);
; #pragma unroll
;     for (int tn = 0; tn < TN; tn++) bfr[tn] = *(const bf16x8*)(cB + tn * 32 * LD + 16);
; #pragma unroll
;     for (int tm = 0; tm < TM; tm++)
; #pragma unroll
;       for (int tn = 0; tn < TN; tn++) acc[tm][tn] = MFMA(af[tm], bfr[tn], acc[tm][tn]);
;     __builtin_amdgcn_sched_group_barrier(0x8, 4, 0);
;     if (kt + 2 < nk) GEMM_GLOAD((kt + 2) * 64)
; #pragma unroll
;     for (int ks = 2; ks < 4; ks++) {
; #pragma unroll
;       for (int tm = 0; tm < TM; tm++) af[tm] = *(const bf16x8*)(cA + tm * 32 * LD + ks * 16);
; #pragma unroll
;       for (int tn = 0; tn < TN; tn++) bfr[tn] = *(const bf16x8*)(cB + tn * 32 * LD + ks * 16);
; #pragma unroll
;       for (int tm = 0; tm < TM; tm++)
; #pragma unroll
;         for (int tn = 0; tn < TN; tn++) acc[tm][tn] = MFMA(af[tm], bfr[tn], acc[tm][tn]);
;     }
;     __builtin_amdgcn_s_setprio(0);
;     __syncthreads();
;   }
	ds_read_b128 v[96:99], v70 offset:18432
	ds_read_b128 v[100:103], v70 offset:23040
	ds_read_b128 v[128:131], v1 offset:55296
	ds_read_b128 v[132:135], v1 offset:59904
	s_setprio 1
	ds_read_b128 v[88:91], v70 offset:18464
	s_waitcnt lgkmcnt(2)
	v_mfma_f32_32x32x16_bf16 v[34:49], v[96:99], v[128:131], v[34:49]
	ds_read_b128 v[92:95], v1 offset:55328
	s_waitcnt lgkmcnt(2)
	v_mfma_f32_32x32x16_bf16 v[50:65], v[96:99], v[132:135], v[50:65]
	ds_read_b128 v[96:99], v1 offset:59936
	s_waitcnt lgkmcnt(1)
	v_mfma_f32_32x32x16_bf16 v[34:49], v[88:91], v[92:95], v[34:49]
	s_waitcnt lgkmcnt(0)
	v_mfma_f32_32x32x16_bf16 v[50:65], v[88:91], v[96:99], v[50:65]
	s_waitcnt vmcnt(1)
	ds_write_b128 v66, v[140:143]
	ds_write_b128 v66, v[104:107] offset:4608
	global_load_dwordx4 v[140:143], v[74:75], off offset:384
	global_load_dwordx4 v[104:107], v[72:73], off offset:384
	ds_read_b128 v[88:91], v70 offset:23072
	v_mfma_f32_32x32x16_bf16 v[2:17], v[100:103], v[128:131], v[2:17]
	v_mfma_f32_32x32x16_bf16 v[18:33], v[100:103], v[132:135], v[18:33]
	ds_read_b128 v[100:103], v70 offset:23136
	s_waitcnt lgkmcnt(1)
	v_mfma_f32_32x32x16_bf16 v[2:17], v[88:91], v[92:95], v[2:17]
	ds_read_b128 v[92:95], v1 offset:55360
	v_mfma_f32_32x32x16_bf16 v[18:33], v[88:91], v[96:99], v[18:33]
	ds_write_b128 v66, v[108:111] offset:9216
	ds_write_b128 v66, v[112:115] offset:13824
	global_load_dwordx4 v[108:111], v[76:77], off offset:384
	global_load_dwordx4 v[112:115], v[86:87], off offset:384
	ds_read_b128 v[88:91], v70 offset:18496
	ds_read_b128 v[96:99], v1 offset:59968
	s_waitcnt lgkmcnt(1)
	v_mfma_f32_32x32x16_bf16 v[34:49], v[88:91], v[92:95], v[34:49]
	s_waitcnt lgkmcnt(0)
	v_mfma_f32_32x32x16_bf16 v[50:65], v[88:91], v[96:99], v[50:65]
	ds_read_b128 v[88:91], v70 offset:23104
	s_waitcnt lgkmcnt(0)
	v_mfma_f32_32x32x16_bf16 v[2:17], v[88:91], v[92:95], v[2:17]
	ds_read_b128 v[92:95], v1 offset:55392
	v_mfma_f32_32x32x16_bf16 v[18:33], v[88:91], v[96:99], v[18:33]
	s_waitcnt vmcnt(4)
	ds_write_b128 v66, v[144:147] offset:36864
	ds_write_b128 v66, v[124:127] offset:41472
	global_load_dwordx4 v[144:147], v[78:79], off offset:384
	global_load_dwordx4 v[124:127], v[80:81], off offset:384
	ds_read_b128 v[88:91], v70 offset:18528
	ds_read_b128 v[96:99], v1 offset:60000
	s_waitcnt lgkmcnt(1)
	v_mfma_f32_32x32x16_bf16 v[34:49], v[88:91], v[92:95], v[34:49]
	s_waitcnt lgkmcnt(0)
	v_mfma_f32_32x32x16_bf16 v[50:65], v[88:91], v[96:99], v[50:65]
	v_mfma_f32_32x32x16_bf16 v[2:17], v[100:103], v[92:95], v[2:17]
	v_mfma_f32_32x32x16_bf16 v[18:33], v[100:103], v[96:99], v[18:33]
	ds_write_b128 v66, v[120:123] offset:46080
	ds_write_b128 v66, v[116:119] offset:50688
	global_load_dwordx4 v[120:123], v[82:83], off offset:384
	global_load_dwordx4 v[116:119], v[84:85], off offset:384
	s_setprio 0
	s_waitcnt lgkmcnt(0)
	s_barrier
	ds_read_b128 v[96:99], v70
	ds_read_b128 v[100:103], v70 offset:4608
	ds_read_b128 v[128:131], v1 offset:36864
	ds_read_b128 v[132:135], v1 offset:41472
	s_setprio 1
	ds_read_b128 v[88:91], v70 offset:32
	s_waitcnt lgkmcnt(2)
	v_mfma_f32_32x32x16_bf16 v[34:49], v[96:99], v[128:131], v[34:49]
	ds_read_b128 v[92:95], v1 offset:36896
	s_waitcnt lgkmcnt(2)
	v_mfma_f32_32x32x16_bf16 v[50:65], v[96:99], v[132:135], v[50:65]
	ds_read_b128 v[96:99], v1 offset:41504
	s_waitcnt lgkmcnt(1)
	v_mfma_f32_32x32x16_bf16 v[34:49], v[88:91], v[92:95], v[34:49]
	s_waitcnt lgkmcnt(0)
	v_mfma_f32_32x32x16_bf16 v[50:65], v[88:91], v[96:99], v[50:65]
	s_waitcnt vmcnt(7)
	ds_write_b128 v66, v[140:143] offset:18432
	s_waitcnt vmcnt(6)
	ds_write_b128 v66, v[104:107] offset:23040
	global_load_dwordx4 v[140:143], v[74:75], off offset:512
	global_load_dwordx4 v[104:107], v[72:73], off offset:512
	ds_read_b128 v[88:91], v70 offset:4640
	v_mfma_f32_32x32x16_bf16 v[2:17], v[100:103], v[128:131], v[2:17]
	v_mfma_f32_32x32x16_bf16 v[18:33], v[100:103], v[132:135], v[18:33]
	ds_read_b128 v[100:103], v70 offset:4704
	s_waitcnt lgkmcnt(1)
	v_mfma_f32_32x32x16_bf16 v[2:17], v[88:91], v[92:95], v[2:17]
	ds_read_b128 v[92:95], v1 offset:36928
	v_mfma_f32_32x32x16_bf16 v[18:33], v[88:91], v[96:99], v[18:33]
	s_waitcnt vmcnt(7)
	ds_write_b128 v66, v[108:111] offset:27648
	s_waitcnt vmcnt(6)
	ds_write_b128 v66, v[112:115] offset:32256
	global_load_dwordx4 v[108:111], v[76:77], off offset:512
	global_load_dwordx4 v[112:115], v[86:87], off offset:512
	ds_read_b128 v[88:91], v70 offset:64
	ds_read_b128 v[96:99], v1 offset:41536
	s_waitcnt lgkmcnt(1)
	v_mfma_f32_32x32x16_bf16 v[34:49], v[88:91], v[92:95], v[34:49]
	s_waitcnt lgkmcnt(0)
	v_mfma_f32_32x32x16_bf16 v[50:65], v[88:91], v[96:99], v[50:65]
	ds_read_b128 v[88:91], v70 offset:4672
	s_waitcnt lgkmcnt(0)
	v_mfma_f32_32x32x16_bf16 v[2:17], v[88:91], v[92:95], v[2:17]
	ds_read_b128 v[92:95], v1 offset:36960
	v_mfma_f32_32x32x16_bf16 v[18:33], v[88:91], v[96:99], v[18:33]
	s_waitcnt vmcnt(7)
	ds_write_b128 v66, v[144:147] offset:55296
	s_waitcnt vmcnt(6)
	ds_write_b128 v66, v[124:127] offset:59904
	global_load_dwordx4 v[144:147], v[78:79], off offset:512
	global_load_dwordx4 v[124:127], v[80:81], off offset:512
	ds_read_b128 v[88:91], v70 offset:96
	ds_read_b128 v[96:99], v1 offset:41568
	s_waitcnt lgkmcnt(1)
	v_mfma_f32_32x32x16_bf16 v[34:49], v[88:91], v[92:95], v[34:49]
	s_waitcnt lgkmcnt(0)
	v_mfma_f32_32x32x16_bf16 v[50:65], v[88:91], v[96:99], v[50:65]
	v_mfma_f32_32x32x16_bf16 v[2:17], v[100:103], v[92:95], v[2:17]
	v_mfma_f32_32x32x16_bf16 v[18:33], v[100:103], v[96:99], v[18:33]
	s_waitcnt vmcnt(7)
	ds_write_b128 v66, v[120:123] offset:64512
	s_waitcnt vmcnt(6)
	ds_write_b128 v71, v[116:119] offset:32256
	global_load_dwordx4 v[120:123], v[82:83], off offset:512
	global_load_dwordx4 v[116:119], v[84:85], off offset:512
	s_setprio 0
	s_waitcnt lgkmcnt(0)
	s_barrier
; #define MFMA(a, b, c) __builtin_amdgcn_mfma_f32_32x32x16_bf16((a), (b), (c), 0, 0, 0)
; template <int TM, int TN>
; DI void gemm_mainloop(const u16* __restrict__ A, long lda, const u16* __restrict__ Bt, long ldb, int K, char* smem,
;                       f32x16 (&acc)[TM][TN]) {
;     ...
;   GEMM_GLOAD(0)
;   __syncthreads();
;   GEMM_SSTORE(0)
;   if (nk > 1) GEMM_GLOAD(64)
;   __syncthreads();
;   for (int kt = 0; kt < nk; kt++) {
;     const int buf = kt & 1;
;     const u16* cA = sA + buf * BM * LD + (wm * 32 * TM + r) * LD + h * 8;
;     const u16* cB = sB + buf * BN * LD + (wn * 32 * TN + r) * LD + h * 8;
;     bf16x8 af[TM], bfr[TN];
; #pragma unroll
;     for (int tm = 0; tm < TM; tm++) af[tm] = *(const bf16x8*)(cA + tm * 32 * LD);
; #pragma unroll
;     for (int tn = 0; tn < TN; tn++) bfr[tn] = *(const bf16x8*)(cB + tn * 32 * LD);
;     if (kt + 1 < nk) GEMM_SSTORE(buf ^ 1)
;     __builtin_amdgcn_sched_barrier(0);
;     __builtin_amdgcn_s_setprio(1);
; #pragma unroll
;     for (int tm = 0; tm < TM; tm++)
; #pragma unroll
;       for (int tn = 0; tn < TN; tn++) acc[tm][tn] = MFMA(af[tm], bfr[tn], acc[tm][tn]);
; #pragma unroll
;     for (int tm = 0; tm < TM; tm++) af[tm] = *(const bf16x8*)(cA + tm * 32 * LD + 16);
; #pragma unroll
;     for (int tn = 0; tn < TN; tn++) bfr[tn] = *(const bf16x8*)(cB + tn * 32 * LD + 16);
; #pragma unroll
;     for (int tm = 0; tm < TM; tm++)
; #pragma unroll
;       for (int tn = 0; tn < TN; tn++) acc[tm][tn] = MFMA(af[tm], bfr[tn], acc[tm][tn]);
;     __builtin_amdgcn_sched_group_barrier(0x8, 4, 0);
;     if (kt + 2 < nk) GEMM_GLOAD((kt + 2) * 64)
; #pragma unroll
;     for (int ks = 2; ks < 4; ks++) {
; #pragma unroll
;       for (int tm = 0; tm < TM; tm++) af[tm] = *(const bf16x8*)(cA + tm * 32 * LD + ks * 16);
; #pragma unroll
;       for (int tn = 0; tn < TN; tn++) bfr[tn] = *(const bf16x8*)(cB + tn * 32 * LD + ks * 16);
; #pragma unroll
;       for (int tm = 0; tm < TM; tm++)
; #pragma unroll
;         for (int tn = 0; tn < TN; tn++) acc[tm][tn] = MFMA(af[tm], bfr[tn], acc[tm][tn]);
;     }
;     __builtin_amdgcn_s_setprio(0);
;     __syncthreads();
;   }
	ds_read_b128 v[96:99], v70 offset:18432
	ds_read_b128 v[100:103], v70 offset:23040
	ds_read_b128 v[128:131], v1 offset:55296
	ds_read_b128 v[132:135], v1 offset:59904
	s_setprio 1
	ds_read_b128 v[88:91], v70 offset:18464
	s_waitcnt lgkmcnt(2)
	v_mfma_f32_32x32x16_bf16 v[34:49], v[96:99], v[128:131], v[34:49]
	ds_read_b128 v[92:95], v1 offset:55328
	s_waitcnt lgkmcnt(2)
	v_mfma_f32_32x32x16_bf16 v[50:65], v[96:99], v[132:135], v[50:65]
	ds_read_b128 v[96:99], v1 offset:59936
	s_waitcnt lgkmcnt(1)
	v_mfma_f32_32x32x16_bf16 v[34:49], v[88:91], v[92:95], v[34:49]
	s_waitcnt lgkmcnt(0)
	v_mfma_f32_32x32x16_bf16 v[50:65], v[88:91], v[96:99], v[50:65]
	s_waitcnt vmcnt(7)
	ds_write_b128 v66, v[140:143]
	s_waitcnt vmcnt(6)
	ds_write_b128 v66, v[104:107] offset:4608
	global_load_dwordx4 v[140:143], v[74:75], off offset:640
	global_load_dwordx4 v[104:107], v[72:73], off offset:640
	ds_read_b128 v[88:91], v70 offset:23072
	v_mfma_f32_32x32x16_bf16 v[2:17], v[100:103], v[128:131], v[2:17]
	v_mfma_f32_32x32x16_bf16 v[18:33], v[100:103], v[132:135], v[18:33]
	ds_read_b128 v[100:103], v70 offset:23136
	s_waitcnt lgkmcnt(1)
	v_mfma_f32_32x32x16_bf16 v[2:17], v[88:91], v[92:95], v[2:17]
	ds_read_b128 v[92:95], v1 offset:55360
	v_mfma_f32_32x32x16_bf16 v[18:33], v[88:91], v[96:99], v[18:33]
	s_waitcnt vmcnt(7)
	ds_write_b128 v66, v[108:111] offset:9216
	s_waitcnt vmcnt(6)
	ds_write_b128 v66, v[112:115] offset:13824
	global_load_dwordx4 v[108:111], v[76:77], off offset:640
	global_load_dwordx4 v[112:115], v[86:87], off offset:640
	ds_read_b128 v[88:91], v70 offset:18496
	ds_read_b128 v[96:99], v1 offset:59968
	s_waitcnt lgkmcnt(1)
	v_mfma_f32_32x32x16_bf16 v[34:49], v[88:91], v[92:95], v[34:49]
	s_waitcnt lgkmcnt(0)
	v_mfma_f32_32x32x16_bf16 v[50:65], v[88:91], v[96:99], v[50:65]
	ds_read_b128 v[88:91], v70 offset:23104
	s_waitcnt lgkmcnt(0)
	v_mfma_f32_32x32x16_bf16 v[2:17], v[88:91], v[92:95], v[2:17]
	ds_read_b128 v[92:95], v1 offset:55392
	v_mfma_f32_32x32x16_bf16 v[18:33], v[88:91], v[96:99], v[18:33]
	s_waitcnt vmcnt(7)
	ds_write_b128 v66, v[144:147] offset:36864
	s_waitcnt vmcnt(6)
	ds_write_b128 v66, v[124:127] offset:41472
	global_load_dwordx4 v[144:147], v[78:79], off offset:640
	global_load_dwordx4 v[124:127], v[80:81], off offset:640
	ds_read_b128 v[88:91], v70 offset:18528
	ds_read_b128 v[96:99], v1 offset:60000
	s_waitcnt lgkmcnt(1)
	v_mfma_f32_32x32x16_bf16 v[34:49], v[88:91], v[92:95], v[34:49]
	s_waitcnt lgkmcnt(0)
	v_mfma_f32_32x32x16_bf16 v[50:65], v[88:91], v[96:99], v[50:65]
	v_mfma_f32_32x32x16_bf16 v[2:17], v[100:103], v[92:95], v[2:17]
	v_mfma_f32_32x32x16_bf16 v[18:33], v[100:103], v[96:99], v[18:33]
	s_waitcnt vmcnt(7)
	ds_write_b128 v66, v[120:123] offset:46080
	s_waitcnt vmcnt(6)
	ds_write_b128 v66, v[116:119] offset:50688
	global_load_dwordx4 v[120:123], v[82:83], off offset:640
	global_load_dwordx4 v[116:119], v[84:85], off offset:640
	s_setprio 0
	s_waitcnt lgkmcnt(0)
	s_barrier
	ds_read_b128 v[96:99], v70
	ds_read_b128 v[100:103], v70 offset:4608
	ds_read_b128 v[128:131], v1 offset:36864
	ds_read_b128 v[132:135], v1 offset:41472
	s_setprio 1
	ds_read_b128 v[88:91], v70 offset:32
	s_waitcnt lgkmcnt(2)
	v_mfma_f32_32x32x16_bf16 v[34:49], v[96:99], v[128:131], v[34:49]
	ds_read_b128 v[92:95], v1 offset:36896
	s_waitcnt lgkmcnt(2)
	v_mfma_f32_32x32x16_bf16 v[50:65], v[96:99], v[132:135], v[50:65]
	ds_read_b128 v[96:99], v1 offset:41504
	s_waitcnt lgkmcnt(1)
	v_mfma_f32_32x32x16_bf16 v[34:49], v[88:91], v[92:95], v[34:49]
	s_waitcnt lgkmcnt(0)
	v_mfma_f32_32x32x16_bf16 v[50:65], v[88:91], v[96:99], v[50:65]
	s_waitcnt vmcnt(7)
	ds_write_b128 v66, v[140:143] offset:18432
	s_waitcnt vmcnt(6)
	ds_write_b128 v66, v[104:107] offset:23040
	global_load_dwordx4 v[140:143], v[74:75], off offset:768
	global_load_dwordx4 v[104:107], v[72:73], off offset:768
	ds_read_b128 v[88:91], v70 offset:4640
	v_mfma_f32_32x32x16_bf16 v[2:17], v[100:103], v[128:131], v[2:17]
	v_mfma_f32_32x32x16_bf16 v[18:33], v[100:103], v[132:135], v[18:33]
	ds_read_b128 v[100:103], v70 offset:4704
	s_waitcnt lgkmcnt(1)
	v_mfma_f32_32x32x16_bf16 v[2:17], v[88:91], v[92:95], v[2:17]
	ds_read_b128 v[92:95], v1 offset:36928
	v_mfma_f32_32x32x16_bf16 v[18:33], v[88:91], v[96:99], v[18:33]
	s_waitcnt vmcnt(7)
	ds_write_b128 v66, v[108:111] offset:27648
	s_waitcnt vmcnt(6)
	ds_write_b128 v66, v[112:115] offset:32256
	global_load_dwordx4 v[108:111], v[76:77], off offset:768
	global_load_dwordx4 v[112:115], v[86:87], off offset:768
	ds_read_b128 v[88:91], v70 offset:64
	ds_read_b128 v[96:99], v1 offset:41536
	s_waitcnt lgkmcnt(1)
	v_mfma_f32_32x32x16_bf16 v[34:49], v[88:91], v[92:95], v[34:49]
	s_waitcnt lgkmcnt(0)
	v_mfma_f32_32x32x16_bf16 v[50:65], v[88:91], v[96:99], v[50:65]
	ds_read_b128 v[88:91], v70 offset:4672
	s_waitcnt lgkmcnt(0)
	v_mfma_f32_32x32x16_bf16 v[2:17], v[88:91], v[92:95], v[2:17]
	ds_read_b128 v[92:95], v1 offset:36960
	v_mfma_f32_32x32x16_bf16 v[18:33], v[88:91], v[96:99], v[18:33]
	s_waitcnt vmcnt(7)
	ds_write_b128 v66, v[144:147] offset:55296
	s_waitcnt vmcnt(6)
	ds_write_b128 v66, v[124:127] offset:59904
	global_load_dwordx4 v[144:147], v[78:79], off offset:768
	global_load_dwordx4 v[124:127], v[80:81], off offset:768
	ds_read_b128 v[88:91], v70 offset:96
	ds_read_b128 v[96:99], v1 offset:41568
	s_waitcnt lgkmcnt(1)
	v_mfma_f32_32x32x16_bf16 v[34:49], v[88:91], v[92:95], v[34:49]
	s_waitcnt lgkmcnt(0)
	v_mfma_f32_32x32x16_bf16 v[50:65], v[88:91], v[96:99], v[50:65]
	v_mfma_f32_32x32x16_bf16 v[2:17], v[100:103], v[92:95], v[2:17]
	v_mfma_f32_32x32x16_bf16 v[18:33], v[100:103], v[96:99], v[18:33]
	s_waitcnt vmcnt(7)
	ds_write_b128 v66, v[120:123] offset:64512
	s_waitcnt vmcnt(6)
	ds_write_b128 v71, v[116:119] offset:32256
	global_load_dwordx4 v[120:123], v[82:83], off offset:768
	global_load_dwordx4 v[116:119], v[84:85], off offset:768
	s_setprio 0
	s_waitcnt lgkmcnt(0)
	s_barrier
; #define MFMA(a, b, c) __builtin_amdgcn_mfma_f32_32x32x16_bf16((a), (b), (c), 0, 0, 0)
; template <int TM, int TN>
; DI void gemm_mainloop(const u16* __restrict__ A, long lda, const u16* __restrict__ Bt, long ldb, int K, char* smem,
;                       f32x16 (&acc)[TM][TN]) {
;     ...
;   GEMM_GLOAD(0)
;   __syncthreads();
;   GEMM_SSTORE(0)
;   if (nk > 1) GEMM_GLOAD(64)
;   __syncthreads();
;   for (int kt = 0; kt < nk; kt++) {
;     const int buf = kt & 1;
;     const u16* cA = sA + buf * BM * LD + (wm * 32 * TM + r) * LD + h * 8;
;     const u16* cB = sB + buf * BN * LD + (wn * 32 * TN + r) * LD + h * 8;
;     bf16x8 af[TM], bfr[TN];
; #pragma unroll
;     for (int tm = 0; tm < TM; tm++) af[tm] = *(const bf16x8*)(cA + tm * 32 * LD);
; #pragma unroll
;     for (int tn = 0; tn < TN; tn++) bfr[tn] = *(const bf16x8*)(cB + tn * 32 * LD);
;     if (kt + 1 < nk) GEMM_SSTORE(buf ^ 1)
;     __builtin_amdgcn_sched_barrier(0);
;     __builtin_amdgcn_s_setprio(1);
; #pragma unroll
;     for (int tm = 0; tm < TM; tm++)
; #pragma unroll
;       for (int tn = 0; tn < TN; tn++) acc[tm][tn] = MFMA(af[tm], bfr[tn], acc[tm][tn]);
; #pragma unroll
;     for (int tm = 0; tm < TM; tm++) af[tm] = *(const bf16x8*)(cA + tm * 32 * LD + 16);
; #pragma unroll
;     for (int tn = 0; tn < TN; tn++) bfr[tn] = *(const bf16x8*)(cB + tn * 32 * LD + 16);
; #pragma unroll
;     for (int tm = 0; tm < TM; tm++)
; #pragma unroll
;       for (int tn = 0; tn < TN; tn++) acc[tm][tn] = MFMA(af[tm], bfr[tn], acc[tm][tn]);
;     __builtin_amdgcn_sched_group_barrier(0x8, 4, 0);
;     if (kt + 2 < nk) GEMM_GLOAD((kt + 2) * 64)
; #pragma unroll
;     for (int ks = 2; ks < 4; ks++) {
; #pragma unroll
;       for (int tm = 0; tm < TM; tm++) af[tm] = *(const bf16x8*)(cA + tm * 32 * LD + ks * 16);
; #pragma unroll
;       for (int tn = 0; tn < TN; tn++) bfr[tn] = *(const bf16x8*)(cB + tn * 32 * LD + ks * 16);
; #pragma unroll
;       for (int tm = 0; tm < TM; tm++)
; #pragma unroll
;         for (int tn = 0; tn < TN; tn++) acc[tm][tn] = MFMA(af[tm], bfr[tn], acc[tm][tn]);
;     }
;     __builtin_amdgcn_s_setprio(0);
;     __syncthreads();
;   }
	ds_read_b128 v[96:99], v70 offset:18432
	ds_read_b128 v[100:103], v70 offset:23040
	ds_read_b128 v[128:131], v1 offset:55296
	ds_read_b128 v[132:135], v1 offset:59904
	s_setprio 1
	ds_read_b128 v[88:91], v70 offset:18464
	s_waitcnt lgkmcnt(2)
	v_mfma_f32_32x32x16_bf16 v[34:49], v[96:99], v[128:131], v[34:49]
	ds_read_b128 v[92:95], v1 offset:55328
	s_waitcnt lgkmcnt(2)
	v_mfma_f32_32x32x16_bf16 v[50:65], v[96:99], v[132:135], v[50:65]
	ds_read_b128 v[96:99], v1 offset:59936
	s_waitcnt lgkmcnt(1)
	v_mfma_f32_32x32x16_bf16 v[34:49], v[88:91], v[92:95], v[34:49]
	s_waitcnt lgkmcnt(0)
	v_mfma_f32_32x32x16_bf16 v[50:65], v[88:91], v[96:99], v[50:65]
	s_waitcnt vmcnt(7)
	ds_write_b128 v66, v[140:143]
	s_waitcnt vmcnt(6)
	ds_write_b128 v66, v[104:107] offset:4608
	global_load_dwordx4 v[140:143], v[74:75], off offset:896
	global_load_dwordx4 v[104:107], v[72:73], off offset:896
	ds_read_b128 v[88:91], v70 offset:23072
	v_mfma_f32_32x32x16_bf16 v[2:17], v[100:103], v[128:131], v[2:17]
	v_mfma_f32_32x32x16_bf16 v[18:33], v[100:103], v[132:135], v[18:33]
	ds_read_b128 v[100:103], v70 offset:23136
	s_waitcnt lgkmcnt(1)
	v_mfma_f32_32x32x16_bf16 v[2:17], v[88:91], v[92:95], v[2:17]
	ds_read_b128 v[92:95], v1 offset:55360
	v_mfma_f32_32x32x16_bf16 v[18:33], v[88:91], v[96:99], v[18:33]
	s_waitcnt vmcnt(7)
	ds_write_b128 v66, v[108:111] offset:9216
	s_waitcnt vmcnt(6)
	ds_write_b128 v66, v[112:115] offset:13824
	global_load_dwordx4 v[108:111], v[76:77], off offset:896
	global_load_dwordx4 v[112:115], v[86:87], off offset:896
	ds_read_b128 v[88:91], v70 offset:18496
	ds_read_b128 v[96:99], v1 offset:59968
	s_waitcnt lgkmcnt(1)
	v_mfma_f32_32x32x16_bf16 v[34:49], v[88:91], v[92:95], v[34:49]
	s_waitcnt lgkmcnt(0)
	v_mfma_f32_32x32x16_bf16 v[50:65], v[88:91], v[96:99], v[50:65]
	ds_read_b128 v[88:91], v70 offset:23104
	s_waitcnt lgkmcnt(0)
	v_mfma_f32_32x32x16_bf16 v[2:17], v[88:91], v[92:95], v[2:17]
	ds_read_b128 v[92:95], v1 offset:55392
	v_mfma_f32_32x32x16_bf16 v[18:33], v[88:91], v[96:99], v[18:33]
	s_waitcnt vmcnt(7)
	ds_write_b128 v66, v[144:147] offset:36864
	s_waitcnt vmcnt(6)
	ds_write_b128 v66, v[124:127] offset:41472
	global_load_dwordx4 v[144:147], v[78:79], off offset:896
	global_load_dwordx4 v[124:127], v[80:81], off offset:896
	ds_read_b128 v[88:91], v70 offset:18528
	ds_read_b128 v[96:99], v1 offset:60000
	s_waitcnt lgkmcnt(1)
	v_mfma_f32_32x32x16_bf16 v[34:49], v[88:91], v[92:95], v[34:49]
	s_waitcnt lgkmcnt(0)
	v_mfma_f32_32x32x16_bf16 v[50:65], v[88:91], v[96:99], v[50:65]
	v_mfma_f32_32x32x16_bf16 v[2:17], v[100:103], v[92:95], v[2:17]
	v_mfma_f32_32x32x16_bf16 v[18:33], v[100:103], v[96:99], v[18:33]
	s_waitcnt vmcnt(7)
	ds_write_b128 v66, v[120:123] offset:46080
	s_waitcnt vmcnt(6)
	ds_write_b128 v66, v[116:119] offset:50688
	global_load_dwordx4 v[120:123], v[82:83], off offset:896
	global_load_dwordx4 v[116:119], v[84:85], off offset:896
	s_setprio 0
	s_waitcnt lgkmcnt(0)
	s_barrier
	ds_read_b128 v[96:99], v70
	ds_read_b128 v[100:103], v70 offset:4608
	ds_read_b128 v[128:131], v1 offset:36864
	ds_read_b128 v[132:135], v1 offset:41472
	s_setprio 1
	ds_read_b128 v[88:91], v70 offset:32
	s_waitcnt lgkmcnt(2)
	v_mfma_f32_32x32x16_bf16 v[34:49], v[96:99], v[128:131], v[34:49]
	ds_read_b128 v[92:95], v1 offset:36896
	s_waitcnt lgkmcnt(2)
	v_mfma_f32_32x32x16_bf16 v[50:65], v[96:99], v[132:135], v[50:65]
	ds_read_b128 v[96:99], v1 offset:41504
	s_waitcnt lgkmcnt(1)
	v_mfma_f32_32x32x16_bf16 v[34:49], v[88:91], v[92:95], v[34:49]
	s_waitcnt lgkmcnt(0)
	v_mfma_f32_32x32x16_bf16 v[50:65], v[88:91], v[96:99], v[50:65]
	s_waitcnt vmcnt(7)
	ds_write_b128 v66, v[140:143] offset:18432
	s_waitcnt vmcnt(6)
	ds_write_b128 v66, v[104:107] offset:23040
	global_load_dwordx4 v[140:143], v[74:75], off offset:1024
	global_load_dwordx4 v[104:107], v[72:73], off offset:1024
	ds_read_b128 v[88:91], v70 offset:4640
	v_mfma_f32_32x32x16_bf16 v[2:17], v[100:103], v[128:131], v[2:17]
	v_mfma_f32_32x32x16_bf16 v[18:33], v[100:103], v[132:135], v[18:33]
	ds_read_b128 v[100:103], v70 offset:4704
	s_waitcnt lgkmcnt(1)
	v_mfma_f32_32x32x16_bf16 v[2:17], v[88:91], v[92:95], v[2:17]
	ds_read_b128 v[92:95], v1 offset:36928
	v_mfma_f32_32x32x16_bf16 v[18:33], v[88:91], v[96:99], v[18:33]
	s_waitcnt vmcnt(7)
	ds_write_b128 v66, v[108:111] offset:27648
	s_waitcnt vmcnt(6)
	ds_write_b128 v66, v[112:115] offset:32256
	global_load_dwordx4 v[108:111], v[76:77], off offset:1024
	global_load_dwordx4 v[112:115], v[86:87], off offset:1024
	ds_read_b128 v[88:91], v70 offset:64
	ds_read_b128 v[96:99], v1 offset:41536
	s_waitcnt lgkmcnt(1)
	v_mfma_f32_32x32x16_bf16 v[34:49], v[88:91], v[92:95], v[34:49]
	s_waitcnt lgkmcnt(0)
	v_mfma_f32_32x32x16_bf16 v[50:65], v[88:91], v[96:99], v[50:65]
	ds_read_b128 v[88:91], v70 offset:4672
	s_waitcnt lgkmcnt(0)
	v_mfma_f32_32x32x16_bf16 v[2:17], v[88:91], v[92:95], v[2:17]
	ds_read_b128 v[92:95], v1 offset:36960
	v_mfma_f32_32x32x16_bf16 v[18:33], v[88:91], v[96:99], v[18:33]
	s_waitcnt vmcnt(7)
	ds_write_b128 v66, v[144:147] offset:55296
	s_waitcnt vmcnt(6)
	ds_write_b128 v66, v[124:127] offset:59904
	global_load_dwordx4 v[144:147], v[78:79], off offset:1024
	global_load_dwordx4 v[124:127], v[80:81], off offset:1024
	ds_read_b128 v[88:91], v70 offset:96
	ds_read_b128 v[96:99], v1 offset:41568
	s_waitcnt lgkmcnt(1)
	v_mfma_f32_32x32x16_bf16 v[34:49], v[88:91], v[92:95], v[34:49]
	s_waitcnt lgkmcnt(0)
	v_mfma_f32_32x32x16_bf16 v[50:65], v[88:91], v[96:99], v[50:65]
	v_mfma_f32_32x32x16_bf16 v[2:17], v[100:103], v[92:95], v[2:17]
	v_mfma_f32_32x32x16_bf16 v[18:33], v[100:103], v[96:99], v[18:33]
	s_waitcnt vmcnt(7)
	ds_write_b128 v66, v[120:123] offset:64512
	s_waitcnt vmcnt(6)
	ds_write_b128 v71, v[116:119] offset:32256
	global_load_dwordx4 v[120:123], v[82:83], off offset:1024
	global_load_dwordx4 v[116:119], v[84:85], off offset:1024
	s_setprio 0
	s_waitcnt lgkmcnt(0)
	s_barrier
; #define MFMA(a, b, c) __builtin_amdgcn_mfma_f32_32x32x16_bf16((a), (b), (c), 0, 0, 0)
; template <int TM, int TN>
; DI void gemm_mainloop(const u16* __restrict__ A, long lda, const u16* __restrict__ Bt, long ldb, int K, char* smem,
;                       f32x16 (&acc)[TM][TN]) {
;     ...
;   GEMM_GLOAD(0)
;   __syncthreads();
;   GEMM_SSTORE(0)
;   if (nk > 1) GEMM_GLOAD(64)
;   __syncthreads();
;   for (int kt = 0; kt < nk; kt++) {
;     const int buf = kt & 1;
;     const u16* cA = sA + buf * BM * LD + (wm * 32 * TM + r) * LD + h * 8;
;     const u16* cB = sB + buf * BN * LD + (wn * 32 * TN + r) * LD + h * 8;
;     bf16x8 af[TM], bfr[TN];
; #pragma unroll
;     for (int tm = 0; tm < TM; tm++) af[tm] = *(const bf16x8*)(cA + tm * 32 * LD);
; #pragma unroll
;     for (int tn = 0; tn < TN; tn++) bfr[tn] = *(const bf16x8*)(cB + tn * 32 * LD);
;     if (kt + 1 < nk) GEMM_SSTORE(buf ^ 1)
;     __builtin_amdgcn_sched_barrier(0);
;     __builtin_amdgcn_s_setprio(1);
; #pragma unroll
;     for (int tm = 0; tm < TM; tm++)
; #pragma unroll
;       for (int tn = 0; tn < TN; tn++) acc[tm][tn] = MFMA(af[tm], bfr[tn], acc[tm][tn]);
; #pragma unroll
;     for (int tm = 0; tm < TM; tm++) af[tm] = *(const bf16x8*)(cA + tm * 32 * LD + 16);
; #pragma unroll
;     for (int tn = 0; tn < TN; tn++) bfr[tn] = *(const bf16x8*)(cB + tn * 32 * LD + 16);
; #pragma unroll
;     for (int tm = 0; tm < TM; tm++)
; #pragma unroll
;       for (int tn = 0; tn < TN; tn++) acc[tm][tn] = MFMA(af[tm], bfr[tn], acc[tm][tn]);
;     __builtin_amdgcn_sched_group_barrier(0x8, 4, 0);
;     if (kt + 2 < nk) GEMM_GLOAD((kt + 2) * 64)
; #pragma unroll
;     for (int ks = 2; ks < 4; ks++) {
; #pragma unroll
;       for (int tm = 0; tm < TM; tm++) af[tm] = *(const bf16x8*)(cA + tm * 32 * LD + ks * 16);
; #pragma unroll
;       for (int tn = 0; tn < TN; tn++) bfr[tn] = *(const bf16x8*)(cB + tn * 32 * LD + ks * 16);
; #pragma unroll
;       for (int tm = 0; tm < TM; tm++)
; #pragma unroll
;         for (int tn = 0; tn < TN; tn++) acc[tm][tn] = MFMA(af[tm], bfr[tn], acc[tm][tn]);
;     }
;     __builtin_amdgcn_s_setprio(0);
;     __syncthreads();
;   }
	ds_read_b128 v[96:99], v70 offset:18432
	ds_read_b128 v[100:103], v70 offset:23040
	ds_read_b128 v[128:131], v1 offset:55296
	ds_read_b128 v[132:135], v1 offset:59904
	s_setprio 1
	ds_read_b128 v[88:91], v70 offset:18464
	s_waitcnt lgkmcnt(2)
	v_mfma_f32_32x32x16_bf16 v[34:49], v[96:99], v[128:131], v[34:49]
	ds_read_b128 v[92:95], v1 offset:55328
	s_waitcnt lgkmcnt(2)
	v_mfma_f32_32x32x16_bf16 v[50:65], v[96:99], v[132:135], v[50:65]
	ds_read_b128 v[96:99], v1 offset:59936
	s_waitcnt lgkmcnt(1)
	v_mfma_f32_32x32x16_bf16 v[34:49], v[88:91], v[92:95], v[34:49]
	s_waitcnt lgkmcnt(0)
	v_mfma_f32_32x32x16_bf16 v[50:65], v[88:91], v[96:99], v[50:65]
	s_waitcnt vmcnt(7)
	ds_write_b128 v66, v[140:143]
	s_waitcnt vmcnt(6)
	ds_write_b128 v66, v[104:107] offset:4608
	global_load_dwordx4 v[140:143], v[74:75], off offset:1152
	global_load_dwordx4 v[104:107], v[72:73], off offset:1152
	ds_read_b128 v[88:91], v70 offset:23072
	v_mfma_f32_32x32x16_bf16 v[2:17], v[100:103], v[128:131], v[2:17]
	v_mfma_f32_32x32x16_bf16 v[18:33], v[100:103], v[132:135], v[18:33]
	ds_read_b128 v[100:103], v70 offset:23136
	s_waitcnt lgkmcnt(1)
	v_mfma_f32_32x32x16_bf16 v[2:17], v[88:91], v[92:95], v[2:17]
	ds_read_b128 v[92:95], v1 offset:55360
	v_mfma_f32_32x32x16_bf16 v[18:33], v[88:91], v[96:99], v[18:33]
	s_waitcnt vmcnt(7)
	ds_write_b128 v66, v[108:111] offset:9216
	s_waitcnt vmcnt(6)
	ds_write_b128 v66, v[112:115] offset:13824
	global_load_dwordx4 v[108:111], v[76:77], off offset:1152
	global_load_dwordx4 v[112:115], v[86:87], off offset:1152
	ds_read_b128 v[88:91], v70 offset:18496
	ds_read_b128 v[96:99], v1 offset:59968
	s_waitcnt lgkmcnt(1)
	v_mfma_f32_32x32x16_bf16 v[34:49], v[88:91], v[92:95], v[34:49]
	s_waitcnt lgkmcnt(0)
	v_mfma_f32_32x32x16_bf16 v[50:65], v[88:91], v[96:99], v[50:65]
	ds_read_b128 v[88:91], v70 offset:23104
	s_waitcnt lgkmcnt(0)
	v_mfma_f32_32x32x16_bf16 v[2:17], v[88:91], v[92:95], v[2:17]
	ds_read_b128 v[92:95], v1 offset:55392
	v_mfma_f32_32x32x16_bf16 v[18:33], v[88:91], v[96:99], v[18:33]
	s_waitcnt vmcnt(7)
	ds_write_b128 v66, v[144:147] offset:36864
	s_waitcnt vmcnt(6)
	ds_write_b128 v66, v[124:127] offset:41472
	global_load_dwordx4 v[144:147], v[78:79], off offset:1152
	global_load_dwordx4 v[124:127], v[80:81], off offset:1152
	ds_read_b128 v[88:91], v70 offset:18528
	ds_read_b128 v[96:99], v1 offset:60000
	s_waitcnt lgkmcnt(1)
	v_mfma_f32_32x32x16_bf16 v[34:49], v[88:91], v[92:95], v[34:49]
	s_waitcnt lgkmcnt(0)
	v_mfma_f32_32x32x16_bf16 v[50:65], v[88:91], v[96:99], v[50:65]
	v_mfma_f32_32x32x16_bf16 v[2:17], v[100:103], v[92:95], v[2:17]
	v_mfma_f32_32x32x16_bf16 v[18:33], v[100:103], v[96:99], v[18:33]
	s_waitcnt vmcnt(7)
	ds_write_b128 v66, v[120:123] offset:46080
	s_waitcnt vmcnt(6)
	ds_write_b128 v66, v[116:119] offset:50688
	global_load_dwordx4 v[120:123], v[82:83], off offset:1152
	global_load_dwordx4 v[116:119], v[84:85], off offset:1152
	s_setprio 0
	s_waitcnt lgkmcnt(0)
	s_barrier
	ds_read_b128 v[96:99], v70
	ds_read_b128 v[100:103], v70 offset:4608
	ds_read_b128 v[128:131], v1 offset:36864
	ds_read_b128 v[132:135], v1 offset:41472
	s_setprio 1
	ds_read_b128 v[88:91], v70 offset:32
	s_waitcnt lgkmcnt(2)
	v_mfma_f32_32x32x16_bf16 v[34:49], v[96:99], v[128:131], v[34:49]
	ds_read_b128 v[92:95], v1 offset:36896
	s_waitcnt lgkmcnt(2)
	v_mfma_f32_32x32x16_bf16 v[50:65], v[96:99], v[132:135], v[50:65]
	ds_read_b128 v[96:99], v1 offset:41504
	s_waitcnt lgkmcnt(1)
	v_mfma_f32_32x32x16_bf16 v[34:49], v[88:91], v[92:95], v[34:49]
	s_waitcnt lgkmcnt(0)
	v_mfma_f32_32x32x16_bf16 v[50:65], v[88:91], v[96:99], v[50:65]
	s_waitcnt vmcnt(7)
	ds_write_b128 v66, v[140:143] offset:18432
	s_waitcnt vmcnt(6)
	ds_write_b128 v66, v[104:107] offset:23040
	global_load_dwordx4 v[140:143], v[74:75], off offset:1280
	global_load_dwordx4 v[104:107], v[72:73], off offset:1280
	ds_read_b128 v[88:91], v70 offset:4640
	v_mfma_f32_32x32x16_bf16 v[2:17], v[100:103], v[128:131], v[2:17]
	v_mfma_f32_32x32x16_bf16 v[18:33], v[100:103], v[132:135], v[18:33]
	ds_read_b128 v[100:103], v70 offset:4704
	s_waitcnt lgkmcnt(1)
	v_mfma_f32_32x32x16_bf16 v[2:17], v[88:91], v[92:95], v[2:17]
	ds_read_b128 v[92:95], v1 offset:36928
	v_mfma_f32_32x32x16_bf16 v[18:33], v[88:91], v[96:99], v[18:33]
	s_waitcnt vmcnt(7)
	ds_write_b128 v66, v[108:111] offset:27648
	s_waitcnt vmcnt(6)
	ds_write_b128 v66, v[112:115] offset:32256
	global_load_dwordx4 v[108:111], v[76:77], off offset:1280
	global_load_dwordx4 v[112:115], v[86:87], off offset:1280
	ds_read_b128 v[88:91], v70 offset:64
	ds_read_b128 v[96:99], v1 offset:41536
	s_waitcnt lgkmcnt(1)
	v_mfma_f32_32x32x16_bf16 v[34:49], v[88:91], v[92:95], v[34:49]
	s_waitcnt lgkmcnt(0)
	v_mfma_f32_32x32x16_bf16 v[50:65], v[88:91], v[96:99], v[50:65]
	ds_read_b128 v[88:91], v70 offset:4672
	s_waitcnt lgkmcnt(0)
	v_mfma_f32_32x32x16_bf16 v[2:17], v[88:91], v[92:95], v[2:17]
	ds_read_b128 v[92:95], v1 offset:36960
	v_mfma_f32_32x32x16_bf16 v[18:33], v[88:91], v[96:99], v[18:33]
	s_waitcnt vmcnt(7)
	ds_write_b128 v66, v[144:147] offset:55296
	s_waitcnt vmcnt(6)
	ds_write_b128 v66, v[124:127] offset:59904
	global_load_dwordx4 v[144:147], v[78:79], off offset:1280
	global_load_dwordx4 v[124:127], v[80:81], off offset:1280
	ds_read_b128 v[88:91], v70 offset:96
	ds_read_b128 v[96:99], v1 offset:41568
	s_waitcnt lgkmcnt(1)
	v_mfma_f32_32x32x16_bf16 v[34:49], v[88:91], v[92:95], v[34:49]
	s_waitcnt lgkmcnt(0)
	v_mfma_f32_32x32x16_bf16 v[50:65], v[88:91], v[96:99], v[50:65]
	v_mfma_f32_32x32x16_bf16 v[2:17], v[100:103], v[92:95], v[2:17]
	v_mfma_f32_32x32x16_bf16 v[18:33], v[100:103], v[96:99], v[18:33]
	s_waitcnt vmcnt(7)
	ds_write_b128 v66, v[120:123] offset:64512
	s_waitcnt vmcnt(6)
	ds_write_b128 v71, v[116:119] offset:32256
	global_load_dwordx4 v[120:123], v[82:83], off offset:1280
	global_load_dwordx4 v[116:119], v[84:85], off offset:1280
	s_setprio 0
	s_waitcnt lgkmcnt(0)
	s_barrier
; #define MFMA(a, b, c) __builtin_amdgcn_mfma_f32_32x32x16_bf16((a), (b), (c), 0, 0, 0)
; template <int TM, int TN>
; DI void gemm_mainloop(const u16* __restrict__ A, long lda, const u16* __restrict__ Bt, long ldb, int K, char* smem,
;                       f32x16 (&acc)[TM][TN]) {
;     ...
;   GEMM_GLOAD(0)
;   __syncthreads();
;   GEMM_SSTORE(0)
;   if (nk > 1) GEMM_GLOAD(64)
;   __syncthreads();
;   for (int kt = 0; kt < nk; kt++) {
;     const int buf = kt & 1;
;     const u16* cA = sA + buf * BM * LD + (wm * 32 * TM + r) * LD + h * 8;
;     const u16* cB = sB + buf * BN * LD + (wn * 32 * TN + r) * LD + h * 8;
;     bf16x8 af[TM], bfr[TN];
; #pragma unroll
;     for (int tm = 0; tm < TM; tm++) af[tm] = *(const bf16x8*)(cA + tm * 32 * LD);
; #pragma unroll
;     for (int tn = 0; tn < TN; tn++) bfr[tn] = *(const bf16x8*)(cB + tn * 32 * LD);
;     if (kt + 1 < nk) GEMM_SSTORE(buf ^ 1)
;     __builtin_amdgcn_sched_barrier(0);
;     __builtin_amdgcn_s_setprio(1);
; #pragma unroll
;     for (int tm = 0; tm < TM; tm++)
; #pragma unroll
;       for (int tn = 0; tn < TN; tn++) acc[tm][tn] = MFMA(af[tm], bfr[tn], acc[tm][tn]);
; #pragma unroll
;     for (int tm = 0; tm < TM; tm++) af[tm] = *(const bf16x8*)(cA + tm * 32 * LD + 16);
; #pragma unroll
;     for (int tn = 0; tn < TN; tn++) bfr[tn] = *(const bf16x8*)(cB + tn * 32 * LD + 16);
; #pragma unroll
;     for (int tm = 0; tm < TM; tm++)
; #pragma unroll
;       for (int tn = 0; tn < TN; tn++) acc[tm][tn] = MFMA(af[tm], bfr[tn], acc[tm][tn]);
;     __builtin_amdgcn_sched_group_barrier(0x8, 4, 0);
;     if (kt + 2 < nk) GEMM_GLOAD((kt + 2) * 64)
; #pragma unroll
;     for (int ks = 2; ks < 4; ks++) {
; #pragma unroll
;       for (int tm = 0; tm < TM; tm++) af[tm] = *(const bf16x8*)(cA + tm * 32 * LD + ks * 16);
; #pragma unroll
;       for (int tn = 0; tn < TN; tn++) bfr[tn] = *(const bf16x8*)(cB + tn * 32 * LD + ks * 16);
; #pragma unroll
;       for (int tm = 0; tm < TM; tm++)
; #pragma unroll
;         for (int tn = 0; tn < TN; tn++) acc[tm][tn] = MFMA(af[tm], bfr[tn], acc[tm][tn]);
;     }
;     __builtin_amdgcn_s_setprio(0);
;     __syncthreads();
;   }
	ds_read_b128 v[96:99], v70 offset:18432
	ds_read_b128 v[100:103], v70 offset:23040
	ds_read_b128 v[128:131], v1 offset:55296
	ds_read_b128 v[132:135], v1 offset:59904
	s_setprio 1
	ds_read_b128 v[88:91], v70 offset:18464
	s_waitcnt lgkmcnt(2)
	v_mfma_f32_32x32x16_bf16 v[34:49], v[96:99], v[128:131], v[34:49]
	ds_read_b128 v[92:95], v1 offset:55328
	s_waitcnt lgkmcnt(2)
	v_mfma_f32_32x32x16_bf16 v[50:65], v[96:99], v[132:135], v[50:65]
	ds_read_b128 v[96:99], v1 offset:59936
	s_waitcnt lgkmcnt(1)
	v_mfma_f32_32x32x16_bf16 v[34:49], v[88:91], v[92:95], v[34:49]
	s_waitcnt lgkmcnt(0)
	v_mfma_f32_32x32x16_bf16 v[50:65], v[88:91], v[96:99], v[50:65]
	s_waitcnt vmcnt(7)
	ds_write_b128 v66, v[140:143]
	s_waitcnt vmcnt(6)
	ds_write_b128 v66, v[104:107] offset:4608
	global_load_dwordx4 v[140:143], v[74:75], off offset:1408
	global_load_dwordx4 v[104:107], v[72:73], off offset:1408
	ds_read_b128 v[88:91], v70 offset:23072
	v_mfma_f32_32x32x16_bf16 v[2:17], v[100:103], v[128:131], v[2:17]
	v_mfma_f32_32x32x16_bf16 v[18:33], v[100:103], v[132:135], v[18:33]
	ds_read_b128 v[100:103], v70 offset:23136
	s_waitcnt lgkmcnt(1)
	v_mfma_f32_32x32x16_bf16 v[2:17], v[88:91], v[92:95], v[2:17]
	ds_read_b128 v[92:95], v1 offset:55360
	v_mfma_f32_32x32x16_bf16 v[18:33], v[88:91], v[96:99], v[18:33]
	s_waitcnt vmcnt(7)
	ds_write_b128 v66, v[108:111] offset:9216
	s_waitcnt vmcnt(6)
	ds_write_b128 v66, v[112:115] offset:13824
	global_load_dwordx4 v[108:111], v[76:77], off offset:1408
	global_load_dwordx4 v[112:115], v[86:87], off offset:1408
	ds_read_b128 v[88:91], v70 offset:18496
	ds_read_b128 v[96:99], v1 offset:59968
	s_waitcnt lgkmcnt(1)
	v_mfma_f32_32x32x16_bf16 v[34:49], v[88:91], v[92:95], v[34:49]
	s_waitcnt lgkmcnt(0)
	v_mfma_f32_32x32x16_bf16 v[50:65], v[88:91], v[96:99], v[50:65]
	ds_read_b128 v[88:91], v70 offset:23104
	s_waitcnt lgkmcnt(0)
	v_mfma_f32_32x32x16_bf16 v[2:17], v[88:91], v[92:95], v[2:17]
	ds_read_b128 v[92:95], v1 offset:55392
	v_mfma_f32_32x32x16_bf16 v[18:33], v[88:91], v[96:99], v[18:33]
	s_waitcnt vmcnt(7)
	ds_write_b128 v66, v[144:147] offset:36864
	s_waitcnt vmcnt(6)
	ds_write_b128 v66, v[124:127] offset:41472
	global_load_dwordx4 v[144:147], v[78:79], off offset:1408
	global_load_dwordx4 v[124:127], v[80:81], off offset:1408
	ds_read_b128 v[88:91], v70 offset:18528
	ds_read_b128 v[96:99], v1 offset:60000
	s_waitcnt lgkmcnt(1)
	v_mfma_f32_32x32x16_bf16 v[34:49], v[88:91], v[92:95], v[34:49]
	s_waitcnt lgkmcnt(0)
	v_mfma_f32_32x32x16_bf16 v[50:65], v[88:91], v[96:99], v[50:65]
	v_mfma_f32_32x32x16_bf16 v[2:17], v[100:103], v[92:95], v[2:17]
	v_mfma_f32_32x32x16_bf16 v[18:33], v[100:103], v[96:99], v[18:33]
	s_waitcnt vmcnt(7)
	ds_write_b128 v66, v[120:123] offset:46080
	s_waitcnt vmcnt(6)
	ds_write_b128 v66, v[116:119] offset:50688
	global_load_dwordx4 v[120:123], v[82:83], off offset:1408
	global_load_dwordx4 v[116:119], v[84:85], off offset:1408
	s_setprio 0
	s_waitcnt lgkmcnt(0)
	s_barrier
	ds_read_b128 v[96:99], v70
	ds_read_b128 v[100:103], v70 offset:4608
	ds_read_b128 v[128:131], v1 offset:36864
	ds_read_b128 v[132:135], v1 offset:41472
	s_setprio 1
	ds_read_b128 v[88:91], v70 offset:32
	s_waitcnt lgkmcnt(2)
	v_mfma_f32_32x32x16_bf16 v[34:49], v[96:99], v[128:131], v[34:49]
	ds_read_b128 v[92:95], v1 offset:36896
	s_waitcnt lgkmcnt(2)
	v_mfma_f32_32x32x16_bf16 v[50:65], v[96:99], v[132:135], v[50:65]
	ds_read_b128 v[96:99], v1 offset:41504
	s_waitcnt lgkmcnt(1)
	v_mfma_f32_32x32x16_bf16 v[34:49], v[88:91], v[92:95], v[34:49]
	s_waitcnt lgkmcnt(0)
	v_mfma_f32_32x32x16_bf16 v[50:65], v[88:91], v[96:99], v[50:65]
	s_waitcnt vmcnt(7)
	ds_write_b128 v66, v[140:143] offset:18432
	s_waitcnt vmcnt(6)
	ds_write_b128 v66, v[104:107] offset:23040
	global_load_dwordx4 v[140:143], v[74:75], off offset:1536
	global_load_dwordx4 v[104:107], v[72:73], off offset:1536
	ds_read_b128 v[88:91], v70 offset:4640
	v_mfma_f32_32x32x16_bf16 v[2:17], v[100:103], v[128:131], v[2:17]
	v_mfma_f32_32x32x16_bf16 v[18:33], v[100:103], v[132:135], v[18:33]
	ds_read_b128 v[100:103], v70 offset:4704
	s_waitcnt lgkmcnt(1)
	v_mfma_f32_32x32x16_bf16 v[2:17], v[88:91], v[92:95], v[2:17]
	ds_read_b128 v[92:95], v1 offset:36928
	v_mfma_f32_32x32x16_bf16 v[18:33], v[88:91], v[96:99], v[18:33]
	s_waitcnt vmcnt(7)
	ds_write_b128 v66, v[108:111] offset:27648
	s_waitcnt vmcnt(6)
	ds_write_b128 v66, v[112:115] offset:32256
	global_load_dwordx4 v[108:111], v[76:77], off offset:1536
	global_load_dwordx4 v[112:115], v[86:87], off offset:1536
	ds_read_b128 v[88:91], v70 offset:64
	ds_read_b128 v[96:99], v1 offset:41536
	s_waitcnt lgkmcnt(1)
	v_mfma_f32_32x32x16_bf16 v[34:49], v[88:91], v[92:95], v[34:49]
	s_waitcnt lgkmcnt(0)
	v_mfma_f32_32x32x16_bf16 v[50:65], v[88:91], v[96:99], v[50:65]
	ds_read_b128 v[88:91], v70 offset:4672
	s_waitcnt lgkmcnt(0)
	v_mfma_f32_32x32x16_bf16 v[2:17], v[88:91], v[92:95], v[2:17]
	ds_read_b128 v[92:95], v1 offset:36960
	v_mfma_f32_32x32x16_bf16 v[18:33], v[88:91], v[96:99], v[18:33]
	s_waitcnt vmcnt(7)
	ds_write_b128 v66, v[144:147] offset:55296
	s_waitcnt vmcnt(6)
	ds_write_b128 v66, v[124:127] offset:59904
	global_load_dwordx4 v[144:147], v[78:79], off offset:1536
	global_load_dwordx4 v[124:127], v[80:81], off offset:1536
	ds_read_b128 v[88:91], v70 offset:96
	ds_read_b128 v[96:99], v1 offset:41568
	s_waitcnt lgkmcnt(1)
	v_mfma_f32_32x32x16_bf16 v[34:49], v[88:91], v[92:95], v[34:49]
	s_waitcnt lgkmcnt(0)
	v_mfma_f32_32x32x16_bf16 v[50:65], v[88:91], v[96:99], v[50:65]
	v_mfma_f32_32x32x16_bf16 v[2:17], v[100:103], v[92:95], v[2:17]
	v_mfma_f32_32x32x16_bf16 v[18:33], v[100:103], v[96:99], v[18:33]
	s_waitcnt vmcnt(7)
	ds_write_b128 v66, v[120:123] offset:64512
	s_waitcnt vmcnt(6)
	ds_write_b128 v71, v[116:119] offset:32256
	global_load_dwordx4 v[120:123], v[82:83], off offset:1536
	global_load_dwordx4 v[116:119], v[84:85], off offset:1536
	s_setprio 0
	s_waitcnt lgkmcnt(0)
	s_barrier
; #define MFMA(a, b, c) __builtin_amdgcn_mfma_f32_32x32x16_bf16((a), (b), (c), 0, 0, 0)
; template <int TM, int TN>
; DI void gemm_mainloop(const u16* __restrict__ A, long lda, const u16* __restrict__ Bt, long ldb, int K, char* smem,
;                       f32x16 (&acc)[TM][TN]) {
;     ...
;   GEMM_GLOAD(0)
;   __syncthreads();
;   GEMM_SSTORE(0)
;   if (nk > 1) GEMM_GLOAD(64)
;   __syncthreads();
;   for (int kt = 0; kt < nk; kt++) {
;     const int buf = kt & 1;
;     const u16* cA = sA + buf * BM * LD + (wm * 32 * TM + r) * LD + h * 8;
;     const u16* cB = sB + buf * BN * LD + (wn * 32 * TN + r) * LD + h * 8;
;     bf16x8 af[TM], bfr[TN];
; #pragma unroll
;     for (int tm = 0; tm < TM; tm++) af[tm] = *(const bf16x8*)(cA + tm * 32 * LD);
; #pragma unroll
;     for (int tn = 0; tn < TN; tn++) bfr[tn] = *(const bf16x8*)(cB + tn * 32 * LD);
;     if (kt + 1 < nk) GEMM_SSTORE(buf ^ 1)
;     __builtin_amdgcn_sched_barrier(0);
;     __builtin_amdgcn_s_setprio(1);
; #pragma unroll
;     for (int tm = 0; tm < TM; tm++)
; #pragma unroll
;       for (int tn = 0; tn < TN; tn++) acc[tm][tn] = MFMA(af[tm], bfr[tn], acc[tm][tn]);
; #pragma unroll
;     for (int tm = 0; tm < TM; tm++) af[tm] = *(const bf16x8*)(cA + tm * 32 * LD + 16);
; #pragma unroll
;     for (int tn = 0; tn < TN; tn++) bfr[tn] = *(const bf16x8*)(cB + tn * 32 * LD + 16);
; #pragma unroll
;     for (int tm = 0; tm < TM; tm++)
; #pragma unroll
;       for (int tn = 0; tn < TN; tn++) acc[tm][tn] = MFMA(af[tm], bfr[tn], acc[tm][tn]);
;     __builtin_amdgcn_sched_group_barrier(0x8, 4, 0);
;     if (kt + 2 < nk) GEMM_GLOAD((kt + 2) * 64)
; #pragma unroll
;     for (int ks = 2; ks < 4; ks++) {
; #pragma unroll
;       for (int tm = 0; tm < TM; tm++) af[tm] = *(const bf16x8*)(cA + tm * 32 * LD + ks * 16);
; #pragma unroll
;       for (int tn = 0; tn < TN; tn++) bfr[tn] = *(const bf16x8*)(cB + tn * 32 * LD + ks * 16);
; #pragma unroll
;       for (int tm = 0; tm < TM; tm++)
; #pragma unroll
;         for (int tn = 0; tn < TN; tn++) acc[tm][tn] = MFMA(af[tm], bfr[tn], acc[tm][tn]);
;     }
;     __builtin_amdgcn_s_setprio(0);
;     __syncthreads();
;   }
	ds_read_b128 v[96:99], v70 offset:18432
	ds_read_b128 v[100:103], v70 offset:23040
	ds_read_b128 v[128:131], v1 offset:55296
	ds_read_b128 v[132:135], v1 offset:59904
	s_setprio 1
	ds_read_b128 v[88:91], v70 offset:18464
	s_waitcnt lgkmcnt(2)
	v_mfma_f32_32x32x16_bf16 v[34:49], v[96:99], v[128:131], v[34:49]
	ds_read_b128 v[92:95], v1 offset:55328
	s_waitcnt lgkmcnt(2)
	v_mfma_f32_32x32x16_bf16 v[50:65], v[96:99], v[132:135], v[50:65]
	ds_read_b128 v[96:99], v1 offset:59936
	s_waitcnt lgkmcnt(1)
	v_mfma_f32_32x32x16_bf16 v[34:49], v[88:91], v[92:95], v[34:49]
	s_waitcnt lgkmcnt(0)
	v_mfma_f32_32x32x16_bf16 v[50:65], v[88:91], v[96:99], v[50:65]
	s_waitcnt vmcnt(7)
	ds_write_b128 v66, v[140:143]
	s_waitcnt vmcnt(6)
	ds_write_b128 v66, v[104:107] offset:4608
	global_load_dwordx4 v[140:143], v[74:75], off offset:1664
	global_load_dwordx4 v[104:107], v[72:73], off offset:1664
	ds_read_b128 v[88:91], v70 offset:23072
	v_mfma_f32_32x32x16_bf16 v[2:17], v[100:103], v[128:131], v[2:17]
	v_mfma_f32_32x32x16_bf16 v[18:33], v[100:103], v[132:135], v[18:33]
	ds_read_b128 v[100:103], v70 offset:23136
	s_waitcnt lgkmcnt(1)
	v_mfma_f32_32x32x16_bf16 v[2:17], v[88:91], v[92:95], v[2:17]
	ds_read_b128 v[92:95], v1 offset:55360
	v_mfma_f32_32x32x16_bf16 v[18:33], v[88:91], v[96:99], v[18:33]
	s_waitcnt vmcnt(7)
	ds_write_b128 v66, v[108:111] offset:9216
	s_waitcnt vmcnt(6)
	ds_write_b128 v66, v[112:115] offset:13824
	global_load_dwordx4 v[108:111], v[76:77], off offset:1664
	global_load_dwordx4 v[112:115], v[86:87], off offset:1664
	ds_read_b128 v[88:91], v70 offset:18496
	ds_read_b128 v[96:99], v1 offset:59968
	s_waitcnt lgkmcnt(1)
	v_mfma_f32_32x32x16_bf16 v[34:49], v[88:91], v[92:95], v[34:49]
	s_waitcnt lgkmcnt(0)
	v_mfma_f32_32x32x16_bf16 v[50:65], v[88:91], v[96:99], v[50:65]
	ds_read_b128 v[88:91], v70 offset:23104
	s_waitcnt lgkmcnt(0)
	v_mfma_f32_32x32x16_bf16 v[2:17], v[88:91], v[92:95], v[2:17]
	ds_read_b128 v[92:95], v1 offset:55392
	v_mfma_f32_32x32x16_bf16 v[18:33], v[88:91], v[96:99], v[18:33]
	s_waitcnt vmcnt(7)
	ds_write_b128 v66, v[144:147] offset:36864
	s_waitcnt vmcnt(6)
	ds_write_b128 v66, v[124:127] offset:41472
	global_load_dwordx4 v[144:147], v[78:79], off offset:1664
	global_load_dwordx4 v[124:127], v[80:81], off offset:1664
	ds_read_b128 v[88:91], v70 offset:18528
	ds_read_b128 v[96:99], v1 offset:60000
	s_waitcnt lgkmcnt(1)
	v_mfma_f32_32x32x16_bf16 v[34:49], v[88:91], v[92:95], v[34:49]
	s_waitcnt lgkmcnt(0)
	v_mfma_f32_32x32x16_bf16 v[50:65], v[88:91], v[96:99], v[50:65]
	v_mfma_f32_32x32x16_bf16 v[2:17], v[100:103], v[92:95], v[2:17]
	v_mfma_f32_32x32x16_bf16 v[18:33], v[100:103], v[96:99], v[18:33]
	s_waitcnt vmcnt(7)
	ds_write_b128 v66, v[120:123] offset:46080
	s_waitcnt vmcnt(6)
	ds_write_b128 v66, v[116:119] offset:50688
	global_load_dwordx4 v[120:123], v[82:83], off offset:1664
	global_load_dwordx4 v[116:119], v[84:85], off offset:1664
	s_setprio 0
	s_waitcnt lgkmcnt(0)
	s_barrier
	ds_read_b128 v[96:99], v70
	ds_read_b128 v[100:103], v70 offset:4608
	ds_read_b128 v[128:131], v1 offset:36864
	ds_read_b128 v[132:135], v1 offset:41472
	s_setprio 1
	ds_read_b128 v[88:91], v70 offset:32
	s_waitcnt lgkmcnt(2)
	v_mfma_f32_32x32x16_bf16 v[34:49], v[96:99], v[128:131], v[34:49]
	ds_read_b128 v[92:95], v1 offset:36896
	s_waitcnt lgkmcnt(2)
	v_mfma_f32_32x32x16_bf16 v[50:65], v[96:99], v[132:135], v[50:65]
	ds_read_b128 v[96:99], v1 offset:41504
	s_waitcnt lgkmcnt(1)
	v_mfma_f32_32x32x16_bf16 v[34:49], v[88:91], v[92:95], v[34:49]
	s_waitcnt lgkmcnt(0)
	v_mfma_f32_32x32x16_bf16 v[50:65], v[88:91], v[96:99], v[50:65]
	s_waitcnt vmcnt(7)
	ds_write_b128 v66, v[140:143] offset:18432
	s_waitcnt vmcnt(6)
	ds_write_b128 v66, v[104:107] offset:23040
	global_load_dwordx4 v[140:143], v[74:75], off offset:1792
	global_load_dwordx4 v[104:107], v[72:73], off offset:1792
	ds_read_b128 v[88:91], v70 offset:4640
	v_mfma_f32_32x32x16_bf16 v[2:17], v[100:103], v[128:131], v[2:17]
	v_mfma_f32_32x32x16_bf16 v[18:33], v[100:103], v[132:135], v[18:33]
	ds_read_b128 v[100:103], v70 offset:4704
	s_waitcnt lgkmcnt(1)
	v_mfma_f32_32x32x16_bf16 v[2:17], v[88:91], v[92:95], v[2:17]
	ds_read_b128 v[92:95], v1 offset:36928
	v_mfma_f32_32x32x16_bf16 v[18:33], v[88:91], v[96:99], v[18:33]
	s_waitcnt vmcnt(7)
	ds_write_b128 v66, v[108:111] offset:27648
	s_waitcnt vmcnt(6)
	ds_write_b128 v66, v[112:115] offset:32256
	global_load_dwordx4 v[108:111], v[76:77], off offset:1792
	global_load_dwordx4 v[112:115], v[86:87], off offset:1792
	ds_read_b128 v[88:91], v70 offset:64
	ds_read_b128 v[96:99], v1 offset:41536
	s_waitcnt lgkmcnt(1)
	v_mfma_f32_32x32x16_bf16 v[34:49], v[88:91], v[92:95], v[34:49]
	s_waitcnt lgkmcnt(0)
	v_mfma_f32_32x32x16_bf16 v[50:65], v[88:91], v[96:99], v[50:65]
	ds_read_b128 v[88:91], v70 offset:4672
	s_waitcnt lgkmcnt(0)
	v_mfma_f32_32x32x16_bf16 v[2:17], v[88:91], v[92:95], v[2:17]
	ds_read_b128 v[92:95], v1 offset:36960
	v_mfma_f32_32x32x16_bf16 v[18:33], v[88:91], v[96:99], v[18:33]
	s_waitcnt vmcnt(7)
	ds_write_b128 v66, v[144:147] offset:55296
	s_waitcnt vmcnt(6)
	ds_write_b128 v66, v[124:127] offset:59904
	global_load_dwordx4 v[144:147], v[78:79], off offset:1792
	global_load_dwordx4 v[124:127], v[80:81], off offset:1792
	ds_read_b128 v[88:91], v70 offset:96
	ds_read_b128 v[96:99], v1 offset:41568
	s_waitcnt lgkmcnt(1)
	v_mfma_f32_32x32x16_bf16 v[34:49], v[88:91], v[92:95], v[34:49]
	s_waitcnt lgkmcnt(0)
	v_mfma_f32_32x32x16_bf16 v[50:65], v[88:91], v[96:99], v[50:65]
	v_mfma_f32_32x32x16_bf16 v[2:17], v[100:103], v[92:95], v[2:17]
	v_mfma_f32_32x32x16_bf16 v[18:33], v[100:103], v[96:99], v[18:33]
	s_waitcnt vmcnt(7)
	ds_write_b128 v66, v[120:123] offset:64512
	s_waitcnt vmcnt(6)
	ds_write_b128 v71, v[116:119] offset:32256
	global_load_dwordx4 v[120:123], v[82:83], off offset:1792
	global_load_dwordx4 v[116:119], v[84:85], off offset:1792
	s_setprio 0
	s_waitcnt lgkmcnt(0)
	s_barrier
; #define MFMA(a, b, c) __builtin_amdgcn_mfma_f32_32x32x16_bf16((a), (b), (c), 0, 0, 0)
; template <int TM, int TN>
; DI void gemm_mainloop(const u16* __restrict__ A, long lda, const u16* __restrict__ Bt, long ldb, int K, char* smem,
;                       f32x16 (&acc)[TM][TN]) {
;     ...
;   for (int kt = 0; kt < nk; kt++) {
;     const int buf = kt & 1;
;     const u16* cA = sA + buf * BM * LD + (wm * 32 * TM + r) * LD + h * 8;
;     const u16* cB = sB + buf * BN * LD + (wn * 32 * TN + r) * LD + h * 8;
;     bf16x8 af[TM], bfr[TN];
; #pragma unroll
;     for (int tm = 0; tm < TM; tm++) af[tm] = *(const bf16x8*)(cA + tm * 32 * LD);
; #pragma unroll
;     for (int tn = 0; tn < TN; tn++) bfr[tn] = *(const bf16x8*)(cB + tn * 32 * LD);
;     if (kt + 1 < nk) GEMM_SSTORE(buf ^ 1)
;     __builtin_amdgcn_sched_barrier(0);
;     __builtin_amdgcn_s_setprio(1);
; #pragma unroll
;     for (int tm = 0; tm < TM; tm++)
; #pragma unroll
;       for (int tn = 0; tn < TN; tn++) acc[tm][tn] = MFMA(af[tm], bfr[tn], acc[tm][tn]);
; #pragma unroll
;     for (int tm = 0; tm < TM; tm++) af[tm] = *(const bf16x8*)(cA + tm * 32 * LD + 16);
; #pragma unroll
;     for (int tn = 0; tn < TN; tn++) bfr[tn] = *(const bf16x8*)(cB + tn * 32 * LD + 16);
; #pragma unroll
;     for (int tm = 0; tm < TM; tm++)
; #pragma unroll
;       for (int tn = 0; tn < TN; tn++) acc[tm][tn] = MFMA(af[tm], bfr[tn], acc[tm][tn]);
;     __builtin_amdgcn_sched_group_barrier(0x8, 4, 0);
;     if (kt + 2 < nk) GEMM_GLOAD((kt + 2) * 64)
; #pragma unroll
;     for (int ks = 2; ks < 4; ks++) {
; #pragma unroll
;       for (int tm = 0; tm < TM; tm++) af[tm] = *(const bf16x8*)(cA + tm * 32 * LD + ks * 16);
; #pragma unroll
;       for (int tn = 0; tn < TN; tn++) bfr[tn] = *(const bf16x8*)(cB + tn * 32 * LD + ks * 16);
; #pragma unroll
;       for (int tm = 0; tm < TM; tm++)
; #pragma unroll
;         for (int tn = 0; tn < TN; tn++) acc[tm][tn] = MFMA(af[tm], bfr[tn], acc[tm][tn]);
;     }
;     __builtin_amdgcn_s_setprio(0);
;     __syncthreads();
;   }
	ds_read_b128 v[96:99], v70 offset:18432
	ds_read_b128 v[100:103], v70 offset:23040
	ds_read_b128 v[128:131], v1 offset:55296
	ds_read_b128 v[132:135], v1 offset:59904
	s_setprio 1
	ds_read_b128 v[88:91], v70 offset:18464
	s_waitcnt lgkmcnt(2)
	v_mfma_f32_32x32x16_bf16 v[34:49], v[96:99], v[128:131], v[34:49]
	ds_read_b128 v[92:95], v1 offset:55328
	s_waitcnt lgkmcnt(2)
	v_mfma_f32_32x32x16_bf16 v[50:65], v[96:99], v[132:135], v[50:65]
	ds_read_b128 v[96:99], v1 offset:59936
	s_waitcnt lgkmcnt(1)
	v_mfma_f32_32x32x16_bf16 v[34:49], v[88:91], v[92:95], v[34:49]
	s_waitcnt lgkmcnt(0)
	v_mfma_f32_32x32x16_bf16 v[50:65], v[88:91], v[96:99], v[50:65]
	s_waitcnt vmcnt(7)
	ds_write_b128 v66, v[140:143]
	s_waitcnt vmcnt(6)
	ds_write_b128 v66, v[104:107] offset:4608
	global_load_dwordx4 v[140:143], v[74:75], off offset:1920
	global_load_dwordx4 v[104:107], v[72:73], off offset:1920
	ds_read_b128 v[88:91], v70 offset:23072
	v_mfma_f32_32x32x16_bf16 v[2:17], v[100:103], v[128:131], v[2:17]
	v_mfma_f32_32x32x16_bf16 v[18:33], v[100:103], v[132:135], v[18:33]
	ds_read_b128 v[100:103], v70 offset:23136
	s_waitcnt lgkmcnt(1)
	v_mfma_f32_32x32x16_bf16 v[2:17], v[88:91], v[92:95], v[2:17]
	ds_read_b128 v[92:95], v1 offset:55360
	v_mfma_f32_32x32x16_bf16 v[18:33], v[88:91], v[96:99], v[18:33]
	s_waitcnt vmcnt(7)
	ds_write_b128 v66, v[108:111] offset:9216
	s_waitcnt vmcnt(6)
	ds_write_b128 v66, v[112:115] offset:13824
	global_load_dwordx4 v[108:111], v[76:77], off offset:1920
	global_load_dwordx4 v[112:115], v[86:87], off offset:1920
	ds_read_b128 v[88:91], v70 offset:18496
	ds_read_b128 v[96:99], v1 offset:59968
	s_waitcnt lgkmcnt(1)
	v_mfma_f32_32x32x16_bf16 v[34:49], v[88:91], v[92:95], v[34:49]
	s_waitcnt lgkmcnt(0)
	v_mfma_f32_32x32x16_bf16 v[50:65], v[88:91], v[96:99], v[50:65]
	ds_read_b128 v[88:91], v70 offset:23104
	s_waitcnt lgkmcnt(0)
	v_mfma_f32_32x32x16_bf16 v[2:17], v[88:91], v[92:95], v[2:17]
	ds_read_b128 v[92:95], v1 offset:55392
	v_mfma_f32_32x32x16_bf16 v[18:33], v[88:91], v[96:99], v[18:33]
	s_waitcnt vmcnt(7)
	ds_write_b128 v66, v[144:147] offset:36864
	s_waitcnt vmcnt(6)
	ds_write_b128 v66, v[124:127] offset:41472
	global_load_dwordx4 v[144:147], v[78:79], off offset:1920
	global_load_dwordx4 v[124:127], v[80:81], off offset:1920
	ds_read_b128 v[88:91], v70 offset:18528
	ds_read_b128 v[96:99], v1 offset:60000
	s_waitcnt lgkmcnt(1)
	v_mfma_f32_32x32x16_bf16 v[34:49], v[88:91], v[92:95], v[34:49]
	s_waitcnt lgkmcnt(0)
	v_mfma_f32_32x32x16_bf16 v[50:65], v[88:91], v[96:99], v[50:65]
	s_nop 0
	v_mfma_f32_32x32x16_bf16 v[2:17], v[100:103], v[92:95], v[2:17]
	v_mfma_f32_32x32x16_bf16 v[18:33], v[100:103], v[96:99], v[18:33]
	s_waitcnt vmcnt(7)
	ds_write_b128 v66, v[120:123] offset:46080
	s_waitcnt vmcnt(6)
	ds_write_b128 v66, v[116:119] offset:50688
	global_load_dwordx4 v[120:123], v[82:83], off offset:1920
	global_load_dwordx4 v[116:119], v[84:85], off offset:1920
	s_setprio 0
	s_waitcnt lgkmcnt(0)
	s_barrier
	ds_read_b128 v[76:79], v70
	ds_read_b128 v[80:83], v70 offset:4608
	ds_read_b128 v[84:87], v1 offset:36864
	ds_read_b128 v[92:95], v1 offset:41472
	s_setprio 1
	ds_read_b128 v[72:75], v70 offset:32
	s_waitcnt lgkmcnt(2)
	v_mfma_f32_32x32x16_bf16 v[34:49], v[76:79], v[84:87], v[34:49]
	s_waitcnt lgkmcnt(1)
	v_mfma_f32_32x32x16_bf16 v[50:65], v[76:79], v[92:95], v[50:65]
	ds_read_b128 v[76:79], v1 offset:36896
	v_mfma_f32_32x32x16_bf16 v[2:17], v[80:83], v[84:87], v[2:17]
	v_mfma_f32_32x32x16_bf16 v[18:33], v[80:83], v[92:95], v[18:33]
	s_waitcnt vmcnt(7)
	ds_write_b128 v66, v[140:143] offset:18432
	s_waitcnt vmcnt(6)
	ds_write_b128 v66, v[104:107] offset:23040
	ds_read_b128 v[80:83], v1 offset:41504
	s_waitcnt lgkmcnt(3)
	v_mfma_f32_32x32x16_bf16 v[34:49], v[72:75], v[76:79], v[34:49]
	s_waitcnt lgkmcnt(0)
	v_mfma_f32_32x32x16_bf16 v[50:65], v[72:75], v[80:83], v[50:65]
	ds_read_b128 v[72:75], v70 offset:4640
	s_waitcnt lgkmcnt(0)
	v_mfma_f32_32x32x16_bf16 v[2:17], v[72:75], v[76:79], v[2:17]
	ds_read_b128 v[76:79], v1 offset:36928
	v_mfma_f32_32x32x16_bf16 v[18:33], v[72:75], v[80:83], v[18:33]
	s_waitcnt vmcnt(5)
	ds_write_b128 v66, v[108:111] offset:27648
	s_waitcnt vmcnt(4)
	ds_write_b128 v66, v[112:115] offset:32256
	ds_read_b128 v[72:75], v70 offset:64
	ds_read_b128 v[80:83], v1 offset:41536
	s_waitcnt lgkmcnt(1)
	v_mfma_f32_32x32x16_bf16 v[34:49], v[72:75], v[76:79], v[34:49]
	s_waitcnt lgkmcnt(0)
	v_mfma_f32_32x32x16_bf16 v[50:65], v[72:75], v[80:83], v[50:65]
	ds_read_b128 v[72:75], v70 offset:4672
	s_waitcnt lgkmcnt(0)
	v_mfma_f32_32x32x16_bf16 v[2:17], v[72:75], v[76:79], v[2:17]
	ds_read_b128 v[76:79], v1 offset:36960
	v_mfma_f32_32x32x16_bf16 v[18:33], v[72:75], v[80:83], v[18:33]
	s_waitcnt vmcnt(3)
	ds_write_b128 v66, v[144:147] offset:55296
	s_waitcnt vmcnt(2)
	ds_write_b128 v66, v[124:127] offset:59904
	ds_read_b128 v[72:75], v70 offset:96
	ds_read_b128 v[80:83], v1 offset:41568
	s_waitcnt lgkmcnt(1)
	v_mfma_f32_32x32x16_bf16 v[34:49], v[72:75], v[76:79], v[34:49]
	s_waitcnt lgkmcnt(0)
	v_mfma_f32_32x32x16_bf16 v[50:65], v[72:75], v[80:83], v[50:65]
	ds_read_b128 v[72:75], v70 offset:4704
	s_waitcnt lgkmcnt(0)
	v_mfma_f32_32x32x16_bf16 v[2:17], v[72:75], v[76:79], v[2:17]
	v_mfma_f32_32x32x16_bf16 v[18:33], v[72:75], v[80:83], v[18:33]
	s_waitcnt vmcnt(1)
	ds_write_b128 v66, v[120:123] offset:64512
	s_waitcnt vmcnt(0)
	ds_write_b128 v71, v[116:119] offset:32256
	s_setprio 0
	s_waitcnt lgkmcnt(0)
	s_barrier
; #define MFMA(a, b, c) __builtin_amdgcn_mfma_f32_32x32x16_bf16((a), (b), (c), 0, 0, 0)
; DI int crow(int i, int h) { return (i & 3) + 8 * (i >> 2) + 4 * h; }
; template <int TM, int TN>
; DI void gemm_mainloop(const u16* __restrict__ A, long lda, const u16* __restrict__ Bt, long ldb, int K, char* smem,
;                       f32x16 (&acc)[TM][TN]) {
;     ...
;     for (int tm = 0; tm < TM; tm++)
; #pragma unroll
;       for (int tn = 0; tn < TN; tn++) acc[tm][tn] = MFMA(af[tm], bfr[tn], acc[tm][tn]);
; #pragma unroll
;     for (int tm = 0; tm < TM; tm++) af[tm] = *(const bf16x8*)(cA + tm * 32 * LD + 16);
; #pragma unroll
;     for (int tn = 0; tn < TN; tn++) bfr[tn] = *(const bf16x8*)(cB + tn * 32 * LD + 16);
; #pragma unroll
;     for (int tm = 0; tm < TM; tm++)
; #pragma unroll
;       for (int tn = 0; tn < TN; tn++) acc[tm][tn] = MFMA(af[tm], bfr[tn], acc[tm][tn]);
;     __builtin_amdgcn_sched_group_barrier(0x8, 4, 0);
;     if (kt + 2 < nk) GEMM_GLOAD((kt + 2) * 64)
; #pragma unroll
;     for (int ks = 2; ks < 4; ks++) {
; #pragma unroll
;       for (int tm = 0; tm < TM; tm++) af[tm] = *(const bf16x8*)(cA + tm * 32 * LD + ks * 16);
; #pragma unroll
;       for (int tn = 0; tn < TN; tn++) bfr[tn] = *(const bf16x8*)(cB + tn * 32 * LD + ks * 16);
; #pragma unroll
;       for (int tm = 0; tm < TM; tm++)
; #pragma unroll
;         for (int tn = 0; tn < TN; tn++) acc[tm][tn] = MFMA(af[tm], bfr[tn], acc[tm][tn]);
;     }
;     __builtin_amdgcn_s_setprio(0);
;     __syncthreads();
;   }
; template <int TM, int TN, class Epi>
; DI void gemm_tile(const u16* A, long lda, const u16* Bt, long ldb, int K, int m0, int n0, char* smem, const Epi& epi) {
;     ...
; #pragma unroll
;   for (int tm = 0; tm < TM; tm++)
; #pragma unroll
;     for (int tn = 0; tn < TN; tn++)
; #pragma unroll
;       for (int i = 0; i < 16; i++)
;         Ct[(wm * 32 * TM + tm * 32 + crow(i, h)) * LDC + wn * 32 * TN + tn * 32 + r] = acc[tm][tn][i];
;   __syncthreads();
;   epi(Ct, LDC, m0, n0, tid, BM);
;   __syncthreads();
;   (void)BM;
; }
;   DI void operator()(const float* Ct, int ldc, int m0, int n0, int tid, int bm) const {
; #pragma unroll 4
;     for (int it = 0; it < bm / 16; it++) {
;       int id = tid + 256 * it; int row = id >> 4, c8 = (id & 15) * 8;
;       int n = n0 + c8;
;       if (n < nmax) {
	ds_read_b128 v[72:75], v70 offset:18432
	ds_read_b128 v[76:79], v70 offset:23040
	ds_read_b128 v[80:83], v1 offset:55296
	ds_read_b128 v[84:87], v1 offset:59904
	s_setprio 1
	s_waitcnt lgkmcnt(1)
	v_mfma_f32_32x32x16_bf16 v[34:49], v[72:75], v[80:83], v[34:49]
	s_waitcnt lgkmcnt(0)
	v_mfma_f32_32x32x16_bf16 v[50:65], v[72:75], v[84:87], v[50:65]
	ds_read_b128 v[72:75], v70 offset:18464
	v_mfma_f32_32x32x16_bf16 v[2:17], v[76:79], v[80:83], v[2:17]
	ds_read_b128 v[80:83], v1 offset:59936
	v_mfma_f32_32x32x16_bf16 v[18:33], v[76:79], v[84:87], v[18:33]
	ds_read_b128 v[76:79], v1 offset:55328
	s_waitcnt lgkmcnt(0)
	v_mfma_f32_32x32x16_bf16 v[34:49], v[72:75], v[76:79], v[34:49]
	v_mfma_f32_32x32x16_bf16 v[50:65], v[72:75], v[80:83], v[50:65]
	ds_read_b128 v[72:75], v70 offset:23072
	s_waitcnt lgkmcnt(0)
	v_mfma_f32_32x32x16_bf16 v[2:17], v[72:75], v[76:79], v[2:17]
	ds_read_b128 v[76:79], v1 offset:55360
	v_mfma_f32_32x32x16_bf16 v[18:33], v[72:75], v[80:83], v[18:33]
	ds_read_b128 v[72:75], v70 offset:18496
	ds_read_b128 v[80:83], v1 offset:59968
	s_waitcnt lgkmcnt(1)
	v_mfma_f32_32x32x16_bf16 v[34:49], v[72:75], v[76:79], v[34:49]
	s_waitcnt lgkmcnt(0)
	v_mfma_f32_32x32x16_bf16 v[50:65], v[72:75], v[80:83], v[50:65]
	ds_read_b128 v[72:75], v70 offset:23104
	s_waitcnt lgkmcnt(0)
	v_mfma_f32_32x32x16_bf16 v[2:17], v[72:75], v[76:79], v[2:17]
	ds_read_b128 v[76:79], v1 offset:55392
	v_mfma_f32_32x32x16_bf16 v[18:33], v[72:75], v[80:83], v[18:33]
	ds_read_b128 v[72:75], v70 offset:18528
	ds_read_b128 v[80:83], v1 offset:60000
	s_waitcnt lgkmcnt(1)
	v_mfma_f32_32x32x16_bf16 v[34:49], v[72:75], v[76:79], v[34:49]
	s_waitcnt lgkmcnt(0)
	v_mfma_f32_32x32x16_bf16 v[50:65], v[72:75], v[80:83], v[50:65]
	ds_read_b128 v[70:73], v70 offset:23136
	s_waitcnt lgkmcnt(0)
	v_mfma_f32_32x32x16_bf16 v[2:17], v[70:73], v[76:79], v[2:17]
	v_mfma_f32_32x32x16_bf16 v[18:33], v[70:73], v[80:83], v[18:33]
	s_setprio 0
	v_mov_b32_e32 v1, v0
	s_barrier
	s_mov_b32 s26, 0
	v_lshrrev_b32_e32 v66, 1, v1
	v_and_b32_e32 v66, 0xfffffc0, v66
	v_lshrrev_b32_e32 v70, 3, v1
	v_and_or_b32 v66, v70, 4, v66
	v_and_b32_e32 v70, 0x5f, v1
	v_mul_lo_u32 v66, v66, s22
	v_lshl_add_u32 v66, v70, 2, v66
	ds_write2_b32 v66, v34, v50 offset1:32
	v_add_u32_e32 v34, 0x400, v66
	ds_write2_b32 v34, v36, v52 offset0:8 offset1:40
	ds_write2_b32 v34, v37, v53 offset0:140 offset1:172
	v_add_u32_e32 v34, 0x1000, v66
	ds_write2_b32 v34, v38, v54 offset0:32 offset1:64
	ds_write2_b32 v34, v39, v55 offset0:164 offset1:196
	v_add_u32_e32 v34, 0x1400, v66
	ds_write2_b32 v34, v40, v56 offset0:40 offset1:72
	ds_write2_b32 v34, v41, v57 offset0:172 offset1:204
	v_add_u32_e32 v34, 0x2000, v66
	ds_write2_b32 v34, v42, v58 offset0:64 offset1:96
	ds_write2_b32 v34, v43, v59 offset0:196 offset1:228
	v_add_u32_e32 v34, 0x2400, v66
	ds_write2_b32 v34, v44, v60 offset0:72 offset1:104
	ds_write2_b32 v34, v45, v61 offset0:204 offset1:236
	v_add_u32_e32 v34, 0x3000, v66
	ds_write2_b32 v34, v46, v62 offset0:96 offset1:128
	v_add_u32_e32 v34, 0x3200, v66
	ds_write2_b32 v34, v47, v63 offset0:100 offset1:132
	v_add_u32_e32 v34, 0x3400, v66
	ds_write2_b32 v34, v48, v64 offset0:104 offset1:136
	v_add_u32_e32 v34, 0x3600, v66
	ds_write2_b32 v34, v49, v65 offset0:108 offset1:140
	v_add_u32_e32 v34, 0x4000, v66
	ds_write2_b32 v34, v2, v18 offset0:128 offset1:160
	v_add_u32_e32 v2, 0x4400, v66
	ds_write2_b32 v2, v3, v19 offset0:4 offset1:36
	ds_write2_b32 v2, v4, v20 offset0:136 offset1:168
	v_add_u32_e32 v2, 0x4800, v66
	ds_write2_b32 v2, v5, v21 offset0:12 offset1:44
	v_add_u32_e32 v2, 0x5000, v66
	ds_write2_b32 v2, v6, v22 offset0:160 offset1:192
	v_add_u32_e32 v2, 0x5400, v66
	ds_write2_b32 v2, v7, v23 offset0:36 offset1:68
	ds_write2_b32 v2, v8, v24 offset0:168 offset1:200
	v_add_u32_e32 v2, 0x5800, v66
	ds_write2_b32 v2, v9, v25 offset0:44 offset1:76
	v_add_u32_e32 v2, 0x6000, v66
	ds_write2_b32 v2, v10, v26 offset0:192 offset1:224
	v_add_u32_e32 v2, 0x6400, v66
	ds_write2_b32 v2, v11, v27 offset0:68 offset1:100
	ds_write2_b32 v2, v12, v28 offset0:200 offset1:232
	v_add_u32_e32 v2, 0x6800, v66
	ds_write2_b32 v2, v13, v29 offset0:76 offset1:108
	v_add_u32_e32 v2, 0x7200, v66
	ds_write2_b32 v2, v14, v30 offset0:96 offset1:128
	v_add_u32_e32 v2, 0x7400, v66
	ds_write2_b32 v2, v15, v31 offset0:100 offset1:132
	v_add_u32_e32 v2, 0x7600, v66
	ds_write2_b32 v2, v16, v32 offset0:104 offset1:136
	v_add_u32_e32 v2, 0x7800, v66
	ds_write2_b32 v2, v17, v33 offset0:108 offset1:140
	v_lshlrev_b32_e32 v2, 3, v1
	v_and_b32_e32 v2, 0x78, v2
	v_or_b32_e32 v4, s11, v2
	v_ashrrev_i32_e32 v5, 31, v4
	v_lshlrev_b32_e32 v2, 2, v2
	v_cmp_gt_i32_e32 vcc, s23, v4
	v_lshl_add_u64 v[4:5], v[4:5], 1, s[8:9]
	ds_write2_b32 v66, v35, v51 offset0:132 offset1:164
	s_waitcnt lgkmcnt(0)
	s_barrier
	s_branch .LBB0_2476

; #define MFMA(a, b, c) __builtin_amdgcn_mfma_f32_32x32x16_bf16((a), (b), (c), 0, 0, 0)
; template <int TM, int TN>
; DI void gemm_mainloop(const u16* __restrict__ A, long lda, const u16* __restrict__ Bt, long ldb, int K, char* smem,
;                       f32x16 (&acc)[TM][TN]) {
;     ...
;   const int nk = K / 64;
;   const int lrow = tid >> 3, lch = (tid & 7) * 8;
;   const u16* gA = A + (long)lrow * lda + lch;
;   const u16* gB = Bt + (long)lrow * ldb + lch;
;   const int soff = lrow * LD + lch;
;     ...
;   GEMM_GLOAD(0)
;   __syncthreads();
;   GEMM_SSTORE(0)
;   if (nk > 1) GEMM_GLOAD(64)
;   __syncthreads();
;   for (int kt = 0; kt < nk; kt++) {
;     const int buf = kt & 1;
;     const u16* cA = sA + buf * BM * LD + (wm * 32 * TM + r) * LD + h * 8;
;     const u16* cB = sB + buf * BN * LD + (wn * 32 * TN + r) * LD + h * 8;
;     bf16x8 af[TM], bfr[TN];
; #pragma unroll
;     for (int tm = 0; tm < TM; tm++) af[tm] = *(const bf16x8*)(cA + tm * 32 * LD);
; #pragma unroll
;     for (int tn = 0; tn < TN; tn++) bfr[tn] = *(const bf16x8*)(cB + tn * 32 * LD);
;     if (kt + 1 < nk) GEMM_SSTORE(buf ^ 1)
;     __builtin_amdgcn_sched_barrier(0);
;     __builtin_amdgcn_s_setprio(1);
; #pragma unroll
;     for (int tm = 0; tm < TM; tm++)
; #pragma unroll
;       for (int tn = 0; tn < TN; tn++) acc[tm][tn] = MFMA(af[tm], bfr[tn], acc[tm][tn]);
; #pragma unroll
;     for (int tm = 0; tm < TM; tm++) af[tm] = *(const bf16x8*)(cA + tm * 32 * LD + 16);
; #pragma unroll
;     for (int tn = 0; tn < TN; tn++) bfr[tn] = *(const bf16x8*)(cB + tn * 32 * LD + 16);
; #pragma unroll
;     for (int tm = 0; tm < TM; tm++)
; #pragma unroll
;       for (int tn = 0; tn < TN; tn++) acc[tm][tn] = MFMA(af[tm], bfr[tn], acc[tm][tn]);
;     __builtin_amdgcn_sched_group_barrier(0x8, 4, 0);
;     if (kt + 2 < nk) GEMM_GLOAD((kt + 2) * 64)
; #pragma unroll
;     for (int ks = 2; ks < 4; ks++) {
; #pragma unroll
;       for (int tm = 0; tm < TM; tm++) af[tm] = *(const bf16x8*)(cA + tm * 32 * LD + ks * 16);
; #pragma unroll
;       for (int tn = 0; tn < TN; tn++) bfr[tn] = *(const bf16x8*)(cB + tn * 32 * LD + ks * 16);
; #pragma unroll
;       for (int tm = 0; tm < TM; tm++)
; #pragma unroll
;         for (int tn = 0; tn < TN; tn++) acc[tm][tn] = MFMA(af[tm], bfr[tn], acc[tm][tn]);
;     }
;     __builtin_amdgcn_s_setprio(0);
;     __syncthreads();
;   }
.LBB0_2745:
	s_lshl_b32 s6, s24, 8
	s_and_b32 s25, s6, 0xfffffe00
	s_lshl_b32 s6, s24, 11
	s_add_i32 s25, s25, s8
	s_and_b32 s6, s6, 0x800
	s_add_i32 s6, s6, s9
	s_mul_i32 s26, s25, 0x880
	s_mul_hi_i32 s7, s25, 0x880
	s_add_u32 s26, s4, s26
	v_mov_b32_e32 v1, v0
	s_addc_u32 s27, s5, s7
	s_ashr_i32 s7, s6, 31
	v_lshlrev_b32_e32 v2, 3, v1
	v_ashrrev_i32_e32 v68, 3, v1
	v_and_b32_e32 v69, 56, v2
	v_mov_b64_e32 v[2:3], s[26:27]
	v_mad_i64_i32 v[2:3], s[26:27], v68, s15, v[2:3]
	v_lshlrev_b32_e32 v66, 1, v69
	v_lshl_add_u64 v[72:73], v[2:3], 0, v[66:67]
	s_mul_i32 s28, s6, 0x880
	v_add_co_u32_e32 v70, vcc, s17, v72
	s_mul_hi_i32 s29, s6, 0x880
	s_add_u32 s28, s11, s28
	v_addc_co_u32_e32 v71, vcc, 0, v73, vcc
	s_addc_u32 s29, s14, s29
	v_add_co_u32_e32 v74, vcc, s18, v72
	v_mov_b64_e32 v[2:3], s[28:29]
	s_nop 0
	v_addc_co_u32_e32 v75, vcc, 0, v73, vcc
	v_mad_i64_i32 v[18:19], s[26:27], v68, s15, v[2:3]
	v_add_co_u32_e32 v78, vcc, s19, v72
	v_lshl_add_u64 v[76:77], v[18:19], 0, v[66:67]
	s_nop 0
	v_addc_co_u32_e32 v79, vcc, 0, v73, vcc
	v_add_co_u32_e32 v80, vcc, s17, v76
	global_load_dwordx4 v[2:5], v[72:73], off
	s_nop 0
	v_addc_co_u32_e32 v81, vcc, 0, v77, vcc
	v_add_co_u32_e32 v82, vcc, s18, v76
	global_load_dwordx4 v[6:9], v[70:71], off
	s_nop 0
	v_addc_co_u32_e32 v83, vcc, 0, v77, vcc
	v_add_co_u32_e32 v84, vcc, s19, v76
	global_load_dwordx4 v[10:13], v[74:75], off
	s_nop 0
	v_addc_co_u32_e32 v85, vcc, 0, v77, vcc
	global_load_dwordx4 v[14:17], v[78:79], off
	global_load_dwordx4 v[18:21], v[76:77], off
	global_load_dwordx4 v[22:25], v[80:81], off
	global_load_dwordx4 v[26:29], v[82:83], off
	global_load_dwordx4 v[30:33], v[84:85], off
	s_barrier
	global_load_dwordx4 v[34:37], v[72:73], off offset:128
	global_load_dwordx4 v[38:41], v[70:71], off offset:128
	global_load_dwordx4 v[42:45], v[74:75], off offset:128
	global_load_dwordx4 v[46:49], v[78:79], off offset:128
	global_load_dwordx4 v[50:53], v[76:77], off offset:128
	global_load_dwordx4 v[54:57], v[80:81], off offset:128
	global_load_dwordx4 v[58:61], v[82:83], off offset:128
	global_load_dwordx4 v[62:65], v[84:85], off offset:128
	v_and_b32_e32 v66, 31, v1
	v_lshrrev_b32_e32 v86, 1, v1
	v_mul_lo_u32 v68, v68, s16
	v_and_or_b32 v87, v86, s20, v66
	v_and_b32_e32 v86, 16, v86
	v_and_b32_e32 v1, 0x5f, v1
	v_add_lshl_u32 v66, v68, v69, 1
	v_mad_u64_u32 v[68:69], s[26:27], v87, s21, v[86:87]
	v_mad_u32_u24 v1, v1, s21, v86
	v_add_u32_e32 v69, 0x9000, v66
	s_waitcnt vmcnt(15)
	ds_write_b128 v66, v[2:5]
	s_waitcnt vmcnt(14)
	ds_write_b128 v66, v[6:9] offset:4608
	s_waitcnt vmcnt(13)
	ds_write_b128 v66, v[10:13] offset:9216
	s_waitcnt vmcnt(12)
	ds_write_b128 v66, v[14:17] offset:13824
	s_waitcnt vmcnt(11)
	ds_write_b128 v66, v[18:21] offset:36864
	s_waitcnt vmcnt(10)
	ds_write_b128 v66, v[22:25] offset:41472
	s_waitcnt vmcnt(9)
	ds_write_b128 v66, v[26:29] offset:46080
	s_waitcnt vmcnt(8)
	ds_write_b128 v66, v[30:33] offset:50688
	s_waitcnt lgkmcnt(0)
	s_barrier
	ds_read_b128 v[2:5], v68
	ds_read_b128 v[18:21], v68 offset:4608
	ds_read_b128 v[6:9], v1 offset:36864
	ds_read_b128 v[22:25], v1 offset:41472
	s_waitcnt vmcnt(7)
	ds_write_b128 v66, v[34:37] offset:18432
	s_waitcnt vmcnt(6)
	ds_write_b128 v66, v[38:41] offset:23040
	s_waitcnt vmcnt(5)
	ds_write_b128 v66, v[42:45] offset:27648
	s_waitcnt vmcnt(4)
	ds_write_b128 v66, v[46:49] offset:32256
	s_waitcnt vmcnt(3)
	ds_write_b128 v66, v[50:53] offset:55296
	s_waitcnt vmcnt(2)
	ds_write_b128 v66, v[54:57] offset:59904
	s_waitcnt vmcnt(1)
	ds_write_b128 v66, v[58:61] offset:64512
	s_waitcnt vmcnt(0)
	ds_write_b128 v69, v[62:65] offset:32256
	s_setprio 1
	ds_read_b128 v[86:89], v68 offset:32
	s_waitcnt lgkmcnt(10)
	v_mfma_f32_32x32x16_bf16 v[34:49], v[2:5], v[6:9], 0
	ds_read_b128 v[90:93], v1 offset:36896
	ds_read_b128 v[94:97], v1 offset:41504
	ds_read_b128 v[98:101], v68 offset:4704
	global_load_dwordx4 v[102:105], v[70:71], off offset:256
	global_load_dwordx4 v[106:109], v[74:75], off offset:256
	global_load_dwordx4 v[110:113], v[78:79], off offset:256
	global_load_dwordx4 v[114:117], v[84:85], off offset:256
	s_waitcnt lgkmcnt(12)
	v_mfma_f32_32x32x16_bf16 v[50:65], v[2:5], v[22:25], 0
	global_load_dwordx4 v[118:121], v[82:83], off offset:256
	global_load_dwordx4 v[122:125], v[80:81], off offset:256
	global_load_dwordx4 v[140:143], v[72:73], off offset:256
	global_load_dwordx4 v[144:147], v[76:77], off offset:256
	s_waitcnt lgkmcnt(2)
	v_mfma_f32_32x32x16_bf16 v[34:49], v[86:89], v[90:93], v[34:49]
	s_waitcnt lgkmcnt(1)
	v_mfma_f32_32x32x16_bf16 v[50:65], v[86:89], v[94:97], v[50:65]
	ds_read_b128 v[86:89], v68 offset:4640
	v_mfma_f32_32x32x16_bf16 v[2:17], v[18:21], v[6:9], 0
	v_mfma_f32_32x32x16_bf16 v[18:33], v[18:21], v[22:25], 0
	s_waitcnt lgkmcnt(0)
	v_mfma_f32_32x32x16_bf16 v[2:17], v[86:89], v[90:93], v[2:17]
	ds_read_b128 v[90:93], v1 offset:36928
	v_mfma_f32_32x32x16_bf16 v[18:33], v[86:89], v[94:97], v[18:33]
	ds_read_b128 v[86:89], v68 offset:64
	ds_read_b128 v[94:97], v1 offset:41536
	s_waitcnt lgkmcnt(1)
	v_mfma_f32_32x32x16_bf16 v[34:49], v[86:89], v[90:93], v[34:49]
	s_waitcnt lgkmcnt(0)
	v_mfma_f32_32x32x16_bf16 v[50:65], v[86:89], v[94:97], v[50:65]
	ds_read_b128 v[86:89], v68 offset:4672
	s_waitcnt lgkmcnt(0)
	v_mfma_f32_32x32x16_bf16 v[2:17], v[86:89], v[90:93], v[2:17]
	ds_read_b128 v[90:93], v1 offset:36960
	v_mfma_f32_32x32x16_bf16 v[18:33], v[86:89], v[94:97], v[18:33]
	ds_read_b128 v[86:89], v68 offset:96
	ds_read_b128 v[94:97], v1 offset:41568
	s_waitcnt lgkmcnt(1)
	v_mfma_f32_32x32x16_bf16 v[34:49], v[86:89], v[90:93], v[34:49]
	s_waitcnt lgkmcnt(0)
	v_mfma_f32_32x32x16_bf16 v[50:65], v[86:89], v[94:97], v[50:65]
	v_mfma_f32_32x32x16_bf16 v[2:17], v[98:101], v[90:93], v[2:17]
	v_mfma_f32_32x32x16_bf16 v[18:33], v[98:101], v[94:97], v[18:33]
	s_setprio 0
	s_barrier
; #define MFMA(a, b, c) __builtin_amdgcn_mfma_f32_32x32x16_bf16((a), (b), (c), 0, 0, 0)
; template <int TM, int TN>
; DI void gemm_mainloop(const u16* __restrict__ A, long lda, const u16* __restrict__ Bt, long ldb, int K, char* smem,
;                       f32x16 (&acc)[TM][TN]) {
;     ...
;   for (int kt = 0; kt < nk; kt++) {
;     const int buf = kt & 1;
;     const u16* cA = sA + buf * BM * LD + (wm * 32 * TM + r) * LD + h * 8;
;     const u16* cB = sB + buf * BN * LD + (wn * 32 * TN + r) * LD + h * 8;
;     bf16x8 af[TM], bfr[TN];
; #pragma unroll
;     for (int tm = 0; tm < TM; tm++) af[tm] = *(const bf16x8*)(cA + tm * 32 * LD);
; #pragma unroll
;     for (int tn = 0; tn < TN; tn++) bfr[tn] = *(const bf16x8*)(cB + tn * 32 * LD);
;     if (kt + 1 < nk) GEMM_SSTORE(buf ^ 1)
;     __builtin_amdgcn_sched_barrier(0);
;     __builtin_amdgcn_s_setprio(1);
; #pragma unroll
;     for (int tm = 0; tm < TM; tm++)
; #pragma unroll
;       for (int tn = 0; tn < TN; tn++) acc[tm][tn] = MFMA(af[tm], bfr[tn], acc[tm][tn]);
; #pragma unroll
;     for (int tm = 0; tm < TM; tm++) af[tm] = *(const bf16x8*)(cA + tm * 32 * LD + 16);
; #pragma unroll
;     for (int tn = 0; tn < TN; tn++) bfr[tn] = *(const bf16x8*)(cB + tn * 32 * LD + 16);
; #pragma unroll
;     for (int tm = 0; tm < TM; tm++)
; #pragma unroll
;       for (int tn = 0; tn < TN; tn++) acc[tm][tn] = MFMA(af[tm], bfr[tn], acc[tm][tn]);
;     __builtin_amdgcn_sched_group_barrier(0x8, 4, 0);
;     if (kt + 2 < nk) GEMM_GLOAD((kt + 2) * 64)
; #pragma unroll
;     for (int ks = 2; ks < 4; ks++) {
; #pragma unroll
;       for (int tm = 0; tm < TM; tm++) af[tm] = *(const bf16x8*)(cA + tm * 32 * LD + ks * 16);
; #pragma unroll
;       for (int tn = 0; tn < TN; tn++) bfr[tn] = *(const bf16x8*)(cB + tn * 32 * LD + ks * 16);
; #pragma unroll
;       for (int tm = 0; tm < TM; tm++)
; #pragma unroll
;         for (int tn = 0; tn < TN; tn++) acc[tm][tn] = MFMA(af[tm], bfr[tn], acc[tm][tn]);
;     }
;     __builtin_amdgcn_s_setprio(0);
;     __syncthreads();
;   }
	ds_read_b128 v[94:97], v68 offset:18432
	ds_read_b128 v[98:101], v68 offset:23040
	ds_read_b128 v[126:129], v1 offset:55296
	ds_read_b128 v[130:133], v1 offset:59904
	s_setprio 1
	ds_read_b128 v[86:89], v68 offset:18464
	s_waitcnt lgkmcnt(2)
	v_mfma_f32_32x32x16_bf16 v[34:49], v[94:97], v[126:129], v[34:49]
	ds_read_b128 v[90:93], v1 offset:55328
	s_waitcnt lgkmcnt(2)
	v_mfma_f32_32x32x16_bf16 v[50:65], v[94:97], v[130:133], v[50:65]
	ds_read_b128 v[94:97], v1 offset:59936
	s_waitcnt lgkmcnt(1)
	v_mfma_f32_32x32x16_bf16 v[34:49], v[86:89], v[90:93], v[34:49]
	s_waitcnt lgkmcnt(0)
	v_mfma_f32_32x32x16_bf16 v[50:65], v[86:89], v[94:97], v[50:65]
	s_waitcnt vmcnt(1)
	ds_write_b128 v66, v[140:143]
	ds_write_b128 v66, v[102:105] offset:4608
	global_load_dwordx4 v[140:143], v[72:73], off offset:384
	global_load_dwordx4 v[102:105], v[70:71], off offset:384
	ds_read_b128 v[86:89], v68 offset:23072
	v_mfma_f32_32x32x16_bf16 v[2:17], v[98:101], v[126:129], v[2:17]
	v_mfma_f32_32x32x16_bf16 v[18:33], v[98:101], v[130:133], v[18:33]
	ds_read_b128 v[98:101], v68 offset:23136
	s_waitcnt lgkmcnt(1)
	v_mfma_f32_32x32x16_bf16 v[2:17], v[86:89], v[90:93], v[2:17]
	ds_read_b128 v[90:93], v1 offset:55360
	v_mfma_f32_32x32x16_bf16 v[18:33], v[86:89], v[94:97], v[18:33]
	ds_write_b128 v66, v[106:109] offset:9216
	ds_write_b128 v66, v[110:113] offset:13824
	global_load_dwordx4 v[106:109], v[74:75], off offset:384
	global_load_dwordx4 v[110:113], v[78:79], off offset:384
	ds_read_b128 v[86:89], v68 offset:18496
	ds_read_b128 v[94:97], v1 offset:59968
	s_waitcnt lgkmcnt(1)
	v_mfma_f32_32x32x16_bf16 v[34:49], v[86:89], v[90:93], v[34:49]
	s_waitcnt lgkmcnt(0)
	v_mfma_f32_32x32x16_bf16 v[50:65], v[86:89], v[94:97], v[50:65]
	ds_read_b128 v[86:89], v68 offset:23104
	s_waitcnt lgkmcnt(0)
	v_mfma_f32_32x32x16_bf16 v[2:17], v[86:89], v[90:93], v[2:17]
	ds_read_b128 v[90:93], v1 offset:55392
	v_mfma_f32_32x32x16_bf16 v[18:33], v[86:89], v[94:97], v[18:33]
	s_waitcnt vmcnt(4)
	ds_write_b128 v66, v[144:147] offset:36864
	ds_write_b128 v66, v[122:125] offset:41472
	global_load_dwordx4 v[144:147], v[76:77], off offset:384
	global_load_dwordx4 v[122:125], v[80:81], off offset:384
	ds_read_b128 v[86:89], v68 offset:18528
	ds_read_b128 v[94:97], v1 offset:60000
	s_waitcnt lgkmcnt(1)
	v_mfma_f32_32x32x16_bf16 v[34:49], v[86:89], v[90:93], v[34:49]
	s_waitcnt lgkmcnt(0)
	v_mfma_f32_32x32x16_bf16 v[50:65], v[86:89], v[94:97], v[50:65]
	v_mfma_f32_32x32x16_bf16 v[2:17], v[98:101], v[90:93], v[2:17]
	v_mfma_f32_32x32x16_bf16 v[18:33], v[98:101], v[94:97], v[18:33]
	ds_write_b128 v66, v[118:121] offset:46080
	ds_write_b128 v66, v[114:117] offset:50688
	global_load_dwordx4 v[118:121], v[82:83], off offset:384
	global_load_dwordx4 v[114:117], v[84:85], off offset:384
	s_setprio 0
	s_waitcnt lgkmcnt(0)
	s_barrier
	ds_read_b128 v[94:97], v68
	ds_read_b128 v[98:101], v68 offset:4608
	ds_read_b128 v[126:129], v1 offset:36864
	ds_read_b128 v[130:133], v1 offset:41472
	s_setprio 1
	ds_read_b128 v[86:89], v68 offset:32
	s_waitcnt lgkmcnt(2)
	v_mfma_f32_32x32x16_bf16 v[34:49], v[94:97], v[126:129], v[34:49]
	ds_read_b128 v[90:93], v1 offset:36896
	s_waitcnt lgkmcnt(2)
	v_mfma_f32_32x32x16_bf16 v[50:65], v[94:97], v[130:133], v[50:65]
	ds_read_b128 v[94:97], v1 offset:41504
	s_waitcnt lgkmcnt(1)
	v_mfma_f32_32x32x16_bf16 v[34:49], v[86:89], v[90:93], v[34:49]
	s_waitcnt lgkmcnt(0)
	v_mfma_f32_32x32x16_bf16 v[50:65], v[86:89], v[94:97], v[50:65]
	s_waitcnt vmcnt(7)
	ds_write_b128 v66, v[140:143] offset:18432
	s_waitcnt vmcnt(6)
	ds_write_b128 v66, v[102:105] offset:23040
	global_load_dwordx4 v[140:143], v[72:73], off offset:512
	global_load_dwordx4 v[102:105], v[70:71], off offset:512
	ds_read_b128 v[86:89], v68 offset:4640
	v_mfma_f32_32x32x16_bf16 v[2:17], v[98:101], v[126:129], v[2:17]
	v_mfma_f32_32x32x16_bf16 v[18:33], v[98:101], v[130:133], v[18:33]
	ds_read_b128 v[98:101], v68 offset:4704
	s_waitcnt lgkmcnt(1)
	v_mfma_f32_32x32x16_bf16 v[2:17], v[86:89], v[90:93], v[2:17]
	ds_read_b128 v[90:93], v1 offset:36928
	v_mfma_f32_32x32x16_bf16 v[18:33], v[86:89], v[94:97], v[18:33]
	s_waitcnt vmcnt(7)
	ds_write_b128 v66, v[106:109] offset:27648
	s_waitcnt vmcnt(6)
	ds_write_b128 v66, v[110:113] offset:32256
	global_load_dwordx4 v[106:109], v[74:75], off offset:512
	global_load_dwordx4 v[110:113], v[78:79], off offset:512
	ds_read_b128 v[86:89], v68 offset:64
	ds_read_b128 v[94:97], v1 offset:41536
	s_waitcnt lgkmcnt(1)
	v_mfma_f32_32x32x16_bf16 v[34:49], v[86:89], v[90:93], v[34:49]
	s_waitcnt lgkmcnt(0)
	v_mfma_f32_32x32x16_bf16 v[50:65], v[86:89], v[94:97], v[50:65]
	ds_read_b128 v[86:89], v68 offset:4672
	s_waitcnt lgkmcnt(0)
	v_mfma_f32_32x32x16_bf16 v[2:17], v[86:89], v[90:93], v[2:17]
	ds_read_b128 v[90:93], v1 offset:36960
	v_mfma_f32_32x32x16_bf16 v[18:33], v[86:89], v[94:97], v[18:33]
	s_waitcnt vmcnt(7)
	ds_write_b128 v66, v[144:147] offset:55296
	s_waitcnt vmcnt(6)
	ds_write_b128 v66, v[122:125] offset:59904
	global_load_dwordx4 v[144:147], v[76:77], off offset:512
	global_load_dwordx4 v[122:125], v[80:81], off offset:512
	ds_read_b128 v[86:89], v68 offset:96
	ds_read_b128 v[94:97], v1 offset:41568
	s_waitcnt lgkmcnt(1)
	v_mfma_f32_32x32x16_bf16 v[34:49], v[86:89], v[90:93], v[34:49]
	s_waitcnt lgkmcnt(0)
	v_mfma_f32_32x32x16_bf16 v[50:65], v[86:89], v[94:97], v[50:65]
	v_mfma_f32_32x32x16_bf16 v[2:17], v[98:101], v[90:93], v[2:17]
	v_mfma_f32_32x32x16_bf16 v[18:33], v[98:101], v[94:97], v[18:33]
	s_waitcnt vmcnt(7)
	ds_write_b128 v66, v[118:121] offset:64512
	s_waitcnt vmcnt(6)
	ds_write_b128 v69, v[114:117] offset:32256
	global_load_dwordx4 v[118:121], v[82:83], off offset:512
	global_load_dwordx4 v[114:117], v[84:85], off offset:512
	s_setprio 0
	s_waitcnt lgkmcnt(0)
	s_barrier
; #define MFMA(a, b, c) __builtin_amdgcn_mfma_f32_32x32x16_bf16((a), (b), (c), 0, 0, 0)
; template <int TM, int TN>
; DI void gemm_mainloop(const u16* __restrict__ A, long lda, const u16* __restrict__ Bt, long ldb, int K, char* smem,
;                       f32x16 (&acc)[TM][TN]) {
;     ...
;   for (int kt = 0; kt < nk; kt++) {
;     const int buf = kt & 1;
;     const u16* cA = sA + buf * BM * LD + (wm * 32 * TM + r) * LD + h * 8;
;     const u16* cB = sB + buf * BN * LD + (wn * 32 * TN + r) * LD + h * 8;
;     bf16x8 af[TM], bfr[TN];
; #pragma unroll
;     for (int tm = 0; tm < TM; tm++) af[tm] = *(const bf16x8*)(cA + tm * 32 * LD);
; #pragma unroll
;     for (int tn = 0; tn < TN; tn++) bfr[tn] = *(const bf16x8*)(cB + tn * 32 * LD);
;     if (kt + 1 < nk) GEMM_SSTORE(buf ^ 1)
;     __builtin_amdgcn_sched_barrier(0);
;     __builtin_amdgcn_s_setprio(1);
; #pragma unroll
;     for (int tm = 0; tm < TM; tm++)
; #pragma unroll
;       for (int tn = 0; tn < TN; tn++) acc[tm][tn] = MFMA(af[tm], bfr[tn], acc[tm][tn]);
; #pragma unroll
;     for (int tm = 0; tm < TM; tm++) af[tm] = *(const bf16x8*)(cA + tm * 32 * LD + 16);
; #pragma unroll
;     for (int tn = 0; tn < TN; tn++) bfr[tn] = *(const bf16x8*)(cB + tn * 32 * LD + 16);
; #pragma unroll
;     for (int tm = 0; tm < TM; tm++)
; #pragma unroll
;       for (int tn = 0; tn < TN; tn++) acc[tm][tn] = MFMA(af[tm], bfr[tn], acc[tm][tn]);
;     __builtin_amdgcn_sched_group_barrier(0x8, 4, 0);
;     if (kt + 2 < nk) GEMM_GLOAD((kt + 2) * 64)
; #pragma unroll
;     for (int ks = 2; ks < 4; ks++) {
; #pragma unroll
;       for (int tm = 0; tm < TM; tm++) af[tm] = *(const bf16x8*)(cA + tm * 32 * LD + ks * 16);
; #pragma unroll
;       for (int tn = 0; tn < TN; tn++) bfr[tn] = *(const bf16x8*)(cB + tn * 32 * LD + ks * 16);
; #pragma unroll
;       for (int tm = 0; tm < TM; tm++)
; #pragma unroll
;         for (int tn = 0; tn < TN; tn++) acc[tm][tn] = MFMA(af[tm], bfr[tn], acc[tm][tn]);
;     }
;     __builtin_amdgcn_s_setprio(0);
;     __syncthreads();
;   }
	ds_read_b128 v[94:97], v68 offset:18432
	ds_read_b128 v[98:101], v68 offset:23040
	ds_read_b128 v[126:129], v1 offset:55296
	ds_read_b128 v[130:133], v1 offset:59904
	s_setprio 1
	ds_read_b128 v[86:89], v68 offset:18464
	s_waitcnt lgkmcnt(2)
	v_mfma_f32_32x32x16_bf16 v[34:49], v[94:97], v[126:129], v[34:49]
	ds_read_b128 v[90:93], v1 offset:55328
	s_waitcnt lgkmcnt(2)
	v_mfma_f32_32x32x16_bf16 v[50:65], v[94:97], v[130:133], v[50:65]
	ds_read_b128 v[94:97], v1 offset:59936
	s_waitcnt lgkmcnt(1)
	v_mfma_f32_32x32x16_bf16 v[34:49], v[86:89], v[90:93], v[34:49]
	s_waitcnt lgkmcnt(0)
	v_mfma_f32_32x32x16_bf16 v[50:65], v[86:89], v[94:97], v[50:65]
	s_waitcnt vmcnt(7)
	ds_write_b128 v66, v[140:143]
	s_waitcnt vmcnt(6)
	ds_write_b128 v66, v[102:105] offset:4608
	global_load_dwordx4 v[140:143], v[72:73], off offset:640
	global_load_dwordx4 v[102:105], v[70:71], off offset:640
	ds_read_b128 v[86:89], v68 offset:23072
	v_mfma_f32_32x32x16_bf16 v[2:17], v[98:101], v[126:129], v[2:17]
	v_mfma_f32_32x32x16_bf16 v[18:33], v[98:101], v[130:133], v[18:33]
	ds_read_b128 v[98:101], v68 offset:23136
	s_waitcnt lgkmcnt(1)
	v_mfma_f32_32x32x16_bf16 v[2:17], v[86:89], v[90:93], v[2:17]
	ds_read_b128 v[90:93], v1 offset:55360
	v_mfma_f32_32x32x16_bf16 v[18:33], v[86:89], v[94:97], v[18:33]
	s_waitcnt vmcnt(7)
	ds_write_b128 v66, v[106:109] offset:9216
	s_waitcnt vmcnt(6)
	ds_write_b128 v66, v[110:113] offset:13824
	global_load_dwordx4 v[106:109], v[74:75], off offset:640
	global_load_dwordx4 v[110:113], v[78:79], off offset:640
	ds_read_b128 v[86:89], v68 offset:18496
	ds_read_b128 v[94:97], v1 offset:59968
	s_waitcnt lgkmcnt(1)
	v_mfma_f32_32x32x16_bf16 v[34:49], v[86:89], v[90:93], v[34:49]
	s_waitcnt lgkmcnt(0)
	v_mfma_f32_32x32x16_bf16 v[50:65], v[86:89], v[94:97], v[50:65]
	ds_read_b128 v[86:89], v68 offset:23104
	s_waitcnt lgkmcnt(0)
	v_mfma_f32_32x32x16_bf16 v[2:17], v[86:89], v[90:93], v[2:17]
	ds_read_b128 v[90:93], v1 offset:55392
	v_mfma_f32_32x32x16_bf16 v[18:33], v[86:89], v[94:97], v[18:33]
	s_waitcnt vmcnt(7)
	ds_write_b128 v66, v[144:147] offset:36864
	s_waitcnt vmcnt(6)
	ds_write_b128 v66, v[122:125] offset:41472
	global_load_dwordx4 v[144:147], v[76:77], off offset:640
	global_load_dwordx4 v[122:125], v[80:81], off offset:640
	ds_read_b128 v[86:89], v68 offset:18528
	ds_read_b128 v[94:97], v1 offset:60000
	s_waitcnt lgkmcnt(1)
	v_mfma_f32_32x32x16_bf16 v[34:49], v[86:89], v[90:93], v[34:49]
	s_waitcnt lgkmcnt(0)
	v_mfma_f32_32x32x16_bf16 v[50:65], v[86:89], v[94:97], v[50:65]
	v_mfma_f32_32x32x16_bf16 v[2:17], v[98:101], v[90:93], v[2:17]
	v_mfma_f32_32x32x16_bf16 v[18:33], v[98:101], v[94:97], v[18:33]
	s_waitcnt vmcnt(7)
	ds_write_b128 v66, v[118:121] offset:46080
	s_waitcnt vmcnt(6)
	ds_write_b128 v66, v[114:117] offset:50688
	global_load_dwordx4 v[118:121], v[82:83], off offset:640
	global_load_dwordx4 v[114:117], v[84:85], off offset:640
	s_setprio 0
	s_waitcnt lgkmcnt(0)
	s_barrier
	ds_read_b128 v[94:97], v68
	ds_read_b128 v[98:101], v68 offset:4608
	ds_read_b128 v[126:129], v1 offset:36864
	ds_read_b128 v[130:133], v1 offset:41472
	s_setprio 1
	ds_read_b128 v[86:89], v68 offset:32
	s_waitcnt lgkmcnt(2)
	v_mfma_f32_32x32x16_bf16 v[34:49], v[94:97], v[126:129], v[34:49]
	ds_read_b128 v[90:93], v1 offset:36896
	s_waitcnt lgkmcnt(2)
	v_mfma_f32_32x32x16_bf16 v[50:65], v[94:97], v[130:133], v[50:65]
	ds_read_b128 v[94:97], v1 offset:41504
	s_waitcnt lgkmcnt(1)
	v_mfma_f32_32x32x16_bf16 v[34:49], v[86:89], v[90:93], v[34:49]
	s_waitcnt lgkmcnt(0)
	v_mfma_f32_32x32x16_bf16 v[50:65], v[86:89], v[94:97], v[50:65]
	s_waitcnt vmcnt(7)
	ds_write_b128 v66, v[140:143] offset:18432
	s_waitcnt vmcnt(6)
	ds_write_b128 v66, v[102:105] offset:23040
	global_load_dwordx4 v[140:143], v[72:73], off offset:768
	global_load_dwordx4 v[102:105], v[70:71], off offset:768
	ds_read_b128 v[86:89], v68 offset:4640
	v_mfma_f32_32x32x16_bf16 v[2:17], v[98:101], v[126:129], v[2:17]
	v_mfma_f32_32x32x16_bf16 v[18:33], v[98:101], v[130:133], v[18:33]
	ds_read_b128 v[98:101], v68 offset:4704
	s_waitcnt lgkmcnt(1)
	v_mfma_f32_32x32x16_bf16 v[2:17], v[86:89], v[90:93], v[2:17]
	ds_read_b128 v[90:93], v1 offset:36928
	v_mfma_f32_32x32x16_bf16 v[18:33], v[86:89], v[94:97], v[18:33]
	s_waitcnt vmcnt(7)
	ds_write_b128 v66, v[106:109] offset:27648
	s_waitcnt vmcnt(6)
	ds_write_b128 v66, v[110:113] offset:32256
	global_load_dwordx4 v[106:109], v[74:75], off offset:768
	global_load_dwordx4 v[110:113], v[78:79], off offset:768
	ds_read_b128 v[86:89], v68 offset:64
	ds_read_b128 v[94:97], v1 offset:41536
	s_waitcnt lgkmcnt(1)
	v_mfma_f32_32x32x16_bf16 v[34:49], v[86:89], v[90:93], v[34:49]
	s_waitcnt lgkmcnt(0)
	v_mfma_f32_32x32x16_bf16 v[50:65], v[86:89], v[94:97], v[50:65]
	ds_read_b128 v[86:89], v68 offset:4672
	s_waitcnt lgkmcnt(0)
	v_mfma_f32_32x32x16_bf16 v[2:17], v[86:89], v[90:93], v[2:17]
	ds_read_b128 v[90:93], v1 offset:36960
	v_mfma_f32_32x32x16_bf16 v[18:33], v[86:89], v[94:97], v[18:33]
	s_waitcnt vmcnt(7)
	ds_write_b128 v66, v[144:147] offset:55296
	s_waitcnt vmcnt(6)
	ds_write_b128 v66, v[122:125] offset:59904
	global_load_dwordx4 v[144:147], v[76:77], off offset:768
	global_load_dwordx4 v[122:125], v[80:81], off offset:768
	ds_read_b128 v[86:89], v68 offset:96
	ds_read_b128 v[94:97], v1 offset:41568
	s_waitcnt lgkmcnt(1)
	v_mfma_f32_32x32x16_bf16 v[34:49], v[86:89], v[90:93], v[34:49]
	s_waitcnt lgkmcnt(0)
	v_mfma_f32_32x32x16_bf16 v[50:65], v[86:89], v[94:97], v[50:65]
	v_mfma_f32_32x32x16_bf16 v[2:17], v[98:101], v[90:93], v[2:17]
	v_mfma_f32_32x32x16_bf16 v[18:33], v[98:101], v[94:97], v[18:33]
	s_waitcnt vmcnt(7)
	ds_write_b128 v66, v[118:121] offset:64512
	s_waitcnt vmcnt(6)
	ds_write_b128 v69, v[114:117] offset:32256
	global_load_dwordx4 v[118:121], v[82:83], off offset:768
	global_load_dwordx4 v[114:117], v[84:85], off offset:768
	s_setprio 0
	s_waitcnt lgkmcnt(0)
	s_barrier
; #define MFMA(a, b, c) __builtin_amdgcn_mfma_f32_32x32x16_bf16((a), (b), (c), 0, 0, 0)
; template <int TM, int TN>
; DI void gemm_mainloop(const u16* __restrict__ A, long lda, const u16* __restrict__ Bt, long ldb, int K, char* smem,
;                       f32x16 (&acc)[TM][TN]) {
;     ...
;   for (int kt = 0; kt < nk; kt++) {
;     const int buf = kt & 1;
;     const u16* cA = sA + buf * BM * LD + (wm * 32 * TM + r) * LD + h * 8;
;     const u16* cB = sB + buf * BN * LD + (wn * 32 * TN + r) * LD + h * 8;
;     bf16x8 af[TM], bfr[TN];
; #pragma unroll
;     for (int tm = 0; tm < TM; tm++) af[tm] = *(const bf16x8*)(cA + tm * 32 * LD);
; #pragma unroll
;     for (int tn = 0; tn < TN; tn++) bfr[tn] = *(const bf16x8*)(cB + tn * 32 * LD);
;     if (kt + 1 < nk) GEMM_SSTORE(buf ^ 1)
;     __builtin_amdgcn_sched_barrier(0);
;     __builtin_amdgcn_s_setprio(1);
; #pragma unroll
;     for (int tm = 0; tm < TM; tm++)
; #pragma unroll
;       for (int tn = 0; tn < TN; tn++) acc[tm][tn] = MFMA(af[tm], bfr[tn], acc[tm][tn]);
; #pragma unroll
;     for (int tm = 0; tm < TM; tm++) af[tm] = *(const bf16x8*)(cA + tm * 32 * LD + 16);
; #pragma unroll
;     for (int tn = 0; tn < TN; tn++) bfr[tn] = *(const bf16x8*)(cB + tn * 32 * LD + 16);
; #pragma unroll
;     for (int tm = 0; tm < TM; tm++)
; #pragma unroll
;       for (int tn = 0; tn < TN; tn++) acc[tm][tn] = MFMA(af[tm], bfr[tn], acc[tm][tn]);
;     __builtin_amdgcn_sched_group_barrier(0x8, 4, 0);
;     if (kt + 2 < nk) GEMM_GLOAD((kt + 2) * 64)
; #pragma unroll
;     for (int ks = 2; ks < 4; ks++) {
; #pragma unroll
;       for (int tm = 0; tm < TM; tm++) af[tm] = *(const bf16x8*)(cA + tm * 32 * LD + ks * 16);
; #pragma unroll
;       for (int tn = 0; tn < TN; tn++) bfr[tn] = *(const bf16x8*)(cB + tn * 32 * LD + ks * 16);
; #pragma unroll
;       for (int tm = 0; tm < TM; tm++)
; #pragma unroll
;         for (int tn = 0; tn < TN; tn++) acc[tm][tn] = MFMA(af[tm], bfr[tn], acc[tm][tn]);
;     }
;     __builtin_amdgcn_s_setprio(0);
;     __syncthreads();
;   }
	ds_read_b128 v[94:97], v68 offset:18432
	ds_read_b128 v[98:101], v68 offset:23040
	ds_read_b128 v[126:129], v1 offset:55296
	ds_read_b128 v[130:133], v1 offset:59904
	s_setprio 1
	ds_read_b128 v[86:89], v68 offset:18464
	s_waitcnt lgkmcnt(2)
	v_mfma_f32_32x32x16_bf16 v[34:49], v[94:97], v[126:129], v[34:49]
	ds_read_b128 v[90:93], v1 offset:55328
	s_waitcnt lgkmcnt(2)
	v_mfma_f32_32x32x16_bf16 v[50:65], v[94:97], v[130:133], v[50:65]
	ds_read_b128 v[94:97], v1 offset:59936
	s_waitcnt lgkmcnt(1)
	v_mfma_f32_32x32x16_bf16 v[34:49], v[86:89], v[90:93], v[34:49]
	s_waitcnt lgkmcnt(0)
	v_mfma_f32_32x32x16_bf16 v[50:65], v[86:89], v[94:97], v[50:65]
	s_waitcnt vmcnt(7)
	ds_write_b128 v66, v[140:143]
	s_waitcnt vmcnt(6)
	ds_write_b128 v66, v[102:105] offset:4608
	global_load_dwordx4 v[140:143], v[72:73], off offset:896
	global_load_dwordx4 v[102:105], v[70:71], off offset:896
	ds_read_b128 v[86:89], v68 offset:23072
	v_mfma_f32_32x32x16_bf16 v[2:17], v[98:101], v[126:129], v[2:17]
	v_mfma_f32_32x32x16_bf16 v[18:33], v[98:101], v[130:133], v[18:33]
	ds_read_b128 v[98:101], v68 offset:23136
	s_waitcnt lgkmcnt(1)
	v_mfma_f32_32x32x16_bf16 v[2:17], v[86:89], v[90:93], v[2:17]
	ds_read_b128 v[90:93], v1 offset:55360
	v_mfma_f32_32x32x16_bf16 v[18:33], v[86:89], v[94:97], v[18:33]
	s_waitcnt vmcnt(7)
	ds_write_b128 v66, v[106:109] offset:9216
	s_waitcnt vmcnt(6)
	ds_write_b128 v66, v[110:113] offset:13824
	global_load_dwordx4 v[106:109], v[74:75], off offset:896
	global_load_dwordx4 v[110:113], v[78:79], off offset:896
	ds_read_b128 v[86:89], v68 offset:18496
	ds_read_b128 v[94:97], v1 offset:59968
	s_waitcnt lgkmcnt(1)
	v_mfma_f32_32x32x16_bf16 v[34:49], v[86:89], v[90:93], v[34:49]
	s_waitcnt lgkmcnt(0)
	v_mfma_f32_32x32x16_bf16 v[50:65], v[86:89], v[94:97], v[50:65]
	ds_read_b128 v[86:89], v68 offset:23104
	s_waitcnt lgkmcnt(0)
	v_mfma_f32_32x32x16_bf16 v[2:17], v[86:89], v[90:93], v[2:17]
	ds_read_b128 v[90:93], v1 offset:55392
	v_mfma_f32_32x32x16_bf16 v[18:33], v[86:89], v[94:97], v[18:33]
	s_waitcnt vmcnt(7)
	ds_write_b128 v66, v[144:147] offset:36864
	s_waitcnt vmcnt(6)
	ds_write_b128 v66, v[122:125] offset:41472
	global_load_dwordx4 v[144:147], v[76:77], off offset:896
	global_load_dwordx4 v[122:125], v[80:81], off offset:896
	ds_read_b128 v[86:89], v68 offset:18528
	ds_read_b128 v[94:97], v1 offset:60000
	s_waitcnt lgkmcnt(1)
	v_mfma_f32_32x32x16_bf16 v[34:49], v[86:89], v[90:93], v[34:49]
	s_waitcnt lgkmcnt(0)
	v_mfma_f32_32x32x16_bf16 v[50:65], v[86:89], v[94:97], v[50:65]
	v_mfma_f32_32x32x16_bf16 v[2:17], v[98:101], v[90:93], v[2:17]
	v_mfma_f32_32x32x16_bf16 v[18:33], v[98:101], v[94:97], v[18:33]
	s_waitcnt vmcnt(7)
	ds_write_b128 v66, v[118:121] offset:46080
	s_waitcnt vmcnt(6)
	ds_write_b128 v66, v[114:117] offset:50688
	global_load_dwordx4 v[118:121], v[82:83], off offset:896
	global_load_dwordx4 v[114:117], v[84:85], off offset:896
	s_setprio 0
	s_waitcnt lgkmcnt(0)
	s_barrier
	ds_read_b128 v[94:97], v68
	ds_read_b128 v[98:101], v68 offset:4608
	ds_read_b128 v[126:129], v1 offset:36864
	ds_read_b128 v[130:133], v1 offset:41472
	s_setprio 1
	ds_read_b128 v[86:89], v68 offset:32
	s_waitcnt lgkmcnt(2)
	v_mfma_f32_32x32x16_bf16 v[34:49], v[94:97], v[126:129], v[34:49]
	ds_read_b128 v[90:93], v1 offset:36896
	s_waitcnt lgkmcnt(2)
	v_mfma_f32_32x32x16_bf16 v[50:65], v[94:97], v[130:133], v[50:65]
	ds_read_b128 v[94:97], v1 offset:41504
	s_waitcnt lgkmcnt(1)
	v_mfma_f32_32x32x16_bf16 v[34:49], v[86:89], v[90:93], v[34:49]
	s_waitcnt lgkmcnt(0)
	v_mfma_f32_32x32x16_bf16 v[50:65], v[86:89], v[94:97], v[50:65]
	s_waitcnt vmcnt(7)
	ds_write_b128 v66, v[140:143] offset:18432
	s_waitcnt vmcnt(6)
	ds_write_b128 v66, v[102:105] offset:23040
	global_load_dwordx4 v[140:143], v[72:73], off offset:1024
	global_load_dwordx4 v[102:105], v[70:71], off offset:1024
	ds_read_b128 v[86:89], v68 offset:4640
	v_mfma_f32_32x32x16_bf16 v[2:17], v[98:101], v[126:129], v[2:17]
	v_mfma_f32_32x32x16_bf16 v[18:33], v[98:101], v[130:133], v[18:33]
	ds_read_b128 v[98:101], v68 offset:4704
	s_waitcnt lgkmcnt(1)
	v_mfma_f32_32x32x16_bf16 v[2:17], v[86:89], v[90:93], v[2:17]
	ds_read_b128 v[90:93], v1 offset:36928
	v_mfma_f32_32x32x16_bf16 v[18:33], v[86:89], v[94:97], v[18:33]
	s_waitcnt vmcnt(7)
	ds_write_b128 v66, v[106:109] offset:27648
	s_waitcnt vmcnt(6)
	ds_write_b128 v66, v[110:113] offset:32256
	global_load_dwordx4 v[106:109], v[74:75], off offset:1024
	global_load_dwordx4 v[110:113], v[78:79], off offset:1024
	ds_read_b128 v[86:89], v68 offset:64
	ds_read_b128 v[94:97], v1 offset:41536
	s_waitcnt lgkmcnt(1)
	v_mfma_f32_32x32x16_bf16 v[34:49], v[86:89], v[90:93], v[34:49]
	s_waitcnt lgkmcnt(0)
	v_mfma_f32_32x32x16_bf16 v[50:65], v[86:89], v[94:97], v[50:65]
	ds_read_b128 v[86:89], v68 offset:4672
	s_waitcnt lgkmcnt(0)
	v_mfma_f32_32x32x16_bf16 v[2:17], v[86:89], v[90:93], v[2:17]
	ds_read_b128 v[90:93], v1 offset:36960
	v_mfma_f32_32x32x16_bf16 v[18:33], v[86:89], v[94:97], v[18:33]
	s_waitcnt vmcnt(7)
	ds_write_b128 v66, v[144:147] offset:55296
	s_waitcnt vmcnt(6)
	ds_write_b128 v66, v[122:125] offset:59904
	global_load_dwordx4 v[144:147], v[76:77], off offset:1024
	global_load_dwordx4 v[122:125], v[80:81], off offset:1024
	ds_read_b128 v[86:89], v68 offset:96
	ds_read_b128 v[94:97], v1 offset:41568
	s_waitcnt lgkmcnt(1)
	v_mfma_f32_32x32x16_bf16 v[34:49], v[86:89], v[90:93], v[34:49]
	s_waitcnt lgkmcnt(0)
	v_mfma_f32_32x32x16_bf16 v[50:65], v[86:89], v[94:97], v[50:65]
	v_mfma_f32_32x32x16_bf16 v[2:17], v[98:101], v[90:93], v[2:17]
	v_mfma_f32_32x32x16_bf16 v[18:33], v[98:101], v[94:97], v[18:33]
	s_waitcnt vmcnt(7)
	ds_write_b128 v66, v[118:121] offset:64512
	s_waitcnt vmcnt(6)
	ds_write_b128 v69, v[114:117] offset:32256
	global_load_dwordx4 v[118:121], v[82:83], off offset:1024
	global_load_dwordx4 v[114:117], v[84:85], off offset:1024
	s_setprio 0
	s_waitcnt lgkmcnt(0)
	s_barrier
; #define MFMA(a, b, c) __builtin_amdgcn_mfma_f32_32x32x16_bf16((a), (b), (c), 0, 0, 0)
; template <int TM, int TN>
; DI void gemm_mainloop(const u16* __restrict__ A, long lda, const u16* __restrict__ Bt, long ldb, int K, char* smem,
;                       f32x16 (&acc)[TM][TN]) {
;     ...
;   for (int kt = 0; kt < nk; kt++) {
;     const int buf = kt & 1;
;     const u16* cA = sA + buf * BM * LD + (wm * 32 * TM + r) * LD + h * 8;
;     const u16* cB = sB + buf * BN * LD + (wn * 32 * TN + r) * LD + h * 8;
;     bf16x8 af[TM], bfr[TN];
; #pragma unroll
;     for (int tm = 0; tm < TM; tm++) af[tm] = *(const bf16x8*)(cA + tm * 32 * LD);
; #pragma unroll
;     for (int tn = 0; tn < TN; tn++) bfr[tn] = *(const bf16x8*)(cB + tn * 32 * LD);
;     if (kt + 1 < nk) GEMM_SSTORE(buf ^ 1)
;     __builtin_amdgcn_sched_barrier(0);
;     __builtin_amdgcn_s_setprio(1);
; #pragma unroll
;     for (int tm = 0; tm < TM; tm++)
; #pragma unroll
;       for (int tn = 0; tn < TN; tn++) acc[tm][tn] = MFMA(af[tm], bfr[tn], acc[tm][tn]);
; #pragma unroll
;     for (int tm = 0; tm < TM; tm++) af[tm] = *(const bf16x8*)(cA + tm * 32 * LD + 16);
; #pragma unroll
;     for (int tn = 0; tn < TN; tn++) bfr[tn] = *(const bf16x8*)(cB + tn * 32 * LD + 16);
; #pragma unroll
;     for (int tm = 0; tm < TM; tm++)
; #pragma unroll
;       for (int tn = 0; tn < TN; tn++) acc[tm][tn] = MFMA(af[tm], bfr[tn], acc[tm][tn]);
;     __builtin_amdgcn_sched_group_barrier(0x8, 4, 0);
;     if (kt + 2 < nk) GEMM_GLOAD((kt + 2) * 64)
; #pragma unroll
;     for (int ks = 2; ks < 4; ks++) {
; #pragma unroll
;       for (int tm = 0; tm < TM; tm++) af[tm] = *(const bf16x8*)(cA + tm * 32 * LD + ks * 16);
; #pragma unroll
;       for (int tn = 0; tn < TN; tn++) bfr[tn] = *(const bf16x8*)(cB + tn * 32 * LD + ks * 16);
; #pragma unroll
;       for (int tm = 0; tm < TM; tm++)
; #pragma unroll
;         for (int tn = 0; tn < TN; tn++) acc[tm][tn] = MFMA(af[tm], bfr[tn], acc[tm][tn]);
;     }
;     __builtin_amdgcn_s_setprio(0);
;     __syncthreads();
;   }
	ds_read_b128 v[94:97], v68 offset:18432
	ds_read_b128 v[98:101], v68 offset:23040
	ds_read_b128 v[126:129], v1 offset:55296
	ds_read_b128 v[130:133], v1 offset:59904
	s_setprio 1
	ds_read_b128 v[86:89], v68 offset:18464
	s_waitcnt lgkmcnt(2)
	v_mfma_f32_32x32x16_bf16 v[34:49], v[94:97], v[126:129], v[34:49]
	ds_read_b128 v[90:93], v1 offset:55328
	s_waitcnt lgkmcnt(2)
	v_mfma_f32_32x32x16_bf16 v[50:65], v[94:97], v[130:133], v[50:65]
	ds_read_b128 v[94:97], v1 offset:59936
	s_waitcnt lgkmcnt(1)
	v_mfma_f32_32x32x16_bf16 v[34:49], v[86:89], v[90:93], v[34:49]
	s_waitcnt lgkmcnt(0)
	v_mfma_f32_32x32x16_bf16 v[50:65], v[86:89], v[94:97], v[50:65]
	s_waitcnt vmcnt(7)
	ds_write_b128 v66, v[140:143]
	s_waitcnt vmcnt(6)
	ds_write_b128 v66, v[102:105] offset:4608
	global_load_dwordx4 v[140:143], v[72:73], off offset:1152
	global_load_dwordx4 v[102:105], v[70:71], off offset:1152
	ds_read_b128 v[86:89], v68 offset:23072
	v_mfma_f32_32x32x16_bf16 v[2:17], v[98:101], v[126:129], v[2:17]
	v_mfma_f32_32x32x16_bf16 v[18:33], v[98:101], v[130:133], v[18:33]
	ds_read_b128 v[98:101], v68 offset:23136
	s_waitcnt lgkmcnt(1)
	v_mfma_f32_32x32x16_bf16 v[2:17], v[86:89], v[90:93], v[2:17]
	ds_read_b128 v[90:93], v1 offset:55360
	v_mfma_f32_32x32x16_bf16 v[18:33], v[86:89], v[94:97], v[18:33]
	s_waitcnt vmcnt(7)
	ds_write_b128 v66, v[106:109] offset:9216
	s_waitcnt vmcnt(6)
	ds_write_b128 v66, v[110:113] offset:13824
	global_load_dwordx4 v[106:109], v[74:75], off offset:1152
	global_load_dwordx4 v[110:113], v[78:79], off offset:1152
	ds_read_b128 v[86:89], v68 offset:18496
	ds_read_b128 v[94:97], v1 offset:59968
	s_waitcnt lgkmcnt(1)
	v_mfma_f32_32x32x16_bf16 v[34:49], v[86:89], v[90:93], v[34:49]
	s_waitcnt lgkmcnt(0)
	v_mfma_f32_32x32x16_bf16 v[50:65], v[86:89], v[94:97], v[50:65]
	ds_read_b128 v[86:89], v68 offset:23104
	s_waitcnt lgkmcnt(0)
	v_mfma_f32_32x32x16_bf16 v[2:17], v[86:89], v[90:93], v[2:17]
	ds_read_b128 v[90:93], v1 offset:55392
	v_mfma_f32_32x32x16_bf16 v[18:33], v[86:89], v[94:97], v[18:33]
	s_waitcnt vmcnt(7)
	ds_write_b128 v66, v[144:147] offset:36864
	s_waitcnt vmcnt(6)
	ds_write_b128 v66, v[122:125] offset:41472
	global_load_dwordx4 v[144:147], v[76:77], off offset:1152
	global_load_dwordx4 v[122:125], v[80:81], off offset:1152
	ds_read_b128 v[86:89], v68 offset:18528
	ds_read_b128 v[94:97], v1 offset:60000
	s_waitcnt lgkmcnt(1)
	v_mfma_f32_32x32x16_bf16 v[34:49], v[86:89], v[90:93], v[34:49]
	s_waitcnt lgkmcnt(0)
	v_mfma_f32_32x32x16_bf16 v[50:65], v[86:89], v[94:97], v[50:65]
	v_mfma_f32_32x32x16_bf16 v[2:17], v[98:101], v[90:93], v[2:17]
	v_mfma_f32_32x32x16_bf16 v[18:33], v[98:101], v[94:97], v[18:33]
	s_waitcnt vmcnt(7)
	ds_write_b128 v66, v[118:121] offset:46080
	s_waitcnt vmcnt(6)
	ds_write_b128 v66, v[114:117] offset:50688
	global_load_dwordx4 v[118:121], v[82:83], off offset:1152
	global_load_dwordx4 v[114:117], v[84:85], off offset:1152
	s_setprio 0
	s_waitcnt lgkmcnt(0)
	s_barrier
	ds_read_b128 v[94:97], v68
	ds_read_b128 v[98:101], v68 offset:4608
	ds_read_b128 v[126:129], v1 offset:36864
	ds_read_b128 v[130:133], v1 offset:41472
	s_setprio 1
	ds_read_b128 v[86:89], v68 offset:32
	s_waitcnt lgkmcnt(2)
	v_mfma_f32_32x32x16_bf16 v[34:49], v[94:97], v[126:129], v[34:49]
	ds_read_b128 v[90:93], v1 offset:36896
	s_waitcnt lgkmcnt(2)
	v_mfma_f32_32x32x16_bf16 v[50:65], v[94:97], v[130:133], v[50:65]
	ds_read_b128 v[94:97], v1 offset:41504
	s_waitcnt lgkmcnt(1)
	v_mfma_f32_32x32x16_bf16 v[34:49], v[86:89], v[90:93], v[34:49]
	s_waitcnt lgkmcnt(0)
	v_mfma_f32_32x32x16_bf16 v[50:65], v[86:89], v[94:97], v[50:65]
	s_waitcnt vmcnt(7)
	ds_write_b128 v66, v[140:143] offset:18432
	s_waitcnt vmcnt(6)
	ds_write_b128 v66, v[102:105] offset:23040
	global_load_dwordx4 v[140:143], v[72:73], off offset:1280
	global_load_dwordx4 v[102:105], v[70:71], off offset:1280
	ds_read_b128 v[86:89], v68 offset:4640
	v_mfma_f32_32x32x16_bf16 v[2:17], v[98:101], v[126:129], v[2:17]
	v_mfma_f32_32x32x16_bf16 v[18:33], v[98:101], v[130:133], v[18:33]
	ds_read_b128 v[98:101], v68 offset:4704
	s_waitcnt lgkmcnt(1)
	v_mfma_f32_32x32x16_bf16 v[2:17], v[86:89], v[90:93], v[2:17]
	ds_read_b128 v[90:93], v1 offset:36928
	v_mfma_f32_32x32x16_bf16 v[18:33], v[86:89], v[94:97], v[18:33]
	s_waitcnt vmcnt(7)
	ds_write_b128 v66, v[106:109] offset:27648
	s_waitcnt vmcnt(6)
	ds_write_b128 v66, v[110:113] offset:32256
	global_load_dwordx4 v[106:109], v[74:75], off offset:1280
	global_load_dwordx4 v[110:113], v[78:79], off offset:1280
	ds_read_b128 v[86:89], v68 offset:64
	ds_read_b128 v[94:97], v1 offset:41536
	s_waitcnt lgkmcnt(1)
	v_mfma_f32_32x32x16_bf16 v[34:49], v[86:89], v[90:93], v[34:49]
	s_waitcnt lgkmcnt(0)
	v_mfma_f32_32x32x16_bf16 v[50:65], v[86:89], v[94:97], v[50:65]
	ds_read_b128 v[86:89], v68 offset:4672
	s_waitcnt lgkmcnt(0)
	v_mfma_f32_32x32x16_bf16 v[2:17], v[86:89], v[90:93], v[2:17]
	ds_read_b128 v[90:93], v1 offset:36960
	v_mfma_f32_32x32x16_bf16 v[18:33], v[86:89], v[94:97], v[18:33]
	s_waitcnt vmcnt(7)
	ds_write_b128 v66, v[144:147] offset:55296
	s_waitcnt vmcnt(6)
	ds_write_b128 v66, v[122:125] offset:59904
	global_load_dwordx4 v[144:147], v[76:77], off offset:1280
	global_load_dwordx4 v[122:125], v[80:81], off offset:1280
	ds_read_b128 v[86:89], v68 offset:96
	ds_read_b128 v[94:97], v1 offset:41568
	s_waitcnt lgkmcnt(1)
	v_mfma_f32_32x32x16_bf16 v[34:49], v[86:89], v[90:93], v[34:49]
	s_waitcnt lgkmcnt(0)
	v_mfma_f32_32x32x16_bf16 v[50:65], v[86:89], v[94:97], v[50:65]
	v_mfma_f32_32x32x16_bf16 v[2:17], v[98:101], v[90:93], v[2:17]
	v_mfma_f32_32x32x16_bf16 v[18:33], v[98:101], v[94:97], v[18:33]
	s_waitcnt vmcnt(7)
	ds_write_b128 v66, v[118:121] offset:64512
	s_waitcnt vmcnt(6)
	ds_write_b128 v69, v[114:117] offset:32256
	global_load_dwordx4 v[118:121], v[82:83], off offset:1280
	global_load_dwordx4 v[114:117], v[84:85], off offset:1280
	s_setprio 0
	s_waitcnt lgkmcnt(0)
	s_barrier
; #define MFMA(a, b, c) __builtin_amdgcn_mfma_f32_32x32x16_bf16((a), (b), (c), 0, 0, 0)
; template <int TM, int TN>
; DI void gemm_mainloop(const u16* __restrict__ A, long lda, const u16* __restrict__ Bt, long ldb, int K, char* smem,
;                       f32x16 (&acc)[TM][TN]) {
;     ...
;   for (int kt = 0; kt < nk; kt++) {
;     const int buf = kt & 1;
;     const u16* cA = sA + buf * BM * LD + (wm * 32 * TM + r) * LD + h * 8;
;     const u16* cB = sB + buf * BN * LD + (wn * 32 * TN + r) * LD + h * 8;
;     bf16x8 af[TM], bfr[TN];
; #pragma unroll
;     for (int tm = 0; tm < TM; tm++) af[tm] = *(const bf16x8*)(cA + tm * 32 * LD);
; #pragma unroll
;     for (int tn = 0; tn < TN; tn++) bfr[tn] = *(const bf16x8*)(cB + tn * 32 * LD);
;     if (kt + 1 < nk) GEMM_SSTORE(buf ^ 1)
;     __builtin_amdgcn_sched_barrier(0);
;     __builtin_amdgcn_s_setprio(1);
; #pragma unroll
;     for (int tm = 0; tm < TM; tm++)
; #pragma unroll
;       for (int tn = 0; tn < TN; tn++) acc[tm][tn] = MFMA(af[tm], bfr[tn], acc[tm][tn]);
; #pragma unroll
;     for (int tm = 0; tm < TM; tm++) af[tm] = *(const bf16x8*)(cA + tm * 32 * LD + 16);
; #pragma unroll
;     for (int tn = 0; tn < TN; tn++) bfr[tn] = *(const bf16x8*)(cB + tn * 32 * LD + 16);
; #pragma unroll
;     for (int tm = 0; tm < TM; tm++)
; #pragma unroll
;       for (int tn = 0; tn < TN; tn++) acc[tm][tn] = MFMA(af[tm], bfr[tn], acc[tm][tn]);
;     __builtin_amdgcn_sched_group_barrier(0x8, 4, 0);
;     if (kt + 2 < nk) GEMM_GLOAD((kt + 2) * 64)
; #pragma unroll
;     for (int ks = 2; ks < 4; ks++) {
; #pragma unroll
;       for (int tm = 0; tm < TM; tm++) af[tm] = *(const bf16x8*)(cA + tm * 32 * LD + ks * 16);
; #pragma unroll
;       for (int tn = 0; tn < TN; tn++) bfr[tn] = *(const bf16x8*)(cB + tn * 32 * LD + ks * 16);
; #pragma unroll
;       for (int tm = 0; tm < TM; tm++)
; #pragma unroll
;         for (int tn = 0; tn < TN; tn++) acc[tm][tn] = MFMA(af[tm], bfr[tn], acc[tm][tn]);
;     }
;     __builtin_amdgcn_s_setprio(0);
;     __syncthreads();
;   }
	ds_read_b128 v[94:97], v68 offset:18432
	ds_read_b128 v[98:101], v68 offset:23040
	ds_read_b128 v[126:129], v1 offset:55296
	ds_read_b128 v[130:133], v1 offset:59904
	s_setprio 1
	ds_read_b128 v[86:89], v68 offset:18464
	s_waitcnt lgkmcnt(2)
	v_mfma_f32_32x32x16_bf16 v[34:49], v[94:97], v[126:129], v[34:49]
	ds_read_b128 v[90:93], v1 offset:55328
	s_waitcnt lgkmcnt(2)
	v_mfma_f32_32x32x16_bf16 v[50:65], v[94:97], v[130:133], v[50:65]
	ds_read_b128 v[94:97], v1 offset:59936
	s_waitcnt lgkmcnt(1)
	v_mfma_f32_32x32x16_bf16 v[34:49], v[86:89], v[90:93], v[34:49]
	s_waitcnt lgkmcnt(0)
	v_mfma_f32_32x32x16_bf16 v[50:65], v[86:89], v[94:97], v[50:65]
	s_waitcnt vmcnt(7)
	ds_write_b128 v66, v[140:143]
	s_waitcnt vmcnt(6)
	ds_write_b128 v66, v[102:105] offset:4608
	global_load_dwordx4 v[140:143], v[72:73], off offset:1408
	global_load_dwordx4 v[102:105], v[70:71], off offset:1408
	ds_read_b128 v[86:89], v68 offset:23072
	v_mfma_f32_32x32x16_bf16 v[2:17], v[98:101], v[126:129], v[2:17]
	v_mfma_f32_32x32x16_bf16 v[18:33], v[98:101], v[130:133], v[18:33]
	ds_read_b128 v[98:101], v68 offset:23136
	s_waitcnt lgkmcnt(1)
	v_mfma_f32_32x32x16_bf16 v[2:17], v[86:89], v[90:93], v[2:17]
	ds_read_b128 v[90:93], v1 offset:55360
	v_mfma_f32_32x32x16_bf16 v[18:33], v[86:89], v[94:97], v[18:33]
	s_waitcnt vmcnt(7)
	ds_write_b128 v66, v[106:109] offset:9216
	s_waitcnt vmcnt(6)
	ds_write_b128 v66, v[110:113] offset:13824
	global_load_dwordx4 v[106:109], v[74:75], off offset:1408
	global_load_dwordx4 v[110:113], v[78:79], off offset:1408
	ds_read_b128 v[86:89], v68 offset:18496
	ds_read_b128 v[94:97], v1 offset:59968
	s_waitcnt lgkmcnt(1)
	v_mfma_f32_32x32x16_bf16 v[34:49], v[86:89], v[90:93], v[34:49]
	s_waitcnt lgkmcnt(0)
	v_mfma_f32_32x32x16_bf16 v[50:65], v[86:89], v[94:97], v[50:65]
	ds_read_b128 v[86:89], v68 offset:23104
	s_waitcnt lgkmcnt(0)
	v_mfma_f32_32x32x16_bf16 v[2:17], v[86:89], v[90:93], v[2:17]
	ds_read_b128 v[90:93], v1 offset:55392
	v_mfma_f32_32x32x16_bf16 v[18:33], v[86:89], v[94:97], v[18:33]
	s_waitcnt vmcnt(7)
	ds_write_b128 v66, v[144:147] offset:36864
	s_waitcnt vmcnt(6)
	ds_write_b128 v66, v[122:125] offset:41472
	global_load_dwordx4 v[144:147], v[76:77], off offset:1408
	global_load_dwordx4 v[122:125], v[80:81], off offset:1408
	ds_read_b128 v[86:89], v68 offset:18528
	ds_read_b128 v[94:97], v1 offset:60000
	s_waitcnt lgkmcnt(1)
	v_mfma_f32_32x32x16_bf16 v[34:49], v[86:89], v[90:93], v[34:49]
	s_waitcnt lgkmcnt(0)
	v_mfma_f32_32x32x16_bf16 v[50:65], v[86:89], v[94:97], v[50:65]
	v_mfma_f32_32x32x16_bf16 v[2:17], v[98:101], v[90:93], v[2:17]
	v_mfma_f32_32x32x16_bf16 v[18:33], v[98:101], v[94:97], v[18:33]
	s_waitcnt vmcnt(7)
	ds_write_b128 v66, v[118:121] offset:46080
	s_waitcnt vmcnt(6)
	ds_write_b128 v66, v[114:117] offset:50688
	global_load_dwordx4 v[118:121], v[82:83], off offset:1408
	global_load_dwordx4 v[114:117], v[84:85], off offset:1408
	s_setprio 0
	s_waitcnt lgkmcnt(0)
	s_barrier
	ds_read_b128 v[94:97], v68
	ds_read_b128 v[98:101], v68 offset:4608
	ds_read_b128 v[126:129], v1 offset:36864
	ds_read_b128 v[130:133], v1 offset:41472
	s_setprio 1
	ds_read_b128 v[86:89], v68 offset:32
	s_waitcnt lgkmcnt(2)
	v_mfma_f32_32x32x16_bf16 v[34:49], v[94:97], v[126:129], v[34:49]
	ds_read_b128 v[90:93], v1 offset:36896
	s_waitcnt lgkmcnt(2)
	v_mfma_f32_32x32x16_bf16 v[50:65], v[94:97], v[130:133], v[50:65]
	ds_read_b128 v[94:97], v1 offset:41504
	s_waitcnt lgkmcnt(1)
	v_mfma_f32_32x32x16_bf16 v[34:49], v[86:89], v[90:93], v[34:49]
	s_waitcnt lgkmcnt(0)
	v_mfma_f32_32x32x16_bf16 v[50:65], v[86:89], v[94:97], v[50:65]
	s_waitcnt vmcnt(7)
	ds_write_b128 v66, v[140:143] offset:18432
	s_waitcnt vmcnt(6)
	ds_write_b128 v66, v[102:105] offset:23040
	global_load_dwordx4 v[140:143], v[72:73], off offset:1536
	global_load_dwordx4 v[102:105], v[70:71], off offset:1536
	ds_read_b128 v[86:89], v68 offset:4640
	v_mfma_f32_32x32x16_bf16 v[2:17], v[98:101], v[126:129], v[2:17]
	v_mfma_f32_32x32x16_bf16 v[18:33], v[98:101], v[130:133], v[18:33]
	ds_read_b128 v[98:101], v68 offset:4704
	s_waitcnt lgkmcnt(1)
	v_mfma_f32_32x32x16_bf16 v[2:17], v[86:89], v[90:93], v[2:17]
	ds_read_b128 v[90:93], v1 offset:36928
	v_mfma_f32_32x32x16_bf16 v[18:33], v[86:89], v[94:97], v[18:33]
	s_waitcnt vmcnt(7)
	ds_write_b128 v66, v[106:109] offset:27648
	s_waitcnt vmcnt(6)
	ds_write_b128 v66, v[110:113] offset:32256
	global_load_dwordx4 v[106:109], v[74:75], off offset:1536
	global_load_dwordx4 v[110:113], v[78:79], off offset:1536
	ds_read_b128 v[86:89], v68 offset:64
	ds_read_b128 v[94:97], v1 offset:41536
	s_waitcnt lgkmcnt(1)
	v_mfma_f32_32x32x16_bf16 v[34:49], v[86:89], v[90:93], v[34:49]
	s_waitcnt lgkmcnt(0)
	v_mfma_f32_32x32x16_bf16 v[50:65], v[86:89], v[94:97], v[50:65]
	ds_read_b128 v[86:89], v68 offset:4672
	s_waitcnt lgkmcnt(0)
	v_mfma_f32_32x32x16_bf16 v[2:17], v[86:89], v[90:93], v[2:17]
	ds_read_b128 v[90:93], v1 offset:36960
	v_mfma_f32_32x32x16_bf16 v[18:33], v[86:89], v[94:97], v[18:33]
	s_waitcnt vmcnt(7)
	ds_write_b128 v66, v[144:147] offset:55296
	s_waitcnt vmcnt(6)
	ds_write_b128 v66, v[122:125] offset:59904
	global_load_dwordx4 v[144:147], v[76:77], off offset:1536
	global_load_dwordx4 v[122:125], v[80:81], off offset:1536
	ds_read_b128 v[86:89], v68 offset:96
	ds_read_b128 v[94:97], v1 offset:41568
	s_waitcnt lgkmcnt(1)
	v_mfma_f32_32x32x16_bf16 v[34:49], v[86:89], v[90:93], v[34:49]
	s_waitcnt lgkmcnt(0)
	v_mfma_f32_32x32x16_bf16 v[50:65], v[86:89], v[94:97], v[50:65]
	v_mfma_f32_32x32x16_bf16 v[2:17], v[98:101], v[90:93], v[2:17]
	v_mfma_f32_32x32x16_bf16 v[18:33], v[98:101], v[94:97], v[18:33]
	s_waitcnt vmcnt(7)
	ds_write_b128 v66, v[118:121] offset:64512
	s_waitcnt vmcnt(6)
	ds_write_b128 v69, v[114:117] offset:32256
	global_load_dwordx4 v[118:121], v[82:83], off offset:1536
	global_load_dwordx4 v[114:117], v[84:85], off offset:1536
	s_setprio 0
	s_waitcnt lgkmcnt(0)
	s_barrier
; #define MFMA(a, b, c) __builtin_amdgcn_mfma_f32_32x32x16_bf16((a), (b), (c), 0, 0, 0)
; template <int TM, int TN>
; DI void gemm_mainloop(const u16* __restrict__ A, long lda, const u16* __restrict__ Bt, long ldb, int K, char* smem,
;                       f32x16 (&acc)[TM][TN]) {
;     ...
;   for (int kt = 0; kt < nk; kt++) {
;     const int buf = kt & 1;
;     const u16* cA = sA + buf * BM * LD + (wm * 32 * TM + r) * LD + h * 8;
;     const u16* cB = sB + buf * BN * LD + (wn * 32 * TN + r) * LD + h * 8;
;     bf16x8 af[TM], bfr[TN];
; #pragma unroll
;     for (int tm = 0; tm < TM; tm++) af[tm] = *(const bf16x8*)(cA + tm * 32 * LD);
; #pragma unroll
;     for (int tn = 0; tn < TN; tn++) bfr[tn] = *(const bf16x8*)(cB + tn * 32 * LD);
;     if (kt + 1 < nk) GEMM_SSTORE(buf ^ 1)
;     __builtin_amdgcn_sched_barrier(0);
;     __builtin_amdgcn_s_setprio(1);
; #pragma unroll
;     for (int tm = 0; tm < TM; tm++)
; #pragma unroll
;       for (int tn = 0; tn < TN; tn++) acc[tm][tn] = MFMA(af[tm], bfr[tn], acc[tm][tn]);
; #pragma unroll
;     for (int tm = 0; tm < TM; tm++) af[tm] = *(const bf16x8*)(cA + tm * 32 * LD + 16);
; #pragma unroll
;     for (int tn = 0; tn < TN; tn++) bfr[tn] = *(const bf16x8*)(cB + tn * 32 * LD + 16);
; #pragma unroll
;     for (int tm = 0; tm < TM; tm++)
; #pragma unroll
;       for (int tn = 0; tn < TN; tn++) acc[tm][tn] = MFMA(af[tm], bfr[tn], acc[tm][tn]);
;     __builtin_amdgcn_sched_group_barrier(0x8, 4, 0);
;     if (kt + 2 < nk) GEMM_GLOAD((kt + 2) * 64)
; #pragma unroll
;     for (int ks = 2; ks < 4; ks++) {
; #pragma unroll
;       for (int tm = 0; tm < TM; tm++) af[tm] = *(const bf16x8*)(cA + tm * 32 * LD + ks * 16);
; #pragma unroll
;       for (int tn = 0; tn < TN; tn++) bfr[tn] = *(const bf16x8*)(cB + tn * 32 * LD + ks * 16);
; #pragma unroll
;       for (int tm = 0; tm < TM; tm++)
; #pragma unroll
;         for (int tn = 0; tn < TN; tn++) acc[tm][tn] = MFMA(af[tm], bfr[tn], acc[tm][tn]);
;     }
;     __builtin_amdgcn_s_setprio(0);
;     __syncthreads();
;   }
	ds_read_b128 v[94:97], v68 offset:18432
	ds_read_b128 v[98:101], v68 offset:23040
	ds_read_b128 v[126:129], v1 offset:55296
	ds_read_b128 v[130:133], v1 offset:59904
	s_setprio 1
	ds_read_b128 v[86:89], v68 offset:18464
	s_waitcnt lgkmcnt(2)
	v_mfma_f32_32x32x16_bf16 v[34:49], v[94:97], v[126:129], v[34:49]
	ds_read_b128 v[90:93], v1 offset:55328
	s_waitcnt lgkmcnt(2)
	v_mfma_f32_32x32x16_bf16 v[50:65], v[94:97], v[130:133], v[50:65]
	ds_read_b128 v[94:97], v1 offset:59936
	s_waitcnt lgkmcnt(1)
	v_mfma_f32_32x32x16_bf16 v[34:49], v[86:89], v[90:93], v[34:49]
	s_waitcnt lgkmcnt(0)
	v_mfma_f32_32x32x16_bf16 v[50:65], v[86:89], v[94:97], v[50:65]
	s_waitcnt vmcnt(7)
	ds_write_b128 v66, v[140:143]
	s_waitcnt vmcnt(6)
	ds_write_b128 v66, v[102:105] offset:4608
	global_load_dwordx4 v[140:143], v[72:73], off offset:1664
	global_load_dwordx4 v[102:105], v[70:71], off offset:1664
	ds_read_b128 v[86:89], v68 offset:23072
	v_mfma_f32_32x32x16_bf16 v[2:17], v[98:101], v[126:129], v[2:17]
	v_mfma_f32_32x32x16_bf16 v[18:33], v[98:101], v[130:133], v[18:33]
	ds_read_b128 v[98:101], v68 offset:23136
	s_waitcnt lgkmcnt(1)
	v_mfma_f32_32x32x16_bf16 v[2:17], v[86:89], v[90:93], v[2:17]
	ds_read_b128 v[90:93], v1 offset:55360
	v_mfma_f32_32x32x16_bf16 v[18:33], v[86:89], v[94:97], v[18:33]
	s_waitcnt vmcnt(7)
	ds_write_b128 v66, v[106:109] offset:9216
	s_waitcnt vmcnt(6)
	ds_write_b128 v66, v[110:113] offset:13824
	global_load_dwordx4 v[106:109], v[74:75], off offset:1664
	global_load_dwordx4 v[110:113], v[78:79], off offset:1664
	ds_read_b128 v[86:89], v68 offset:18496
	ds_read_b128 v[94:97], v1 offset:59968
	s_waitcnt lgkmcnt(1)
	v_mfma_f32_32x32x16_bf16 v[34:49], v[86:89], v[90:93], v[34:49]
	s_waitcnt lgkmcnt(0)
	v_mfma_f32_32x32x16_bf16 v[50:65], v[86:89], v[94:97], v[50:65]
	ds_read_b128 v[86:89], v68 offset:23104
	s_waitcnt lgkmcnt(0)
	v_mfma_f32_32x32x16_bf16 v[2:17], v[86:89], v[90:93], v[2:17]
	ds_read_b128 v[90:93], v1 offset:55392
	v_mfma_f32_32x32x16_bf16 v[18:33], v[86:89], v[94:97], v[18:33]
	s_waitcnt vmcnt(7)
	ds_write_b128 v66, v[144:147] offset:36864
	s_waitcnt vmcnt(6)
	ds_write_b128 v66, v[122:125] offset:41472
	global_load_dwordx4 v[144:147], v[76:77], off offset:1664
	global_load_dwordx4 v[122:125], v[80:81], off offset:1664
	ds_read_b128 v[86:89], v68 offset:18528
	ds_read_b128 v[94:97], v1 offset:60000
	s_waitcnt lgkmcnt(1)
	v_mfma_f32_32x32x16_bf16 v[34:49], v[86:89], v[90:93], v[34:49]
	s_waitcnt lgkmcnt(0)
	v_mfma_f32_32x32x16_bf16 v[50:65], v[86:89], v[94:97], v[50:65]
	v_mfma_f32_32x32x16_bf16 v[2:17], v[98:101], v[90:93], v[2:17]
	v_mfma_f32_32x32x16_bf16 v[18:33], v[98:101], v[94:97], v[18:33]
	s_waitcnt vmcnt(7)
	ds_write_b128 v66, v[118:121] offset:46080
	s_waitcnt vmcnt(6)
	ds_write_b128 v66, v[114:117] offset:50688
	global_load_dwordx4 v[118:121], v[82:83], off offset:1664
	global_load_dwordx4 v[114:117], v[84:85], off offset:1664
	s_setprio 0
	s_waitcnt lgkmcnt(0)
	s_barrier
	ds_read_b128 v[94:97], v68
	ds_read_b128 v[98:101], v68 offset:4608
	ds_read_b128 v[126:129], v1 offset:36864
	ds_read_b128 v[130:133], v1 offset:41472
	s_setprio 1
	ds_read_b128 v[86:89], v68 offset:32
	s_waitcnt lgkmcnt(2)
	v_mfma_f32_32x32x16_bf16 v[34:49], v[94:97], v[126:129], v[34:49]
	ds_read_b128 v[90:93], v1 offset:36896
	s_waitcnt lgkmcnt(2)
	v_mfma_f32_32x32x16_bf16 v[50:65], v[94:97], v[130:133], v[50:65]
	ds_read_b128 v[94:97], v1 offset:41504
	s_waitcnt lgkmcnt(1)
	v_mfma_f32_32x32x16_bf16 v[34:49], v[86:89], v[90:93], v[34:49]
	s_waitcnt lgkmcnt(0)
	v_mfma_f32_32x32x16_bf16 v[50:65], v[86:89], v[94:97], v[50:65]
	s_waitcnt vmcnt(7)
	ds_write_b128 v66, v[140:143] offset:18432
	s_waitcnt vmcnt(6)
	ds_write_b128 v66, v[102:105] offset:23040
	global_load_dwordx4 v[140:143], v[72:73], off offset:1792
	global_load_dwordx4 v[102:105], v[70:71], off offset:1792
	ds_read_b128 v[86:89], v68 offset:4640
	v_mfma_f32_32x32x16_bf16 v[2:17], v[98:101], v[126:129], v[2:17]
	v_mfma_f32_32x32x16_bf16 v[18:33], v[98:101], v[130:133], v[18:33]
	ds_read_b128 v[98:101], v68 offset:4704
	s_waitcnt lgkmcnt(1)
	v_mfma_f32_32x32x16_bf16 v[2:17], v[86:89], v[90:93], v[2:17]
	ds_read_b128 v[90:93], v1 offset:36928
	v_mfma_f32_32x32x16_bf16 v[18:33], v[86:89], v[94:97], v[18:33]
	s_waitcnt vmcnt(7)
	ds_write_b128 v66, v[106:109] offset:27648
	s_waitcnt vmcnt(6)
	ds_write_b128 v66, v[110:113] offset:32256
	global_load_dwordx4 v[106:109], v[74:75], off offset:1792
	global_load_dwordx4 v[110:113], v[78:79], off offset:1792
	ds_read_b128 v[86:89], v68 offset:64
	ds_read_b128 v[94:97], v1 offset:41536
	s_waitcnt lgkmcnt(1)
	v_mfma_f32_32x32x16_bf16 v[34:49], v[86:89], v[90:93], v[34:49]
	s_waitcnt lgkmcnt(0)
	v_mfma_f32_32x32x16_bf16 v[50:65], v[86:89], v[94:97], v[50:65]
	ds_read_b128 v[86:89], v68 offset:4672
	s_waitcnt lgkmcnt(0)
	v_mfma_f32_32x32x16_bf16 v[2:17], v[86:89], v[90:93], v[2:17]
	ds_read_b128 v[90:93], v1 offset:36960
	v_mfma_f32_32x32x16_bf16 v[18:33], v[86:89], v[94:97], v[18:33]
	s_waitcnt vmcnt(7)
	ds_write_b128 v66, v[144:147] offset:55296
	s_waitcnt vmcnt(6)
	ds_write_b128 v66, v[122:125] offset:59904
	global_load_dwordx4 v[144:147], v[76:77], off offset:1792
	global_load_dwordx4 v[122:125], v[80:81], off offset:1792
	ds_read_b128 v[86:89], v68 offset:96
	ds_read_b128 v[94:97], v1 offset:41568
	s_waitcnt lgkmcnt(1)
	v_mfma_f32_32x32x16_bf16 v[34:49], v[86:89], v[90:93], v[34:49]
	s_waitcnt lgkmcnt(0)
	v_mfma_f32_32x32x16_bf16 v[50:65], v[86:89], v[94:97], v[50:65]
	v_mfma_f32_32x32x16_bf16 v[2:17], v[98:101], v[90:93], v[2:17]
	v_mfma_f32_32x32x16_bf16 v[18:33], v[98:101], v[94:97], v[18:33]
	s_waitcnt vmcnt(7)
	ds_write_b128 v66, v[118:121] offset:64512
	s_waitcnt vmcnt(6)
	ds_write_b128 v69, v[114:117] offset:32256
	global_load_dwordx4 v[118:121], v[82:83], off offset:1792
	global_load_dwordx4 v[114:117], v[84:85], off offset:1792
	s_setprio 0
	s_waitcnt lgkmcnt(0)
	s_barrier
; #define MFMA(a, b, c) __builtin_amdgcn_mfma_f32_32x32x16_bf16((a), (b), (c), 0, 0, 0)
; template <int TM, int TN>
; DI void gemm_mainloop(const u16* __restrict__ A, long lda, const u16* __restrict__ Bt, long ldb, int K, char* smem,
;                       f32x16 (&acc)[TM][TN]) {
;     ...
;   for (int kt = 0; kt < nk; kt++) {
;     const int buf = kt & 1;
;     const u16* cA = sA + buf * BM * LD + (wm * 32 * TM + r) * LD + h * 8;
;     const u16* cB = sB + buf * BN * LD + (wn * 32 * TN + r) * LD + h * 8;
;     bf16x8 af[TM], bfr[TN];
; #pragma unroll
;     for (int tm = 0; tm < TM; tm++) af[tm] = *(const bf16x8*)(cA + tm * 32 * LD);
; #pragma unroll
;     for (int tn = 0; tn < TN; tn++) bfr[tn] = *(const bf16x8*)(cB + tn * 32 * LD);
;     if (kt + 1 < nk) GEMM_SSTORE(buf ^ 1)
;     __builtin_amdgcn_sched_barrier(0);
;     __builtin_amdgcn_s_setprio(1);
; #pragma unroll
;     for (int tm = 0; tm < TM; tm++)
; #pragma unroll
;       for (int tn = 0; tn < TN; tn++) acc[tm][tn] = MFMA(af[tm], bfr[tn], acc[tm][tn]);
; #pragma unroll
;     for (int tm = 0; tm < TM; tm++) af[tm] = *(const bf16x8*)(cA + tm * 32 * LD + 16);
; #pragma unroll
;     for (int tn = 0; tn < TN; tn++) bfr[tn] = *(const bf16x8*)(cB + tn * 32 * LD + 16);
; #pragma unroll
;     for (int tm = 0; tm < TM; tm++)
; #pragma unroll
;       for (int tn = 0; tn < TN; tn++) acc[tm][tn] = MFMA(af[tm], bfr[tn], acc[tm][tn]);
;     __builtin_amdgcn_sched_group_barrier(0x8, 4, 0);
;     if (kt + 2 < nk) GEMM_GLOAD((kt + 2) * 64)
; #pragma unroll
;     for (int ks = 2; ks < 4; ks++) {
; #pragma unroll
;       for (int tm = 0; tm < TM; tm++) af[tm] = *(const bf16x8*)(cA + tm * 32 * LD + ks * 16);
; #pragma unroll
;       for (int tn = 0; tn < TN; tn++) bfr[tn] = *(const bf16x8*)(cB + tn * 32 * LD + ks * 16);
; #pragma unroll
;       for (int tm = 0; tm < TM; tm++)
; #pragma unroll
;         for (int tn = 0; tn < TN; tn++) acc[tm][tn] = MFMA(af[tm], bfr[tn], acc[tm][tn]);
;     }
;     __builtin_amdgcn_s_setprio(0);
;     __syncthreads();
;   }
	ds_read_b128 v[94:97], v68 offset:18432
	ds_read_b128 v[98:101], v68 offset:23040
	ds_read_b128 v[126:129], v1 offset:55296
	ds_read_b128 v[130:133], v1 offset:59904
	s_setprio 1
	ds_read_b128 v[86:89], v68 offset:18464
	s_waitcnt lgkmcnt(2)
	v_mfma_f32_32x32x16_bf16 v[34:49], v[94:97], v[126:129], v[34:49]
	ds_read_b128 v[90:93], v1 offset:55328
	s_waitcnt lgkmcnt(2)
	v_mfma_f32_32x32x16_bf16 v[50:65], v[94:97], v[130:133], v[50:65]
	ds_read_b128 v[94:97], v1 offset:59936
	s_waitcnt lgkmcnt(1)
	v_mfma_f32_32x32x16_bf16 v[34:49], v[86:89], v[90:93], v[34:49]
	s_waitcnt lgkmcnt(0)
	v_mfma_f32_32x32x16_bf16 v[50:65], v[86:89], v[94:97], v[50:65]
	s_waitcnt vmcnt(7)
	ds_write_b128 v66, v[140:143]
	s_waitcnt vmcnt(6)
	ds_write_b128 v66, v[102:105] offset:4608
	global_load_dwordx4 v[140:143], v[72:73], off offset:1920
	global_load_dwordx4 v[102:105], v[70:71], off offset:1920
	ds_read_b128 v[86:89], v68 offset:23072
	v_mfma_f32_32x32x16_bf16 v[2:17], v[98:101], v[126:129], v[2:17]
	v_mfma_f32_32x32x16_bf16 v[18:33], v[98:101], v[130:133], v[18:33]
	ds_read_b128 v[98:101], v68 offset:23136
	s_waitcnt lgkmcnt(1)
	v_mfma_f32_32x32x16_bf16 v[2:17], v[86:89], v[90:93], v[2:17]
	ds_read_b128 v[90:93], v1 offset:55360
	v_mfma_f32_32x32x16_bf16 v[18:33], v[86:89], v[94:97], v[18:33]
	s_waitcnt vmcnt(7)
	ds_write_b128 v66, v[106:109] offset:9216
	s_waitcnt vmcnt(6)
	ds_write_b128 v66, v[110:113] offset:13824
	global_load_dwordx4 v[106:109], v[74:75], off offset:1920
	global_load_dwordx4 v[110:113], v[78:79], off offset:1920
	ds_read_b128 v[86:89], v68 offset:18496
	ds_read_b128 v[94:97], v1 offset:59968
	s_waitcnt lgkmcnt(1)
	v_mfma_f32_32x32x16_bf16 v[34:49], v[86:89], v[90:93], v[34:49]
	s_waitcnt lgkmcnt(0)
	v_mfma_f32_32x32x16_bf16 v[50:65], v[86:89], v[94:97], v[50:65]
	ds_read_b128 v[86:89], v68 offset:23104
	s_waitcnt lgkmcnt(0)
	v_mfma_f32_32x32x16_bf16 v[2:17], v[86:89], v[90:93], v[2:17]
	ds_read_b128 v[90:93], v1 offset:55392
	v_mfma_f32_32x32x16_bf16 v[18:33], v[86:89], v[94:97], v[18:33]
	s_waitcnt vmcnt(7)
	ds_write_b128 v66, v[144:147] offset:36864
	s_waitcnt vmcnt(6)
	ds_write_b128 v66, v[122:125] offset:41472
	global_load_dwordx4 v[144:147], v[76:77], off offset:1920
	global_load_dwordx4 v[122:125], v[80:81], off offset:1920
	ds_read_b128 v[86:89], v68 offset:18528
	ds_read_b128 v[94:97], v1 offset:60000
	s_waitcnt lgkmcnt(1)
	v_mfma_f32_32x32x16_bf16 v[34:49], v[86:89], v[90:93], v[34:49]
	s_waitcnt lgkmcnt(0)
	v_mfma_f32_32x32x16_bf16 v[50:65], v[86:89], v[94:97], v[50:65]
	s_nop 0
	v_mfma_f32_32x32x16_bf16 v[2:17], v[98:101], v[90:93], v[2:17]
	v_mfma_f32_32x32x16_bf16 v[18:33], v[98:101], v[94:97], v[18:33]
	s_waitcnt vmcnt(7)
	ds_write_b128 v66, v[118:121] offset:46080
	s_waitcnt vmcnt(6)
	ds_write_b128 v66, v[114:117] offset:50688
	global_load_dwordx4 v[118:121], v[82:83], off offset:1920
	global_load_dwordx4 v[114:117], v[84:85], off offset:1920
	s_setprio 0
	s_waitcnt lgkmcnt(0)
	s_barrier
	ds_read_b128 v[74:77], v68
	ds_read_b128 v[78:81], v68 offset:4608
	ds_read_b128 v[82:85], v1 offset:36864
	ds_read_b128 v[90:93], v1 offset:41472
	s_setprio 1
	ds_read_b128 v[70:73], v68 offset:32
	s_waitcnt lgkmcnt(2)
	v_mfma_f32_32x32x16_bf16 v[34:49], v[74:77], v[82:85], v[34:49]
	s_waitcnt lgkmcnt(1)
	v_mfma_f32_32x32x16_bf16 v[50:65], v[74:77], v[90:93], v[50:65]
	ds_read_b128 v[74:77], v1 offset:36896
	v_mfma_f32_32x32x16_bf16 v[2:17], v[78:81], v[82:85], v[2:17]
	v_mfma_f32_32x32x16_bf16 v[18:33], v[78:81], v[90:93], v[18:33]
	s_waitcnt vmcnt(7)
	ds_write_b128 v66, v[140:143] offset:18432
	s_waitcnt vmcnt(6)
	ds_write_b128 v66, v[102:105] offset:23040
	ds_read_b128 v[78:81], v1 offset:41504
	s_waitcnt lgkmcnt(3)
	v_mfma_f32_32x32x16_bf16 v[34:49], v[70:73], v[74:77], v[34:49]
	s_waitcnt lgkmcnt(0)
	v_mfma_f32_32x32x16_bf16 v[50:65], v[70:73], v[78:81], v[50:65]
	ds_read_b128 v[70:73], v68 offset:4640
	s_waitcnt lgkmcnt(0)
	v_mfma_f32_32x32x16_bf16 v[2:17], v[70:73], v[74:77], v[2:17]
	ds_read_b128 v[74:77], v1 offset:36928
	v_mfma_f32_32x32x16_bf16 v[18:33], v[70:73], v[78:81], v[18:33]
	s_waitcnt vmcnt(5)
	ds_write_b128 v66, v[106:109] offset:27648
	s_waitcnt vmcnt(4)
	ds_write_b128 v66, v[110:113] offset:32256
	ds_read_b128 v[70:73], v68 offset:64
	ds_read_b128 v[78:81], v1 offset:41536
	s_waitcnt lgkmcnt(1)
	v_mfma_f32_32x32x16_bf16 v[34:49], v[70:73], v[74:77], v[34:49]
	s_waitcnt lgkmcnt(0)
	v_mfma_f32_32x32x16_bf16 v[50:65], v[70:73], v[78:81], v[50:65]
	ds_read_b128 v[70:73], v68 offset:4672
	s_waitcnt lgkmcnt(0)
	v_mfma_f32_32x32x16_bf16 v[2:17], v[70:73], v[74:77], v[2:17]
	ds_read_b128 v[74:77], v1 offset:36960
	v_mfma_f32_32x32x16_bf16 v[18:33], v[70:73], v[78:81], v[18:33]
	s_waitcnt vmcnt(3)
	ds_write_b128 v66, v[144:147] offset:55296
	s_waitcnt vmcnt(2)
	ds_write_b128 v66, v[122:125] offset:59904
	ds_read_b128 v[70:73], v68 offset:96
	ds_read_b128 v[78:81], v1 offset:41568
	s_waitcnt lgkmcnt(1)
	v_mfma_f32_32x32x16_bf16 v[34:49], v[70:73], v[74:77], v[34:49]
	s_waitcnt lgkmcnt(0)
	v_mfma_f32_32x32x16_bf16 v[50:65], v[70:73], v[78:81], v[50:65]
	ds_read_b128 v[70:73], v68 offset:4704
	s_waitcnt lgkmcnt(0)
	v_mfma_f32_32x32x16_bf16 v[2:17], v[70:73], v[74:77], v[2:17]
	v_mfma_f32_32x32x16_bf16 v[18:33], v[70:73], v[78:81], v[18:33]
	s_waitcnt vmcnt(1)
	ds_write_b128 v66, v[118:121] offset:64512
	s_waitcnt vmcnt(0)
	ds_write_b128 v69, v[114:117] offset:32256
	s_setprio 0
	s_waitcnt lgkmcnt(0)
	s_barrier
; #define MFMA(a, b, c) __builtin_amdgcn_mfma_f32_32x32x16_bf16((a), (b), (c), 0, 0, 0)
; DI int crow(int i, int h) { return (i & 3) + 8 * (i >> 2) + 4 * h; }
; template <int TM, int TN>
; DI void gemm_mainloop(const u16* __restrict__ A, long lda, const u16* __restrict__ Bt, long ldb, int K, char* smem,
;                       f32x16 (&acc)[TM][TN]) {
;     ...
;     for (int tm = 0; tm < TM; tm++)
; #pragma unroll
;       for (int tn = 0; tn < TN; tn++) acc[tm][tn] = MFMA(af[tm], bfr[tn], acc[tm][tn]);
; #pragma unroll
;     for (int tm = 0; tm < TM; tm++) af[tm] = *(const bf16x8*)(cA + tm * 32 * LD + 16);
; #pragma unroll
;     for (int tn = 0; tn < TN; tn++) bfr[tn] = *(const bf16x8*)(cB + tn * 32 * LD + 16);
; #pragma unroll
;     for (int tm = 0; tm < TM; tm++)
; #pragma unroll
;       for (int tn = 0; tn < TN; tn++) acc[tm][tn] = MFMA(af[tm], bfr[tn], acc[tm][tn]);
;     __builtin_amdgcn_sched_group_barrier(0x8, 4, 0);
;     if (kt + 2 < nk) GEMM_GLOAD((kt + 2) * 64)
; #pragma unroll
;     for (int ks = 2; ks < 4; ks++) {
; #pragma unroll
;       for (int tm = 0; tm < TM; tm++) af[tm] = *(const bf16x8*)(cA + tm * 32 * LD + ks * 16);
; #pragma unroll
;       for (int tn = 0; tn < TN; tn++) bfr[tn] = *(const bf16x8*)(cB + tn * 32 * LD + ks * 16);
; #pragma unroll
;       for (int tm = 0; tm < TM; tm++)
; #pragma unroll
;         for (int tn = 0; tn < TN; tn++) acc[tm][tn] = MFMA(af[tm], bfr[tn], acc[tm][tn]);
;     }
;     __builtin_amdgcn_s_setprio(0);
;     __syncthreads();
;   }
; template <int TM, int TN, class Epi>
; DI void gemm_tile(const u16* A, long lda, const u16* Bt, long ldb, int K, int m0, int n0, char* smem, const Epi& epi) {
;     ...
; #pragma unroll
;   for (int tm = 0; tm < TM; tm++)
; #pragma unroll
;     for (int tn = 0; tn < TN; tn++)
; #pragma unroll
;       for (int i = 0; i < 16; i++)
;         Ct[(wm * 32 * TM + tm * 32 + crow(i, h)) * LDC + wn * 32 * TN + tn * 32 + r] = acc[tm][tn][i];
;   __syncthreads();
	ds_read_b128 v[70:73], v68 offset:18432
	ds_read_b128 v[74:77], v68 offset:23040
	ds_read_b128 v[78:81], v1 offset:55296
	ds_read_b128 v[82:85], v1 offset:59904
	s_setprio 1
	s_waitcnt lgkmcnt(1)
	v_mfma_f32_32x32x16_bf16 v[34:49], v[70:73], v[78:81], v[34:49]
	s_waitcnt lgkmcnt(0)
	v_mfma_f32_32x32x16_bf16 v[50:65], v[70:73], v[82:85], v[50:65]
	ds_read_b128 v[70:73], v68 offset:18464
	v_mfma_f32_32x32x16_bf16 v[2:17], v[74:77], v[78:81], v[2:17]
	ds_read_b128 v[78:81], v1 offset:59936
	v_mfma_f32_32x32x16_bf16 v[18:33], v[74:77], v[82:85], v[18:33]
	ds_read_b128 v[74:77], v1 offset:55328
	s_waitcnt lgkmcnt(0)
	v_mfma_f32_32x32x16_bf16 v[34:49], v[70:73], v[74:77], v[34:49]
	v_mfma_f32_32x32x16_bf16 v[50:65], v[70:73], v[78:81], v[50:65]
	ds_read_b128 v[70:73], v68 offset:23072
	s_waitcnt lgkmcnt(0)
	v_mfma_f32_32x32x16_bf16 v[2:17], v[70:73], v[74:77], v[2:17]
	ds_read_b128 v[74:77], v1 offset:55360
	v_mfma_f32_32x32x16_bf16 v[18:33], v[70:73], v[78:81], v[18:33]
	ds_read_b128 v[70:73], v68 offset:18496
	ds_read_b128 v[78:81], v1 offset:59968
	s_waitcnt lgkmcnt(1)
	v_mfma_f32_32x32x16_bf16 v[34:49], v[70:73], v[74:77], v[34:49]
	s_waitcnt lgkmcnt(0)
	v_mfma_f32_32x32x16_bf16 v[50:65], v[70:73], v[78:81], v[50:65]
	ds_read_b128 v[70:73], v68 offset:23104
	s_waitcnt lgkmcnt(0)
	v_mfma_f32_32x32x16_bf16 v[2:17], v[70:73], v[74:77], v[2:17]
	ds_read_b128 v[74:77], v1 offset:55392
	v_mfma_f32_32x32x16_bf16 v[18:33], v[70:73], v[78:81], v[18:33]
	ds_read_b128 v[70:73], v68 offset:18528
	ds_read_b128 v[78:81], v1 offset:60000
	s_waitcnt lgkmcnt(1)
	v_mfma_f32_32x32x16_bf16 v[34:49], v[70:73], v[74:77], v[34:49]
	s_waitcnt lgkmcnt(0)
	v_mfma_f32_32x32x16_bf16 v[50:65], v[70:73], v[78:81], v[50:65]
	ds_read_b128 v[68:71], v68 offset:23136
	s_waitcnt lgkmcnt(0)
	v_mfma_f32_32x32x16_bf16 v[2:17], v[68:71], v[74:77], v[2:17]
	v_mfma_f32_32x32x16_bf16 v[18:33], v[68:71], v[78:81], v[18:33]
	s_setprio 0
	v_mov_b32_e32 v1, v0
	s_barrier
	s_lshl_b64 s[6:7], s[6:7], 1
	v_lshrrev_b32_e32 v66, 1, v1
	v_and_b32_e32 v66, 0xfffffc0, v66
	v_lshrrev_b32_e32 v68, 3, v1
	v_and_or_b32 v66, v68, 4, v66
	v_and_b32_e32 v68, 0x5f, v1
	v_mul_lo_u32 v66, v66, s22
	v_lshl_add_u32 v66, v68, 2, v66
	ds_write2_b32 v66, v34, v50 offset1:32
	v_add_u32_e32 v34, 0x400, v66
	ds_write2_b32 v34, v36, v52 offset0:8 offset1:40
	ds_write2_b32 v34, v37, v53 offset0:140 offset1:172
	v_add_u32_e32 v34, 0x1000, v66
	ds_write2_b32 v34, v38, v54 offset0:32 offset1:64
	ds_write2_b32 v34, v39, v55 offset0:164 offset1:196
	v_add_u32_e32 v34, 0x1400, v66
	ds_write2_b32 v34, v40, v56 offset0:40 offset1:72
	ds_write2_b32 v34, v41, v57 offset0:172 offset1:204
	v_add_u32_e32 v34, 0x2000, v66
	ds_write2_b32 v34, v42, v58 offset0:64 offset1:96
	ds_write2_b32 v34, v43, v59 offset0:196 offset1:228
	v_add_u32_e32 v34, 0x2400, v66
	ds_write2_b32 v34, v44, v60 offset0:72 offset1:104
	ds_write2_b32 v34, v45, v61 offset0:204 offset1:236
	v_add_u32_e32 v34, 0x3000, v66
	ds_write2_b32 v34, v46, v62 offset0:96 offset1:128
	v_add_u32_e32 v34, 0x3200, v66
	ds_write2_b32 v34, v47, v63 offset0:100 offset1:132
	v_add_u32_e32 v34, 0x3400, v66
	ds_write2_b32 v34, v48, v64 offset0:104 offset1:136
	v_add_u32_e32 v34, 0x3600, v66
	ds_write2_b32 v34, v49, v65 offset0:108 offset1:140
	v_add_u32_e32 v34, 0x4000, v66
	ds_write2_b32 v34, v2, v18 offset0:128 offset1:160
	v_add_u32_e32 v2, 0x4400, v66
	ds_write2_b32 v2, v3, v19 offset0:4 offset1:36
	ds_write2_b32 v2, v4, v20 offset0:136 offset1:168
	v_add_u32_e32 v2, 0x4800, v66
	ds_write2_b32 v2, v5, v21 offset0:12 offset1:44
	v_add_u32_e32 v2, 0x5000, v66
	ds_write2_b32 v2, v6, v22 offset0:160 offset1:192
	v_add_u32_e32 v2, 0x5400, v66
	ds_write2_b32 v2, v7, v23 offset0:36 offset1:68
	ds_write2_b32 v2, v8, v24 offset0:168 offset1:200
	v_add_u32_e32 v2, 0x5800, v66
	ds_write2_b32 v2, v9, v25 offset0:44 offset1:76
	v_add_u32_e32 v2, 0x6000, v66
	ds_write2_b32 v2, v10, v26 offset0:192 offset1:224
	v_add_u32_e32 v2, 0x6400, v66
	ds_write2_b32 v2, v11, v27 offset0:68 offset1:100
	ds_write2_b32 v2, v12, v28 offset0:200 offset1:232
	v_add_u32_e32 v2, 0x6800, v66
	ds_write2_b32 v2, v13, v29 offset0:76 offset1:108
	v_add_u32_e32 v2, 0x7200, v66
	ds_write2_b32 v2, v14, v30 offset0:96 offset1:128
	v_add_u32_e32 v2, 0x7400, v66
	ds_write2_b32 v2, v15, v31 offset0:100 offset1:132
	v_add_u32_e32 v2, 0x7600, v66
	ds_write2_b32 v2, v16, v32 offset0:104 offset1:136
	v_add_u32_e32 v2, 0x7800, v66
	ds_write2_b32 v2, v17, v33 offset0:108 offset1:140
	v_lshlrev_b32_e32 v2, 3, v1
	v_and_b32_e32 v3, 0x78, v2
	s_add_u32 s6, s3, s6
	ds_write2_b32 v66, v35, v51 offset0:132 offset1:164
	s_addc_u32 s7, s10, s7
	v_lshlrev_b32_e32 v66, 1, v3
	v_lshlrev_b32_e32 v2, 2, v3
	v_lshl_add_u64 v[4:5], s[6:7], 0, v[66:67]
	s_mov_b32 s6, 0
	s_waitcnt lgkmcnt(0)
	s_barrier
